# mlstm score tiles merged (shared K operand, interleaved MFMA chains); prep_gdn triangular solve rescheduled (v_mov broadcast temps folded into op_sel, chains interleaved, reads hoisted)
# baseline (speedup 1.0000x reference)
.LBB0_257:
	s_or_b64 exec, exec, s[0:1]
	v_mad_u64_u32 v[124:125], s[0:1], v22, s29, 0
	s_waitcnt lgkmcnt(0)
	v_mul_f32_e32 v0, v9, v0
	v_cmp_gt_u32_e32 vcc, v14, v10
	v_cvt_pk_bf16_f32 v0, v0, s0
	v_lshlrev_b32_e32 v20, 1, v8
	v_cndmask_b32_e64 v0, v0, 0, vcc
	v_lshl_add_u64 v[4:5], v[4:5], 0, v[20:21]
	global_store_short v[4:5], v0, off
	v_mul_f32_e32 v0, v9, v1
	v_cvt_pk_bf16_f32 v0, v0, s0
	v_cndmask_b32_e64 v4, v0, 0, vcc
	v_lshl_add_u64 v[0:1], v[2:3], 0, v[20:21]
	global_store_short v[0:1], v4, off
	v_lshlrev_b32_e32 v0, 8, v136
	ds_write2st64_b32 v11, v6, v7 offset0:152 offset1:216
	v_add_u32_e32 v140, v13, v0
	v_lshlrev_b32_e32 v126, 1, v32
	v_mad_i32_i24 v125, v37, s29, v125
	v_add_u32_e32 v25, v12, v0
	v_add_u32_e32 v20, v196, v126
	ds_read_b128 v[4:7], v140
	ds_read_b128 v[8:11], v140 offset:16
	ds_read_b128 v[36:39], v140 offset:32
	ds_read_b128 v[42:45], v140 offset:48
	ds_read_u16 v0, v20 offset:21504
	s_waitcnt lgkmcnt(4)
	v_mov_b32_e32 v112, v4
	v_lshlrev_b32_e32 v120, 16, v84
	v_pk_mul_f32 v[16:17], v[34:35], v[28:29]
	v_lshlrev_b32_e32 v121, 16, v85
	s_waitcnt lgkmcnt(0)
	v_lshlrev_b32_e32 v19, 16, v0
	ds_read_b128 v[12:15], v25
	ds_read_b128 v[46:49], v25 offset:16
	ds_read_b128 v[108:111], v25 offset:32
	ds_read_b128 v[0:3], v25 offset:48
	ds_read_u16 v4, v20 offset:21776
	v_mov_b32_e32 v84, v33
	v_mov_b32_e32 v85, v120
	s_waitcnt lgkmcnt(4)
	v_mov_b32_e32 v113, v12
	v_mov_b32_e32 v12, v5
	s_waitcnt lgkmcnt(0)
	v_lshlrev_b32_e32 v115, 16, v4
	ds_read_u16 v4, v20 offset:22048
	v_pk_mul_f32 v[84:85], v[84:85], v[30:31]
	v_mov_b32_e32 v118, v6
	v_mov_b32_e32 v32, v35
	v_pk_mul_f32 v[34:35], v[32:33], v[28:29]
	s_waitcnt lgkmcnt(0)
	v_lshlrev_b32_e32 v5, 16, v4
	v_add_f32_e32 v4, v16, v17
	v_add_f32_e32 v4, v4, v84
	v_add_f32_e32 v4, v4, v85
	v_mul_f32_e32 v6, 0xbfb8aa3b, v4
	v_exp_f32_e32 v6, v6
	v_pk_mul_f32 v[16:17], v[30:31], v[120:121]
	v_mov_b32_e32 v119, v14
	v_mov_b32_e32 v14, v7
	v_add_f32_e32 v6, 1.0, v6
	v_rcp_f32_e32 v6, v6
	v_lshlrev_b32_e32 v7, 16, v104
	v_mov_b32_e32 v84, v8
	v_mov_b32_e32 v85, v46
	v_mul_f32_e32 v18, v4, v6
	v_add_f32_e32 v4, v34, v35
	v_add_f32_e32 v4, v4, v16
	v_add_f32_e32 v4, v4, v17
	v_mul_f32_e32 v6, 0xbfb8aa3b, v4
	v_exp_f32_e32 v6, v6
	v_mov_b32_e32 v16, v28
	v_mov_b32_e32 v17, v120
	v_pk_mul_f32 v[128:129], v[18:19], v[112:113]
	v_add_f32_e32 v6, 1.0, v6
	v_rcp_f32_e32 v6, v6
	v_pk_mul_f32 v[18:19], v[28:29], v[120:121]
	v_mov_b32_e32 v46, v9
	v_lshlrev_b32_e32 v71, 16, v71
	v_mul_f32_e32 v114, v4, v6
	ds_read_u16 v4, v20 offset:22320
	v_pk_mul_f32 v[130:131], v[114:115], v[12:13]
	v_mov_b32_e32 v12, v33
	v_mov_b32_e32 v13, v29
	v_lshlrev_b32_e32 v6, 16, v99
	s_waitcnt lgkmcnt(0)
	v_lshlrev_b32_e32 v33, 16, v4
	ds_read_u16 v4, v20 offset:22592
	v_pk_mul_f32 v[12:13], v[12:13], v[16:17]
	v_pk_mov_b32 v[34:35], v[120:121], v[6:7] op_sel:[1,0]
	v_lshlrev_b32_e32 v51, 16, v51
	v_pk_mul_f32 v[104:105], v[30:31], v[34:35]
	s_waitcnt lgkmcnt(0)
	v_lshlrev_b32_e32 v17, 16, v4
	v_add_f32_e32 v4, v12, v13
	v_add_f32_e32 v4, v4, v104
	v_add_f32_e32 v4, v4, v105
	v_mul_f32_e32 v8, 0xbfb8aa3b, v4
	v_exp_f32_e32 v8, v8
	v_pk_mul_f32 v[12:13], v[28:29], v[6:7]
	v_lshlrev_b32_e32 v105, 16, v58
	v_lshlrev_b32_e32 v104, 16, v55
	v_add_f32_e32 v8, 1.0, v8
	v_rcp_f32_e32 v8, v8
	v_lshlrev_b32_e32 v113, 16, v69
	v_lshlrev_b32_e32 v112, 16, v68
	v_lshlrev_b32_e32 v115, 16, v77
	v_mul_f32_e32 v4, v4, v8
	v_pk_mul_f32 v[132:133], v[4:5], v[118:119]
	v_pk_mul_f32 v[4:5], v[30:31], v[6:7]
	v_add_f32_e32 v8, v18, v19
	v_add_f32_e32 v4, v8, v4
	v_add_f32_e32 v4, v4, v5
	v_mul_f32_e32 v5, 0xbfb8aa3b, v4
	v_exp_f32_e32 v5, v5
	ds_read_u16 v8, v20 offset:22864
	v_mov_b32_e32 v19, v48
	v_mov_b32_e32 v48, v11
	v_add_f32_e32 v5, 1.0, v5
	v_rcp_f32_e32 v5, v5
	v_mov_b32_e32 v18, v10
	v_lshlrev_b32_e32 v114, 16, v76
	v_lshlrev_b32_e32 v145, 16, v100
	v_mul_f32_e32 v32, v4, v5
	v_pk_mul_f32 v[134:135], v[32:33], v[14:15]
	v_lshlrev_b32_e32 v33, 16, v101
	v_lshlrev_b32_e32 v32, 16, v91
	v_pk_mul_f32 v[4:5], v[28:29], v[34:35]
	v_pk_mov_b32 v[6:7], v[6:7], v[32:33] op_sel:[1,0]
	v_add_f32_e32 v4, v4, v5
	v_pk_mul_f32 v[34:35], v[30:31], v[6:7]
	s_waitcnt lgkmcnt(0)
	v_lshlrev_b32_e32 v15, 16, v8
	v_add_f32_e32 v4, v4, v34
	v_add_f32_e32 v4, v4, v35
	v_mul_f32_e32 v5, 0xbfb8aa3b, v4
	v_exp_f32_e32 v5, v5
	ds_read_u16 v8, v20 offset:23136
	v_lshlrev_b32_e32 v35, 16, v93
	v_lshlrev_b32_e32 v34, 16, v88
	v_add_f32_e32 v5, 1.0, v5
	v_rcp_f32_e32 v5, v5
	s_waitcnt lgkmcnt(0)
	v_lshlrev_b32_e32 v9, 16, v8
	v_add_f32_e32 v8, v12, v13
	v_lshlrev_b32_e32 v144, 16, v98
	v_mul_f32_e32 v16, v4, v5
	v_pk_mul_f32 v[4:5], v[30:31], v[32:33]
	v_pk_mul_f32 v[148:149], v[28:29], v[144:145]
	v_add_f32_e32 v4, v8, v4
	v_add_f32_e32 v4, v4, v5
	v_mul_f32_e32 v5, 0xbfb8aa3b, v4
	v_exp_f32_e32 v5, v5
	ds_read_u16 v8, v20 offset:23408
	v_lshlrev_b32_e32 v215, 16, v143
	v_lshlrev_b32_e32 v214, 16, v142
	v_add_f32_e32 v5, 1.0, v5
	v_rcp_f32_e32 v5, v5
	s_waitcnt lgkmcnt(0)
	v_lshlrev_b32_e32 v13, 16, v8
	ds_read_u16 v8, v20 offset:23680
	v_lshlrev_b32_e32 v139, 16, v139
	v_mul_f32_e32 v14, v4, v5
	v_pk_mul_f32 v[4:5], v[28:29], v[6:7]
	v_pk_mul_f32 v[6:7], v[28:29], v[32:33]
	v_pk_mov_b32 v[32:33], v[32:33], v[34:35] op_sel:[1,0]
	v_pk_mul_f32 v[122:123], v[14:15], v[46:47]
	v_pk_mul_f32 v[46:47], v[30:31], v[32:33]
	v_add_f32_e32 v4, v4, v5
	v_add_f32_e32 v4, v4, v46
	v_add_f32_e32 v4, v4, v47
	v_mul_f32_e32 v5, 0xbfb8aa3b, v4
	v_exp_f32_e32 v5, v5
	s_waitcnt lgkmcnt(0)
	v_lshlrev_b32_e32 v11, 16, v8
	v_add_f32_e32 v6, v6, v7
	v_mov_b32_e32 v14, v36
	v_add_f32_e32 v5, 1.0, v5
	v_rcp_f32_e32 v5, v5
	v_mov_b32_e32 v15, v108
	v_mov_b32_e32 v108, v37
	v_lshlrev_b32_e32 v37, 16, v97
	v_mul_f32_e32 v8, v4, v5
	v_pk_mul_f32 v[4:5], v[30:31], v[34:35]
	v_lshlrev_b32_e32 v36, 16, v96
	v_add_f32_e32 v4, v6, v4
	v_add_f32_e32 v4, v4, v5
	v_mul_f32_e32 v5, 0xbfb8aa3b, v4
	v_exp_f32_e32 v5, v5
	v_pk_mul_f32 v[6:7], v[28:29], v[34:35]
	v_pk_mul_f32 v[186:187], v[8:9], v[18:19]
	v_add_f32_e32 v6, v6, v7
	v_add_f32_e32 v5, 1.0, v5
	v_rcp_f32_e32 v5, v5
	ds_read_u16 v8, v20 offset:23952
	v_lshlrev_b32_e32 v138, 16, v138
	v_lshl_add_u64 v[124:125], s[68:69], 0, v[124:125]
	v_mul_f32_e32 v12, v4, v5
	v_pk_mul_f32 v[184:185], v[12:13], v[48:49]
	v_pk_mul_f32 v[4:5], v[28:29], v[32:33]
	v_pk_mov_b32 v[12:13], v[34:35], v[36:37] op_sel:[1,0]
	v_add_f32_e32 v4, v4, v5
	v_pk_mul_f32 v[34:35], v[30:31], v[12:13]
	s_waitcnt lgkmcnt(0)
	v_lshlrev_b32_e32 v9, 16, v8
	v_add_f32_e32 v4, v4, v34
	v_add_f32_e32 v4, v4, v35
	v_mul_f32_e32 v5, 0xbfb8aa3b, v4
	v_exp_f32_e32 v5, v5
	ds_read_u16 v8, v20 offset:24224
	v_mov_b32_e32 v32, v38
	v_mov_b32_e32 v33, v110
	v_add_f32_e32 v5, 1.0, v5
	v_rcp_f32_e32 v5, v5
	v_mov_b32_e32 v110, v39
	v_lshlrev_b32_e32 v39, 16, v89
	v_lshlrev_b32_e32 v38, 16, v83
	v_mul_f32_e32 v10, v4, v5
	v_pk_mul_f32 v[4:5], v[30:31], v[36:37]
	s_waitcnt lgkmcnt(0)
	v_lshlrev_b32_e32 v19, 16, v8
	v_add_f32_e32 v4, v6, v4
	v_add_f32_e32 v4, v4, v5
	v_mul_f32_e32 v5, 0xbfb8aa3b, v4
	v_exp_f32_e32 v5, v5
	v_pk_mul_f32 v[6:7], v[28:29], v[36:37]
	v_pk_mov_b32 v[36:37], v[36:37], v[38:39] op_sel:[1,0]
	v_lshlrev_b32_e32 v49, 16, v81
	v_add_f32_e32 v5, 1.0, v5
	v_rcp_f32_e32 v5, v5
	v_pk_mul_f32 v[46:47], v[30:31], v[36:37]
	v_lshlrev_b32_e32 v48, 16, v78
	s_add_i32 s33, s33, s26
	v_mul_f32_e32 v8, v4, v5
	v_pk_mul_f32 v[4:5], v[28:29], v[12:13]
	v_mov_b32_e32 v13, v0
	v_add_f32_e32 v0, v4, v5
	v_add_f32_e32 v0, v0, v46
	v_add_f32_e32 v0, v0, v47
	v_mul_f32_e32 v4, 0xbfb8aa3b, v0
	v_exp_f32_e32 v4, v4
	v_pk_mul_f32 v[182:183], v[8:9], v[108:109]
	ds_read_u16 v8, v20 offset:24496
	v_mov_b32_e32 v47, v2
	v_add_f32_e32 v4, 1.0, v4
	v_rcp_f32_e32 v4, v4
	v_mov_b32_e32 v46, v44
	v_lshlrev_b32_e32 v44, 16, v70
	v_mov_b32_e32 v12, v42
	v_mul_f32_e32 v18, v0, v4
	v_pk_mul_f32 v[4:5], v[30:31], v[38:39]
	v_add_f32_e32 v0, v6, v7
	v_add_f32_e32 v0, v0, v4
	v_add_f32_e32 v0, v0, v5
	v_mul_f32_e32 v4, 0xbfb8aa3b, v0
	v_exp_f32_e32 v4, v4
	v_pk_mul_f32 v[180:181], v[18:19], v[32:33]
	v_pk_mul_f32 v[6:7], v[28:29], v[38:39]
	v_lshlrev_b32_e32 v70, 16, v67
	v_add_f32_e32 v4, 1.0, v4
	v_rcp_f32_e32 v4, v4
	s_cmpk_gt_i32 s33, 0xfff
	v_mul_f32_e32 v34, v0, v4
	ds_read_u16 v0, v20 offset:25040
	s_waitcnt lgkmcnt(1)
	v_lshlrev_b32_e32 v35, 16, v8
	v_pk_mul_f32 v[18:19], v[34:35], v[110:111]
	v_pk_mul_f32 v[4:5], v[28:29], v[36:37]
	v_pk_mov_b32 v[34:35], v[38:39], v[48:49] op_sel:[1,0]
	v_add_f32_e32 v2, v4, v5
	v_pk_mul_f32 v[36:37], v[30:31], v[34:35]
	ds_read_u16 v8, v20 offset:24768
	v_add_f32_e32 v2, v2, v36
	v_add_f32_e32 v2, v2, v37
	v_mul_f32_e32 v4, 0xbfb8aa3b, v2
	v_exp_f32_e32 v4, v4
	s_waitcnt lgkmcnt(0)
	v_lshlrev_b32_e32 v9, 16, v8
	ds_read_u16 v8, v20 offset:25312
	v_lshlrev_b32_e32 v33, 16, v0
	v_add_f32_e32 v4, 1.0, v4
	v_rcp_f32_e32 v4, v4
	v_mov_b32_e32 v0, v43
	s_waitcnt lgkmcnt(0)
	v_lshlrev_b32_e32 v43, 16, v8
	v_mul_f32_e32 v8, v2, v4
	v_pk_mul_f32 v[4:5], v[30:31], v[48:49]
	v_add_f32_e32 v2, v6, v7
	v_add_f32_e32 v2, v2, v4
	v_add_f32_e32 v2, v2, v5
	v_mul_f32_e32 v4, 0xbfb8aa3b, v2
	v_exp_f32_e32 v4, v4
	s_nop 0
	v_add_f32_e32 v4, 1.0, v4
	v_rcp_f32_e32 v4, v4
	s_nop 0
	v_mul_f32_e32 v32, v2, v4
	ds_read_u16 v2, v20 offset:25584
	v_pk_mul_f32 v[178:179], v[32:33], v[0:1]
	v_pk_mul_f32 v[0:1], v[28:29], v[34:35]
	v_pk_mul_f32 v[32:33], v[28:29], v[48:49]
	v_add_f32_e32 v0, v0, v1
	s_waitcnt lgkmcnt(0)
	v_lshlrev_b32_e32 v39, 16, v2
	v_mov_b32_e32 v2, v45
	v_lshlrev_b32_e32 v45, 16, v73
	v_pk_mov_b32 v[48:49], v[48:49], v[44:45] op_sel:[1,0]
	ds_read_b128 v[4:7], v140 offset:64
	ds_read_u16 v34, v20 offset:25856
	v_pk_mul_f32 v[88:89], v[30:31], v[48:49]
	s_waitcnt lgkmcnt(1)
	v_mov_b32_e32 v170, v4
	v_add_f32_e32 v0, v0, v88
	v_add_f32_e32 v0, v0, v89
	v_mul_f32_e32 v1, 0xbfb8aa3b, v0
	v_exp_f32_e32 v1, v1
	v_add_f32_e32 v4, v32, v33
	s_waitcnt lgkmcnt(0)
	v_lshlrev_b32_e32 v169, 16, v34
	ds_read_b128 v[34:37], v25 offset:64
	v_add_f32_e32 v1, 1.0, v1
	v_rcp_f32_e32 v1, v1
	s_nop 0
	v_mul_f32_e32 v42, v0, v1
	v_pk_mul_f32 v[0:1], v[30:31], v[44:45]
	v_pk_mul_f32 v[176:177], v[42:43], v[46:47]
	v_add_f32_e32 v0, v4, v0
	v_add_f32_e32 v0, v0, v1
	v_mul_f32_e32 v1, 0xbfb8aa3b, v0
	v_exp_f32_e32 v1, v1
	ds_read_u16 v4, v20 offset:26128
	v_lshlrev_b32_e32 v47, 16, v79
	v_lshlrev_b32_e32 v46, 16, v75
	v_add_f32_e32 v1, 1.0, v1
	v_rcp_f32_e32 v1, v1
	s_waitcnt lgkmcnt(0)
	v_lshlrev_b32_e32 v33, 16, v4
	ds_read_u16 v4, v20 offset:26400
	v_mov_b32_e32 v171, v34
	v_mul_f32_e32 v38, v0, v1
	v_pk_mul_f32 v[174:175], v[38:39], v[2:3]
	v_pk_mul_f32 v[0:1], v[28:29], v[48:49]
	v_mov_b32_e32 v34, v5
	s_waitcnt lgkmcnt(0)
	v_lshlrev_b32_e32 v39, 16, v4
	v_pk_mov_b32 v[4:5], v[44:45], v[46:47] op_sel:[1,0]
	v_pk_mul_f32 v[2:3], v[28:29], v[44:45]
	v_pk_mul_f32 v[44:45], v[30:31], v[4:5]
	v_add_f32_e32 v0, v0, v1
	v_add_f32_e32 v0, v0, v44
	v_add_f32_e32 v0, v0, v45
	v_mul_f32_e32 v1, 0xbfb8aa3b, v0
	v_exp_f32_e32 v1, v1
	v_add_f32_e32 v2, v2, v3
	v_pk_mul_f32 v[44:45], v[28:29], v[4:5]
	v_mov_b32_e32 v42, v6
	v_add_f32_e32 v1, 1.0, v1
	v_rcp_f32_e32 v1, v1
	v_mov_b32_e32 v43, v36
	v_mov_b32_e32 v36, v7
	v_pk_mul_f32 v[48:49], v[28:29], v[46:47]
	v_mul_f32_e32 v168, v0, v1
	v_pk_mul_f32 v[0:1], v[30:31], v[46:47]
	v_pk_mov_b32 v[46:47], v[46:47], v[70:71] op_sel:[1,0]
	v_add_f32_e32 v0, v2, v0
	v_add_f32_e32 v0, v0, v1
	v_mul_f32_e32 v1, 0xbfb8aa3b, v0
	v_exp_f32_e32 v1, v1
	v_pk_mul_f32 v[88:89], v[30:31], v[46:47]
	v_add_f32_e32 v1, 1.0, v1
	v_rcp_f32_e32 v1, v1
	s_nop 0
	v_mul_f32_e32 v32, v0, v1
	ds_read_u16 v0, v20 offset:26672
	v_pk_mul_f32 v[172:173], v[32:33], v[34:35]
	s_waitcnt lgkmcnt(0)
	v_lshlrev_b32_e32 v79, 16, v0
	ds_read_b128 v[0:3], v140 offset:80
	ds_read_u16 v4, v20 offset:26944
	s_waitcnt lgkmcnt(1)
	v_mov_b32_e32 v34, v0
	s_waitcnt lgkmcnt(0)
	v_lshlrev_b32_e32 v33, 16, v4
	ds_read_b128 v[4:7], v25 offset:80
	v_add_f32_e32 v0, v44, v45
	v_add_f32_e32 v0, v0, v88
	v_add_f32_e32 v0, v0, v89
	v_lshlrev_b32_e32 v89, 16, v65
	s_waitcnt lgkmcnt(0)
	v_mov_b32_e32 v35, v4
	v_mul_f32_e32 v4, 0xbfb8aa3b, v0
	v_exp_f32_e32 v4, v4
	v_lshlrev_b32_e32 v88, 16, v50
	v_lshlrev_b32_e32 v50, 16, v41
	v_add_f32_e32 v4, 1.0, v4
	v_rcp_f32_e32 v4, v4
	s_nop 0
	v_mul_f32_e32 v38, v0, v4
	v_pk_mul_f32 v[166:167], v[38:39], v[42:43]
	v_pk_mul_f32 v[38:39], v[30:31], v[70:71]
	v_add_f32_e32 v0, v48, v49
	v_add_f32_e32 v0, v0, v38
	v_add_f32_e32 v0, v0, v39
	v_mul_f32_e32 v4, 0xbfb8aa3b, v0
	v_exp_f32_e32 v4, v4
	v_pk_mul_f32 v[38:39], v[28:29], v[70:71]
	v_add_f32_e32 v4, 1.0, v4
	v_rcp_f32_e32 v4, v4
	s_nop 0
	v_mul_f32_e32 v78, v0, v4
	ds_read_u16 v0, v20 offset:27216
	v_pk_mul_f32 v[162:163], v[78:79], v[36:37]
	v_pk_mul_f32 v[36:37], v[28:29], v[46:47]
	v_mov_b32_e32 v4, v1
	v_mov_b32_e32 v78, v2
	s_waitcnt lgkmcnt(0)
	v_lshlrev_b32_e32 v43, 16, v0
	ds_read_u16 v0, v20 offset:27488
	v_add_f32_e32 v2, v36, v37
	v_mov_b32_e32 v79, v6
	v_pk_mul_f32 v[36:37], v[30:31], v[88:89]
	s_waitcnt lgkmcnt(0)
	v_lshlrev_b32_e32 v49, 16, v0
	v_pk_mov_b32 v[0:1], v[70:71], v[88:89] op_sel:[1,0]
	v_pk_mul_f32 v[70:71], v[28:29], v[88:89]
	v_pk_mul_f32 v[44:45], v[30:31], v[0:1]
	v_pk_mov_b32 v[88:89], v[88:89], v[50:51] op_sel:[1,0]
	v_add_f32_e32 v2, v2, v44
	v_add_f32_e32 v2, v2, v45
	v_mul_f32_e32 v6, 0xbfb8aa3b, v2
	v_exp_f32_e32 v6, v6
	s_nop 0
	v_add_f32_e32 v6, 1.0, v6
	v_rcp_f32_e32 v6, v6
	s_nop 0
	v_mul_f32_e32 v32, v2, v6
	v_add_f32_e32 v2, v38, v39
	v_add_f32_e32 v2, v2, v36
	v_add_f32_e32 v2, v2, v37
	v_mul_f32_e32 v6, 0xbfb8aa3b, v2
	v_exp_f32_e32 v6, v6
	s_nop 0
	v_add_f32_e32 v6, 1.0, v6
	v_rcp_f32_e32 v6, v6
	s_nop 0
	v_mul_f32_e32 v42, v2, v6
	v_pk_mul_f32 v[160:161], v[42:43], v[4:5]
	v_pk_mul_f32 v[4:5], v[28:29], v[0:1]
	ds_read_u16 v0, v20 offset:27760
	v_mov_b32_e32 v6, v3
	s_waitcnt lgkmcnt(0)
	v_lshlrev_b32_e32 v97, 16, v0
	ds_read_b128 v[0:3], v140 offset:96
	ds_read_u16 v36, v20 offset:28032
	ds_read_b128 v[44:47], v25 offset:96
	s_waitcnt lgkmcnt(2)
	v_mov_b32_e32 v42, v0
	s_waitcnt lgkmcnt(1)
	v_lshlrev_b32_e32 v39, 16, v36
	v_pk_mul_f32 v[36:37], v[30:31], v[88:89]
	v_add_f32_e32 v0, v4, v5
	v_add_f32_e32 v0, v0, v36
	v_add_f32_e32 v0, v0, v37
	v_mul_f32_e32 v4, 0xbfb8aa3b, v0
	v_exp_f32_e32 v4, v4
	s_nop 0
	v_add_f32_e32 v4, 1.0, v4
	v_rcp_f32_e32 v4, v4
	s_nop 0
	v_mul_f32_e32 v48, v0, v4
	v_pk_mul_f32 v[4:5], v[30:31], v[50:51]
	v_add_f32_e32 v0, v70, v71
	v_add_f32_e32 v0, v0, v4
	v_add_f32_e32 v0, v0, v5
	v_mul_f32_e32 v4, 0xbfb8aa3b, v0
	v_exp_f32_e32 v4, v4
	v_pk_mul_f32 v[36:37], v[48:49], v[78:79]
	v_mov_b32_e32 v78, v2
	v_add_f32_e32 v4, 1.0, v4
	v_rcp_f32_e32 v4, v4
	s_nop 0
	v_mul_f32_e32 v96, v0, v4
	ds_read_u16 v0, v20 offset:28304
	v_pk_mul_f32 v[4:5], v[28:29], v[88:89]
	v_lshlrev_b32_e32 v89, 16, v63
	v_lshlrev_b32_e32 v88, 16, v59
	s_waitcnt lgkmcnt(1)
	v_mov_b32_e32 v43, v44
	s_waitcnt lgkmcnt(0)
	v_lshlrev_b32_e32 v49, 16, v0
	ds_read_u16 v0, v20 offset:28576
	v_mov_b32_e32 v44, v1
	v_pk_mul_f32 v[40:41], v[96:97], v[6:7]
	v_pk_mul_f32 v[6:7], v[28:29], v[50:51]
	v_add_f32_e32 v2, v4, v5
	s_waitcnt lgkmcnt(0)
	v_lshlrev_b32_e32 v71, 16, v0
	v_pk_mov_b32 v[0:1], v[50:51], v[88:89] op_sel:[1,0]
	v_mov_b32_e32 v79, v46
	v_pk_mul_f32 v[50:51], v[30:31], v[0:1]
	v_mov_b32_e32 v46, v3
	v_add_f32_e32 v2, v2, v50
	v_add_f32_e32 v2, v2, v51
	v_mul_f32_e32 v4, 0xbfb8aa3b, v2
	v_exp_f32_e32 v4, v4
	v_pk_mul_f32 v[96:97], v[28:29], v[88:89]
	v_add_f32_e32 v4, 1.0, v4
	v_rcp_f32_e32 v4, v4
	s_nop 0
	v_mul_f32_e32 v38, v2, v4
	v_pk_mul_f32 v[4:5], v[30:31], v[88:89]
	v_add_f32_e32 v2, v6, v7
	v_add_f32_e32 v2, v2, v4
	v_add_f32_e32 v2, v2, v5
	v_mul_f32_e32 v4, 0xbfb8aa3b, v2
	v_exp_f32_e32 v4, v4
	v_pk_mov_b32 v[88:89], v[88:89], v[104:105] op_sel:[1,0]
	v_add_f32_e32 v4, 1.0, v4
	v_rcp_f32_e32 v4, v4
	v_pk_mul_f32 v[108:109], v[30:31], v[88:89]
	v_mul_f32_e32 v48, v2, v4
	v_pk_mul_f32 v[158:159], v[48:49], v[44:45]
	v_pk_mul_f32 v[44:45], v[28:29], v[0:1]
	ds_read_u16 v0, v20 offset:28848
	s_waitcnt lgkmcnt(0)
	v_lshlrev_b32_e32 v59, 16, v0
	ds_read_b128 v[0:3], v140 offset:112
	ds_read_u16 v4, v20 offset:29120
	s_waitcnt lgkmcnt(1)
	v_mov_b32_e32 v50, v0
	s_waitcnt lgkmcnt(0)
	v_lshlrev_b32_e32 v49, 16, v4
	ds_read_b128 v[4:7], v25 offset:112
	v_add_f32_e32 v0, v44, v45
	v_add_f32_e32 v0, v0, v108
	v_add_f32_e32 v0, v0, v109
	s_waitcnt lgkmcnt(0)
	v_mov_b32_e32 v51, v4
	v_mul_f32_e32 v4, 0xbfb8aa3b, v0
	v_exp_f32_e32 v4, v4
	s_nop 0
	v_add_f32_e32 v4, 1.0, v4
	v_rcp_f32_e32 v4, v4
	s_nop 0
	v_mul_f32_e32 v70, v0, v4
	v_pk_mul_f32 v[44:45], v[70:71], v[78:79]
	v_pk_mul_f32 v[70:71], v[30:31], v[104:105]
	v_add_f32_e32 v0, v96, v97
	v_add_f32_e32 v0, v0, v70
	v_add_f32_e32 v0, v0, v71
	v_mul_f32_e32 v4, 0xbfb8aa3b, v0
	v_exp_f32_e32 v4, v4
	v_lshlrev_b32_e32 v97, 16, v57
	v_lshlrev_b32_e32 v96, 16, v53
	v_pk_mul_f32 v[70:71], v[28:29], v[104:105]
	v_add_f32_e32 v4, 1.0, v4
	v_rcp_f32_e32 v4, v4
	s_nop 0
	v_mul_f32_e32 v58, v0, v4
	ds_read_u16 v0, v20 offset:29392
	v_pk_mul_f32 v[46:47], v[58:59], v[46:47]
	v_pk_mul_f32 v[58:59], v[28:29], v[88:89]
	v_mov_b32_e32 v4, v1
	v_mov_b32_e32 v88, v2
	s_waitcnt lgkmcnt(0)
	v_lshlrev_b32_e32 v79, 16, v0
	ds_read_u16 v0, v20 offset:29664
	v_add_f32_e32 v2, v58, v59
	v_mov_b32_e32 v89, v6
	v_pk_mul_f32 v[58:59], v[30:31], v[96:97]
	s_waitcnt lgkmcnt(0)
	v_lshlrev_b32_e32 v55, 16, v0
	v_pk_mov_b32 v[0:1], v[104:105], v[96:97] op_sel:[1,0]
	s_nop 0
	v_pk_mul_f32 v[104:105], v[30:31], v[0:1]
	s_nop 0
	v_add_f32_e32 v2, v2, v104
	v_add_f32_e32 v2, v2, v105
	v_mul_f32_e32 v6, 0xbfb8aa3b, v2
	v_exp_f32_e32 v6, v6
	v_lshlrev_b32_e32 v105, 16, v54
	v_lshlrev_b32_e32 v104, 16, v52
	v_add_f32_e32 v6, 1.0, v6
	v_rcp_f32_e32 v6, v6
	s_nop 0
	v_mul_f32_e32 v48, v2, v6
	v_add_f32_e32 v2, v70, v71
	v_add_f32_e32 v2, v2, v58
	v_add_f32_e32 v2, v2, v59
	v_mul_f32_e32 v6, 0xbfb8aa3b, v2
	v_exp_f32_e32 v6, v6
	v_pk_mul_f32 v[70:71], v[28:29], v[96:97]
	v_pk_mov_b32 v[96:97], v[96:97], v[104:105] op_sel:[1,0]
	v_add_f32_e32 v6, 1.0, v6
	v_rcp_f32_e32 v6, v6
	s_nop 0
	v_mul_f32_e32 v78, v2, v6
	v_pk_mul_f32 v[156:157], v[78:79], v[4:5]
	v_pk_mul_f32 v[4:5], v[28:29], v[0:1]
	ds_read_u16 v0, v20 offset:29936
	v_mov_b32_e32 v6, v3
	s_waitcnt lgkmcnt(0)
	v_lshlrev_b32_e32 v79, 16, v0
	ds_read_b128 v[0:3], v140 offset:128
	ds_read_u16 v53, v20 offset:30208
	ds_read_b128 v[108:111], v25 offset:128
	s_waitcnt lgkmcnt(2)
	v_mov_b32_e32 v58, v0
	s_waitcnt lgkmcnt(1)
	v_lshlrev_b32_e32 v57, 16, v53
	v_pk_mul_f32 v[52:53], v[30:31], v[96:97]
	v_add_f32_e32 v0, v4, v5
	v_add_f32_e32 v0, v0, v52
	v_add_f32_e32 v0, v0, v53
	v_mul_f32_e32 v4, 0xbfb8aa3b, v0
	v_exp_f32_e32 v4, v4
	s_nop 0
	v_add_f32_e32 v4, 1.0, v4
	v_rcp_f32_e32 v4, v4
	s_nop 0
	v_mul_f32_e32 v54, v0, v4
	v_pk_mul_f32 v[4:5], v[30:31], v[104:105]
	v_add_f32_e32 v0, v70, v71
	v_add_f32_e32 v0, v0, v4
	v_add_f32_e32 v0, v0, v5
	v_mul_f32_e32 v4, 0xbfb8aa3b, v0
	v_exp_f32_e32 v4, v4
	v_pk_mul_f32 v[52:53], v[54:55], v[88:89]
	v_lshlrev_b32_e32 v89, 16, v62
	v_lshlrev_b32_e32 v88, 16, v56
	v_add_f32_e32 v4, 1.0, v4
	v_rcp_f32_e32 v4, v4
	s_nop 0
	v_mul_f32_e32 v78, v0, v4
	ds_read_u16 v0, v20 offset:30480
	s_waitcnt lgkmcnt(1)
	v_mov_b32_e32 v59, v108
	v_pk_mul_f32 v[4:5], v[28:29], v[96:97]
	v_mov_b32_e32 v108, v1
	v_pk_mul_f32 v[54:55], v[78:79], v[6:7]
	s_waitcnt lgkmcnt(0)
	v_lshlrev_b32_e32 v63, 16, v0
	ds_read_u16 v0, v20 offset:30752
	v_mov_b32_e32 v78, v2
	v_add_f32_e32 v2, v4, v5
	v_pk_mul_f32 v[6:7], v[28:29], v[104:105]
	v_mov_b32_e32 v79, v110
	s_waitcnt lgkmcnt(0)
	v_lshlrev_b32_e32 v71, 16, v0
	v_pk_mov_b32 v[0:1], v[104:105], v[88:89] op_sel:[1,0]
	v_mov_b32_e32 v110, v3
	v_pk_mul_f32 v[96:97], v[30:31], v[0:1]
	s_nop 0
	v_add_f32_e32 v2, v2, v96
	v_add_f32_e32 v2, v2, v97
	v_mul_f32_e32 v4, 0xbfb8aa3b, v2
	v_exp_f32_e32 v4, v4
	v_pk_mul_f32 v[96:97], v[28:29], v[88:89]
	v_add_f32_e32 v4, 1.0, v4
	v_rcp_f32_e32 v4, v4
	s_nop 0
	v_mul_f32_e32 v56, v2, v4
	v_pk_mul_f32 v[4:5], v[30:31], v[88:89]
	v_add_f32_e32 v2, v6, v7
	v_add_f32_e32 v2, v2, v4
	v_add_f32_e32 v2, v2, v5
	v_mul_f32_e32 v4, 0xbfb8aa3b, v2
	v_exp_f32_e32 v4, v4
	s_nop 0
	v_add_f32_e32 v4, 1.0, v4
	v_rcp_f32_e32 v4, v4
	s_nop 0
	v_mul_f32_e32 v62, v2, v4
	v_pk_mul_f32 v[154:155], v[62:63], v[108:109]
	v_pk_mul_f32 v[62:63], v[28:29], v[0:1]
	ds_read_u16 v0, v20 offset:31024
	v_lshlrev_b32_e32 v109, 16, v61
	v_lshlrev_b32_e32 v108, 16, v60
	v_pk_mov_b32 v[88:89], v[88:89], v[108:109] op_sel:[1,0]
	s_waitcnt lgkmcnt(0)
	v_lshlrev_b32_e32 v105, 16, v0
	ds_read_b128 v[0:3], v140 offset:144
	ds_read_u16 v4, v20 offset:31296
	v_pk_mul_f32 v[60:61], v[30:31], v[88:89]
	s_waitcnt lgkmcnt(1)
	v_mov_b32_e32 v152, v0
	s_waitcnt lgkmcnt(0)
	v_lshlrev_b32_e32 v65, 16, v4
	ds_read_b128 v[4:7], v25 offset:144
	v_add_f32_e32 v0, v62, v63
	v_add_f32_e32 v0, v0, v60
	v_add_f32_e32 v0, v0, v61
	v_pk_mul_f32 v[62:63], v[30:31], v[108:109]
	s_waitcnt lgkmcnt(0)
	v_mov_b32_e32 v153, v4
	v_mul_f32_e32 v4, 0xbfb8aa3b, v0
	v_exp_f32_e32 v4, v4
	s_nop 0
	v_add_f32_e32 v4, 1.0, v4
	v_rcp_f32_e32 v4, v4
	s_nop 0
	v_mul_f32_e32 v70, v0, v4
	v_add_f32_e32 v0, v96, v97
	v_add_f32_e32 v0, v0, v62
	v_add_f32_e32 v0, v0, v63
	v_mul_f32_e32 v4, 0xbfb8aa3b, v0
	v_exp_f32_e32 v4, v4
	v_pk_mul_f32 v[60:61], v[70:71], v[78:79]
	v_pk_mul_f32 v[70:71], v[28:29], v[88:89]
	v_pk_mul_f32 v[78:79], v[28:29], v[108:109]
	v_add_f32_e32 v4, 1.0, v4
	v_rcp_f32_e32 v4, v4
	v_mov_b32_e32 v96, v2
	v_add_f32_e32 v2, v70, v71
	v_mov_b32_e32 v97, v6
	v_mul_f32_e32 v104, v0, v4
	ds_read_u16 v0, v20 offset:31568
	v_pk_mul_f32 v[62:63], v[104:105], v[110:111]
	v_lshlrev_b32_e32 v105, 16, v66
	v_lshlrev_b32_e32 v104, 16, v64
	v_mov_b32_e32 v4, v1
	s_waitcnt lgkmcnt(0)
	v_lshlrev_b32_e32 v67, 16, v0
	ds_read_u16 v0, v20 offset:31840
	v_pk_mul_f32 v[70:71], v[30:31], v[104:105]
	s_waitcnt lgkmcnt(0)
	v_lshlrev_b32_e32 v89, 16, v0
	v_pk_mov_b32 v[0:1], v[108:109], v[104:105] op_sel:[1,0]
	s_nop 0
	v_pk_mul_f32 v[108:109], v[30:31], v[0:1]
	s_nop 0
	v_add_f32_e32 v2, v2, v108
	v_add_f32_e32 v2, v2, v109
	v_mul_f32_e32 v6, 0xbfb8aa3b, v2
	v_exp_f32_e32 v6, v6
	s_nop 0
	v_add_f32_e32 v6, 1.0, v6
	v_rcp_f32_e32 v6, v6
	s_nop 0
	v_mul_f32_e32 v64, v2, v6
	v_add_f32_e32 v2, v78, v79
	v_add_f32_e32 v2, v2, v70
	v_add_f32_e32 v2, v2, v71
	v_mul_f32_e32 v6, 0xbfb8aa3b, v2
	v_exp_f32_e32 v6, v6
	v_pk_mul_f32 v[70:71], v[28:29], v[104:105]
	v_pk_mov_b32 v[104:105], v[104:105], v[112:113] op_sel:[1,0]
	v_add_f32_e32 v6, 1.0, v6
	v_rcp_f32_e32 v6, v6
	v_pk_mul_f32 v[68:69], v[30:31], v[104:105]
	v_mul_f32_e32 v66, v2, v6
	v_pk_mul_f32 v[66:67], v[66:67], v[4:5]
	v_pk_mul_f32 v[4:5], v[28:29], v[0:1]
	ds_read_u16 v0, v20 offset:32112
	v_mov_b32_e32 v6, v3
	s_waitcnt lgkmcnt(0)
	v_lshlrev_b32_e32 v79, 16, v0
	ds_read_b128 v[0:3], v140 offset:160
	ds_read_u16 v73, v20 offset:32384
	ds_read_b128 v[108:111], v25 offset:160
	s_waitcnt lgkmcnt(2)
	v_mov_b32_e32 v150, v0
	v_add_f32_e32 v0, v4, v5
	v_add_f32_e32 v0, v0, v68
	v_add_f32_e32 v0, v0, v69
	v_mul_f32_e32 v4, 0xbfb8aa3b, v0
	v_exp_f32_e32 v4, v4
	s_waitcnt lgkmcnt(1)
	v_lshlrev_b32_e32 v73, 16, v73
	v_add_f32_e32 v4, 1.0, v4
	v_rcp_f32_e32 v4, v4
	s_nop 0
	v_mul_f32_e32 v88, v0, v4
	v_pk_mul_f32 v[4:5], v[30:31], v[112:113]
	v_add_f32_e32 v0, v70, v71
	v_add_f32_e32 v0, v0, v4
	v_add_f32_e32 v0, v0, v5
	v_mul_f32_e32 v4, 0xbfb8aa3b, v0
	v_exp_f32_e32 v4, v4
	v_pk_mul_f32 v[68:69], v[88:89], v[96:97]
	v_lshlrev_b32_e32 v97, 16, v74
	v_lshlrev_b32_e32 v96, 16, v72
	v_add_f32_e32 v4, 1.0, v4
	v_rcp_f32_e32 v4, v4
	v_mov_b32_e32 v88, v2
	v_mul_f32_e32 v78, v0, v4
	ds_read_u16 v0, v20 offset:32656
	v_pk_mul_f32 v[70:71], v[78:79], v[6:7]
	v_pk_mul_f32 v[4:5], v[28:29], v[104:105]
	v_pk_mul_f32 v[6:7], v[28:29], v[112:113]
	v_add_f32_e32 v2, v4, v5
	s_waitcnt lgkmcnt(0)
	v_lshlrev_b32_e32 v75, 16, v0
	ds_read_u16 v0, v20 offset:32928
	v_mov_b32_e32 v151, v108
	v_mov_b32_e32 v108, v1
	v_mov_b32_e32 v89, v110
	v_mov_b32_e32 v110, v3
	s_waitcnt lgkmcnt(0)
	v_lshlrev_b32_e32 v79, 16, v0
	v_pk_mov_b32 v[0:1], v[112:113], v[96:97] op_sel:[1,0]
	s_nop 0
	v_pk_mul_f32 v[104:105], v[30:31], v[0:1]
	s_nop 0
	v_add_f32_e32 v2, v2, v104
	v_add_f32_e32 v2, v2, v105
	v_mul_f32_e32 v4, 0xbfb8aa3b, v2
	v_exp_f32_e32 v4, v4
	v_pk_mul_f32 v[104:105], v[28:29], v[0:1]
	ds_read_u16 v0, v20 offset:33200
	v_add_f32_e32 v4, 1.0, v4
	v_rcp_f32_e32 v4, v4
	s_waitcnt lgkmcnt(0)
	v_lshlrev_b32_e32 v113, 16, v0
	v_mul_f32_e32 v72, v2, v4
	v_pk_mul_f32 v[4:5], v[30:31], v[96:97]
	v_add_f32_e32 v2, v6, v7
	v_add_f32_e32 v2, v2, v4
	v_add_f32_e32 v2, v2, v5
	v_mul_f32_e32 v4, 0xbfb8aa3b, v2
	v_exp_f32_e32 v4, v4
	s_nop 0
	v_add_f32_e32 v4, 1.0, v4
	v_rcp_f32_e32 v4, v4
	s_nop 0
	v_mul_f32_e32 v74, v2, v4
	ds_read_b128 v[0:3], v140 offset:176
	ds_read_u16 v4, v20 offset:33472
	v_pk_mul_f32 v[74:75], v[74:75], v[108:109]
	v_pk_mul_f32 v[108:109], v[28:29], v[96:97]
	v_pk_mov_b32 v[96:97], v[96:97], v[114:115] op_sel:[1,0]
	s_waitcnt lgkmcnt(1)
	v_mov_b32_e32 v146, v0
	s_waitcnt lgkmcnt(0)
	v_lshlrev_b32_e32 v81, 16, v4
	ds_read_b128 v[4:7], v25 offset:176
	v_pk_mul_f32 v[76:77], v[30:31], v[96:97]
	v_add_f32_e32 v0, v104, v105
	v_add_f32_e32 v0, v0, v76
	v_add_f32_e32 v0, v0, v77
	s_waitcnt lgkmcnt(0)
	v_mov_b32_e32 v147, v4
	v_mul_f32_e32 v4, 0xbfb8aa3b, v0
	v_exp_f32_e32 v4, v4
	s_nop 0
	v_add_f32_e32 v4, 1.0, v4
	v_rcp_f32_e32 v4, v4
	s_nop 0
	v_mul_f32_e32 v78, v0, v4
	v_pk_mul_f32 v[76:77], v[78:79], v[88:89]
	v_pk_mul_f32 v[78:79], v[30:31], v[114:115]
	v_add_f32_e32 v0, v108, v109
	v_add_f32_e32 v0, v0, v78
	v_add_f32_e32 v0, v0, v79
	v_mul_f32_e32 v4, 0xbfb8aa3b, v0
	v_exp_f32_e32 v4, v4
	v_pk_mul_f32 v[88:89], v[28:29], v[96:97]
	v_mov_b32_e32 v108, v2
	v_add_f32_e32 v2, v88, v89
	v_add_f32_e32 v4, 1.0, v4
	v_rcp_f32_e32 v4, v4
	v_mov_b32_e32 v109, v6
	v_pk_mul_f32 v[96:97], v[28:29], v[114:115]
	v_mul_f32_e32 v112, v0, v4
	ds_read_u16 v0, v20 offset:33744
	v_pk_mul_f32 v[78:79], v[112:113], v[110:111]
	v_lshlrev_b32_e32 v111, 16, v82
	v_lshlrev_b32_e32 v110, 16, v80
	v_mov_b32_e32 v4, v1
	s_waitcnt lgkmcnt(0)
	v_lshlrev_b32_e32 v83, 16, v0
	ds_read_u16 v0, v20 offset:34016
	v_pk_mul_f32 v[88:89], v[30:31], v[110:111]
	s_waitcnt lgkmcnt(0)
	v_lshlrev_b32_e32 v105, 16, v0
	v_pk_mov_b32 v[0:1], v[114:115], v[110:111] op_sel:[1,0]
	v_lshlrev_b32_e32 v115, 16, v87
	v_pk_mul_f32 v[112:113], v[30:31], v[0:1]
	v_lshlrev_b32_e32 v114, 16, v86
	v_add_f32_e32 v2, v2, v112
	v_add_f32_e32 v2, v2, v113
	v_mul_f32_e32 v6, 0xbfb8aa3b, v2
	v_exp_f32_e32 v6, v6
	s_nop 0
	v_add_f32_e32 v6, 1.0, v6
	v_rcp_f32_e32 v6, v6
	s_nop 0
	v_mul_f32_e32 v80, v2, v6
	v_add_f32_e32 v2, v96, v97
	v_add_f32_e32 v2, v2, v88
	v_add_f32_e32 v2, v2, v89
	v_mul_f32_e32 v6, 0xbfb8aa3b, v2
	v_exp_f32_e32 v6, v6
	v_pk_mul_f32 v[88:89], v[28:29], v[110:111]
	v_pk_mov_b32 v[110:111], v[110:111], v[114:115] op_sel:[1,0]
	v_add_f32_e32 v6, 1.0, v6
	v_rcp_f32_e32 v6, v6
	v_pk_mul_f32 v[86:87], v[30:31], v[110:111]
	v_mul_f32_e32 v82, v2, v6
	v_pk_mul_f32 v[82:83], v[82:83], v[4:5]
	v_pk_mul_f32 v[4:5], v[28:29], v[0:1]
	ds_read_u16 v0, v20 offset:34288
	v_mov_b32_e32 v6, v3
	s_waitcnt lgkmcnt(0)
	v_lshlrev_b32_e32 v97, 16, v0
	ds_read_b128 v[0:3], v140 offset:192
	ds_read_u16 v91, v20 offset:34560
	ds_read_b128 v[118:121], v25 offset:192
	s_waitcnt lgkmcnt(2)
	v_mov_b32_e32 v112, v0
	v_add_f32_e32 v0, v4, v5
	v_add_f32_e32 v0, v0, v86
	v_add_f32_e32 v0, v0, v87
	v_mul_f32_e32 v4, 0xbfb8aa3b, v0
	v_exp_f32_e32 v4, v4
	s_waitcnt lgkmcnt(1)
	v_lshlrev_b32_e32 v91, 16, v91
	v_add_f32_e32 v4, 1.0, v4
	v_rcp_f32_e32 v4, v4
	s_nop 0
	v_mul_f32_e32 v104, v0, v4
	v_pk_mul_f32 v[4:5], v[30:31], v[114:115]
	v_add_f32_e32 v0, v88, v89
	v_add_f32_e32 v0, v0, v4
	v_add_f32_e32 v0, v0, v5
	v_mul_f32_e32 v4, 0xbfb8aa3b, v0
	v_exp_f32_e32 v4, v4
	v_pk_mul_f32 v[86:87], v[104:105], v[108:109]
	v_lshlrev_b32_e32 v109, 16, v92
	v_lshlrev_b32_e32 v108, 16, v90
	v_add_f32_e32 v4, 1.0, v4
	v_rcp_f32_e32 v4, v4
	v_mov_b32_e32 v104, v2
	v_mul_f32_e32 v96, v0, v4
	ds_read_u16 v0, v20 offset:34832
	s_waitcnt lgkmcnt(1)
	v_mov_b32_e32 v113, v118
	v_pk_mul_f32 v[88:89], v[96:97], v[6:7]
	v_pk_mul_f32 v[4:5], v[28:29], v[110:111]
	v_mov_b32_e32 v118, v1
	s_waitcnt lgkmcnt(0)
	v_lshlrev_b32_e32 v93, 16, v0
	ds_read_u16 v0, v20 offset:35104
	v_add_f32_e32 v2, v4, v5
	v_pk_mul_f32 v[6:7], v[28:29], v[114:115]
	v_mov_b32_e32 v105, v120
	v_mov_b32_e32 v120, v3
	s_waitcnt lgkmcnt(0)
	v_lshlrev_b32_e32 v97, 16, v0
	v_pk_mov_b32 v[0:1], v[114:115], v[108:109] op_sel:[1,0]
	s_nop 0
	v_pk_mul_f32 v[110:111], v[30:31], v[0:1]
	s_nop 0
	v_add_f32_e32 v2, v2, v110
	v_add_f32_e32 v2, v2, v111
	v_mul_f32_e32 v4, 0xbfb8aa3b, v2
	v_exp_f32_e32 v4, v4
	s_nop 0
	v_add_f32_e32 v4, 1.0, v4
	v_rcp_f32_e32 v4, v4
	s_nop 0
	v_mul_f32_e32 v90, v2, v4
	v_pk_mul_f32 v[4:5], v[30:31], v[108:109]
	v_add_f32_e32 v2, v6, v7
	v_add_f32_e32 v2, v2, v4
	v_add_f32_e32 v2, v2, v5
	v_mul_f32_e32 v4, 0xbfb8aa3b, v2
	v_exp_f32_e32 v4, v4
	v_pk_mul_f32 v[6:7], v[28:29], v[108:109]
	v_add_f32_e32 v4, 1.0, v4
	v_rcp_f32_e32 v4, v4
	s_nop 0
	v_mul_f32_e32 v92, v2, v4
	v_pk_mul_f32 v[4:5], v[28:29], v[0:1]
	ds_read_u16 v0, v20 offset:35376
	v_pk_mul_f32 v[92:93], v[92:93], v[118:119]
	v_lshlrev_b32_e32 v119, 16, v95
	v_lshlrev_b32_e32 v118, 16, v94
	v_pk_mov_b32 v[108:109], v[108:109], v[118:119] op_sel:[1,0]
	s_waitcnt lgkmcnt(0)
	v_lshlrev_b32_e32 v115, 16, v0
	ds_read_b128 v[0:3], v140 offset:208
	ds_read_u16 v96, v20 offset:35648
	v_pk_mul_f32 v[94:95], v[30:31], v[108:109]
	ds_read_b128 v[208:211], v25 offset:208
	s_waitcnt lgkmcnt(2)
	v_mov_b32_e32 v110, v0
	v_add_f32_e32 v0, v4, v5
	v_add_f32_e32 v0, v0, v94
	v_add_f32_e32 v0, v0, v95
	v_mul_f32_e32 v4, 0xbfb8aa3b, v0
	v_exp_f32_e32 v4, v4
	s_waitcnt lgkmcnt(1)
	v_lshlrev_b32_e32 v99, 16, v96
	v_add_f32_e32 v4, 1.0, v4
	v_rcp_f32_e32 v4, v4
	s_nop 0
	v_mul_f32_e32 v96, v0, v4
	v_pk_mul_f32 v[4:5], v[30:31], v[118:119]
	v_add_f32_e32 v0, v6, v7
	v_add_f32_e32 v0, v0, v4
	v_add_f32_e32 v0, v0, v5
	v_mul_f32_e32 v4, 0xbfb8aa3b, v0
	v_exp_f32_e32 v4, v4
	v_pk_mul_f32 v[94:95], v[96:97], v[104:105]
	v_pk_mul_f32 v[6:7], v[28:29], v[118:119]
	v_add_f32_e32 v4, 1.0, v4
	v_rcp_f32_e32 v4, v4
	s_nop 0
	v_mul_f32_e32 v114, v0, v4
	ds_read_u16 v0, v20 offset:35920
	s_waitcnt lgkmcnt(1)
	v_mov_b32_e32 v111, v208
	v_pk_mul_f32 v[4:5], v[28:29], v[108:109]
	v_mov_b32_e32 v208, v1
	v_pk_mul_f32 v[96:97], v[114:115], v[120:121]
	s_waitcnt lgkmcnt(0)
	v_lshlrev_b32_e32 v101, 16, v0
	ds_read_u16 v0, v20 offset:36192
	v_mov_b32_e32 v120, v2
	v_add_f32_e32 v2, v4, v5
	v_mov_b32_e32 v121, v210
	v_mov_b32_e32 v210, v3
	s_waitcnt lgkmcnt(0)
	v_lshlrev_b32_e32 v105, 16, v0
	v_pk_mov_b32 v[0:1], v[118:119], v[144:145] op_sel:[1,0]
	v_lshlrev_b32_e32 v115, 16, v103
	v_pk_mul_f32 v[108:109], v[30:31], v[0:1]
	v_pk_mul_f32 v[118:119], v[28:29], v[0:1]
	v_add_f32_e32 v2, v2, v108
	v_add_f32_e32 v2, v2, v109
	v_mul_f32_e32 v4, 0xbfb8aa3b, v2
	v_exp_f32_e32 v4, v4
	ds_read_u16 v0, v20 offset:36464
	v_lshlrev_b32_e32 v114, 16, v102
	v_add_f32_e32 v4, 1.0, v4
	v_rcp_f32_e32 v4, v4
	s_nop 0
	v_mul_f32_e32 v98, v2, v4
	v_pk_mul_f32 v[4:5], v[30:31], v[144:145]
	v_add_f32_e32 v2, v6, v7
	v_add_f32_e32 v2, v2, v4
	v_add_f32_e32 v2, v2, v5
	v_mul_f32_e32 v4, 0xbfb8aa3b, v2
	v_exp_f32_e32 v4, v4
	v_pk_mov_b32 v[144:145], v[144:145], v[114:115] op_sel:[1,0]
	v_add_f32_e32 v4, 1.0, v4
	v_rcp_f32_e32 v4, v4
	v_pk_mul_f32 v[102:103], v[30:31], v[144:145]
	v_mul_f32_e32 v100, v2, v4
	v_pk_mul_f32 v[100:101], v[100:101], v[208:209]
	s_waitcnt lgkmcnt(0)
	v_lshlrev_b32_e32 v209, 16, v0
	ds_read_b128 v[4:7], v140 offset:224
	ds_read_u16 v0, v20 offset:36736
	s_waitcnt lgkmcnt(1)
	v_mov_b32_e32 v108, v4
	s_waitcnt lgkmcnt(0)
	v_lshlrev_b32_e32 v107, 16, v0
	ds_read_b128 v[0:3], v25 offset:224
	s_waitcnt lgkmcnt(0)
	v_mov_b32_e32 v109, v0
	v_add_f32_e32 v0, v118, v119
	v_add_f32_e32 v0, v0, v102
	v_add_f32_e32 v0, v0, v103
	v_mul_f32_e32 v4, 0xbfb8aa3b, v0
	v_exp_f32_e32 v4, v4
	v_pk_mul_f32 v[118:119], v[28:29], v[114:115]
	v_add_f32_e32 v4, 1.0, v4
	v_rcp_f32_e32 v4, v4
	s_nop 0
	v_mul_f32_e32 v104, v0, v4
	v_pk_mul_f32 v[102:103], v[104:105], v[120:121]
	v_pk_mul_f32 v[104:105], v[30:31], v[114:115]
	v_add_f32_e32 v0, v148, v149
	v_add_f32_e32 v0, v0, v104
	v_add_f32_e32 v0, v0, v105
	v_mul_f32_e32 v4, 0xbfb8aa3b, v0
	v_exp_f32_e32 v4, v4
	v_pk_mul_f32 v[120:121], v[28:29], v[144:145]
	v_add_f32_e32 v4, 1.0, v4
	v_rcp_f32_e32 v4, v4
	s_nop 0
	v_mul_f32_e32 v208, v0, v4
	ds_read_u16 v0, v20 offset:37008
	ds_read_u16 v4, v20 offset:37280
	v_pk_mul_f32 v[104:105], v[208:209], v[210:211]
	v_lshlrev_b32_e32 v211, 16, v116
	v_lshlrev_b32_e32 v210, 16, v106
	s_waitcnt lgkmcnt(1)
	v_lshlrev_b32_e32 v117, 16, v0
	v_mov_b32_e32 v0, v5
	s_waitcnt lgkmcnt(0)
	v_lshlrev_b32_e32 v145, 16, v4
	v_pk_mov_b32 v[4:5], v[114:115], v[210:211] op_sel:[1,0]
	v_mov_b32_e32 v209, v2
	v_pk_mul_f32 v[114:115], v[30:31], v[4:5]
	v_add_f32_e32 v2, v120, v121
	v_add_f32_e32 v2, v2, v114
	v_add_f32_e32 v2, v2, v115
	v_mov_b32_e32 v208, v6
	v_mul_f32_e32 v6, 0xbfb8aa3b, v2
	v_exp_f32_e32 v6, v6
	v_pk_mul_f32 v[114:115], v[30:31], v[210:211]
	v_add_f32_e32 v6, 1.0, v6
	v_rcp_f32_e32 v6, v6
	s_nop 0
	v_mul_f32_e32 v106, v2, v6
	v_add_f32_e32 v2, v118, v119
	v_add_f32_e32 v2, v2, v114
	v_add_f32_e32 v2, v2, v115
	v_mul_f32_e32 v6, 0xbfb8aa3b, v2
	v_exp_f32_e32 v6, v6
	s_nop 0
	v_add_f32_e32 v6, 1.0, v6
	v_rcp_f32_e32 v6, v6
	s_nop 0
	v_mul_f32_e32 v116, v2, v6
	v_pk_mul_f32 v[148:149], v[116:117], v[0:1]
	v_pk_mul_f32 v[0:1], v[28:29], v[4:5]
	v_pk_mul_f32 v[116:117], v[28:29], v[210:211]
	v_pk_mov_b32 v[210:211], v[210:211], v[214:215] op_sel:[1,0]
	v_add_f32_e32 v0, v0, v1
	v_pk_mul_f32 v[142:143], v[30:31], v[210:211]
	ds_read_u16 v2, v20 offset:37552
	v_add_f32_e32 v0, v0, v142
	v_add_f32_e32 v0, v0, v143
	v_mul_f32_e32 v1, 0xbfb8aa3b, v0
	v_exp_f32_e32 v1, v1
	s_waitcnt lgkmcnt(0)
	v_lshlrev_b32_e32 v213, 16, v2
	v_mov_b32_e32 v2, v7
	ds_read_b128 v[4:7], v140 offset:240
	ds_read_u16 v114, v20 offset:37824
	v_add_f32_e32 v1, 1.0, v1
	v_rcp_f32_e32 v1, v1
	ds_read_b128 v[118:121], v25 offset:240
	s_waitcnt lgkmcnt(2)
	v_mov_b32_e32 v140, v4
	v_add_f32_e32 v4, v116, v117
	v_mul_f32_e32 v144, v0, v1
	v_pk_mul_f32 v[0:1], v[30:31], v[214:215]
	s_waitcnt lgkmcnt(1)
	v_lshlrev_b32_e32 v115, 16, v114
	v_add_f32_e32 v0, v4, v0
	v_add_f32_e32 v0, v0, v1
	v_mul_f32_e32 v1, 0xbfb8aa3b, v0
	v_exp_f32_e32 v1, v1
	ds_read_u16 v4, v20 offset:38096
	s_waitcnt lgkmcnt(1)
	v_mov_b32_e32 v141, v118
	v_mov_b32_e32 v118, v5
	v_add_f32_e32 v1, 1.0, v1
	v_rcp_f32_e32 v1, v1
	s_waitcnt lgkmcnt(0)
	v_lshlrev_b32_e32 v117, 16, v4
	ds_read_u16 v4, v20 offset:38368
	v_pk_mul_f32 v[144:145], v[144:145], v[208:209]
	v_mul_f32_e32 v212, v0, v1
	v_pk_mul_f32 v[0:1], v[28:29], v[210:211]
	v_pk_mov_b32 v[210:211], v[214:215], v[138:139] op_sel:[1,0]
	v_pk_mul_f32 v[142:143], v[212:213], v[2:3]
	v_pk_mul_f32 v[212:213], v[30:31], v[210:211]
	v_add_f32_e32 v0, v0, v1
	v_add_f32_e32 v0, v0, v212
	v_add_f32_e32 v0, v0, v213
	v_mul_f32_e32 v1, 0xbfb8aa3b, v0
	v_exp_f32_e32 v1, v1
	v_pk_mul_f32 v[2:3], v[28:29], v[214:215]
	s_waitcnt lgkmcnt(0)
	v_lshlrev_b32_e32 v5, 16, v4
	v_add_f32_e32 v2, v2, v3
	v_add_f32_e32 v1, 1.0, v1
	v_rcp_f32_e32 v1, v1
	v_mov_b32_e32 v209, v120
	v_mov_b32_e32 v120, v7
	v_mov_b32_e32 v208, v6
	v_mul_f32_e32 v114, v0, v1
	v_pk_mul_f32 v[0:1], v[30:31], v[138:139]
	s_nop 0
	v_add_f32_e32 v0, v2, v0
	v_add_f32_e32 v0, v0, v1
	v_mul_f32_e32 v1, 0xbfb8aa3b, v0
	v_exp_f32_e32 v1, v1
	v_pk_mul_f32 v[2:3], v[28:29], v[138:139]
	v_add_f32_e32 v1, 1.0, v1
	v_rcp_f32_e32 v1, v1
	v_add_f32_e32 v2, v2, v3
	v_mul_f32_e32 v116, v0, v1
	v_pk_mul_f32 v[0:1], v[28:29], v[210:211]
	v_lshlrev_b32_e32 v28, 16, v137
	v_lshlrev_b32_e32 v29, 16, v207
	v_pk_mul_f32 v[116:117], v[116:117], v[118:119]
	v_pk_mov_b32 v[118:119], v[138:139], v[28:29] op_sel:[1,0]
	v_add_f32_e32 v0, v0, v1
	v_pk_mul_f32 v[118:119], v[30:31], v[118:119]
	s_nop 0
	v_add_f32_e32 v0, v0, v118
	v_add_f32_e32 v0, v0, v119
	v_mul_f32_e32 v1, 0xbfb8aa3b, v0
	v_exp_f32_e32 v1, v1
	s_nop 0
	v_add_f32_e32 v1, 1.0, v1
	v_rcp_f32_e32 v1, v1
	s_nop 0
	v_mul_f32_e32 v4, v0, v1
	v_pk_mul_f32 v[0:1], v[30:31], v[28:29]
	v_pk_mul_f32 v[118:119], v[4:5], v[208:209]
	v_add_f32_e32 v0, v2, v0
	v_add_f32_e32 v0, v0, v1
	v_mul_f32_e32 v1, 0xbfb8aa3b, v0
	v_exp_f32_e32 v1, v1
	s_nop 0
	v_add_f32_e32 v1, 1.0, v1
	v_rcp_f32_e32 v1, v1
	s_nop 0
	v_mul_f32_e32 v0, v0, v1
	ds_read_u16 v1, v20 offset:38640
	v_lshl_add_u32 v20, v136, 14, v196
	s_waitcnt lgkmcnt(0)
	s_barrier
	v_lshlrev_b32_e32 v1, 16, v1
	v_pk_mul_f32 v[120:121], v[0:1], v[120:121]
	ds_read_b128 v[0:3], v20 offset:39168
	s_waitcnt lgkmcnt(0)
	v_pk_fma_f32 v[4:5], v[130:131], v[0:1], 0 op_sel:[0,1,0] op_sel_hi:[1,1,0] neg_lo:[1,0,0] neg_hi:[1,0,0]
	v_pk_fma_f32 v[0:1], v[128:129], v[0:1], v[130:131] op_sel_hi:[1,0,1] neg_lo:[1,0,0] neg_hi:[1,0,0]
	v_pk_fma_f32 v[4:5], v[134:135], v[2:3], v[4:5] op_sel:[0,1,0] neg_lo:[1,0,0] neg_hi:[1,0,0]
	v_pk_fma_f32 v[0:1], v[132:133], v[2:3], v[0:1] op_sel_hi:[1,0,1] neg_lo:[1,0,0] neg_hi:[1,0,0]
	ds_read_b128 v[28:31], v20 offset:41248
	v_pk_add_f32 v[138:139], v[0:1], v[4:5]
	ds_read_b128 v[0:3], v20 offset:39424
	s_waitcnt lgkmcnt(0)
	v_pk_fma_f32 v[4:5], v[0:1], v[138:139], 0 op_sel:[1,0,0] op_sel_hi:[1,1,0] neg_lo:[1,0,0] neg_hi:[1,0,0]
	v_pk_fma_f32 v[0:1], v[128:129], v[0:1], v[132:133] op_sel_hi:[1,0,1] neg_lo:[1,0,0] neg_hi:[1,0,0]
	v_pk_fma_f32 v[4:5], v[134:135], v[2:3], v[4:5] op_sel:[0,1,0] neg_lo:[1,0,0] neg_hi:[1,0,0]
	v_pk_fma_f32 v[0:1], v[132:133], v[2:3], v[0:1] op_sel_hi:[1,0,1] neg_lo:[1,0,0] neg_hi:[1,0,0]
	ds_read_b128 v[208:211], v20 offset:44368
	v_pk_add_f32 v[136:137], v[0:1], v[4:5]
	ds_read_b128 v[0:3], v20 offset:39680
	s_waitcnt lgkmcnt(0)
	v_pk_fma_f32 v[4:5], v[0:1], v[138:139], 0 op_sel:[1,0,0] op_sel_hi:[1,1,0] neg_lo:[1,0,0] neg_hi:[1,0,0]
	v_pk_fma_f32 v[0:1], v[128:129], v[0:1], v[134:135] op_sel_hi:[1,0,1] neg_lo:[1,0,0] neg_hi:[1,0,0]
	v_pk_fma_f32 v[4:5], v[134:135], v[2:3], v[4:5] op_sel:[0,1,0] neg_lo:[1,0,0] neg_hi:[1,0,0]
	v_pk_fma_f32 v[0:1], v[2:3], v[136:137], v[0:1] op_sel_hi:[0,1,1] neg_lo:[1,0,0] neg_hi:[1,0,0]
	ds_read_b128 v[212:215], v20 offset:46448
	v_pk_add_f32 v[134:135], v[4:5], v[0:1]
	ds_read_b128 v[0:3], v20 offset:39936
	s_waitcnt lgkmcnt(0)
	v_pk_fma_f32 v[4:5], v[0:1], v[138:139], 0 op_sel:[1,0,0] op_sel_hi:[1,1,0] neg_lo:[1,0,0] neg_hi:[1,0,0]
	v_pk_mul_f32 v[0:1], v[128:129], v[0:1] op_sel_hi:[1,0]
	v_pk_fma_f32 v[4:5], v[2:3], v[134:135], v[4:5] op_sel:[1,0,0] neg_lo:[1,0,0] neg_hi:[1,0,0]
	v_pk_fma_f32 v[0:1], v[16:17], v[84:85], v[0:1] neg_lo:[0,0,1] neg_hi:[0,0,1]
	ds_read_b128 v[216:219], v20 offset:49568
	v_pk_fma_f32 v[0:1], v[2:3], v[136:137], v[0:1] op_sel_hi:[0,1,1] neg_lo:[1,0,0] neg_hi:[1,0,0]
	ds_read_b128 v[220:223], v20 offset:50608
	v_pk_add_f32 v[132:133], v[0:1], v[4:5]
	ds_read_b128 v[0:3], v20 offset:40192
	ds_read_b128 v[4:7], v20 offset:40208
	s_waitcnt lgkmcnt(1)
	v_pk_fma_f32 v[16:17], v[0:1], v[138:139], 0 op_sel:[1,0,0] op_sel_hi:[1,1,0] neg_lo:[1,0,0] neg_hi:[1,0,0]
	v_pk_fma_f32 v[0:1], v[128:129], v[0:1], v[122:123] op_sel_hi:[1,0,1] neg_lo:[1,0,0] neg_hi:[1,0,0]
	v_pk_fma_f32 v[16:17], v[2:3], v[134:135], v[16:17] op_sel:[1,0,0] neg_lo:[1,0,0] neg_hi:[1,0,0]
	v_pk_fma_f32 v[0:1], v[2:3], v[136:137], v[0:1] op_sel_hi:[0,1,1] neg_lo:[1,0,0] neg_hi:[1,0,0]
	s_waitcnt lgkmcnt(0)
	v_pk_fma_f32 v[16:17], v[122:123], v[4:5], v[16:17] op_sel:[0,1,0] neg_lo:[1,0,0] neg_hi:[1,0,0]
	v_pk_fma_f32 v[0:1], v[4:5], v[132:133], v[0:1] op_sel_hi:[0,1,1] neg_lo:[1,0,0] neg_hi:[1,0,0]
	v_pk_fma_f32 v[16:17], v[184:185], v[6:7], v[16:17] op_sel:[0,1,0] neg_lo:[1,0,0] neg_hi:[1,0,0]
	v_pk_fma_f32 v[0:1], v[186:187], v[6:7], v[0:1] op_sel_hi:[1,0,1] neg_lo:[1,0,0] neg_hi:[1,0,0]
	ds_read_b128 v[4:7], v20 offset:40464
	v_pk_add_f32 v[130:131], v[16:17], v[0:1]
	ds_read_b128 v[0:3], v20 offset:40448
	s_waitcnt lgkmcnt(0)
	v_pk_fma_f32 v[16:17], v[138:139], v[0:1], 0 op_sel:[0,1,0] op_sel_hi:[1,1,0] neg_lo:[1,0,0] neg_hi:[1,0,0]
	v_pk_fma_f32 v[0:1], v[128:129], v[0:1], v[186:187] op_sel_hi:[1,0,1] neg_lo:[1,0,0] neg_hi:[1,0,0]
	v_pk_fma_f32 v[16:17], v[2:3], v[134:135], v[16:17] op_sel:[1,0,0] neg_lo:[1,0,0] neg_hi:[1,0,0]
	v_pk_fma_f32 v[0:1], v[2:3], v[136:137], v[0:1] op_sel_hi:[0,1,1] neg_lo:[1,0,0] neg_hi:[1,0,0]
	v_pk_fma_f32 v[16:17], v[4:5], v[130:131], v[16:17] op_sel:[1,0,0] neg_lo:[1,0,0] neg_hi:[1,0,0]
	v_pk_fma_f32 v[0:1], v[4:5], v[132:133], v[0:1] op_sel_hi:[0,1,1] neg_lo:[1,0,0] neg_hi:[1,0,0]
	v_pk_fma_f32 v[16:17], v[184:185], v[6:7], v[16:17] op_sel:[0,1,0] neg_lo:[1,0,0] neg_hi:[1,0,0]
	v_pk_fma_f32 v[0:1], v[186:187], v[6:7], v[0:1] op_sel_hi:[1,0,1] neg_lo:[1,0,0] neg_hi:[1,0,0]
	ds_read_b128 v[4:7], v20 offset:40720
	v_pk_add_f32 v[122:123], v[0:1], v[16:17]
	ds_read_b128 v[0:3], v20 offset:40704
	s_waitcnt lgkmcnt(0)
	v_pk_fma_f32 v[16:17], v[138:139], v[0:1], 0 op_sel:[0,1,0] op_sel_hi:[1,1,0] neg_lo:[1,0,0] neg_hi:[1,0,0]
	v_pk_fma_f32 v[0:1], v[128:129], v[0:1], v[184:185] op_sel_hi:[1,0,1] neg_lo:[1,0,0] neg_hi:[1,0,0]
	v_pk_fma_f32 v[16:17], v[2:3], v[134:135], v[16:17] op_sel:[1,0,0] neg_lo:[1,0,0] neg_hi:[1,0,0]
	v_pk_fma_f32 v[0:1], v[2:3], v[136:137], v[0:1] op_sel_hi:[0,1,1] neg_lo:[1,0,0] neg_hi:[1,0,0]
	v_pk_fma_f32 v[16:17], v[4:5], v[130:131], v[16:17] op_sel:[1,0,0] neg_lo:[1,0,0] neg_hi:[1,0,0]
	v_pk_fma_f32 v[0:1], v[4:5], v[132:133], v[0:1] op_sel_hi:[0,1,1] neg_lo:[1,0,0] neg_hi:[1,0,0]
	v_pk_fma_f32 v[16:17], v[184:185], v[6:7], v[16:17] op_sel:[0,1,0] neg_lo:[1,0,0] neg_hi:[1,0,0]
	v_pk_fma_f32 v[0:1], v[6:7], v[122:123], v[0:1] op_sel_hi:[0,1,1] neg_lo:[1,0,0] neg_hi:[1,0,0]
	ds_read_b128 v[4:7], v20 offset:40976
	v_pk_add_f32 v[84:85], v[16:17], v[0:1]
	ds_read_b128 v[0:3], v20 offset:40960
	s_waitcnt lgkmcnt(0)
	v_pk_fma_f32 v[16:17], v[138:139], v[0:1], 0 op_sel:[0,1,0] op_sel_hi:[1,1,0] neg_lo:[1,0,0] neg_hi:[1,0,0]
	v_pk_mul_f32 v[0:1], v[128:129], v[0:1] op_sel_hi:[1,0]
	v_pk_fma_f32 v[16:17], v[2:3], v[134:135], v[16:17] op_sel:[1,0,0] neg_lo:[1,0,0] neg_hi:[1,0,0]
	v_pk_fma_f32 v[0:1], v[10:11], v[14:15], v[0:1] neg_lo:[0,0,1] neg_hi:[0,0,1]
	v_pk_fma_f32 v[16:17], v[4:5], v[130:131], v[16:17] op_sel:[1,0,0] neg_lo:[1,0,0] neg_hi:[1,0,0]
	v_pk_fma_f32 v[0:1], v[136:137], v[2:3], v[0:1] op_sel_hi:[1,0,1] neg_lo:[1,0,0] neg_hi:[1,0,0]
	v_pk_fma_f32 v[16:17], v[6:7], v[84:85], v[16:17] op_sel:[1,0,0] neg_lo:[1,0,0] neg_hi:[1,0,0]
	v_pk_fma_f32 v[0:1], v[4:5], v[132:133], v[0:1] op_sel_hi:[0,1,1] neg_lo:[1,0,0] neg_hi:[1,0,0]
	ds_read_b128 v[184:187], v20 offset:42288
	v_pk_fma_f32 v[0:1], v[6:7], v[122:123], v[0:1] op_sel_hi:[0,1,1] neg_lo:[1,0,0] neg_hi:[1,0,0]
	ds_read_b128 v[4:7], v20 offset:41232
	v_pk_add_f32 v[14:15], v[0:1], v[16:17]
	ds_read_b128 v[0:3], v20 offset:41216
	s_waitcnt lgkmcnt(0)
	v_pk_fma_f32 v[10:11], v[138:139], v[0:1], 0 op_sel:[0,1,0] op_sel_hi:[1,1,0] neg_lo:[1,0,0] neg_hi:[1,0,0]
	v_pk_fma_f32 v[0:1], v[128:129], v[0:1], v[182:183] op_sel_hi:[1,0,1] neg_lo:[1,0,0] neg_hi:[1,0,0]
	v_pk_fma_f32 v[10:11], v[134:135], v[2:3], v[10:11] op_sel:[0,1,0] neg_lo:[1,0,0] neg_hi:[1,0,0]
	v_pk_fma_f32 v[0:1], v[136:137], v[2:3], v[0:1] op_sel_hi:[1,0,1] neg_lo:[1,0,0] neg_hi:[1,0,0]
	v_pk_fma_f32 v[10:11], v[4:5], v[130:131], v[10:11] op_sel:[1,0,0] neg_lo:[1,0,0] neg_hi:[1,0,0]
	v_pk_fma_f32 v[0:1], v[4:5], v[132:133], v[0:1] op_sel_hi:[0,1,1] neg_lo:[1,0,0] neg_hi:[1,0,0]
	v_pk_fma_f32 v[10:11], v[6:7], v[84:85], v[10:11] op_sel:[1,0,0] neg_lo:[1,0,0] neg_hi:[1,0,0]
	v_pk_fma_f32 v[0:1], v[6:7], v[122:123], v[0:1] op_sel_hi:[0,1,1] neg_lo:[1,0,0] neg_hi:[1,0,0]
	ds_read_b128 v[4:7], v20 offset:41488
	v_pk_fma_f32 v[10:11], v[182:183], v[28:29], v[10:11] op_sel:[0,1,0] neg_lo:[1,0,0] neg_hi:[1,0,0]
	v_pk_fma_f32 v[0:1], v[28:29], v[14:15], v[0:1] op_sel_hi:[0,1,1] neg_lo:[1,0,0] neg_hi:[1,0,0]
	v_pk_fma_f32 v[10:11], v[18:19], v[30:31], v[10:11] op_sel:[0,1,0] neg_lo:[1,0,0] neg_hi:[1,0,0]
	v_pk_fma_f32 v[0:1], v[180:181], v[30:31], v[0:1] op_sel_hi:[1,0,1] neg_lo:[1,0,0] neg_hi:[1,0,0]
	ds_read_b128 v[28:31], v20 offset:41504
	v_pk_add_f32 v[10:11], v[10:11], v[0:1]
	ds_read_b128 v[0:3], v20 offset:41472
	s_waitcnt lgkmcnt(0)
	v_pk_fma_f32 v[16:17], v[138:139], v[0:1], 0 op_sel:[0,1,0] op_sel_hi:[1,1,0] neg_lo:[1,0,0] neg_hi:[1,0,0]
	v_pk_fma_f32 v[0:1], v[128:129], v[0:1], v[180:181] op_sel_hi:[1,0,1] neg_lo:[1,0,0] neg_hi:[1,0,0]
	v_pk_fma_f32 v[16:17], v[134:135], v[2:3], v[16:17] op_sel:[0,1,0] neg_lo:[1,0,0] neg_hi:[1,0,0]
	v_pk_fma_f32 v[0:1], v[136:137], v[2:3], v[0:1] op_sel_hi:[1,0,1] neg_lo:[1,0,0] neg_hi:[1,0,0]
	v_pk_fma_f32 v[16:17], v[4:5], v[130:131], v[16:17] op_sel:[1,0,0] neg_lo:[1,0,0] neg_hi:[1,0,0]
	v_pk_fma_f32 v[0:1], v[132:133], v[4:5], v[0:1] op_sel_hi:[1,0,1] neg_lo:[1,0,0] neg_hi:[1,0,0]
	v_pk_fma_f32 v[16:17], v[6:7], v[84:85], v[16:17] op_sel:[1,0,0] neg_lo:[1,0,0] neg_hi:[1,0,0]
	v_pk_fma_f32 v[0:1], v[6:7], v[122:123], v[0:1] op_sel_hi:[0,1,1] neg_lo:[1,0,0] neg_hi:[1,0,0]
	ds_read_b128 v[4:7], v20 offset:41744
	v_pk_fma_f32 v[16:17], v[28:29], v[10:11], v[16:17] op_sel:[1,0,0] neg_lo:[1,0,0] neg_hi:[1,0,0]
	v_pk_fma_f32 v[0:1], v[28:29], v[14:15], v[0:1] op_sel_hi:[0,1,1] neg_lo:[1,0,0] neg_hi:[1,0,0]
	v_pk_fma_f32 v[16:17], v[18:19], v[30:31], v[16:17] op_sel:[0,1,0] neg_lo:[1,0,0] neg_hi:[1,0,0]
	v_pk_fma_f32 v[0:1], v[180:181], v[30:31], v[0:1] op_sel_hi:[1,0,1] neg_lo:[1,0,0] neg_hi:[1,0,0]
	ds_read_b128 v[28:31], v20 offset:41760
	v_pk_add_f32 v[16:17], v[0:1], v[16:17]
	ds_read_b128 v[0:3], v20 offset:41728
	s_waitcnt lgkmcnt(0)
	v_pk_fma_f32 v[180:181], v[138:139], v[0:1], 0 op_sel:[0,1,0] op_sel_hi:[1,1,0] neg_lo:[1,0,0] neg_hi:[1,0,0]
	v_pk_fma_f32 v[0:1], v[128:129], v[0:1], v[18:19] op_sel_hi:[1,0,1] neg_lo:[1,0,0] neg_hi:[1,0,0]
	v_pk_fma_f32 v[180:181], v[134:135], v[2:3], v[180:181] op_sel:[0,1,0] neg_lo:[1,0,0] neg_hi:[1,0,0]
	v_pk_fma_f32 v[0:1], v[136:137], v[2:3], v[0:1] op_sel_hi:[1,0,1] neg_lo:[1,0,0] neg_hi:[1,0,0]
	v_pk_fma_f32 v[180:181], v[130:131], v[4:5], v[180:181] op_sel:[0,1,0] neg_lo:[1,0,0] neg_hi:[1,0,0]
	v_pk_fma_f32 v[0:1], v[132:133], v[4:5], v[0:1] op_sel_hi:[1,0,1] neg_lo:[1,0,0] neg_hi:[1,0,0]
	v_pk_fma_f32 v[180:181], v[6:7], v[84:85], v[180:181] op_sel:[1,0,0] neg_lo:[1,0,0] neg_hi:[1,0,0]
	v_pk_fma_f32 v[0:1], v[6:7], v[122:123], v[0:1] op_sel_hi:[0,1,1] neg_lo:[1,0,0] neg_hi:[1,0,0]
	v_pk_fma_f32 v[180:181], v[28:29], v[10:11], v[180:181] op_sel:[1,0,0] neg_lo:[1,0,0] neg_hi:[1,0,0]
	v_pk_fma_f32 v[0:1], v[28:29], v[14:15], v[0:1] op_sel_hi:[0,1,1] neg_lo:[1,0,0] neg_hi:[1,0,0]
	v_pk_fma_f32 v[180:181], v[18:19], v[30:31], v[180:181] op_sel:[0,1,0] neg_lo:[1,0,0] neg_hi:[1,0,0]
	v_pk_fma_f32 v[0:1], v[30:31], v[16:17], v[0:1] op_sel_hi:[0,1,1] neg_lo:[1,0,0] neg_hi:[1,0,0]
	ds_read_b128 v[28:31], v20 offset:42000
	v_pk_add_f32 v[6:7], v[180:181], v[0:1]
	ds_read_b128 v[0:3], v20 offset:41984
	ds_read_b128 v[180:183], v20 offset:42016
	s_waitcnt lgkmcnt(1)
	v_pk_fma_f32 v[4:5], v[138:139], v[0:1], 0 op_sel:[0,1,0] op_sel_hi:[1,1,0] neg_lo:[1,0,0] neg_hi:[1,0,0]
	v_pk_mul_f32 v[0:1], v[128:129], v[0:1] op_sel_hi:[1,0]
	v_pk_fma_f32 v[4:5], v[134:135], v[2:3], v[4:5] op_sel:[0,1,0] neg_lo:[1,0,0] neg_hi:[1,0,0]
	v_pk_fma_f32 v[0:1], v[8:9], v[12:13], v[0:1] neg_lo:[0,0,1] neg_hi:[0,0,1]
	v_pk_fma_f32 v[4:5], v[130:131], v[28:29], v[4:5] op_sel:[0,1,0] neg_lo:[1,0,0] neg_hi:[1,0,0]
	v_pk_fma_f32 v[0:1], v[136:137], v[2:3], v[0:1] op_sel_hi:[1,0,1] neg_lo:[1,0,0] neg_hi:[1,0,0]
	v_pk_fma_f32 v[4:5], v[30:31], v[84:85], v[4:5] op_sel:[1,0,0] neg_lo:[1,0,0] neg_hi:[1,0,0]
	v_pk_fma_f32 v[0:1], v[132:133], v[28:29], v[0:1] op_sel_hi:[1,0,1] neg_lo:[1,0,0] neg_hi:[1,0,0]
	s_waitcnt lgkmcnt(0)
	v_pk_fma_f32 v[4:5], v[180:181], v[10:11], v[4:5] op_sel:[1,0,0] neg_lo:[1,0,0] neg_hi:[1,0,0]
	v_pk_fma_f32 v[0:1], v[30:31], v[122:123], v[0:1] op_sel_hi:[0,1,1] neg_lo:[1,0,0] neg_hi:[1,0,0]
	ds_read_b128 v[28:31], v20 offset:42256
	v_pk_fma_f32 v[0:1], v[180:181], v[14:15], v[0:1] op_sel_hi:[0,1,1] neg_lo:[1,0,0] neg_hi:[1,0,0]
	v_pk_fma_f32 v[4:5], v[182:183], v[6:7], v[4:5] op_sel:[1,0,0] neg_lo:[1,0,0] neg_hi:[1,0,0]
	v_pk_fma_f32 v[0:1], v[182:183], v[16:17], v[0:1] op_sel_hi:[0,1,1] neg_lo:[1,0,0] neg_hi:[1,0,0]
	ds_read_b128 v[180:183], v20 offset:42272
	v_pk_add_f32 v[18:19], v[0:1], v[4:5]
	ds_read_b128 v[0:3], v20 offset:42240
	s_waitcnt lgkmcnt(0)
	v_pk_fma_f32 v[4:5], v[138:139], v[0:1], 0 op_sel:[0,1,0] op_sel_hi:[1,1,0] neg_lo:[1,0,0] neg_hi:[1,0,0]
	v_pk_fma_f32 v[0:1], v[128:129], v[0:1], v[178:179] op_sel_hi:[1,0,1] neg_lo:[1,0,0] neg_hi:[1,0,0]
	v_pk_fma_f32 v[4:5], v[134:135], v[2:3], v[4:5] op_sel:[0,1,0] neg_lo:[1,0,0] neg_hi:[1,0,0]
	v_pk_fma_f32 v[0:1], v[136:137], v[2:3], v[0:1] op_sel_hi:[1,0,1] neg_lo:[1,0,0] neg_hi:[1,0,0]
	v_pk_fma_f32 v[4:5], v[130:131], v[28:29], v[4:5] op_sel:[0,1,0] neg_lo:[1,0,0] neg_hi:[1,0,0]
	v_pk_fma_f32 v[0:1], v[132:133], v[28:29], v[0:1] op_sel_hi:[1,0,1] neg_lo:[1,0,0] neg_hi:[1,0,0]
	v_pk_fma_f32 v[4:5], v[30:31], v[84:85], v[4:5] op_sel:[1,0,0] neg_lo:[1,0,0] neg_hi:[1,0,0]
	v_pk_fma_f32 v[0:1], v[122:123], v[30:31], v[0:1] op_sel_hi:[1,0,1] neg_lo:[1,0,0] neg_hi:[1,0,0]
	ds_read_b128 v[28:31], v20 offset:42512
	v_pk_fma_f32 v[4:5], v[180:181], v[10:11], v[4:5] op_sel:[1,0,0] neg_lo:[1,0,0] neg_hi:[1,0,0]
	v_pk_fma_f32 v[0:1], v[180:181], v[14:15], v[0:1] op_sel_hi:[0,1,1] neg_lo:[1,0,0] neg_hi:[1,0,0]
	v_pk_fma_f32 v[4:5], v[182:183], v[6:7], v[4:5] op_sel:[1,0,0] neg_lo:[1,0,0] neg_hi:[1,0,0]
	v_pk_fma_f32 v[0:1], v[182:183], v[16:17], v[0:1] op_sel_hi:[0,1,1] neg_lo:[1,0,0] neg_hi:[1,0,0]
	v_pk_fma_f32 v[4:5], v[178:179], v[184:185], v[4:5] op_sel:[0,1,0] neg_lo:[1,0,0] neg_hi:[1,0,0]
	ds_read_b128 v[178:181], v20 offset:42528
	v_pk_fma_f32 v[0:1], v[184:185], v[18:19], v[0:1] op_sel_hi:[0,1,1] neg_lo:[1,0,0] neg_hi:[1,0,0]
	ds_read_b128 v[182:185], v20 offset:42544
	v_pk_fma_f32 v[4:5], v[174:175], v[186:187], v[4:5] op_sel:[0,1,0] neg_lo:[1,0,0] neg_hi:[1,0,0]
	v_pk_fma_f32 v[0:1], v[176:177], v[186:187], v[0:1] op_sel_hi:[1,0,1] neg_lo:[1,0,0] neg_hi:[1,0,0]
	ds_read_b128 v[224:227], v20 offset:51648
	v_pk_add_f32 v[12:13], v[4:5], v[0:1]
	ds_read_b128 v[0:3], v20 offset:42496
	s_waitcnt lgkmcnt(0)
	v_pk_fma_f32 v[4:5], v[138:139], v[0:1], 0 op_sel:[0,1,0] op_sel_hi:[1,1,0] neg_lo:[1,0,0] neg_hi:[1,0,0]
	v_pk_fma_f32 v[0:1], v[128:129], v[0:1], v[176:177] op_sel_hi:[1,0,1] neg_lo:[1,0,0] neg_hi:[1,0,0]
	v_pk_fma_f32 v[4:5], v[134:135], v[2:3], v[4:5] op_sel:[0,1,0] neg_lo:[1,0,0] neg_hi:[1,0,0]
	v_pk_fma_f32 v[0:1], v[136:137], v[2:3], v[0:1] op_sel_hi:[1,0,1] neg_lo:[1,0,0] neg_hi:[1,0,0]
	v_pk_fma_f32 v[4:5], v[130:131], v[28:29], v[4:5] op_sel:[0,1,0] neg_lo:[1,0,0] neg_hi:[1,0,0]
	v_pk_fma_f32 v[0:1], v[132:133], v[28:29], v[0:1] op_sel_hi:[1,0,1] neg_lo:[1,0,0] neg_hi:[1,0,0]
	v_pk_fma_f32 v[4:5], v[84:85], v[30:31], v[4:5] op_sel:[0,1,0] neg_lo:[1,0,0] neg_hi:[1,0,0]
	v_pk_fma_f32 v[0:1], v[122:123], v[30:31], v[0:1] op_sel_hi:[1,0,1] neg_lo:[1,0,0] neg_hi:[1,0,0]
	ds_read_b128 v[28:31], v20 offset:42768
	v_pk_fma_f32 v[4:5], v[178:179], v[10:11], v[4:5] op_sel:[1,0,0] neg_lo:[1,0,0] neg_hi:[1,0,0]
	v_pk_fma_f32 v[0:1], v[14:15], v[178:179], v[0:1] op_sel_hi:[1,0,1] neg_lo:[1,0,0] neg_hi:[1,0,0]
	v_pk_fma_f32 v[4:5], v[180:181], v[6:7], v[4:5] op_sel:[1,0,0] neg_lo:[1,0,0] neg_hi:[1,0,0]
	v_pk_fma_f32 v[0:1], v[180:181], v[16:17], v[0:1] op_sel_hi:[0,1,1] neg_lo:[1,0,0] neg_hi:[1,0,0]
	v_pk_fma_f32 v[4:5], v[182:183], v[12:13], v[4:5] op_sel:[1,0,0] neg_lo:[1,0,0] neg_hi:[1,0,0]
	v_pk_fma_f32 v[0:1], v[182:183], v[18:19], v[0:1] op_sel_hi:[0,1,1] neg_lo:[1,0,0] neg_hi:[1,0,0]
	ds_read_b128 v[180:183], v20 offset:42800
	v_pk_fma_f32 v[4:5], v[174:175], v[184:185], v[4:5] op_sel:[0,1,0] neg_lo:[1,0,0] neg_hi:[1,0,0]
	v_pk_fma_f32 v[0:1], v[176:177], v[184:185], v[0:1] op_sel_hi:[1,0,1] neg_lo:[1,0,0] neg_hi:[1,0,0]
	ds_read_b128 v[176:179], v20 offset:42784
	v_pk_add_f32 v[8:9], v[0:1], v[4:5]
	ds_read_b128 v[0:3], v20 offset:42752
	s_waitcnt lgkmcnt(0)
	v_pk_fma_f32 v[4:5], v[138:139], v[0:1], 0 op_sel:[0,1,0] op_sel_hi:[1,1,0] neg_lo:[1,0,0] neg_hi:[1,0,0]
	v_pk_fma_f32 v[0:1], v[128:129], v[0:1], v[174:175] op_sel_hi:[1,0,1] neg_lo:[1,0,0] neg_hi:[1,0,0]
	v_pk_fma_f32 v[4:5], v[134:135], v[2:3], v[4:5] op_sel:[0,1,0] neg_lo:[1,0,0] neg_hi:[1,0,0]
	v_pk_fma_f32 v[0:1], v[136:137], v[2:3], v[0:1] op_sel_hi:[1,0,1] neg_lo:[1,0,0] neg_hi:[1,0,0]
	v_pk_fma_f32 v[4:5], v[130:131], v[28:29], v[4:5] op_sel:[0,1,0] neg_lo:[1,0,0] neg_hi:[1,0,0]
	v_pk_fma_f32 v[0:1], v[132:133], v[28:29], v[0:1] op_sel_hi:[1,0,1] neg_lo:[1,0,0] neg_hi:[1,0,0]
	v_pk_fma_f32 v[4:5], v[84:85], v[30:31], v[4:5] op_sel:[0,1,0] neg_lo:[1,0,0] neg_hi:[1,0,0]
	v_pk_fma_f32 v[0:1], v[122:123], v[30:31], v[0:1] op_sel_hi:[1,0,1] neg_lo:[1,0,0] neg_hi:[1,0,0]
	ds_read_b128 v[28:31], v20 offset:43024
	v_pk_fma_f32 v[4:5], v[10:11], v[176:177], v[4:5] op_sel:[0,1,0] neg_lo:[1,0,0] neg_hi:[1,0,0]
	v_pk_fma_f32 v[0:1], v[14:15], v[176:177], v[0:1] op_sel_hi:[1,0,1] neg_lo:[1,0,0] neg_hi:[1,0,0]
	v_pk_fma_f32 v[4:5], v[178:179], v[6:7], v[4:5] op_sel:[1,0,0] neg_lo:[1,0,0] neg_hi:[1,0,0]
	v_pk_fma_f32 v[0:1], v[178:179], v[16:17], v[0:1] op_sel_hi:[0,1,1] neg_lo:[1,0,0] neg_hi:[1,0,0]
	v_pk_fma_f32 v[4:5], v[180:181], v[12:13], v[4:5] op_sel:[1,0,0] neg_lo:[1,0,0] neg_hi:[1,0,0]
	v_pk_fma_f32 v[0:1], v[180:181], v[18:19], v[0:1] op_sel_hi:[0,1,1] neg_lo:[1,0,0] neg_hi:[1,0,0]
	ds_read_b128 v[178:181], v20 offset:43056
	v_pk_fma_f32 v[4:5], v[174:175], v[182:183], v[4:5] op_sel:[0,1,0] neg_lo:[1,0,0] neg_hi:[1,0,0]
	ds_read_b128 v[174:177], v20 offset:43040
	v_pk_fma_f32 v[0:1], v[182:183], v[8:9], v[0:1] op_sel_hi:[0,1,1] neg_lo:[1,0,0] neg_hi:[1,0,0]
	ds_read_b128 v[228:231], v20 offset:53728
	v_pk_add_f32 v[4:5], v[4:5], v[0:1]
	ds_read_b128 v[0:3], v20 offset:43008
	s_waitcnt lgkmcnt(0)
	v_pk_fma_f32 v[182:183], v[138:139], v[0:1], 0 op_sel:[0,1,0] op_sel_hi:[1,1,0] neg_lo:[1,0,0] neg_hi:[1,0,0]
	v_pk_mul_f32 v[0:1], v[128:129], v[0:1] op_sel_hi:[1,0]
	v_pk_fma_f32 v[182:183], v[134:135], v[2:3], v[182:183] op_sel:[0,1,0] neg_lo:[1,0,0] neg_hi:[1,0,0]
	v_pk_fma_f32 v[0:1], v[168:169], v[170:171], v[0:1] neg_lo:[0,0,1] neg_hi:[0,0,1]
	ds_read_b128 v[168:171], v20 offset:43280
	v_pk_fma_f32 v[0:1], v[136:137], v[2:3], v[0:1] op_sel_hi:[1,0,1] neg_lo:[1,0,0] neg_hi:[1,0,0]
	v_pk_fma_f32 v[182:183], v[130:131], v[28:29], v[182:183] op_sel:[0,1,0] neg_lo:[1,0,0] neg_hi:[1,0,0]
	v_pk_fma_f32 v[0:1], v[132:133], v[28:29], v[0:1] op_sel_hi:[1,0,1] neg_lo:[1,0,0] neg_hi:[1,0,0]
	v_pk_fma_f32 v[182:183], v[84:85], v[30:31], v[182:183] op_sel:[0,1,0] neg_lo:[1,0,0] neg_hi:[1,0,0]
	v_pk_fma_f32 v[0:1], v[122:123], v[30:31], v[0:1] op_sel_hi:[1,0,1] neg_lo:[1,0,0] neg_hi:[1,0,0]
	ds_read_b128 v[28:31], v20 offset:43264
	v_pk_fma_f32 v[182:183], v[10:11], v[174:175], v[182:183] op_sel:[0,1,0] neg_lo:[1,0,0] neg_hi:[1,0,0]
	v_pk_fma_f32 v[0:1], v[14:15], v[174:175], v[0:1] op_sel_hi:[1,0,1] neg_lo:[1,0,0] neg_hi:[1,0,0]
	v_pk_fma_f32 v[182:183], v[176:177], v[6:7], v[182:183] op_sel:[1,0,0] neg_lo:[1,0,0] neg_hi:[1,0,0]
	v_pk_fma_f32 v[0:1], v[16:17], v[176:177], v[0:1] op_sel_hi:[1,0,1] neg_lo:[1,0,0] neg_hi:[1,0,0]
	ds_read_b128 v[174:177], v20 offset:43296
	v_pk_fma_f32 v[182:183], v[178:179], v[12:13], v[182:183] op_sel:[1,0,0] neg_lo:[1,0,0] neg_hi:[1,0,0]
	v_pk_fma_f32 v[0:1], v[178:179], v[18:19], v[0:1] op_sel_hi:[0,1,1] neg_lo:[1,0,0] neg_hi:[1,0,0]
	v_pk_fma_f32 v[182:183], v[180:181], v[4:5], v[182:183] op_sel:[1,0,0] neg_lo:[1,0,0] neg_hi:[1,0,0]
	v_pk_fma_f32 v[0:1], v[180:181], v[8:9], v[0:1] op_sel_hi:[0,1,1] neg_lo:[1,0,0] neg_hi:[1,0,0]
	ds_read_b128 v[178:181], v20 offset:43312
	v_pk_add_f32 v[2:3], v[0:1], v[182:183]
	ds_read_b128 v[182:185], v20 offset:43328
	s_waitcnt lgkmcnt(3)
	v_pk_fma_f32 v[0:1], v[138:139], v[28:29], 0 op_sel:[0,1,0] op_sel_hi:[1,1,0] neg_lo:[1,0,0] neg_hi:[1,0,0]
	v_pk_fma_f32 v[28:29], v[128:129], v[28:29], v[172:173] op_sel_hi:[1,0,1] neg_lo:[1,0,0] neg_hi:[1,0,0]
	v_pk_fma_f32 v[0:1], v[134:135], v[30:31], v[0:1] op_sel:[0,1,0] neg_lo:[1,0,0] neg_hi:[1,0,0]
	v_pk_fma_f32 v[28:29], v[136:137], v[30:31], v[28:29] op_sel_hi:[1,0,1] neg_lo:[1,0,0] neg_hi:[1,0,0]
	v_pk_fma_f32 v[0:1], v[130:131], v[168:169], v[0:1] op_sel:[0,1,0] neg_lo:[1,0,0] neg_hi:[1,0,0]
	v_pk_fma_f32 v[28:29], v[132:133], v[168:169], v[28:29] op_sel_hi:[1,0,1] neg_lo:[1,0,0] neg_hi:[1,0,0]
	v_pk_fma_f32 v[0:1], v[84:85], v[170:171], v[0:1] op_sel:[0,1,0] neg_lo:[1,0,0] neg_hi:[1,0,0]
	v_pk_fma_f32 v[28:29], v[122:123], v[170:171], v[28:29] op_sel_hi:[1,0,1] neg_lo:[1,0,0] neg_hi:[1,0,0]
	ds_read_b128 v[168:171], v20 offset:43536
	s_waitcnt lgkmcnt(3)
	v_pk_fma_f32 v[0:1], v[10:11], v[174:175], v[0:1] op_sel:[0,1,0] neg_lo:[1,0,0] neg_hi:[1,0,0]
	v_pk_fma_f32 v[28:29], v[14:15], v[174:175], v[28:29] op_sel_hi:[1,0,1] neg_lo:[1,0,0] neg_hi:[1,0,0]
	v_pk_fma_f32 v[0:1], v[6:7], v[176:177], v[0:1] op_sel:[0,1,0] neg_lo:[1,0,0] neg_hi:[1,0,0]
	v_pk_fma_f32 v[28:29], v[16:17], v[176:177], v[28:29] op_sel_hi:[1,0,1] neg_lo:[1,0,0] neg_hi:[1,0,0]
	s_waitcnt lgkmcnt(2)
	v_pk_fma_f32 v[0:1], v[178:179], v[12:13], v[0:1] op_sel:[1,0,0] neg_lo:[1,0,0] neg_hi:[1,0,0]
	v_pk_fma_f32 v[28:29], v[18:19], v[178:179], v[28:29] op_sel_hi:[1,0,1] neg_lo:[1,0,0] neg_hi:[1,0,0]
	ds_read_b128 v[176:179], v20 offset:43568
	v_pk_fma_f32 v[0:1], v[180:181], v[4:5], v[0:1] op_sel:[1,0,0] neg_lo:[1,0,0] neg_hi:[1,0,0]
	v_pk_fma_f32 v[28:29], v[180:181], v[8:9], v[28:29] op_sel_hi:[0,1,1] neg_lo:[1,0,0] neg_hi:[1,0,0]
	s_waitcnt lgkmcnt(2)
	v_pk_fma_f32 v[0:1], v[172:173], v[182:183], v[0:1] op_sel:[0,1,0] neg_lo:[1,0,0] neg_hi:[1,0,0]
	ds_read_b128 v[172:175], v20 offset:43552
	v_pk_fma_f32 v[28:29], v[182:183], v[2:3], v[28:29] op_sel_hi:[0,1,1] neg_lo:[1,0,0] neg_hi:[1,0,0]
	ds_read_b128 v[180:183], v20 offset:43584
	v_pk_fma_f32 v[0:1], v[162:163], v[184:185], v[0:1] op_sel:[0,1,0] neg_lo:[1,0,0] neg_hi:[1,0,0]
	v_pk_fma_f32 v[28:29], v[166:167], v[184:185], v[28:29] op_sel_hi:[1,0,1] neg_lo:[1,0,0] neg_hi:[1,0,0]
	s_nop 0
	v_pk_add_f32 v[0:1], v[0:1], v[28:29]
	ds_read_b128 v[28:31], v20 offset:43520
	s_waitcnt lgkmcnt(0)
	v_pk_fma_f32 v[184:185], v[138:139], v[28:29], 0 op_sel:[0,1,0] op_sel_hi:[1,1,0] neg_lo:[1,0,0] neg_hi:[1,0,0]
	v_pk_fma_f32 v[28:29], v[128:129], v[28:29], v[166:167] op_sel_hi:[1,0,1] neg_lo:[1,0,0] neg_hi:[1,0,0]
	v_pk_fma_f32 v[184:185], v[134:135], v[30:31], v[184:185] op_sel:[0,1,0] neg_lo:[1,0,0] neg_hi:[1,0,0]
	v_pk_fma_f32 v[28:29], v[136:137], v[30:31], v[28:29] op_sel_hi:[1,0,1] neg_lo:[1,0,0] neg_hi:[1,0,0]
	v_pk_fma_f32 v[184:185], v[130:131], v[168:169], v[184:185] op_sel:[0,1,0] neg_lo:[1,0,0] neg_hi:[1,0,0]
	v_pk_fma_f32 v[28:29], v[132:133], v[168:169], v[28:29] op_sel_hi:[1,0,1] neg_lo:[1,0,0] neg_hi:[1,0,0]
	v_pk_fma_f32 v[184:185], v[84:85], v[170:171], v[184:185] op_sel:[0,1,0] neg_lo:[1,0,0] neg_hi:[1,0,0]
	v_pk_fma_f32 v[28:29], v[122:123], v[170:171], v[28:29] op_sel_hi:[1,0,1] neg_lo:[1,0,0] neg_hi:[1,0,0]
	v_pk_fma_f32 v[184:185], v[10:11], v[172:173], v[184:185] op_sel:[0,1,0] neg_lo:[1,0,0] neg_hi:[1,0,0]
	v_pk_fma_f32 v[28:29], v[14:15], v[172:173], v[28:29] op_sel_hi:[1,0,1] neg_lo:[1,0,0] neg_hi:[1,0,0]
	ds_read_b128 v[170:173], v20 offset:43792
	v_pk_fma_f32 v[184:185], v[6:7], v[174:175], v[184:185] op_sel:[0,1,0] neg_lo:[1,0,0] neg_hi:[1,0,0]
	v_pk_fma_f32 v[28:29], v[16:17], v[174:175], v[28:29] op_sel_hi:[1,0,1] neg_lo:[1,0,0] neg_hi:[1,0,0]
	v_pk_fma_f32 v[184:185], v[12:13], v[176:177], v[184:185] op_sel:[0,1,0] neg_lo:[1,0,0] neg_hi:[1,0,0]
	v_pk_fma_f32 v[28:29], v[18:19], v[176:177], v[28:29] op_sel_hi:[1,0,1] neg_lo:[1,0,0] neg_hi:[1,0,0]
	ds_read_b128 v[174:177], v20 offset:43808
	v_pk_fma_f32 v[184:185], v[178:179], v[4:5], v[184:185] op_sel:[1,0,0] neg_lo:[1,0,0] neg_hi:[1,0,0]
	v_pk_fma_f32 v[28:29], v[178:179], v[8:9], v[28:29] op_sel_hi:[0,1,1] neg_lo:[1,0,0] neg_hi:[1,0,0]
	v_pk_fma_f32 v[184:185], v[180:181], v[0:1], v[184:185] op_sel:[1,0,0] neg_lo:[1,0,0] neg_hi:[1,0,0]
	v_pk_fma_f32 v[28:29], v[180:181], v[2:3], v[28:29] op_sel_hi:[0,1,1] neg_lo:[1,0,0] neg_hi:[1,0,0]
	ds_read_b128 v[178:181], v20 offset:43824
	v_pk_fma_f32 v[184:185], v[162:163], v[182:183], v[184:185] op_sel:[0,1,0] neg_lo:[1,0,0] neg_hi:[1,0,0]
	v_pk_fma_f32 v[28:29], v[166:167], v[182:183], v[28:29] op_sel_hi:[1,0,1] neg_lo:[1,0,0] neg_hi:[1,0,0]
	ds_read_b128 v[166:169], v20 offset:43776
	v_pk_add_f32 v[30:31], v[28:29], v[184:185]
	ds_read_b128 v[182:185], v20 offset:43840
	s_waitcnt lgkmcnt(1)
	v_pk_fma_f32 v[28:29], v[138:139], v[166:167], 0 op_sel:[0,1,0] op_sel_hi:[1,1,0] neg_lo:[1,0,0] neg_hi:[1,0,0]
	v_pk_fma_f32 v[252:253], v[128:129], v[166:167], v[162:163] op_sel_hi:[1,0,1] neg_lo:[1,0,0] neg_hi:[1,0,0]
	v_pk_fma_f32 v[28:29], v[134:135], v[168:169], v[28:29] op_sel:[0,1,0] neg_lo:[1,0,0] neg_hi:[1,0,0]
	v_pk_fma_f32 v[252:253], v[136:137], v[168:169], v[252:253] op_sel_hi:[1,0,1] neg_lo:[1,0,0] neg_hi:[1,0,0]
	ds_read_b128 v[166:169], v20 offset:44032
	v_pk_fma_f32 v[28:29], v[130:131], v[170:171], v[28:29] op_sel:[0,1,0] neg_lo:[1,0,0] neg_hi:[1,0,0]
	v_pk_fma_f32 v[252:253], v[132:133], v[170:171], v[252:253] op_sel_hi:[1,0,1] neg_lo:[1,0,0] neg_hi:[1,0,0]
	v_pk_fma_f32 v[28:29], v[84:85], v[172:173], v[28:29] op_sel:[0,1,0] neg_lo:[1,0,0] neg_hi:[1,0,0]
	v_pk_fma_f32 v[252:253], v[122:123], v[172:173], v[252:253] op_sel_hi:[1,0,1] neg_lo:[1,0,0] neg_hi:[1,0,0]
	ds_read_b128 v[170:173], v20 offset:44048
	v_pk_fma_f32 v[28:29], v[10:11], v[174:175], v[28:29] op_sel:[0,1,0] neg_lo:[1,0,0] neg_hi:[1,0,0]
	v_pk_fma_f32 v[252:253], v[14:15], v[174:175], v[252:253] op_sel_hi:[1,0,1] neg_lo:[1,0,0] neg_hi:[1,0,0]
	v_pk_fma_f32 v[28:29], v[6:7], v[176:177], v[28:29] op_sel:[0,1,0] neg_lo:[1,0,0] neg_hi:[1,0,0]
	v_pk_fma_f32 v[252:253], v[16:17], v[176:177], v[252:253] op_sel_hi:[1,0,1] neg_lo:[1,0,0] neg_hi:[1,0,0]
	ds_read_b128 v[174:177], v20 offset:44064
	v_pk_fma_f32 v[28:29], v[12:13], v[178:179], v[28:29] op_sel:[0,1,0] neg_lo:[1,0,0] neg_hi:[1,0,0]
	v_pk_fma_f32 v[252:253], v[18:19], v[178:179], v[252:253] op_sel_hi:[1,0,1] neg_lo:[1,0,0] neg_hi:[1,0,0]
	v_pk_fma_f32 v[28:29], v[180:181], v[4:5], v[28:29] op_sel:[1,0,0] neg_lo:[1,0,0] neg_hi:[1,0,0]
	v_pk_fma_f32 v[252:253], v[8:9], v[180:181], v[252:253] op_sel_hi:[1,0,1] neg_lo:[1,0,0] neg_hi:[1,0,0]
	ds_read_b128 v[178:181], v20 offset:44080
	s_waitcnt lgkmcnt(4)
	v_pk_fma_f32 v[28:29], v[182:183], v[0:1], v[28:29] op_sel:[1,0,0] neg_lo:[1,0,0] neg_hi:[1,0,0]
	v_pk_fma_f32 v[252:253], v[182:183], v[2:3], v[252:253] op_sel_hi:[0,1,1] neg_lo:[1,0,0] neg_hi:[1,0,0]
	v_pk_fma_f32 v[28:29], v[162:163], v[184:185], v[28:29] op_sel:[0,1,0] neg_lo:[1,0,0] neg_hi:[1,0,0]
	v_pk_fma_f32 v[252:253], v[184:185], v[30:31], v[252:253] op_sel_hi:[0,1,1] neg_lo:[1,0,0] neg_hi:[1,0,0]
	ds_read_b128 v[182:185], v20 offset:44096
	v_pk_add_f32 v[28:29], v[28:29], v[252:253]
	s_waitcnt lgkmcnt(4)
	v_pk_fma_f32 v[162:163], v[138:139], v[166:167], 0 op_sel:[0,1,0] op_sel_hi:[1,1,0] neg_lo:[1,0,0] neg_hi:[1,0,0]
	v_pk_mul_f32 v[166:167], v[128:129], v[166:167] op_sel_hi:[1,0]
	v_pk_fma_f32 v[162:163], v[134:135], v[168:169], v[162:163] op_sel:[0,1,0] neg_lo:[1,0,0] neg_hi:[1,0,0]
	v_pk_fma_f32 v[32:33], v[32:33], v[34:35], v[166:167] neg_lo:[0,0,1] neg_hi:[0,0,1]
	s_waitcnt lgkmcnt(3)
	v_pk_fma_f32 v[162:163], v[130:131], v[170:171], v[162:163] op_sel:[0,1,0] neg_lo:[1,0,0] neg_hi:[1,0,0]
	v_pk_fma_f32 v[32:33], v[136:137], v[168:169], v[32:33] op_sel_hi:[1,0,1] neg_lo:[1,0,0] neg_hi:[1,0,0]
	ds_read_b128 v[166:169], v20 offset:44288
	v_pk_fma_f32 v[32:33], v[132:133], v[170:171], v[32:33] op_sel_hi:[1,0,1] neg_lo:[1,0,0] neg_hi:[1,0,0]
	v_pk_fma_f32 v[162:163], v[84:85], v[172:173], v[162:163] op_sel:[0,1,0] neg_lo:[1,0,0] neg_hi:[1,0,0]
	v_pk_fma_f32 v[32:33], v[122:123], v[172:173], v[32:33] op_sel_hi:[1,0,1] neg_lo:[1,0,0] neg_hi:[1,0,0]
	ds_read_b128 v[170:173], v20 offset:44304
	s_waitcnt lgkmcnt(4)
	v_pk_fma_f32 v[162:163], v[10:11], v[174:175], v[162:163] op_sel:[0,1,0] neg_lo:[1,0,0] neg_hi:[1,0,0]
	v_pk_fma_f32 v[32:33], v[14:15], v[174:175], v[32:33] op_sel_hi:[1,0,1] neg_lo:[1,0,0] neg_hi:[1,0,0]
	v_pk_fma_f32 v[162:163], v[6:7], v[176:177], v[162:163] op_sel:[0,1,0] neg_lo:[1,0,0] neg_hi:[1,0,0]
	v_pk_fma_f32 v[32:33], v[16:17], v[176:177], v[32:33] op_sel_hi:[1,0,1] neg_lo:[1,0,0] neg_hi:[1,0,0]
	ds_read_b128 v[174:177], v20 offset:44320
	s_waitcnt lgkmcnt(4)
	v_pk_fma_f32 v[162:163], v[12:13], v[178:179], v[162:163] op_sel:[0,1,0] neg_lo:[1,0,0] neg_hi:[1,0,0]
	v_pk_fma_f32 v[32:33], v[18:19], v[178:179], v[32:33] op_sel_hi:[1,0,1] neg_lo:[1,0,0] neg_hi:[1,0,0]
	v_pk_fma_f32 v[162:163], v[4:5], v[180:181], v[162:163] op_sel:[0,1,0] neg_lo:[1,0,0] neg_hi:[1,0,0]
	v_pk_fma_f32 v[32:33], v[8:9], v[180:181], v[32:33] op_sel_hi:[1,0,1] neg_lo:[1,0,0] neg_hi:[1,0,0]
	ds_read_b128 v[178:181], v20 offset:44336
	s_waitcnt lgkmcnt(4)
	v_pk_fma_f32 v[162:163], v[182:183], v[0:1], v[162:163] op_sel:[1,0,0] neg_lo:[1,0,0] neg_hi:[1,0,0]
	v_pk_fma_f32 v[32:33], v[2:3], v[182:183], v[32:33] op_sel_hi:[1,0,1] neg_lo:[1,0,0] neg_hi:[1,0,0]
	v_pk_fma_f32 v[162:163], v[184:185], v[28:29], v[162:163] op_sel:[1,0,0] neg_lo:[1,0,0] neg_hi:[1,0,0]
	v_pk_fma_f32 v[32:33], v[184:185], v[30:31], v[32:33] op_sel_hi:[0,1,1] neg_lo:[1,0,0] neg_hi:[1,0,0]
	ds_read_b128 v[182:185], v20 offset:44352
	v_pk_add_f32 v[32:33], v[32:33], v[162:163]
	s_waitcnt lgkmcnt(4)
	v_pk_fma_f32 v[34:35], v[138:139], v[166:167], 0 op_sel:[0,1,0] op_sel_hi:[1,1,0] neg_lo:[1,0,0] neg_hi:[1,0,0]
	v_pk_fma_f32 v[252:253], v[128:129], v[166:167], v[160:161] op_sel_hi:[1,0,1] neg_lo:[1,0,0] neg_hi:[1,0,0]
	v_pk_fma_f32 v[34:35], v[134:135], v[168:169], v[34:35] op_sel:[0,1,0] neg_lo:[1,0,0] neg_hi:[1,0,0]
	v_pk_fma_f32 v[252:253], v[136:137], v[168:169], v[252:253] op_sel_hi:[1,0,1] neg_lo:[1,0,0] neg_hi:[1,0,0]
	ds_read_b128 v[166:169], v20 offset:44560
	s_waitcnt lgkmcnt(4)
	v_pk_fma_f32 v[34:35], v[130:131], v[170:171], v[34:35] op_sel:[0,1,0] neg_lo:[1,0,0] neg_hi:[1,0,0]
	v_pk_fma_f32 v[252:253], v[132:133], v[170:171], v[252:253] op_sel_hi:[1,0,1] neg_lo:[1,0,0] neg_hi:[1,0,0]
	v_pk_fma_f32 v[34:35], v[84:85], v[172:173], v[34:35] op_sel:[0,1,0] neg_lo:[1,0,0] neg_hi:[1,0,0]
	v_pk_fma_f32 v[252:253], v[122:123], v[172:173], v[252:253] op_sel_hi:[1,0,1] neg_lo:[1,0,0] neg_hi:[1,0,0]
	ds_read_b128 v[170:173], v20 offset:44576
	s_waitcnt lgkmcnt(4)
	v_pk_fma_f32 v[34:35], v[10:11], v[174:175], v[34:35] op_sel:[0,1,0] neg_lo:[1,0,0] neg_hi:[1,0,0]
	v_pk_fma_f32 v[252:253], v[14:15], v[174:175], v[252:253] op_sel_hi:[1,0,1] neg_lo:[1,0,0] neg_hi:[1,0,0]
	v_pk_fma_f32 v[34:35], v[6:7], v[176:177], v[34:35] op_sel:[0,1,0] neg_lo:[1,0,0] neg_hi:[1,0,0]
	v_pk_fma_f32 v[252:253], v[16:17], v[176:177], v[252:253] op_sel_hi:[1,0,1] neg_lo:[1,0,0] neg_hi:[1,0,0]
	ds_read_b128 v[174:177], v20 offset:44592
	s_waitcnt lgkmcnt(4)
	v_pk_fma_f32 v[34:35], v[12:13], v[178:179], v[34:35] op_sel:[0,1,0] neg_lo:[1,0,0] neg_hi:[1,0,0]
	v_pk_fma_f32 v[252:253], v[18:19], v[178:179], v[252:253] op_sel_hi:[1,0,1] neg_lo:[1,0,0] neg_hi:[1,0,0]
	v_pk_fma_f32 v[34:35], v[4:5], v[180:181], v[34:35] op_sel:[0,1,0] neg_lo:[1,0,0] neg_hi:[1,0,0]
	v_pk_fma_f32 v[252:253], v[8:9], v[180:181], v[252:253] op_sel_hi:[1,0,1] neg_lo:[1,0,0] neg_hi:[1,0,0]
	ds_read_b128 v[178:181], v20 offset:44608
	s_waitcnt lgkmcnt(4)
	v_pk_fma_f32 v[34:35], v[0:1], v[182:183], v[34:35] op_sel:[0,1,0] neg_lo:[1,0,0] neg_hi:[1,0,0]
	v_pk_fma_f32 v[252:253], v[2:3], v[182:183], v[252:253] op_sel_hi:[1,0,1] neg_lo:[1,0,0] neg_hi:[1,0,0]
	v_pk_fma_f32 v[34:35], v[184:185], v[28:29], v[34:35] op_sel:[1,0,0] neg_lo:[1,0,0] neg_hi:[1,0,0]
	v_pk_fma_f32 v[252:253], v[184:185], v[30:31], v[252:253] op_sel_hi:[0,1,1] neg_lo:[1,0,0] neg_hi:[1,0,0]
	ds_read_b128 v[182:185], v20 offset:44624
	v_pk_fma_f32 v[34:35], v[160:161], v[208:209], v[34:35] op_sel:[0,1,0] neg_lo:[1,0,0] neg_hi:[1,0,0]
	ds_read_b128 v[160:163], v20 offset:44544
	v_pk_fma_f32 v[34:35], v[40:41], v[210:211], v[34:35] op_sel:[0,1,0] neg_lo:[1,0,0] neg_hi:[1,0,0]
	v_pk_fma_f32 v[252:253], v[208:209], v[32:33], v[252:253] op_sel_hi:[0,1,1] neg_lo:[1,0,0] neg_hi:[1,0,0]
	s_waitcnt lgkmcnt(0)
	v_pk_fma_f32 v[186:187], v[138:139], v[160:161], 0 op_sel:[0,1,0] op_sel_hi:[1,1,0] neg_lo:[1,0,0] neg_hi:[1,0,0]
	v_pk_fma_f32 v[252:253], v[36:37], v[210:211], v[252:253] op_sel_hi:[1,0,1] neg_lo:[1,0,0] neg_hi:[1,0,0]
	v_pk_fma_f32 v[160:161], v[128:129], v[160:161], v[36:37] op_sel_hi:[1,0,1] neg_lo:[1,0,0] neg_hi:[1,0,0]
	v_pk_add_f32 v[34:35], v[252:253], v[34:35]
	v_pk_fma_f32 v[186:187], v[134:135], v[162:163], v[186:187] op_sel:[0,1,0] neg_lo:[1,0,0] neg_hi:[1,0,0]
	v_pk_fma_f32 v[160:161], v[136:137], v[162:163], v[160:161] op_sel_hi:[1,0,1] neg_lo:[1,0,0] neg_hi:[1,0,0]
	v_pk_fma_f32 v[186:187], v[130:131], v[166:167], v[186:187] op_sel:[0,1,0] neg_lo:[1,0,0] neg_hi:[1,0,0]
	v_pk_fma_f32 v[160:161], v[132:133], v[166:167], v[160:161] op_sel_hi:[1,0,1] neg_lo:[1,0,0] neg_hi:[1,0,0]
	v_pk_fma_f32 v[186:187], v[84:85], v[168:169], v[186:187] op_sel:[0,1,0] neg_lo:[1,0,0] neg_hi:[1,0,0]
	v_pk_fma_f32 v[160:161], v[122:123], v[168:169], v[160:161] op_sel_hi:[1,0,1] neg_lo:[1,0,0] neg_hi:[1,0,0]
	ds_read_b128 v[166:169], v20 offset:44816
	v_pk_fma_f32 v[186:187], v[10:11], v[170:171], v[186:187] op_sel:[0,1,0] neg_lo:[1,0,0] neg_hi:[1,0,0]
	v_pk_fma_f32 v[160:161], v[14:15], v[170:171], v[160:161] op_sel_hi:[1,0,1] neg_lo:[1,0,0] neg_hi:[1,0,0]
	v_pk_fma_f32 v[186:187], v[6:7], v[172:173], v[186:187] op_sel:[0,1,0] neg_lo:[1,0,0] neg_hi:[1,0,0]
	v_pk_fma_f32 v[160:161], v[16:17], v[172:173], v[160:161] op_sel_hi:[1,0,1] neg_lo:[1,0,0] neg_hi:[1,0,0]
	ds_read_b128 v[170:173], v20 offset:44832
	v_pk_fma_f32 v[186:187], v[12:13], v[174:175], v[186:187] op_sel:[0,1,0] neg_lo:[1,0,0] neg_hi:[1,0,0]
	v_pk_fma_f32 v[160:161], v[18:19], v[174:175], v[160:161] op_sel_hi:[1,0,1] neg_lo:[1,0,0] neg_hi:[1,0,0]
	v_pk_fma_f32 v[186:187], v[4:5], v[176:177], v[186:187] op_sel:[0,1,0] neg_lo:[1,0,0] neg_hi:[1,0,0]
	v_pk_fma_f32 v[160:161], v[8:9], v[176:177], v[160:161] op_sel_hi:[1,0,1] neg_lo:[1,0,0] neg_hi:[1,0,0]
	ds_read_b128 v[174:177], v20 offset:44848
	v_pk_fma_f32 v[186:187], v[0:1], v[178:179], v[186:187] op_sel:[0,1,0] neg_lo:[1,0,0] neg_hi:[1,0,0]
	v_pk_fma_f32 v[160:161], v[2:3], v[178:179], v[160:161] op_sel_hi:[1,0,1] neg_lo:[1,0,0] neg_hi:[1,0,0]
	v_pk_fma_f32 v[186:187], v[28:29], v[180:181], v[186:187] op_sel:[0,1,0] neg_lo:[1,0,0] neg_hi:[1,0,0]
	v_pk_fma_f32 v[160:161], v[30:31], v[180:181], v[160:161] op_sel_hi:[1,0,1] neg_lo:[1,0,0] neg_hi:[1,0,0]
	ds_read_b128 v[178:181], v20 offset:44864
	v_pk_fma_f32 v[186:187], v[182:183], v[34:35], v[186:187] op_sel:[1,0,0] neg_lo:[1,0,0] neg_hi:[1,0,0]
	v_pk_fma_f32 v[160:161], v[32:33], v[182:183], v[160:161] op_sel_hi:[1,0,1] neg_lo:[1,0,0] neg_hi:[1,0,0]
	v_pk_fma_f32 v[186:187], v[40:41], v[184:185], v[186:187] op_sel:[0,1,0] neg_lo:[1,0,0] neg_hi:[1,0,0]
	v_pk_fma_f32 v[36:37], v[36:37], v[184:185], v[160:161] op_sel_hi:[1,0,1] neg_lo:[1,0,0] neg_hi:[1,0,0]
	ds_read_b128 v[160:163], v20 offset:44800
	ds_read_b128 v[182:185], v20 offset:44880
	v_pk_add_f32 v[36:37], v[36:37], v[186:187]
	s_waitcnt lgkmcnt(1)
	v_pk_fma_f32 v[186:187], v[138:139], v[160:161], 0 op_sel:[0,1,0] op_sel_hi:[1,1,0] neg_lo:[1,0,0] neg_hi:[1,0,0]
	ds_read_b128 v[208:211], v20 offset:45408
	v_pk_fma_f32 v[186:187], v[134:135], v[162:163], v[186:187] op_sel:[0,1,0] neg_lo:[1,0,0] neg_hi:[1,0,0]
	v_pk_fma_f32 v[252:253], v[128:129], v[160:161], v[40:41] op_sel_hi:[1,0,1] neg_lo:[1,0,0] neg_hi:[1,0,0]
	v_pk_fma_f32 v[186:187], v[130:131], v[166:167], v[186:187] op_sel:[0,1,0] neg_lo:[1,0,0] neg_hi:[1,0,0]
	v_pk_fma_f32 v[252:253], v[136:137], v[162:163], v[252:253] op_sel_hi:[1,0,1] neg_lo:[1,0,0] neg_hi:[1,0,0]
	ds_read_b128 v[160:163], v20 offset:45056
	v_pk_fma_f32 v[186:187], v[84:85], v[168:169], v[186:187] op_sel:[0,1,0] neg_lo:[1,0,0] neg_hi:[1,0,0]
	v_pk_fma_f32 v[252:253], v[132:133], v[166:167], v[252:253] op_sel_hi:[1,0,1] neg_lo:[1,0,0] neg_hi:[1,0,0]
	v_pk_fma_f32 v[186:187], v[10:11], v[170:171], v[186:187] op_sel:[0,1,0] neg_lo:[1,0,0] neg_hi:[1,0,0]
	v_pk_fma_f32 v[252:253], v[122:123], v[168:169], v[252:253] op_sel_hi:[1,0,1] neg_lo:[1,0,0] neg_hi:[1,0,0]
	ds_read_b128 v[166:169], v20 offset:45072
	v_pk_fma_f32 v[186:187], v[6:7], v[172:173], v[186:187] op_sel:[0,1,0] neg_lo:[1,0,0] neg_hi:[1,0,0]
	v_pk_fma_f32 v[252:253], v[14:15], v[170:171], v[252:253] op_sel_hi:[1,0,1] neg_lo:[1,0,0] neg_hi:[1,0,0]
	v_pk_fma_f32 v[186:187], v[12:13], v[174:175], v[186:187] op_sel:[0,1,0] neg_lo:[1,0,0] neg_hi:[1,0,0]
	v_pk_fma_f32 v[252:253], v[16:17], v[172:173], v[252:253] op_sel_hi:[1,0,1] neg_lo:[1,0,0] neg_hi:[1,0,0]
	ds_read_b128 v[170:173], v20 offset:45088
	v_pk_fma_f32 v[186:187], v[4:5], v[176:177], v[186:187] op_sel:[0,1,0] neg_lo:[1,0,0] neg_hi:[1,0,0]
	v_pk_fma_f32 v[252:253], v[18:19], v[174:175], v[252:253] op_sel_hi:[1,0,1] neg_lo:[1,0,0] neg_hi:[1,0,0]
	v_pk_fma_f32 v[186:187], v[0:1], v[178:179], v[186:187] op_sel:[0,1,0] neg_lo:[1,0,0] neg_hi:[1,0,0]
	v_pk_fma_f32 v[252:253], v[8:9], v[176:177], v[252:253] op_sel_hi:[1,0,1] neg_lo:[1,0,0] neg_hi:[1,0,0]
	ds_read_b128 v[174:177], v20 offset:45104
	v_pk_fma_f32 v[186:187], v[28:29], v[180:181], v[186:187] op_sel:[0,1,0] neg_lo:[1,0,0] neg_hi:[1,0,0]
	v_pk_fma_f32 v[252:253], v[2:3], v[178:179], v[252:253] op_sel_hi:[1,0,1] neg_lo:[1,0,0] neg_hi:[1,0,0]
	s_waitcnt lgkmcnt(5)
	v_pk_fma_f32 v[186:187], v[34:35], v[182:183], v[186:187] op_sel:[0,1,0] neg_lo:[1,0,0] neg_hi:[1,0,0]
	v_pk_fma_f32 v[252:253], v[30:31], v[180:181], v[252:253] op_sel_hi:[1,0,1] neg_lo:[1,0,0] neg_hi:[1,0,0]
	ds_read_b128 v[178:181], v20 offset:45120
	v_pk_fma_f32 v[186:187], v[40:41], v[184:185], v[186:187] op_sel:[0,1,0] neg_lo:[1,0,0] neg_hi:[1,0,0]
	v_pk_fma_f32 v[252:253], v[32:33], v[182:183], v[252:253] op_sel_hi:[1,0,1] neg_lo:[1,0,0] neg_hi:[1,0,0]
	s_nop 0
	v_pk_fma_f32 v[252:253], v[184:185], v[36:37], v[252:253] op_sel_hi:[0,1,1] neg_lo:[1,0,0] neg_hi:[1,0,0]
	ds_read_b128 v[182:185], v20 offset:45136
	v_pk_add_f32 v[40:41], v[252:253], v[186:187]
	s_waitcnt lgkmcnt(5)
	v_pk_fma_f32 v[186:187], v[138:139], v[160:161], 0 op_sel:[0,1,0] op_sel_hi:[1,1,0] neg_lo:[1,0,0] neg_hi:[1,0,0]
	v_pk_mul_f32 v[160:161], v[128:129], v[160:161] op_sel_hi:[1,0]
	v_pk_fma_f32 v[186:187], v[134:135], v[162:163], v[186:187] op_sel:[0,1,0] neg_lo:[1,0,0] neg_hi:[1,0,0]
	v_pk_fma_f32 v[38:39], v[38:39], v[42:43], v[160:161] neg_lo:[0,0,1] neg_hi:[0,0,1]
	s_waitcnt lgkmcnt(4)
	v_pk_fma_f32 v[186:187], v[130:131], v[166:167], v[186:187] op_sel:[0,1,0] neg_lo:[1,0,0] neg_hi:[1,0,0]
	v_pk_fma_f32 v[38:39], v[136:137], v[162:163], v[38:39] op_sel_hi:[1,0,1] neg_lo:[1,0,0] neg_hi:[1,0,0]
	ds_read_b128 v[160:163], v20 offset:45312
	v_pk_fma_f32 v[38:39], v[132:133], v[166:167], v[38:39] op_sel_hi:[1,0,1] neg_lo:[1,0,0] neg_hi:[1,0,0]
	v_pk_fma_f32 v[186:187], v[84:85], v[168:169], v[186:187] op_sel:[0,1,0] neg_lo:[1,0,0] neg_hi:[1,0,0]
	v_pk_fma_f32 v[38:39], v[122:123], v[168:169], v[38:39] op_sel_hi:[1,0,1] neg_lo:[1,0,0] neg_hi:[1,0,0]
	ds_read_b128 v[166:169], v20 offset:45328
	s_waitcnt lgkmcnt(5)
	v_pk_fma_f32 v[186:187], v[10:11], v[170:171], v[186:187] op_sel:[0,1,0] neg_lo:[1,0,0] neg_hi:[1,0,0]
	v_pk_fma_f32 v[38:39], v[14:15], v[170:171], v[38:39] op_sel_hi:[1,0,1] neg_lo:[1,0,0] neg_hi:[1,0,0]
	v_pk_fma_f32 v[186:187], v[6:7], v[172:173], v[186:187] op_sel:[0,1,0] neg_lo:[1,0,0] neg_hi:[1,0,0]
	v_pk_fma_f32 v[38:39], v[16:17], v[172:173], v[38:39] op_sel_hi:[1,0,1] neg_lo:[1,0,0] neg_hi:[1,0,0]
	ds_read_b128 v[170:173], v20 offset:45344
	s_waitcnt lgkmcnt(5)
	v_pk_fma_f32 v[186:187], v[12:13], v[174:175], v[186:187] op_sel:[0,1,0] neg_lo:[1,0,0] neg_hi:[1,0,0]
	v_pk_fma_f32 v[38:39], v[18:19], v[174:175], v[38:39] op_sel_hi:[1,0,1] neg_lo:[1,0,0] neg_hi:[1,0,0]
	v_pk_fma_f32 v[186:187], v[4:5], v[176:177], v[186:187] op_sel:[0,1,0] neg_lo:[1,0,0] neg_hi:[1,0,0]
	v_pk_fma_f32 v[38:39], v[8:9], v[176:177], v[38:39] op_sel_hi:[1,0,1] neg_lo:[1,0,0] neg_hi:[1,0,0]
	ds_read_b128 v[174:177], v20 offset:45360
	s_waitcnt lgkmcnt(5)
	v_pk_fma_f32 v[186:187], v[0:1], v[178:179], v[186:187] op_sel:[0,1,0] neg_lo:[1,0,0] neg_hi:[1,0,0]
	v_pk_fma_f32 v[38:39], v[2:3], v[178:179], v[38:39] op_sel_hi:[1,0,1] neg_lo:[1,0,0] neg_hi:[1,0,0]
	v_pk_fma_f32 v[186:187], v[28:29], v[180:181], v[186:187] op_sel:[0,1,0] neg_lo:[1,0,0] neg_hi:[1,0,0]
	v_pk_fma_f32 v[38:39], v[30:31], v[180:181], v[38:39] op_sel_hi:[1,0,1] neg_lo:[1,0,0] neg_hi:[1,0,0]
	ds_read_b128 v[178:181], v20 offset:45376
	s_waitcnt lgkmcnt(5)
	v_pk_fma_f32 v[186:187], v[34:35], v[182:183], v[186:187] op_sel:[0,1,0] neg_lo:[1,0,0] neg_hi:[1,0,0]
	v_pk_fma_f32 v[38:39], v[32:33], v[182:183], v[38:39] op_sel_hi:[1,0,1] neg_lo:[1,0,0] neg_hi:[1,0,0]
	v_pk_fma_f32 v[186:187], v[184:185], v[40:41], v[186:187] op_sel:[1,0,0] neg_lo:[1,0,0] neg_hi:[1,0,0]
	v_pk_fma_f32 v[38:39], v[36:37], v[184:185], v[38:39] op_sel_hi:[1,0,1] neg_lo:[1,0,0] neg_hi:[1,0,0]
	ds_read_b128 v[182:185], v20 offset:45392
	v_pk_add_f32 v[38:39], v[38:39], v[186:187]
	s_waitcnt lgkmcnt(5)
	v_pk_fma_f32 v[42:43], v[138:139], v[160:161], 0 op_sel:[0,1,0] op_sel_hi:[1,1,0] neg_lo:[1,0,0] neg_hi:[1,0,0]
	v_pk_fma_f32 v[252:253], v[128:129], v[160:161], v[158:159] op_sel_hi:[1,0,1] neg_lo:[1,0,0] neg_hi:[1,0,0]
	v_pk_fma_f32 v[42:43], v[134:135], v[162:163], v[42:43] op_sel:[0,1,0] neg_lo:[1,0,0] neg_hi:[1,0,0]
	v_pk_fma_f32 v[252:253], v[136:137], v[162:163], v[252:253] op_sel_hi:[1,0,1] neg_lo:[1,0,0] neg_hi:[1,0,0]
	s_waitcnt lgkmcnt(4)
	v_pk_fma_f32 v[42:43], v[130:131], v[166:167], v[42:43] op_sel:[0,1,0] neg_lo:[1,0,0] neg_hi:[1,0,0]
	v_pk_fma_f32 v[252:253], v[132:133], v[166:167], v[252:253] op_sel_hi:[1,0,1] neg_lo:[1,0,0] neg_hi:[1,0,0]
	v_pk_fma_f32 v[42:43], v[84:85], v[168:169], v[42:43] op_sel:[0,1,0] neg_lo:[1,0,0] neg_hi:[1,0,0]
	v_pk_fma_f32 v[252:253], v[122:123], v[168:169], v[252:253] op_sel_hi:[1,0,1] neg_lo:[1,0,0] neg_hi:[1,0,0]
	ds_read_b128 v[166:169], v20 offset:45584
	s_waitcnt lgkmcnt(4)
	v_pk_fma_f32 v[42:43], v[10:11], v[170:171], v[42:43] op_sel:[0,1,0] neg_lo:[1,0,0] neg_hi:[1,0,0]
	v_pk_fma_f32 v[252:253], v[14:15], v[170:171], v[252:253] op_sel_hi:[1,0,1] neg_lo:[1,0,0] neg_hi:[1,0,0]
	v_pk_fma_f32 v[42:43], v[6:7], v[172:173], v[42:43] op_sel:[0,1,0] neg_lo:[1,0,0] neg_hi:[1,0,0]
	v_pk_fma_f32 v[252:253], v[16:17], v[172:173], v[252:253] op_sel_hi:[1,0,1] neg_lo:[1,0,0] neg_hi:[1,0,0]
	ds_read_b128 v[170:173], v20 offset:45600
	s_waitcnt lgkmcnt(4)
	v_pk_fma_f32 v[42:43], v[12:13], v[174:175], v[42:43] op_sel:[0,1,0] neg_lo:[1,0,0] neg_hi:[1,0,0]
	v_pk_fma_f32 v[252:253], v[18:19], v[174:175], v[252:253] op_sel_hi:[1,0,1] neg_lo:[1,0,0] neg_hi:[1,0,0]
	v_pk_fma_f32 v[42:43], v[4:5], v[176:177], v[42:43] op_sel:[0,1,0] neg_lo:[1,0,0] neg_hi:[1,0,0]
	v_pk_fma_f32 v[252:253], v[8:9], v[176:177], v[252:253] op_sel_hi:[1,0,1] neg_lo:[1,0,0] neg_hi:[1,0,0]
	ds_read_b128 v[174:177], v20 offset:45616
	s_waitcnt lgkmcnt(4)
	v_pk_fma_f32 v[42:43], v[0:1], v[178:179], v[42:43] op_sel:[0,1,0] neg_lo:[1,0,0] neg_hi:[1,0,0]
	v_pk_fma_f32 v[252:253], v[2:3], v[178:179], v[252:253] op_sel_hi:[1,0,1] neg_lo:[1,0,0] neg_hi:[1,0,0]
	v_pk_fma_f32 v[42:43], v[28:29], v[180:181], v[42:43] op_sel:[0,1,0] neg_lo:[1,0,0] neg_hi:[1,0,0]
	v_pk_fma_f32 v[252:253], v[30:31], v[180:181], v[252:253] op_sel_hi:[1,0,1] neg_lo:[1,0,0] neg_hi:[1,0,0]
	ds_read_b128 v[178:181], v20 offset:45632
	s_waitcnt lgkmcnt(4)
	v_pk_fma_f32 v[42:43], v[34:35], v[182:183], v[42:43] op_sel:[0,1,0] neg_lo:[1,0,0] neg_hi:[1,0,0]
	v_pk_fma_f32 v[252:253], v[32:33], v[182:183], v[252:253] op_sel_hi:[1,0,1] neg_lo:[1,0,0] neg_hi:[1,0,0]
	v_pk_fma_f32 v[42:43], v[40:41], v[184:185], v[42:43] op_sel:[0,1,0] neg_lo:[1,0,0] neg_hi:[1,0,0]
	v_pk_fma_f32 v[252:253], v[36:37], v[184:185], v[252:253] op_sel_hi:[1,0,1] neg_lo:[1,0,0] neg_hi:[1,0,0]
	ds_read_b128 v[182:185], v20 offset:45648
	v_pk_fma_f32 v[42:43], v[158:159], v[208:209], v[42:43] op_sel:[0,1,0] neg_lo:[1,0,0] neg_hi:[1,0,0]
	ds_read_b128 v[158:161], v20 offset:45568
	v_pk_fma_f32 v[42:43], v[46:47], v[210:211], v[42:43] op_sel:[0,1,0] neg_lo:[1,0,0] neg_hi:[1,0,0]
	v_pk_fma_f32 v[252:253], v[208:209], v[38:39], v[252:253] op_sel_hi:[0,1,1] neg_lo:[1,0,0] neg_hi:[1,0,0]
	s_waitcnt lgkmcnt(0)
	v_pk_fma_f32 v[162:163], v[138:139], v[158:159], 0 op_sel:[0,1,0] op_sel_hi:[1,1,0] neg_lo:[1,0,0] neg_hi:[1,0,0]
	v_pk_fma_f32 v[252:253], v[44:45], v[210:211], v[252:253] op_sel_hi:[1,0,1] neg_lo:[1,0,0] neg_hi:[1,0,0]
	ds_read_b128 v[208:211], v20 offset:45664
	v_pk_add_f32 v[42:43], v[252:253], v[42:43]
	v_pk_fma_f32 v[158:159], v[128:129], v[158:159], v[44:45] op_sel_hi:[1,0,1] neg_lo:[1,0,0] neg_hi:[1,0,0]
	v_pk_fma_f32 v[162:163], v[134:135], v[160:161], v[162:163] op_sel:[0,1,0] neg_lo:[1,0,0] neg_hi:[1,0,0]
	v_pk_fma_f32 v[158:159], v[136:137], v[160:161], v[158:159] op_sel_hi:[1,0,1] neg_lo:[1,0,0] neg_hi:[1,0,0]
	v_pk_fma_f32 v[162:163], v[130:131], v[166:167], v[162:163] op_sel:[0,1,0] neg_lo:[1,0,0] neg_hi:[1,0,0]
	v_pk_fma_f32 v[158:159], v[132:133], v[166:167], v[158:159] op_sel_hi:[1,0,1] neg_lo:[1,0,0] neg_hi:[1,0,0]
	v_pk_fma_f32 v[162:163], v[84:85], v[168:169], v[162:163] op_sel:[0,1,0] neg_lo:[1,0,0] neg_hi:[1,0,0]
	v_pk_fma_f32 v[158:159], v[122:123], v[168:169], v[158:159] op_sel_hi:[1,0,1] neg_lo:[1,0,0] neg_hi:[1,0,0]
	ds_read_b128 v[166:169], v20 offset:45840
	v_pk_fma_f32 v[162:163], v[10:11], v[170:171], v[162:163] op_sel:[0,1,0] neg_lo:[1,0,0] neg_hi:[1,0,0]
	v_pk_fma_f32 v[158:159], v[14:15], v[170:171], v[158:159] op_sel_hi:[1,0,1] neg_lo:[1,0,0] neg_hi:[1,0,0]
	v_pk_fma_f32 v[162:163], v[6:7], v[172:173], v[162:163] op_sel:[0,1,0] neg_lo:[1,0,0] neg_hi:[1,0,0]
	v_pk_fma_f32 v[158:159], v[16:17], v[172:173], v[158:159] op_sel_hi:[1,0,1] neg_lo:[1,0,0] neg_hi:[1,0,0]
	ds_read_b128 v[170:173], v20 offset:45856
	v_pk_fma_f32 v[162:163], v[12:13], v[174:175], v[162:163] op_sel:[0,1,0] neg_lo:[1,0,0] neg_hi:[1,0,0]
	v_pk_fma_f32 v[158:159], v[18:19], v[174:175], v[158:159] op_sel_hi:[1,0,1] neg_lo:[1,0,0] neg_hi:[1,0,0]
	v_pk_fma_f32 v[162:163], v[4:5], v[176:177], v[162:163] op_sel:[0,1,0] neg_lo:[1,0,0] neg_hi:[1,0,0]
	v_pk_fma_f32 v[158:159], v[8:9], v[176:177], v[158:159] op_sel_hi:[1,0,1] neg_lo:[1,0,0] neg_hi:[1,0,0]
	ds_read_b128 v[174:177], v20 offset:45872
	v_pk_fma_f32 v[162:163], v[0:1], v[178:179], v[162:163] op_sel:[0,1,0] neg_lo:[1,0,0] neg_hi:[1,0,0]
	v_pk_fma_f32 v[158:159], v[2:3], v[178:179], v[158:159] op_sel_hi:[1,0,1] neg_lo:[1,0,0] neg_hi:[1,0,0]
	v_pk_fma_f32 v[162:163], v[28:29], v[180:181], v[162:163] op_sel:[0,1,0] neg_lo:[1,0,0] neg_hi:[1,0,0]
	v_pk_fma_f32 v[158:159], v[30:31], v[180:181], v[158:159] op_sel_hi:[1,0,1] neg_lo:[1,0,0] neg_hi:[1,0,0]
	ds_read_b128 v[178:181], v20 offset:45888
	v_pk_fma_f32 v[162:163], v[34:35], v[182:183], v[162:163] op_sel:[0,1,0] neg_lo:[1,0,0] neg_hi:[1,0,0]
	v_pk_fma_f32 v[158:159], v[32:33], v[182:183], v[158:159] op_sel_hi:[1,0,1] neg_lo:[1,0,0] neg_hi:[1,0,0]
	v_pk_fma_f32 v[162:163], v[40:41], v[184:185], v[162:163] op_sel:[0,1,0] neg_lo:[1,0,0] neg_hi:[1,0,0]
	v_pk_fma_f32 v[158:159], v[36:37], v[184:185], v[158:159] op_sel_hi:[1,0,1] neg_lo:[1,0,0] neg_hi:[1,0,0]
	ds_read_b128 v[182:185], v20 offset:45904
	s_waitcnt lgkmcnt(5)
	v_pk_fma_f32 v[162:163], v[208:209], v[42:43], v[162:163] op_sel:[1,0,0] neg_lo:[1,0,0] neg_hi:[1,0,0]
	v_pk_fma_f32 v[158:159], v[38:39], v[208:209], v[158:159] op_sel_hi:[1,0,1] neg_lo:[1,0,0] neg_hi:[1,0,0]
	v_pk_fma_f32 v[162:163], v[46:47], v[210:211], v[162:163] op_sel:[0,1,0] neg_lo:[1,0,0] neg_hi:[1,0,0]
	v_pk_fma_f32 v[44:45], v[44:45], v[210:211], v[158:159] op_sel_hi:[1,0,1] neg_lo:[1,0,0] neg_hi:[1,0,0]
	ds_read_b128 v[158:161], v20 offset:45824
	ds_read_b128 v[208:211], v20 offset:45920
	v_pk_add_f32 v[44:45], v[44:45], v[162:163]
	s_waitcnt lgkmcnt(1)
	v_pk_fma_f32 v[162:163], v[138:139], v[158:159], 0 op_sel:[0,1,0] op_sel_hi:[1,1,0] neg_lo:[1,0,0] neg_hi:[1,0,0]
	v_pk_fma_f32 v[252:253], v[128:129], v[158:159], v[46:47] op_sel_hi:[1,0,1] neg_lo:[1,0,0] neg_hi:[1,0,0]
	v_pk_fma_f32 v[162:163], v[134:135], v[160:161], v[162:163] op_sel:[0,1,0] neg_lo:[1,0,0] neg_hi:[1,0,0]
	v_pk_fma_f32 v[252:253], v[136:137], v[160:161], v[252:253] op_sel_hi:[1,0,1] neg_lo:[1,0,0] neg_hi:[1,0,0]
	ds_read_b128 v[158:161], v20 offset:46080
	v_pk_fma_f32 v[162:163], v[130:131], v[166:167], v[162:163] op_sel:[0,1,0] neg_lo:[1,0,0] neg_hi:[1,0,0]
	v_pk_fma_f32 v[252:253], v[132:133], v[166:167], v[252:253] op_sel_hi:[1,0,1] neg_lo:[1,0,0] neg_hi:[1,0,0]
	v_pk_fma_f32 v[162:163], v[84:85], v[168:169], v[162:163] op_sel:[0,1,0] neg_lo:[1,0,0] neg_hi:[1,0,0]
	v_pk_fma_f32 v[252:253], v[122:123], v[168:169], v[252:253] op_sel_hi:[1,0,1] neg_lo:[1,0,0] neg_hi:[1,0,0]
	ds_read_b128 v[166:169], v20 offset:46096
	v_pk_fma_f32 v[162:163], v[10:11], v[170:171], v[162:163] op_sel:[0,1,0] neg_lo:[1,0,0] neg_hi:[1,0,0]
	v_pk_fma_f32 v[252:253], v[14:15], v[170:171], v[252:253] op_sel_hi:[1,0,1] neg_lo:[1,0,0] neg_hi:[1,0,0]
	v_pk_fma_f32 v[162:163], v[6:7], v[172:173], v[162:163] op_sel:[0,1,0] neg_lo:[1,0,0] neg_hi:[1,0,0]
	v_pk_fma_f32 v[252:253], v[16:17], v[172:173], v[252:253] op_sel_hi:[1,0,1] neg_lo:[1,0,0] neg_hi:[1,0,0]
	ds_read_b128 v[170:173], v20 offset:46112
	v_pk_fma_f32 v[162:163], v[12:13], v[174:175], v[162:163] op_sel:[0,1,0] neg_lo:[1,0,0] neg_hi:[1,0,0]
	v_pk_fma_f32 v[252:253], v[18:19], v[174:175], v[252:253] op_sel_hi:[1,0,1] neg_lo:[1,0,0] neg_hi:[1,0,0]
	v_pk_fma_f32 v[162:163], v[4:5], v[176:177], v[162:163] op_sel:[0,1,0] neg_lo:[1,0,0] neg_hi:[1,0,0]
	v_pk_fma_f32 v[252:253], v[8:9], v[176:177], v[252:253] op_sel_hi:[1,0,1] neg_lo:[1,0,0] neg_hi:[1,0,0]
	ds_read_b128 v[174:177], v20 offset:46128
	v_pk_fma_f32 v[162:163], v[0:1], v[178:179], v[162:163] op_sel:[0,1,0] neg_lo:[1,0,0] neg_hi:[1,0,0]
	v_pk_fma_f32 v[252:253], v[2:3], v[178:179], v[252:253] op_sel_hi:[1,0,1] neg_lo:[1,0,0] neg_hi:[1,0,0]
	v_pk_fma_f32 v[162:163], v[28:29], v[180:181], v[162:163] op_sel:[0,1,0] neg_lo:[1,0,0] neg_hi:[1,0,0]
	v_pk_fma_f32 v[252:253], v[30:31], v[180:181], v[252:253] op_sel_hi:[1,0,1] neg_lo:[1,0,0] neg_hi:[1,0,0]
	ds_read_b128 v[178:181], v20 offset:46144
	v_pk_fma_f32 v[162:163], v[34:35], v[182:183], v[162:163] op_sel:[0,1,0] neg_lo:[1,0,0] neg_hi:[1,0,0]
	v_pk_fma_f32 v[252:253], v[32:33], v[182:183], v[252:253] op_sel_hi:[1,0,1] neg_lo:[1,0,0] neg_hi:[1,0,0]
	v_pk_fma_f32 v[162:163], v[40:41], v[184:185], v[162:163] op_sel:[0,1,0] neg_lo:[1,0,0] neg_hi:[1,0,0]
	v_pk_fma_f32 v[252:253], v[36:37], v[184:185], v[252:253] op_sel_hi:[1,0,1] neg_lo:[1,0,0] neg_hi:[1,0,0]
	ds_read_b128 v[182:185], v20 offset:46160
	s_waitcnt lgkmcnt(6)
	v_pk_fma_f32 v[162:163], v[42:43], v[208:209], v[162:163] op_sel:[0,1,0] neg_lo:[1,0,0] neg_hi:[1,0,0]
	v_pk_fma_f32 v[252:253], v[38:39], v[208:209], v[252:253] op_sel_hi:[1,0,1] neg_lo:[1,0,0] neg_hi:[1,0,0]
	v_pk_fma_f32 v[162:163], v[46:47], v[210:211], v[162:163] op_sel:[0,1,0] neg_lo:[1,0,0] neg_hi:[1,0,0]
	v_pk_fma_f32 v[252:253], v[210:211], v[44:45], v[252:253] op_sel_hi:[0,1,1] neg_lo:[1,0,0] neg_hi:[1,0,0]
	ds_read_b128 v[208:211], v20 offset:46176
	v_pk_add_f32 v[46:47], v[252:253], v[162:163]
	s_waitcnt lgkmcnt(6)
	v_pk_fma_f32 v[162:163], v[138:139], v[158:159], 0 op_sel:[0,1,0] op_sel_hi:[1,1,0] neg_lo:[1,0,0] neg_hi:[1,0,0]
	v_pk_mul_f32 v[158:159], v[128:129], v[158:159] op_sel_hi:[1,0]
	v_pk_fma_f32 v[162:163], v[134:135], v[160:161], v[162:163] op_sel:[0,1,0] neg_lo:[1,0,0] neg_hi:[1,0,0]
	v_pk_fma_f32 v[48:49], v[48:49], v[50:51], v[158:159] neg_lo:[0,0,1] neg_hi:[0,0,1]
	s_waitcnt lgkmcnt(5)
	v_pk_fma_f32 v[162:163], v[130:131], v[166:167], v[162:163] op_sel:[0,1,0] neg_lo:[1,0,0] neg_hi:[1,0,0]
	v_pk_fma_f32 v[48:49], v[136:137], v[160:161], v[48:49] op_sel_hi:[1,0,1] neg_lo:[1,0,0] neg_hi:[1,0,0]
	ds_read_b128 v[158:161], v20 offset:46336
	v_pk_fma_f32 v[48:49], v[132:133], v[166:167], v[48:49] op_sel_hi:[1,0,1] neg_lo:[1,0,0] neg_hi:[1,0,0]
	v_pk_fma_f32 v[162:163], v[84:85], v[168:169], v[162:163] op_sel:[0,1,0] neg_lo:[1,0,0] neg_hi:[1,0,0]
	v_pk_fma_f32 v[48:49], v[122:123], v[168:169], v[48:49] op_sel_hi:[1,0,1] neg_lo:[1,0,0] neg_hi:[1,0,0]
	ds_read_b128 v[166:169], v20 offset:46352
	s_waitcnt lgkmcnt(6)
	v_pk_fma_f32 v[162:163], v[10:11], v[170:171], v[162:163] op_sel:[0,1,0] neg_lo:[1,0,0] neg_hi:[1,0,0]
	v_pk_fma_f32 v[48:49], v[14:15], v[170:171], v[48:49] op_sel_hi:[1,0,1] neg_lo:[1,0,0] neg_hi:[1,0,0]
	v_pk_fma_f32 v[162:163], v[6:7], v[172:173], v[162:163] op_sel:[0,1,0] neg_lo:[1,0,0] neg_hi:[1,0,0]
	v_pk_fma_f32 v[48:49], v[16:17], v[172:173], v[48:49] op_sel_hi:[1,0,1] neg_lo:[1,0,0] neg_hi:[1,0,0]
	ds_read_b128 v[170:173], v20 offset:46368
	s_waitcnt lgkmcnt(6)
	v_pk_fma_f32 v[162:163], v[12:13], v[174:175], v[162:163] op_sel:[0,1,0] neg_lo:[1,0,0] neg_hi:[1,0,0]
	v_pk_fma_f32 v[48:49], v[18:19], v[174:175], v[48:49] op_sel_hi:[1,0,1] neg_lo:[1,0,0] neg_hi:[1,0,0]
	v_pk_fma_f32 v[162:163], v[4:5], v[176:177], v[162:163] op_sel:[0,1,0] neg_lo:[1,0,0] neg_hi:[1,0,0]
	v_pk_fma_f32 v[48:49], v[8:9], v[176:177], v[48:49] op_sel_hi:[1,0,1] neg_lo:[1,0,0] neg_hi:[1,0,0]
	ds_read_b128 v[174:177], v20 offset:46384
	s_waitcnt lgkmcnt(6)
	v_pk_fma_f32 v[162:163], v[0:1], v[178:179], v[162:163] op_sel:[0,1,0] neg_lo:[1,0,0] neg_hi:[1,0,0]
	v_pk_fma_f32 v[48:49], v[2:3], v[178:179], v[48:49] op_sel_hi:[1,0,1] neg_lo:[1,0,0] neg_hi:[1,0,0]
	v_pk_fma_f32 v[162:163], v[28:29], v[180:181], v[162:163] op_sel:[0,1,0] neg_lo:[1,0,0] neg_hi:[1,0,0]
	v_pk_fma_f32 v[48:49], v[30:31], v[180:181], v[48:49] op_sel_hi:[1,0,1] neg_lo:[1,0,0] neg_hi:[1,0,0]
	ds_read_b128 v[178:181], v20 offset:46400
	s_waitcnt lgkmcnt(6)
	v_pk_fma_f32 v[162:163], v[34:35], v[182:183], v[162:163] op_sel:[0,1,0] neg_lo:[1,0,0] neg_hi:[1,0,0]
	v_pk_fma_f32 v[48:49], v[32:33], v[182:183], v[48:49] op_sel_hi:[1,0,1] neg_lo:[1,0,0] neg_hi:[1,0,0]
	v_pk_fma_f32 v[162:163], v[40:41], v[184:185], v[162:163] op_sel:[0,1,0] neg_lo:[1,0,0] neg_hi:[1,0,0]
	v_pk_fma_f32 v[48:49], v[36:37], v[184:185], v[48:49] op_sel_hi:[1,0,1] neg_lo:[1,0,0] neg_hi:[1,0,0]
	ds_read_b128 v[182:185], v20 offset:46416
	s_waitcnt lgkmcnt(6)
	v_pk_fma_f32 v[162:163], v[42:43], v[208:209], v[162:163] op_sel:[0,1,0] neg_lo:[1,0,0] neg_hi:[1,0,0]
	v_pk_fma_f32 v[48:49], v[38:39], v[208:209], v[48:49] op_sel_hi:[1,0,1] neg_lo:[1,0,0] neg_hi:[1,0,0]
	v_pk_fma_f32 v[162:163], v[210:211], v[46:47], v[162:163] op_sel:[1,0,0] neg_lo:[1,0,0] neg_hi:[1,0,0]
	v_pk_fma_f32 v[48:49], v[44:45], v[210:211], v[48:49] op_sel_hi:[1,0,1] neg_lo:[1,0,0] neg_hi:[1,0,0]
	ds_read_b128 v[208:211], v20 offset:46432
	v_pk_add_f32 v[48:49], v[48:49], v[162:163]
	s_waitcnt lgkmcnt(6)
	v_pk_fma_f32 v[50:51], v[138:139], v[158:159], 0 op_sel:[0,1,0] op_sel_hi:[1,1,0] neg_lo:[1,0,0] neg_hi:[1,0,0]
	v_pk_fma_f32 v[252:253], v[128:129], v[158:159], v[156:157] op_sel_hi:[1,0,1] neg_lo:[1,0,0] neg_hi:[1,0,0]
	v_pk_fma_f32 v[50:51], v[134:135], v[160:161], v[50:51] op_sel:[0,1,0] neg_lo:[1,0,0] neg_hi:[1,0,0]
	v_pk_fma_f32 v[252:253], v[136:137], v[160:161], v[252:253] op_sel_hi:[1,0,1] neg_lo:[1,0,0] neg_hi:[1,0,0]
	ds_read_b128 v[160:163], v20 offset:46608
	s_waitcnt lgkmcnt(6)
	v_pk_fma_f32 v[50:51], v[130:131], v[166:167], v[50:51] op_sel:[0,1,0] neg_lo:[1,0,0] neg_hi:[1,0,0]
	v_pk_fma_f32 v[252:253], v[132:133], v[166:167], v[252:253] op_sel_hi:[1,0,1] neg_lo:[1,0,0] neg_hi:[1,0,0]
	v_pk_fma_f32 v[50:51], v[84:85], v[168:169], v[50:51] op_sel:[0,1,0] neg_lo:[1,0,0] neg_hi:[1,0,0]
	v_pk_fma_f32 v[252:253], v[122:123], v[168:169], v[252:253] op_sel_hi:[1,0,1] neg_lo:[1,0,0] neg_hi:[1,0,0]
	ds_read_b128 v[166:169], v20 offset:46624
	s_waitcnt lgkmcnt(6)
	v_pk_fma_f32 v[50:51], v[10:11], v[170:171], v[50:51] op_sel:[0,1,0] neg_lo:[1,0,0] neg_hi:[1,0,0]
	v_pk_fma_f32 v[252:253], v[14:15], v[170:171], v[252:253] op_sel_hi:[1,0,1] neg_lo:[1,0,0] neg_hi:[1,0,0]
	v_pk_fma_f32 v[50:51], v[6:7], v[172:173], v[50:51] op_sel:[0,1,0] neg_lo:[1,0,0] neg_hi:[1,0,0]
	v_pk_fma_f32 v[252:253], v[16:17], v[172:173], v[252:253] op_sel_hi:[1,0,1] neg_lo:[1,0,0] neg_hi:[1,0,0]
	ds_read_b128 v[170:173], v20 offset:46640
	s_waitcnt lgkmcnt(6)
	v_pk_fma_f32 v[50:51], v[12:13], v[174:175], v[50:51] op_sel:[0,1,0] neg_lo:[1,0,0] neg_hi:[1,0,0]
	v_pk_fma_f32 v[252:253], v[18:19], v[174:175], v[252:253] op_sel_hi:[1,0,1] neg_lo:[1,0,0] neg_hi:[1,0,0]
	v_pk_fma_f32 v[50:51], v[4:5], v[176:177], v[50:51] op_sel:[0,1,0] neg_lo:[1,0,0] neg_hi:[1,0,0]
	v_pk_fma_f32 v[252:253], v[8:9], v[176:177], v[252:253] op_sel_hi:[1,0,1] neg_lo:[1,0,0] neg_hi:[1,0,0]
	ds_read_b128 v[174:177], v20 offset:46656
	s_waitcnt lgkmcnt(6)
	v_pk_fma_f32 v[50:51], v[0:1], v[178:179], v[50:51] op_sel:[0,1,0] neg_lo:[1,0,0] neg_hi:[1,0,0]
	v_pk_fma_f32 v[252:253], v[2:3], v[178:179], v[252:253] op_sel_hi:[1,0,1] neg_lo:[1,0,0] neg_hi:[1,0,0]
	v_pk_fma_f32 v[50:51], v[28:29], v[180:181], v[50:51] op_sel:[0,1,0] neg_lo:[1,0,0] neg_hi:[1,0,0]
	v_pk_fma_f32 v[252:253], v[30:31], v[180:181], v[252:253] op_sel_hi:[1,0,1] neg_lo:[1,0,0] neg_hi:[1,0,0]
	ds_read_b128 v[178:181], v20 offset:46672
	s_waitcnt lgkmcnt(6)
	v_pk_fma_f32 v[50:51], v[34:35], v[182:183], v[50:51] op_sel:[0,1,0] neg_lo:[1,0,0] neg_hi:[1,0,0]
	v_pk_fma_f32 v[252:253], v[32:33], v[182:183], v[252:253] op_sel_hi:[1,0,1] neg_lo:[1,0,0] neg_hi:[1,0,0]
	v_pk_fma_f32 v[50:51], v[40:41], v[184:185], v[50:51] op_sel:[0,1,0] neg_lo:[1,0,0] neg_hi:[1,0,0]
	v_pk_fma_f32 v[252:253], v[36:37], v[184:185], v[252:253] op_sel_hi:[1,0,1] neg_lo:[1,0,0] neg_hi:[1,0,0]
	ds_read_b128 v[182:185], v20 offset:46688
	s_waitcnt lgkmcnt(6)
	v_pk_fma_f32 v[50:51], v[42:43], v[208:209], v[50:51] op_sel:[0,1,0] neg_lo:[1,0,0] neg_hi:[1,0,0]
	v_pk_fma_f32 v[252:253], v[38:39], v[208:209], v[252:253] op_sel_hi:[1,0,1] neg_lo:[1,0,0] neg_hi:[1,0,0]
	v_pk_fma_f32 v[50:51], v[46:47], v[210:211], v[50:51] op_sel:[0,1,0] neg_lo:[1,0,0] neg_hi:[1,0,0]
	v_pk_fma_f32 v[252:253], v[44:45], v[210:211], v[252:253] op_sel_hi:[1,0,1] neg_lo:[1,0,0] neg_hi:[1,0,0]
	ds_read_b128 v[208:211], v20 offset:46704
	v_pk_fma_f32 v[50:51], v[156:157], v[212:213], v[50:51] op_sel:[0,1,0] neg_lo:[1,0,0] neg_hi:[1,0,0]
	ds_read_b128 v[156:159], v20 offset:46592
	v_pk_fma_f32 v[50:51], v[54:55], v[214:215], v[50:51] op_sel:[0,1,0] neg_lo:[1,0,0] neg_hi:[1,0,0]
	v_pk_fma_f32 v[252:253], v[212:213], v[48:49], v[252:253] op_sel_hi:[0,1,1] neg_lo:[1,0,0] neg_hi:[1,0,0]
	s_waitcnt lgkmcnt(0)
	v_pk_fma_f32 v[186:187], v[138:139], v[156:157], 0 op_sel:[0,1,0] op_sel_hi:[1,1,0] neg_lo:[1,0,0] neg_hi:[1,0,0]
	v_pk_fma_f32 v[252:253], v[52:53], v[214:215], v[252:253] op_sel_hi:[1,0,1] neg_lo:[1,0,0] neg_hi:[1,0,0]
	v_pk_fma_f32 v[156:157], v[128:129], v[156:157], v[52:53] op_sel_hi:[1,0,1] neg_lo:[1,0,0] neg_hi:[1,0,0]
	v_pk_add_f32 v[50:51], v[252:253], v[50:51]
	v_pk_fma_f32 v[186:187], v[134:135], v[158:159], v[186:187] op_sel:[0,1,0] neg_lo:[1,0,0] neg_hi:[1,0,0]
	v_pk_fma_f32 v[156:157], v[136:137], v[158:159], v[156:157] op_sel_hi:[1,0,1] neg_lo:[1,0,0] neg_hi:[1,0,0]
	v_pk_fma_f32 v[186:187], v[130:131], v[160:161], v[186:187] op_sel:[0,1,0] neg_lo:[1,0,0] neg_hi:[1,0,0]
	v_pk_fma_f32 v[156:157], v[132:133], v[160:161], v[156:157] op_sel_hi:[1,0,1] neg_lo:[1,0,0] neg_hi:[1,0,0]
	v_pk_fma_f32 v[186:187], v[84:85], v[162:163], v[186:187] op_sel:[0,1,0] neg_lo:[1,0,0] neg_hi:[1,0,0]
	v_pk_fma_f32 v[156:157], v[122:123], v[162:163], v[156:157] op_sel_hi:[1,0,1] neg_lo:[1,0,0] neg_hi:[1,0,0]
	ds_read_b128 v[160:163], v20 offset:46864
	v_pk_fma_f32 v[186:187], v[10:11], v[166:167], v[186:187] op_sel:[0,1,0] neg_lo:[1,0,0] neg_hi:[1,0,0]
	v_pk_fma_f32 v[156:157], v[14:15], v[166:167], v[156:157] op_sel_hi:[1,0,1] neg_lo:[1,0,0] neg_hi:[1,0,0]
	v_pk_fma_f32 v[186:187], v[6:7], v[168:169], v[186:187] op_sel:[0,1,0] neg_lo:[1,0,0] neg_hi:[1,0,0]
	v_pk_fma_f32 v[156:157], v[16:17], v[168:169], v[156:157] op_sel_hi:[1,0,1] neg_lo:[1,0,0] neg_hi:[1,0,0]
	ds_read_b128 v[166:169], v20 offset:46880
	v_pk_fma_f32 v[186:187], v[12:13], v[170:171], v[186:187] op_sel:[0,1,0] neg_lo:[1,0,0] neg_hi:[1,0,0]
	v_pk_fma_f32 v[156:157], v[18:19], v[170:171], v[156:157] op_sel_hi:[1,0,1] neg_lo:[1,0,0] neg_hi:[1,0,0]
	v_pk_fma_f32 v[186:187], v[4:5], v[172:173], v[186:187] op_sel:[0,1,0] neg_lo:[1,0,0] neg_hi:[1,0,0]
	v_pk_fma_f32 v[156:157], v[8:9], v[172:173], v[156:157] op_sel_hi:[1,0,1] neg_lo:[1,0,0] neg_hi:[1,0,0]
	ds_read_b128 v[170:173], v20 offset:46896
	v_pk_fma_f32 v[186:187], v[0:1], v[174:175], v[186:187] op_sel:[0,1,0] neg_lo:[1,0,0] neg_hi:[1,0,0]
	v_pk_fma_f32 v[156:157], v[2:3], v[174:175], v[156:157] op_sel_hi:[1,0,1] neg_lo:[1,0,0] neg_hi:[1,0,0]
	v_pk_fma_f32 v[186:187], v[28:29], v[176:177], v[186:187] op_sel:[0,1,0] neg_lo:[1,0,0] neg_hi:[1,0,0]
	v_pk_fma_f32 v[156:157], v[30:31], v[176:177], v[156:157] op_sel_hi:[1,0,1] neg_lo:[1,0,0] neg_hi:[1,0,0]
	ds_read_b128 v[174:177], v20 offset:46912
	v_pk_fma_f32 v[186:187], v[34:35], v[178:179], v[186:187] op_sel:[0,1,0] neg_lo:[1,0,0] neg_hi:[1,0,0]
	v_pk_fma_f32 v[156:157], v[32:33], v[178:179], v[156:157] op_sel_hi:[1,0,1] neg_lo:[1,0,0] neg_hi:[1,0,0]
	v_pk_fma_f32 v[186:187], v[40:41], v[180:181], v[186:187] op_sel:[0,1,0] neg_lo:[1,0,0] neg_hi:[1,0,0]
	v_pk_fma_f32 v[156:157], v[36:37], v[180:181], v[156:157] op_sel_hi:[1,0,1] neg_lo:[1,0,0] neg_hi:[1,0,0]
	ds_read_b128 v[178:181], v20 offset:46928
	v_pk_fma_f32 v[186:187], v[42:43], v[182:183], v[186:187] op_sel:[0,1,0] neg_lo:[1,0,0] neg_hi:[1,0,0]
	v_pk_fma_f32 v[156:157], v[38:39], v[182:183], v[156:157] op_sel_hi:[1,0,1] neg_lo:[1,0,0] neg_hi:[1,0,0]
	v_pk_fma_f32 v[186:187], v[46:47], v[184:185], v[186:187] op_sel:[0,1,0] neg_lo:[1,0,0] neg_hi:[1,0,0]
	v_pk_fma_f32 v[156:157], v[44:45], v[184:185], v[156:157] op_sel_hi:[1,0,1] neg_lo:[1,0,0] neg_hi:[1,0,0]
	ds_read_b128 v[182:185], v20 offset:46944
	v_pk_fma_f32 v[186:187], v[208:209], v[50:51], v[186:187] op_sel:[1,0,0] neg_lo:[1,0,0] neg_hi:[1,0,0]
	v_pk_fma_f32 v[156:157], v[48:49], v[208:209], v[156:157] op_sel_hi:[1,0,1] neg_lo:[1,0,0] neg_hi:[1,0,0]
	v_pk_fma_f32 v[186:187], v[54:55], v[210:211], v[186:187] op_sel:[0,1,0] neg_lo:[1,0,0] neg_hi:[1,0,0]
	v_pk_fma_f32 v[52:53], v[52:53], v[210:211], v[156:157] op_sel_hi:[1,0,1] neg_lo:[1,0,0] neg_hi:[1,0,0]
	ds_read_b128 v[156:159], v20 offset:46848
	ds_read_b128 v[208:211], v20 offset:46960
	v_pk_add_f32 v[52:53], v[52:53], v[186:187]
	s_waitcnt lgkmcnt(1)
	v_pk_fma_f32 v[186:187], v[138:139], v[156:157], 0 op_sel:[0,1,0] op_sel_hi:[1,1,0] neg_lo:[1,0,0] neg_hi:[1,0,0]
	v_pk_fma_f32 v[252:253], v[128:129], v[156:157], v[54:55] op_sel_hi:[1,0,1] neg_lo:[1,0,0] neg_hi:[1,0,0]
	v_pk_fma_f32 v[186:187], v[134:135], v[158:159], v[186:187] op_sel:[0,1,0] neg_lo:[1,0,0] neg_hi:[1,0,0]
	v_pk_fma_f32 v[252:253], v[136:137], v[158:159], v[252:253] op_sel_hi:[1,0,1] neg_lo:[1,0,0] neg_hi:[1,0,0]
	ds_read_b128 v[156:159], v20 offset:47104
	v_pk_fma_f32 v[186:187], v[130:131], v[160:161], v[186:187] op_sel:[0,1,0] neg_lo:[1,0,0] neg_hi:[1,0,0]
	v_pk_fma_f32 v[252:253], v[132:133], v[160:161], v[252:253] op_sel_hi:[1,0,1] neg_lo:[1,0,0] neg_hi:[1,0,0]
	v_pk_fma_f32 v[186:187], v[84:85], v[162:163], v[186:187] op_sel:[0,1,0] neg_lo:[1,0,0] neg_hi:[1,0,0]
	v_pk_fma_f32 v[252:253], v[122:123], v[162:163], v[252:253] op_sel_hi:[1,0,1] neg_lo:[1,0,0] neg_hi:[1,0,0]
	ds_read_b128 v[160:163], v20 offset:47120
	v_pk_fma_f32 v[186:187], v[10:11], v[166:167], v[186:187] op_sel:[0,1,0] neg_lo:[1,0,0] neg_hi:[1,0,0]
	v_pk_fma_f32 v[252:253], v[14:15], v[166:167], v[252:253] op_sel_hi:[1,0,1] neg_lo:[1,0,0] neg_hi:[1,0,0]
	v_pk_fma_f32 v[186:187], v[6:7], v[168:169], v[186:187] op_sel:[0,1,0] neg_lo:[1,0,0] neg_hi:[1,0,0]
	v_pk_fma_f32 v[252:253], v[16:17], v[168:169], v[252:253] op_sel_hi:[1,0,1] neg_lo:[1,0,0] neg_hi:[1,0,0]
	ds_read_b128 v[166:169], v20 offset:47136
	v_pk_fma_f32 v[186:187], v[12:13], v[170:171], v[186:187] op_sel:[0,1,0] neg_lo:[1,0,0] neg_hi:[1,0,0]
	v_pk_fma_f32 v[252:253], v[18:19], v[170:171], v[252:253] op_sel_hi:[1,0,1] neg_lo:[1,0,0] neg_hi:[1,0,0]
	v_pk_fma_f32 v[186:187], v[4:5], v[172:173], v[186:187] op_sel:[0,1,0] neg_lo:[1,0,0] neg_hi:[1,0,0]
	v_pk_fma_f32 v[252:253], v[8:9], v[172:173], v[252:253] op_sel_hi:[1,0,1] neg_lo:[1,0,0] neg_hi:[1,0,0]
	ds_read_b128 v[170:173], v20 offset:47152
	v_pk_fma_f32 v[186:187], v[0:1], v[174:175], v[186:187] op_sel:[0,1,0] neg_lo:[1,0,0] neg_hi:[1,0,0]
	v_pk_fma_f32 v[252:253], v[2:3], v[174:175], v[252:253] op_sel_hi:[1,0,1] neg_lo:[1,0,0] neg_hi:[1,0,0]
	v_pk_fma_f32 v[186:187], v[28:29], v[176:177], v[186:187] op_sel:[0,1,0] neg_lo:[1,0,0] neg_hi:[1,0,0]
	ds_read_b128 v[212:215], v20 offset:47488
	v_pk_fma_f32 v[186:187], v[34:35], v[178:179], v[186:187] op_sel:[0,1,0] neg_lo:[1,0,0] neg_hi:[1,0,0]
	v_pk_fma_f32 v[252:253], v[30:31], v[176:177], v[252:253] op_sel_hi:[1,0,1] neg_lo:[1,0,0] neg_hi:[1,0,0]
	ds_read_b128 v[174:177], v20 offset:47168
	v_pk_fma_f32 v[186:187], v[40:41], v[180:181], v[186:187] op_sel:[0,1,0] neg_lo:[1,0,0] neg_hi:[1,0,0]
	v_pk_fma_f32 v[252:253], v[32:33], v[178:179], v[252:253] op_sel_hi:[1,0,1] neg_lo:[1,0,0] neg_hi:[1,0,0]
	v_pk_fma_f32 v[186:187], v[42:43], v[182:183], v[186:187] op_sel:[0,1,0] neg_lo:[1,0,0] neg_hi:[1,0,0]
	v_pk_fma_f32 v[252:253], v[36:37], v[180:181], v[252:253] op_sel_hi:[1,0,1] neg_lo:[1,0,0] neg_hi:[1,0,0]
	ds_read_b128 v[178:181], v20 offset:47184
	v_pk_fma_f32 v[186:187], v[46:47], v[184:185], v[186:187] op_sel:[0,1,0] neg_lo:[1,0,0] neg_hi:[1,0,0]
	v_pk_fma_f32 v[252:253], v[38:39], v[182:183], v[252:253] op_sel_hi:[1,0,1] neg_lo:[1,0,0] neg_hi:[1,0,0]
	s_waitcnt lgkmcnt(7)
	v_pk_fma_f32 v[186:187], v[50:51], v[208:209], v[186:187] op_sel:[0,1,0] neg_lo:[1,0,0] neg_hi:[1,0,0]
	v_pk_fma_f32 v[252:253], v[44:45], v[184:185], v[252:253] op_sel_hi:[1,0,1] neg_lo:[1,0,0] neg_hi:[1,0,0]
	ds_read_b128 v[182:185], v20 offset:47200
	v_pk_fma_f32 v[186:187], v[54:55], v[210:211], v[186:187] op_sel:[0,1,0] neg_lo:[1,0,0] neg_hi:[1,0,0]
	v_pk_fma_f32 v[252:253], v[48:49], v[208:209], v[252:253] op_sel_hi:[1,0,1] neg_lo:[1,0,0] neg_hi:[1,0,0]
	s_nop 0
	v_pk_fma_f32 v[252:253], v[210:211], v[52:53], v[252:253] op_sel_hi:[0,1,1] neg_lo:[1,0,0] neg_hi:[1,0,0]
	ds_read_b128 v[208:211], v20 offset:47216
	v_pk_add_f32 v[54:55], v[252:253], v[186:187]
	s_waitcnt lgkmcnt(8)
	v_pk_fma_f32 v[186:187], v[138:139], v[156:157], 0 op_sel:[0,1,0] op_sel_hi:[1,1,0] neg_lo:[1,0,0] neg_hi:[1,0,0]
	v_pk_mul_f32 v[156:157], v[128:129], v[156:157] op_sel_hi:[1,0]
	v_pk_fma_f32 v[186:187], v[134:135], v[158:159], v[186:187] op_sel:[0,1,0] neg_lo:[1,0,0] neg_hi:[1,0,0]
	v_pk_fma_f32 v[56:57], v[56:57], v[58:59], v[156:157] neg_lo:[0,0,1] neg_hi:[0,0,1]
	s_waitcnt lgkmcnt(7)
	v_pk_fma_f32 v[186:187], v[130:131], v[160:161], v[186:187] op_sel:[0,1,0] neg_lo:[1,0,0] neg_hi:[1,0,0]
	v_pk_fma_f32 v[56:57], v[136:137], v[158:159], v[56:57] op_sel_hi:[1,0,1] neg_lo:[1,0,0] neg_hi:[1,0,0]
	ds_read_b128 v[156:159], v20 offset:47360
	v_pk_fma_f32 v[56:57], v[132:133], v[160:161], v[56:57] op_sel_hi:[1,0,1] neg_lo:[1,0,0] neg_hi:[1,0,0]
	v_pk_fma_f32 v[186:187], v[84:85], v[162:163], v[186:187] op_sel:[0,1,0] neg_lo:[1,0,0] neg_hi:[1,0,0]
	v_pk_fma_f32 v[56:57], v[122:123], v[162:163], v[56:57] op_sel_hi:[1,0,1] neg_lo:[1,0,0] neg_hi:[1,0,0]
	ds_read_b128 v[160:163], v20 offset:47376
	s_waitcnt lgkmcnt(8)
	v_pk_fma_f32 v[186:187], v[10:11], v[166:167], v[186:187] op_sel:[0,1,0] neg_lo:[1,0,0] neg_hi:[1,0,0]
	v_pk_fma_f32 v[56:57], v[14:15], v[166:167], v[56:57] op_sel_hi:[1,0,1] neg_lo:[1,0,0] neg_hi:[1,0,0]
	v_pk_fma_f32 v[186:187], v[6:7], v[168:169], v[186:187] op_sel:[0,1,0] neg_lo:[1,0,0] neg_hi:[1,0,0]
	v_pk_fma_f32 v[56:57], v[16:17], v[168:169], v[56:57] op_sel_hi:[1,0,1] neg_lo:[1,0,0] neg_hi:[1,0,0]
	ds_read_b128 v[166:169], v20 offset:47392
	s_waitcnt lgkmcnt(8)
	v_pk_fma_f32 v[186:187], v[12:13], v[170:171], v[186:187] op_sel:[0,1,0] neg_lo:[1,0,0] neg_hi:[1,0,0]
	v_pk_fma_f32 v[56:57], v[18:19], v[170:171], v[56:57] op_sel_hi:[1,0,1] neg_lo:[1,0,0] neg_hi:[1,0,0]
	v_pk_fma_f32 v[186:187], v[4:5], v[172:173], v[186:187] op_sel:[0,1,0] neg_lo:[1,0,0] neg_hi:[1,0,0]
	v_pk_fma_f32 v[56:57], v[8:9], v[172:173], v[56:57] op_sel_hi:[1,0,1] neg_lo:[1,0,0] neg_hi:[1,0,0]
	ds_read_b128 v[170:173], v20 offset:47408
	s_waitcnt lgkmcnt(7)
	v_pk_fma_f32 v[186:187], v[0:1], v[174:175], v[186:187] op_sel:[0,1,0] neg_lo:[1,0,0] neg_hi:[1,0,0]
	v_pk_fma_f32 v[56:57], v[2:3], v[174:175], v[56:57] op_sel_hi:[1,0,1] neg_lo:[1,0,0] neg_hi:[1,0,0]
	v_pk_fma_f32 v[186:187], v[28:29], v[176:177], v[186:187] op_sel:[0,1,0] neg_lo:[1,0,0] neg_hi:[1,0,0]
	v_pk_fma_f32 v[56:57], v[30:31], v[176:177], v[56:57] op_sel_hi:[1,0,1] neg_lo:[1,0,0] neg_hi:[1,0,0]
	ds_read_b128 v[174:177], v20 offset:47424
	s_waitcnt lgkmcnt(7)
	v_pk_fma_f32 v[186:187], v[34:35], v[178:179], v[186:187] op_sel:[0,1,0] neg_lo:[1,0,0] neg_hi:[1,0,0]
	v_pk_fma_f32 v[56:57], v[32:33], v[178:179], v[56:57] op_sel_hi:[1,0,1] neg_lo:[1,0,0] neg_hi:[1,0,0]
	v_pk_fma_f32 v[186:187], v[40:41], v[180:181], v[186:187] op_sel:[0,1,0] neg_lo:[1,0,0] neg_hi:[1,0,0]
	v_pk_fma_f32 v[56:57], v[36:37], v[180:181], v[56:57] op_sel_hi:[1,0,1] neg_lo:[1,0,0] neg_hi:[1,0,0]
	ds_read_b128 v[178:181], v20 offset:47440
	s_waitcnt lgkmcnt(7)
	v_pk_fma_f32 v[186:187], v[42:43], v[182:183], v[186:187] op_sel:[0,1,0] neg_lo:[1,0,0] neg_hi:[1,0,0]
	v_pk_fma_f32 v[56:57], v[38:39], v[182:183], v[56:57] op_sel_hi:[1,0,1] neg_lo:[1,0,0] neg_hi:[1,0,0]
	v_pk_fma_f32 v[186:187], v[46:47], v[184:185], v[186:187] op_sel:[0,1,0] neg_lo:[1,0,0] neg_hi:[1,0,0]
	v_pk_fma_f32 v[56:57], v[44:45], v[184:185], v[56:57] op_sel_hi:[1,0,1] neg_lo:[1,0,0] neg_hi:[1,0,0]
	ds_read_b128 v[182:185], v20 offset:47456
	s_waitcnt lgkmcnt(7)
	v_pk_fma_f32 v[186:187], v[50:51], v[208:209], v[186:187] op_sel:[0,1,0] neg_lo:[1,0,0] neg_hi:[1,0,0]
	v_pk_fma_f32 v[56:57], v[48:49], v[208:209], v[56:57] op_sel_hi:[1,0,1] neg_lo:[1,0,0] neg_hi:[1,0,0]
	v_pk_fma_f32 v[186:187], v[210:211], v[54:55], v[186:187] op_sel:[1,0,0] neg_lo:[1,0,0] neg_hi:[1,0,0]
	v_pk_fma_f32 v[56:57], v[52:53], v[210:211], v[56:57] op_sel_hi:[1,0,1] neg_lo:[1,0,0] neg_hi:[1,0,0]
	ds_read_b128 v[208:211], v20 offset:47472
	v_pk_add_f32 v[56:57], v[56:57], v[186:187]
	s_waitcnt lgkmcnt(7)
	v_pk_fma_f32 v[58:59], v[138:139], v[156:157], 0 op_sel:[0,1,0] op_sel_hi:[1,1,0] neg_lo:[1,0,0] neg_hi:[1,0,0]
	v_pk_fma_f32 v[252:253], v[128:129], v[156:157], v[154:155] op_sel_hi:[1,0,1] neg_lo:[1,0,0] neg_hi:[1,0,0]
	v_pk_fma_f32 v[58:59], v[134:135], v[158:159], v[58:59] op_sel:[0,1,0] neg_lo:[1,0,0] neg_hi:[1,0,0]
	v_pk_fma_f32 v[252:253], v[136:137], v[158:159], v[252:253] op_sel_hi:[1,0,1] neg_lo:[1,0,0] neg_hi:[1,0,0]
	s_waitcnt lgkmcnt(6)
	v_pk_fma_f32 v[58:59], v[130:131], v[160:161], v[58:59] op_sel:[0,1,0] neg_lo:[1,0,0] neg_hi:[1,0,0]
	v_pk_fma_f32 v[252:253], v[132:133], v[160:161], v[252:253] op_sel_hi:[1,0,1] neg_lo:[1,0,0] neg_hi:[1,0,0]
	ds_read_b128 v[158:161], v20 offset:47632
	v_pk_fma_f32 v[58:59], v[84:85], v[162:163], v[58:59] op_sel:[0,1,0] neg_lo:[1,0,0] neg_hi:[1,0,0]
	v_pk_fma_f32 v[252:253], v[122:123], v[162:163], v[252:253] op_sel_hi:[1,0,1] neg_lo:[1,0,0] neg_hi:[1,0,0]
	s_waitcnt lgkmcnt(6)
	v_pk_fma_f32 v[58:59], v[10:11], v[166:167], v[58:59] op_sel:[0,1,0] neg_lo:[1,0,0] neg_hi:[1,0,0]
	v_pk_fma_f32 v[252:253], v[14:15], v[166:167], v[252:253] op_sel_hi:[1,0,1] neg_lo:[1,0,0] neg_hi:[1,0,0]
	v_pk_fma_f32 v[58:59], v[6:7], v[168:169], v[58:59] op_sel:[0,1,0] neg_lo:[1,0,0] neg_hi:[1,0,0]
	v_pk_fma_f32 v[252:253], v[16:17], v[168:169], v[252:253] op_sel_hi:[1,0,1] neg_lo:[1,0,0] neg_hi:[1,0,0]
	ds_read_b128 v[166:169], v20 offset:47648
	s_waitcnt lgkmcnt(6)
	v_pk_fma_f32 v[58:59], v[12:13], v[170:171], v[58:59] op_sel:[0,1,0] neg_lo:[1,0,0] neg_hi:[1,0,0]
	v_pk_fma_f32 v[252:253], v[18:19], v[170:171], v[252:253] op_sel_hi:[1,0,1] neg_lo:[1,0,0] neg_hi:[1,0,0]
	v_pk_fma_f32 v[58:59], v[4:5], v[172:173], v[58:59] op_sel:[0,1,0] neg_lo:[1,0,0] neg_hi:[1,0,0]
	v_pk_fma_f32 v[252:253], v[8:9], v[172:173], v[252:253] op_sel_hi:[1,0,1] neg_lo:[1,0,0] neg_hi:[1,0,0]
	ds_read_b128 v[170:173], v20 offset:47664
	s_waitcnt lgkmcnt(6)
	v_pk_fma_f32 v[58:59], v[0:1], v[174:175], v[58:59] op_sel:[0,1,0] neg_lo:[1,0,0] neg_hi:[1,0,0]
	v_pk_fma_f32 v[252:253], v[2:3], v[174:175], v[252:253] op_sel_hi:[1,0,1] neg_lo:[1,0,0] neg_hi:[1,0,0]
	v_pk_fma_f32 v[58:59], v[28:29], v[176:177], v[58:59] op_sel:[0,1,0] neg_lo:[1,0,0] neg_hi:[1,0,0]
	v_pk_fma_f32 v[252:253], v[30:31], v[176:177], v[252:253] op_sel_hi:[1,0,1] neg_lo:[1,0,0] neg_hi:[1,0,0]
	ds_read_b128 v[174:177], v20 offset:47680
	s_waitcnt lgkmcnt(6)
	v_pk_fma_f32 v[58:59], v[34:35], v[178:179], v[58:59] op_sel:[0,1,0] neg_lo:[1,0,0] neg_hi:[1,0,0]
	v_pk_fma_f32 v[252:253], v[32:33], v[178:179], v[252:253] op_sel_hi:[1,0,1] neg_lo:[1,0,0] neg_hi:[1,0,0]
	v_pk_fma_f32 v[58:59], v[40:41], v[180:181], v[58:59] op_sel:[0,1,0] neg_lo:[1,0,0] neg_hi:[1,0,0]
	v_pk_fma_f32 v[252:253], v[36:37], v[180:181], v[252:253] op_sel_hi:[1,0,1] neg_lo:[1,0,0] neg_hi:[1,0,0]
	ds_read_b128 v[178:181], v20 offset:47696
	s_waitcnt lgkmcnt(6)
	v_pk_fma_f32 v[58:59], v[42:43], v[182:183], v[58:59] op_sel:[0,1,0] neg_lo:[1,0,0] neg_hi:[1,0,0]
	v_pk_fma_f32 v[252:253], v[38:39], v[182:183], v[252:253] op_sel_hi:[1,0,1] neg_lo:[1,0,0] neg_hi:[1,0,0]
	v_pk_fma_f32 v[58:59], v[46:47], v[184:185], v[58:59] op_sel:[0,1,0] neg_lo:[1,0,0] neg_hi:[1,0,0]
	v_pk_fma_f32 v[252:253], v[44:45], v[184:185], v[252:253] op_sel_hi:[1,0,1] neg_lo:[1,0,0] neg_hi:[1,0,0]
	ds_read_b128 v[182:185], v20 offset:47712
	s_waitcnt lgkmcnt(6)
	v_pk_fma_f32 v[58:59], v[50:51], v[208:209], v[58:59] op_sel:[0,1,0] neg_lo:[1,0,0] neg_hi:[1,0,0]
	v_pk_fma_f32 v[252:253], v[48:49], v[208:209], v[252:253] op_sel_hi:[1,0,1] neg_lo:[1,0,0] neg_hi:[1,0,0]
	v_pk_fma_f32 v[58:59], v[54:55], v[210:211], v[58:59] op_sel:[0,1,0] neg_lo:[1,0,0] neg_hi:[1,0,0]
	v_pk_fma_f32 v[252:253], v[52:53], v[210:211], v[252:253] op_sel_hi:[1,0,1] neg_lo:[1,0,0] neg_hi:[1,0,0]
	ds_read_b128 v[208:211], v20 offset:47728
	v_pk_fma_f32 v[58:59], v[154:155], v[212:213], v[58:59] op_sel:[0,1,0] neg_lo:[1,0,0] neg_hi:[1,0,0]
	ds_read_b128 v[154:157], v20 offset:47616
	v_pk_fma_f32 v[58:59], v[62:63], v[214:215], v[58:59] op_sel:[0,1,0] neg_lo:[1,0,0] neg_hi:[1,0,0]
	v_pk_fma_f32 v[252:253], v[212:213], v[56:57], v[252:253] op_sel_hi:[0,1,1] neg_lo:[1,0,0] neg_hi:[1,0,0]
	s_waitcnt lgkmcnt(0)
	v_pk_fma_f32 v[162:163], v[138:139], v[154:155], 0 op_sel:[0,1,0] op_sel_hi:[1,1,0] neg_lo:[1,0,0] neg_hi:[1,0,0]
	v_pk_fma_f32 v[252:253], v[60:61], v[214:215], v[252:253] op_sel_hi:[1,0,1] neg_lo:[1,0,0] neg_hi:[1,0,0]
	ds_read_b128 v[212:215], v20 offset:47744
	v_pk_add_f32 v[58:59], v[252:253], v[58:59]
	v_pk_fma_f32 v[154:155], v[128:129], v[154:155], v[60:61] op_sel_hi:[1,0,1] neg_lo:[1,0,0] neg_hi:[1,0,0]
	v_pk_fma_f32 v[162:163], v[134:135], v[156:157], v[162:163] op_sel:[0,1,0] neg_lo:[1,0,0] neg_hi:[1,0,0]
	v_pk_fma_f32 v[154:155], v[136:137], v[156:157], v[154:155] op_sel_hi:[1,0,1] neg_lo:[1,0,0] neg_hi:[1,0,0]
	v_pk_fma_f32 v[162:163], v[130:131], v[158:159], v[162:163] op_sel:[0,1,0] neg_lo:[1,0,0] neg_hi:[1,0,0]
	v_pk_fma_f32 v[154:155], v[132:133], v[158:159], v[154:155] op_sel_hi:[1,0,1] neg_lo:[1,0,0] neg_hi:[1,0,0]
	v_pk_fma_f32 v[162:163], v[84:85], v[160:161], v[162:163] op_sel:[0,1,0] neg_lo:[1,0,0] neg_hi:[1,0,0]
	v_pk_fma_f32 v[154:155], v[122:123], v[160:161], v[154:155] op_sel_hi:[1,0,1] neg_lo:[1,0,0] neg_hi:[1,0,0]
	ds_read_b128 v[158:161], v20 offset:47888
	v_pk_fma_f32 v[162:163], v[10:11], v[166:167], v[162:163] op_sel:[0,1,0] neg_lo:[1,0,0] neg_hi:[1,0,0]
	v_pk_fma_f32 v[154:155], v[14:15], v[166:167], v[154:155] op_sel_hi:[1,0,1] neg_lo:[1,0,0] neg_hi:[1,0,0]
	v_pk_fma_f32 v[162:163], v[6:7], v[168:169], v[162:163] op_sel:[0,1,0] neg_lo:[1,0,0] neg_hi:[1,0,0]
	v_pk_fma_f32 v[154:155], v[16:17], v[168:169], v[154:155] op_sel_hi:[1,0,1] neg_lo:[1,0,0] neg_hi:[1,0,0]
	ds_read_b128 v[166:169], v20 offset:47904
	v_pk_fma_f32 v[162:163], v[12:13], v[170:171], v[162:163] op_sel:[0,1,0] neg_lo:[1,0,0] neg_hi:[1,0,0]
	v_pk_fma_f32 v[154:155], v[18:19], v[170:171], v[154:155] op_sel_hi:[1,0,1] neg_lo:[1,0,0] neg_hi:[1,0,0]
	v_pk_fma_f32 v[162:163], v[4:5], v[172:173], v[162:163] op_sel:[0,1,0] neg_lo:[1,0,0] neg_hi:[1,0,0]
	v_pk_fma_f32 v[154:155], v[8:9], v[172:173], v[154:155] op_sel_hi:[1,0,1] neg_lo:[1,0,0] neg_hi:[1,0,0]
	ds_read_b128 v[170:173], v20 offset:47920
	v_pk_fma_f32 v[162:163], v[0:1], v[174:175], v[162:163] op_sel:[0,1,0] neg_lo:[1,0,0] neg_hi:[1,0,0]
	v_pk_fma_f32 v[154:155], v[2:3], v[174:175], v[154:155] op_sel_hi:[1,0,1] neg_lo:[1,0,0] neg_hi:[1,0,0]
	v_pk_fma_f32 v[162:163], v[28:29], v[176:177], v[162:163] op_sel:[0,1,0] neg_lo:[1,0,0] neg_hi:[1,0,0]
	v_pk_fma_f32 v[154:155], v[30:31], v[176:177], v[154:155] op_sel_hi:[1,0,1] neg_lo:[1,0,0] neg_hi:[1,0,0]
	ds_read_b128 v[174:177], v20 offset:47936
	v_pk_fma_f32 v[162:163], v[34:35], v[178:179], v[162:163] op_sel:[0,1,0] neg_lo:[1,0,0] neg_hi:[1,0,0]
	v_pk_fma_f32 v[154:155], v[32:33], v[178:179], v[154:155] op_sel_hi:[1,0,1] neg_lo:[1,0,0] neg_hi:[1,0,0]
	v_pk_fma_f32 v[162:163], v[40:41], v[180:181], v[162:163] op_sel:[0,1,0] neg_lo:[1,0,0] neg_hi:[1,0,0]
	v_pk_fma_f32 v[154:155], v[36:37], v[180:181], v[154:155] op_sel_hi:[1,0,1] neg_lo:[1,0,0] neg_hi:[1,0,0]
	ds_read_b128 v[178:181], v20 offset:47952
	v_pk_fma_f32 v[162:163], v[42:43], v[182:183], v[162:163] op_sel:[0,1,0] neg_lo:[1,0,0] neg_hi:[1,0,0]
	v_pk_fma_f32 v[154:155], v[38:39], v[182:183], v[154:155] op_sel_hi:[1,0,1] neg_lo:[1,0,0] neg_hi:[1,0,0]
	v_pk_fma_f32 v[162:163], v[46:47], v[184:185], v[162:163] op_sel:[0,1,0] neg_lo:[1,0,0] neg_hi:[1,0,0]
	v_pk_fma_f32 v[154:155], v[44:45], v[184:185], v[154:155] op_sel_hi:[1,0,1] neg_lo:[1,0,0] neg_hi:[1,0,0]
	ds_read_b128 v[182:185], v20 offset:47968
	v_pk_fma_f32 v[162:163], v[50:51], v[208:209], v[162:163] op_sel:[0,1,0] neg_lo:[1,0,0] neg_hi:[1,0,0]
	v_pk_fma_f32 v[154:155], v[48:49], v[208:209], v[154:155] op_sel_hi:[1,0,1] neg_lo:[1,0,0] neg_hi:[1,0,0]
	v_pk_fma_f32 v[162:163], v[54:55], v[210:211], v[162:163] op_sel:[0,1,0] neg_lo:[1,0,0] neg_hi:[1,0,0]
	v_pk_fma_f32 v[154:155], v[52:53], v[210:211], v[154:155] op_sel_hi:[1,0,1] neg_lo:[1,0,0] neg_hi:[1,0,0]
	ds_read_b128 v[208:211], v20 offset:47984
	s_waitcnt lgkmcnt(7)
	v_pk_fma_f32 v[162:163], v[212:213], v[58:59], v[162:163] op_sel:[1,0,0] neg_lo:[1,0,0] neg_hi:[1,0,0]
	v_pk_fma_f32 v[154:155], v[56:57], v[212:213], v[154:155] op_sel_hi:[1,0,1] neg_lo:[1,0,0] neg_hi:[1,0,0]
	v_pk_fma_f32 v[162:163], v[62:63], v[214:215], v[162:163] op_sel:[0,1,0] neg_lo:[1,0,0] neg_hi:[1,0,0]
	v_pk_fma_f32 v[60:61], v[60:61], v[214:215], v[154:155] op_sel_hi:[1,0,1] neg_lo:[1,0,0] neg_hi:[1,0,0]
	ds_read_b128 v[154:157], v20 offset:47872
	ds_read_b128 v[212:215], v20 offset:48000
	v_pk_add_f32 v[60:61], v[60:61], v[162:163]
	s_waitcnt lgkmcnt(1)
	v_pk_fma_f32 v[162:163], v[138:139], v[154:155], 0 op_sel:[0,1,0] op_sel_hi:[1,1,0] neg_lo:[1,0,0] neg_hi:[1,0,0]
	v_pk_fma_f32 v[252:253], v[128:129], v[154:155], v[62:63] op_sel_hi:[1,0,1] neg_lo:[1,0,0] neg_hi:[1,0,0]
	v_pk_fma_f32 v[162:163], v[134:135], v[156:157], v[162:163] op_sel:[0,1,0] neg_lo:[1,0,0] neg_hi:[1,0,0]
	v_pk_fma_f32 v[252:253], v[136:137], v[156:157], v[252:253] op_sel_hi:[1,0,1] neg_lo:[1,0,0] neg_hi:[1,0,0]
	ds_read_b128 v[154:157], v20 offset:48128
	v_pk_fma_f32 v[162:163], v[130:131], v[158:159], v[162:163] op_sel:[0,1,0] neg_lo:[1,0,0] neg_hi:[1,0,0]
	v_pk_fma_f32 v[252:253], v[132:133], v[158:159], v[252:253] op_sel_hi:[1,0,1] neg_lo:[1,0,0] neg_hi:[1,0,0]
	v_pk_fma_f32 v[162:163], v[84:85], v[160:161], v[162:163] op_sel:[0,1,0] neg_lo:[1,0,0] neg_hi:[1,0,0]
	v_pk_fma_f32 v[252:253], v[122:123], v[160:161], v[252:253] op_sel_hi:[1,0,1] neg_lo:[1,0,0] neg_hi:[1,0,0]
	ds_read_b128 v[158:161], v20 offset:48144
	v_pk_fma_f32 v[162:163], v[10:11], v[166:167], v[162:163] op_sel:[0,1,0] neg_lo:[1,0,0] neg_hi:[1,0,0]
	v_pk_fma_f32 v[252:253], v[14:15], v[166:167], v[252:253] op_sel_hi:[1,0,1] neg_lo:[1,0,0] neg_hi:[1,0,0]
	v_pk_fma_f32 v[162:163], v[6:7], v[168:169], v[162:163] op_sel:[0,1,0] neg_lo:[1,0,0] neg_hi:[1,0,0]
	v_pk_fma_f32 v[252:253], v[16:17], v[168:169], v[252:253] op_sel_hi:[1,0,1] neg_lo:[1,0,0] neg_hi:[1,0,0]
	ds_read_b128 v[166:169], v20 offset:48160
	v_pk_fma_f32 v[162:163], v[12:13], v[170:171], v[162:163] op_sel:[0,1,0] neg_lo:[1,0,0] neg_hi:[1,0,0]
	v_pk_fma_f32 v[252:253], v[18:19], v[170:171], v[252:253] op_sel_hi:[1,0,1] neg_lo:[1,0,0] neg_hi:[1,0,0]
	v_pk_fma_f32 v[162:163], v[4:5], v[172:173], v[162:163] op_sel:[0,1,0] neg_lo:[1,0,0] neg_hi:[1,0,0]
	v_pk_fma_f32 v[252:253], v[8:9], v[172:173], v[252:253] op_sel_hi:[1,0,1] neg_lo:[1,0,0] neg_hi:[1,0,0]
	ds_read_b128 v[170:173], v20 offset:48176
	v_pk_fma_f32 v[162:163], v[0:1], v[174:175], v[162:163] op_sel:[0,1,0] neg_lo:[1,0,0] neg_hi:[1,0,0]
	v_pk_fma_f32 v[252:253], v[2:3], v[174:175], v[252:253] op_sel_hi:[1,0,1] neg_lo:[1,0,0] neg_hi:[1,0,0]
	v_pk_fma_f32 v[162:163], v[28:29], v[176:177], v[162:163] op_sel:[0,1,0] neg_lo:[1,0,0] neg_hi:[1,0,0]
	v_pk_fma_f32 v[252:253], v[30:31], v[176:177], v[252:253] op_sel_hi:[1,0,1] neg_lo:[1,0,0] neg_hi:[1,0,0]
	ds_read_b128 v[174:177], v20 offset:48192
	v_pk_fma_f32 v[162:163], v[34:35], v[178:179], v[162:163] op_sel:[0,1,0] neg_lo:[1,0,0] neg_hi:[1,0,0]
	v_pk_fma_f32 v[252:253], v[32:33], v[178:179], v[252:253] op_sel_hi:[1,0,1] neg_lo:[1,0,0] neg_hi:[1,0,0]
	v_pk_fma_f32 v[162:163], v[40:41], v[180:181], v[162:163] op_sel:[0,1,0] neg_lo:[1,0,0] neg_hi:[1,0,0]
	v_pk_fma_f32 v[252:253], v[36:37], v[180:181], v[252:253] op_sel_hi:[1,0,1] neg_lo:[1,0,0] neg_hi:[1,0,0]
	ds_read_b128 v[178:181], v20 offset:48208
	v_pk_fma_f32 v[162:163], v[42:43], v[182:183], v[162:163] op_sel:[0,1,0] neg_lo:[1,0,0] neg_hi:[1,0,0]
	v_pk_fma_f32 v[252:253], v[38:39], v[182:183], v[252:253] op_sel_hi:[1,0,1] neg_lo:[1,0,0] neg_hi:[1,0,0]
	v_pk_fma_f32 v[162:163], v[46:47], v[184:185], v[162:163] op_sel:[0,1,0] neg_lo:[1,0,0] neg_hi:[1,0,0]
	v_pk_fma_f32 v[252:253], v[44:45], v[184:185], v[252:253] op_sel_hi:[1,0,1] neg_lo:[1,0,0] neg_hi:[1,0,0]
	ds_read_b128 v[182:185], v20 offset:48224
	v_pk_fma_f32 v[162:163], v[50:51], v[208:209], v[162:163] op_sel:[0,1,0] neg_lo:[1,0,0] neg_hi:[1,0,0]
	v_pk_fma_f32 v[252:253], v[48:49], v[208:209], v[252:253] op_sel_hi:[1,0,1] neg_lo:[1,0,0] neg_hi:[1,0,0]
	v_pk_fma_f32 v[162:163], v[54:55], v[210:211], v[162:163] op_sel:[0,1,0] neg_lo:[1,0,0] neg_hi:[1,0,0]
	v_pk_fma_f32 v[252:253], v[52:53], v[210:211], v[252:253] op_sel_hi:[1,0,1] neg_lo:[1,0,0] neg_hi:[1,0,0]
	ds_read_b128 v[208:211], v20 offset:48240
	s_waitcnt lgkmcnt(8)
	v_pk_fma_f32 v[162:163], v[58:59], v[212:213], v[162:163] op_sel:[0,1,0] neg_lo:[1,0,0] neg_hi:[1,0,0]
	v_pk_fma_f32 v[252:253], v[56:57], v[212:213], v[252:253] op_sel_hi:[1,0,1] neg_lo:[1,0,0] neg_hi:[1,0,0]
	v_pk_fma_f32 v[162:163], v[62:63], v[214:215], v[162:163] op_sel:[0,1,0] neg_lo:[1,0,0] neg_hi:[1,0,0]
	v_pk_fma_f32 v[252:253], v[214:215], v[60:61], v[252:253] op_sel_hi:[0,1,1] neg_lo:[1,0,0] neg_hi:[1,0,0]
	ds_read_b128 v[212:215], v20 offset:48256
	v_pk_add_f32 v[62:63], v[252:253], v[162:163]
	s_waitcnt lgkmcnt(8)
	v_pk_fma_f32 v[162:163], v[138:139], v[154:155], 0 op_sel:[0,1,0] op_sel_hi:[1,1,0] neg_lo:[1,0,0] neg_hi:[1,0,0]
	v_pk_mul_f32 v[154:155], v[128:129], v[154:155] op_sel_hi:[1,0]
	v_pk_fma_f32 v[162:163], v[134:135], v[156:157], v[162:163] op_sel:[0,1,0] neg_lo:[1,0,0] neg_hi:[1,0,0]
	v_pk_fma_f32 v[64:65], v[64:65], v[152:153], v[154:155] neg_lo:[0,0,1] neg_hi:[0,0,1]
	ds_read_b128 v[152:155], v20 offset:48384
	v_pk_fma_f32 v[64:65], v[136:137], v[156:157], v[64:65] op_sel_hi:[1,0,1] neg_lo:[1,0,0] neg_hi:[1,0,0]
	s_waitcnt lgkmcnt(8)
	v_pk_fma_f32 v[162:163], v[130:131], v[158:159], v[162:163] op_sel:[0,1,0] neg_lo:[1,0,0] neg_hi:[1,0,0]
	v_pk_fma_f32 v[64:65], v[132:133], v[158:159], v[64:65] op_sel_hi:[1,0,1] neg_lo:[1,0,0] neg_hi:[1,0,0]
	ds_read_b128 v[156:159], v20 offset:48400
	v_pk_fma_f32 v[162:163], v[84:85], v[160:161], v[162:163] op_sel:[0,1,0] neg_lo:[1,0,0] neg_hi:[1,0,0]
	v_pk_fma_f32 v[64:65], v[122:123], v[160:161], v[64:65] op_sel_hi:[1,0,1] neg_lo:[1,0,0] neg_hi:[1,0,0]
	s_waitcnt lgkmcnt(8)
	v_pk_fma_f32 v[162:163], v[10:11], v[166:167], v[162:163] op_sel:[0,1,0] neg_lo:[1,0,0] neg_hi:[1,0,0]
	v_pk_fma_f32 v[64:65], v[14:15], v[166:167], v[64:65] op_sel_hi:[1,0,1] neg_lo:[1,0,0] neg_hi:[1,0,0]
	v_pk_fma_f32 v[162:163], v[6:7], v[168:169], v[162:163] op_sel:[0,1,0] neg_lo:[1,0,0] neg_hi:[1,0,0]
	v_pk_fma_f32 v[64:65], v[16:17], v[168:169], v[64:65] op_sel_hi:[1,0,1] neg_lo:[1,0,0] neg_hi:[1,0,0]
	ds_read_b128 v[166:169], v20 offset:48432
	s_waitcnt lgkmcnt(8)
	v_pk_fma_f32 v[162:163], v[12:13], v[170:171], v[162:163] op_sel:[0,1,0] neg_lo:[1,0,0] neg_hi:[1,0,0]
	v_pk_fma_f32 v[64:65], v[18:19], v[170:171], v[64:65] op_sel_hi:[1,0,1] neg_lo:[1,0,0] neg_hi:[1,0,0]
	v_pk_fma_f32 v[162:163], v[4:5], v[172:173], v[162:163] op_sel:[0,1,0] neg_lo:[1,0,0] neg_hi:[1,0,0]
	v_pk_fma_f32 v[64:65], v[8:9], v[172:173], v[64:65] op_sel_hi:[1,0,1] neg_lo:[1,0,0] neg_hi:[1,0,0]
	ds_read_b128 v[170:173], v20 offset:48448
	s_waitcnt lgkmcnt(8)
	v_pk_fma_f32 v[162:163], v[0:1], v[174:175], v[162:163] op_sel:[0,1,0] neg_lo:[1,0,0] neg_hi:[1,0,0]
	v_pk_fma_f32 v[64:65], v[2:3], v[174:175], v[64:65] op_sel_hi:[1,0,1] neg_lo:[1,0,0] neg_hi:[1,0,0]
	v_pk_fma_f32 v[162:163], v[28:29], v[176:177], v[162:163] op_sel:[0,1,0] neg_lo:[1,0,0] neg_hi:[1,0,0]
	v_pk_fma_f32 v[64:65], v[30:31], v[176:177], v[64:65] op_sel_hi:[1,0,1] neg_lo:[1,0,0] neg_hi:[1,0,0]
	ds_read_b128 v[174:177], v20 offset:48464
	s_waitcnt lgkmcnt(8)
	v_pk_fma_f32 v[162:163], v[34:35], v[178:179], v[162:163] op_sel:[0,1,0] neg_lo:[1,0,0] neg_hi:[1,0,0]
	v_pk_fma_f32 v[64:65], v[32:33], v[178:179], v[64:65] op_sel_hi:[1,0,1] neg_lo:[1,0,0] neg_hi:[1,0,0]
	v_pk_fma_f32 v[162:163], v[40:41], v[180:181], v[162:163] op_sel:[0,1,0] neg_lo:[1,0,0] neg_hi:[1,0,0]
	v_pk_fma_f32 v[64:65], v[36:37], v[180:181], v[64:65] op_sel_hi:[1,0,1] neg_lo:[1,0,0] neg_hi:[1,0,0]
	ds_read_b128 v[178:181], v20 offset:48480
	s_waitcnt lgkmcnt(8)
	v_pk_fma_f32 v[162:163], v[42:43], v[182:183], v[162:163] op_sel:[0,1,0] neg_lo:[1,0,0] neg_hi:[1,0,0]
	v_pk_fma_f32 v[64:65], v[38:39], v[182:183], v[64:65] op_sel_hi:[1,0,1] neg_lo:[1,0,0] neg_hi:[1,0,0]
	v_pk_fma_f32 v[162:163], v[46:47], v[184:185], v[162:163] op_sel:[0,1,0] neg_lo:[1,0,0] neg_hi:[1,0,0]
	v_pk_fma_f32 v[64:65], v[44:45], v[184:185], v[64:65] op_sel_hi:[1,0,1] neg_lo:[1,0,0] neg_hi:[1,0,0]
	ds_read_b128 v[182:185], v20 offset:48496
	s_waitcnt lgkmcnt(8)
	v_pk_fma_f32 v[162:163], v[50:51], v[208:209], v[162:163] op_sel:[0,1,0] neg_lo:[1,0,0] neg_hi:[1,0,0]
	v_pk_fma_f32 v[64:65], v[48:49], v[208:209], v[64:65] op_sel_hi:[1,0,1] neg_lo:[1,0,0] neg_hi:[1,0,0]
	v_pk_fma_f32 v[162:163], v[54:55], v[210:211], v[162:163] op_sel:[0,1,0] neg_lo:[1,0,0] neg_hi:[1,0,0]
	v_pk_fma_f32 v[64:65], v[52:53], v[210:211], v[64:65] op_sel_hi:[1,0,1] neg_lo:[1,0,0] neg_hi:[1,0,0]
	ds_read_b128 v[208:211], v20 offset:48512
	s_waitcnt lgkmcnt(8)
	v_pk_fma_f32 v[162:163], v[58:59], v[212:213], v[162:163] op_sel:[0,1,0] neg_lo:[1,0,0] neg_hi:[1,0,0]
	v_pk_fma_f32 v[64:65], v[56:57], v[212:213], v[64:65] op_sel_hi:[1,0,1] neg_lo:[1,0,0] neg_hi:[1,0,0]
	v_pk_fma_f32 v[162:163], v[214:215], v[62:63], v[162:163] op_sel:[1,0,0] neg_lo:[1,0,0] neg_hi:[1,0,0]
	v_pk_fma_f32 v[64:65], v[60:61], v[214:215], v[64:65] op_sel_hi:[1,0,1] neg_lo:[1,0,0] neg_hi:[1,0,0]
	ds_read_b128 v[212:215], v20 offset:48528
	v_pk_add_f32 v[64:65], v[64:65], v[162:163]
	ds_read_b128 v[160:163], v20 offset:48416
	s_waitcnt lgkmcnt(9)
	v_pk_fma_f32 v[186:187], v[138:139], v[152:153], 0 op_sel:[0,1,0] op_sel_hi:[1,1,0] neg_lo:[1,0,0] neg_hi:[1,0,0]
	v_pk_fma_f32 v[252:253], v[128:129], v[152:153], v[66:67] op_sel_hi:[1,0,1] neg_lo:[1,0,0] neg_hi:[1,0,0]
	v_pk_fma_f32 v[186:187], v[134:135], v[154:155], v[186:187] op_sel:[0,1,0] neg_lo:[1,0,0] neg_hi:[1,0,0]
	v_pk_fma_f32 v[252:253], v[136:137], v[154:155], v[252:253] op_sel_hi:[1,0,1] neg_lo:[1,0,0] neg_hi:[1,0,0]
	ds_read_b128 v[152:155], v20 offset:48640
	s_waitcnt lgkmcnt(9)
	v_pk_fma_f32 v[186:187], v[130:131], v[156:157], v[186:187] op_sel:[0,1,0] neg_lo:[1,0,0] neg_hi:[1,0,0]
	v_pk_fma_f32 v[252:253], v[132:133], v[156:157], v[252:253] op_sel_hi:[1,0,1] neg_lo:[1,0,0] neg_hi:[1,0,0]
	v_pk_fma_f32 v[186:187], v[84:85], v[158:159], v[186:187] op_sel:[0,1,0] neg_lo:[1,0,0] neg_hi:[1,0,0]
	v_pk_fma_f32 v[252:253], v[122:123], v[158:159], v[252:253] op_sel_hi:[1,0,1] neg_lo:[1,0,0] neg_hi:[1,0,0]
	ds_read_b128 v[156:159], v20 offset:48656
	s_waitcnt lgkmcnt(2)
	v_pk_fma_f32 v[186:187], v[10:11], v[160:161], v[186:187] op_sel:[0,1,0] neg_lo:[1,0,0] neg_hi:[1,0,0]
	v_pk_fma_f32 v[252:253], v[14:15], v[160:161], v[252:253] op_sel_hi:[1,0,1] neg_lo:[1,0,0] neg_hi:[1,0,0]
	v_pk_fma_f32 v[186:187], v[6:7], v[162:163], v[186:187] op_sel:[0,1,0] neg_lo:[1,0,0] neg_hi:[1,0,0]
	v_pk_fma_f32 v[252:253], v[16:17], v[162:163], v[252:253] op_sel_hi:[1,0,1] neg_lo:[1,0,0] neg_hi:[1,0,0]
	ds_read_b128 v[160:163], v20 offset:48672
	v_pk_fma_f32 v[186:187], v[12:13], v[166:167], v[186:187] op_sel:[0,1,0] neg_lo:[1,0,0] neg_hi:[1,0,0]
	v_pk_fma_f32 v[252:253], v[18:19], v[166:167], v[252:253] op_sel_hi:[1,0,1] neg_lo:[1,0,0] neg_hi:[1,0,0]
	v_pk_fma_f32 v[186:187], v[4:5], v[168:169], v[186:187] op_sel:[0,1,0] neg_lo:[1,0,0] neg_hi:[1,0,0]
	v_pk_fma_f32 v[252:253], v[8:9], v[168:169], v[252:253] op_sel_hi:[1,0,1] neg_lo:[1,0,0] neg_hi:[1,0,0]
	ds_read_b128 v[166:169], v20 offset:48688
	v_pk_fma_f32 v[186:187], v[0:1], v[170:171], v[186:187] op_sel:[0,1,0] neg_lo:[1,0,0] neg_hi:[1,0,0]
	v_pk_fma_f32 v[252:253], v[2:3], v[170:171], v[252:253] op_sel_hi:[1,0,1] neg_lo:[1,0,0] neg_hi:[1,0,0]
	v_pk_fma_f32 v[186:187], v[28:29], v[172:173], v[186:187] op_sel:[0,1,0] neg_lo:[1,0,0] neg_hi:[1,0,0]
	v_pk_fma_f32 v[252:253], v[30:31], v[172:173], v[252:253] op_sel_hi:[1,0,1] neg_lo:[1,0,0] neg_hi:[1,0,0]
	ds_read_b128 v[170:173], v20 offset:48704
	v_pk_fma_f32 v[186:187], v[34:35], v[174:175], v[186:187] op_sel:[0,1,0] neg_lo:[1,0,0] neg_hi:[1,0,0]
	v_pk_fma_f32 v[252:253], v[32:33], v[174:175], v[252:253] op_sel_hi:[1,0,1] neg_lo:[1,0,0] neg_hi:[1,0,0]
	v_pk_fma_f32 v[186:187], v[40:41], v[176:177], v[186:187] op_sel:[0,1,0] neg_lo:[1,0,0] neg_hi:[1,0,0]
	v_pk_fma_f32 v[252:253], v[36:37], v[176:177], v[252:253] op_sel_hi:[1,0,1] neg_lo:[1,0,0] neg_hi:[1,0,0]
	ds_read_b128 v[174:177], v20 offset:48720
	v_pk_fma_f32 v[186:187], v[42:43], v[178:179], v[186:187] op_sel:[0,1,0] neg_lo:[1,0,0] neg_hi:[1,0,0]
	v_pk_fma_f32 v[252:253], v[38:39], v[178:179], v[252:253] op_sel_hi:[1,0,1] neg_lo:[1,0,0] neg_hi:[1,0,0]
	v_pk_fma_f32 v[186:187], v[46:47], v[180:181], v[186:187] op_sel:[0,1,0] neg_lo:[1,0,0] neg_hi:[1,0,0]
	v_pk_fma_f32 v[252:253], v[44:45], v[180:181], v[252:253] op_sel_hi:[1,0,1] neg_lo:[1,0,0] neg_hi:[1,0,0]
	ds_read_b128 v[178:181], v20 offset:48736
	v_pk_fma_f32 v[186:187], v[50:51], v[182:183], v[186:187] op_sel:[0,1,0] neg_lo:[1,0,0] neg_hi:[1,0,0]
	v_pk_fma_f32 v[252:253], v[48:49], v[182:183], v[252:253] op_sel_hi:[1,0,1] neg_lo:[1,0,0] neg_hi:[1,0,0]
	v_pk_fma_f32 v[186:187], v[54:55], v[184:185], v[186:187] op_sel:[0,1,0] neg_lo:[1,0,0] neg_hi:[1,0,0]
	v_pk_fma_f32 v[252:253], v[52:53], v[184:185], v[252:253] op_sel_hi:[1,0,1] neg_lo:[1,0,0] neg_hi:[1,0,0]
	ds_read_b128 v[182:185], v20 offset:48752
	v_pk_fma_f32 v[186:187], v[58:59], v[208:209], v[186:187] op_sel:[0,1,0] neg_lo:[1,0,0] neg_hi:[1,0,0]
	v_pk_fma_f32 v[252:253], v[56:57], v[208:209], v[252:253] op_sel_hi:[1,0,1] neg_lo:[1,0,0] neg_hi:[1,0,0]
	v_pk_fma_f32 v[186:187], v[62:63], v[210:211], v[186:187] op_sel:[0,1,0] neg_lo:[1,0,0] neg_hi:[1,0,0]
	v_pk_fma_f32 v[252:253], v[60:61], v[210:211], v[252:253] op_sel_hi:[1,0,1] neg_lo:[1,0,0] neg_hi:[1,0,0]
	ds_read_b128 v[208:211], v20 offset:48768
	v_pk_fma_f32 v[186:187], v[66:67], v[212:213], v[186:187] op_sel:[0,1,0] neg_lo:[1,0,0] neg_hi:[1,0,0]
	v_pk_fma_f32 v[252:253], v[212:213], v[64:65], v[252:253] op_sel_hi:[0,1,1] neg_lo:[1,0,0] neg_hi:[1,0,0]
	v_pk_fma_f32 v[186:187], v[70:71], v[214:215], v[186:187] op_sel:[0,1,0] neg_lo:[1,0,0] neg_hi:[1,0,0]
	v_pk_fma_f32 v[252:253], v[68:69], v[214:215], v[252:253] op_sel_hi:[1,0,1] neg_lo:[1,0,0] neg_hi:[1,0,0]
	ds_read_b128 v[212:215], v20 offset:48784
	v_pk_add_f32 v[66:67], v[252:253], v[186:187]
	s_waitcnt lgkmcnt(9)
	v_pk_fma_f32 v[186:187], v[138:139], v[152:153], 0 op_sel:[0,1,0] op_sel_hi:[1,1,0] neg_lo:[1,0,0] neg_hi:[1,0,0]
	v_pk_fma_f32 v[152:153], v[128:129], v[152:153], v[68:69] op_sel_hi:[1,0,1] neg_lo:[1,0,0] neg_hi:[1,0,0]
	v_pk_fma_f32 v[186:187], v[134:135], v[154:155], v[186:187] op_sel:[0,1,0] neg_lo:[1,0,0] neg_hi:[1,0,0]
	v_pk_fma_f32 v[152:153], v[136:137], v[154:155], v[152:153] op_sel_hi:[1,0,1] neg_lo:[1,0,0] neg_hi:[1,0,0]
	s_waitcnt lgkmcnt(8)
	v_pk_fma_f32 v[186:187], v[130:131], v[156:157], v[186:187] op_sel:[0,1,0] neg_lo:[1,0,0] neg_hi:[1,0,0]
	v_pk_fma_f32 v[152:153], v[132:133], v[156:157], v[152:153] op_sel_hi:[1,0,1] neg_lo:[1,0,0] neg_hi:[1,0,0]
	v_pk_fma_f32 v[186:187], v[84:85], v[158:159], v[186:187] op_sel:[0,1,0] neg_lo:[1,0,0] neg_hi:[1,0,0]
	v_pk_fma_f32 v[152:153], v[122:123], v[158:159], v[152:153] op_sel_hi:[1,0,1] neg_lo:[1,0,0] neg_hi:[1,0,0]
	ds_read_b128 v[156:159], v20 offset:48912
	s_waitcnt lgkmcnt(8)
	v_pk_fma_f32 v[186:187], v[10:11], v[160:161], v[186:187] op_sel:[0,1,0] neg_lo:[1,0,0] neg_hi:[1,0,0]
	v_pk_fma_f32 v[152:153], v[14:15], v[160:161], v[152:153] op_sel_hi:[1,0,1] neg_lo:[1,0,0] neg_hi:[1,0,0]
	v_pk_fma_f32 v[186:187], v[6:7], v[162:163], v[186:187] op_sel:[0,1,0] neg_lo:[1,0,0] neg_hi:[1,0,0]
	v_pk_fma_f32 v[152:153], v[16:17], v[162:163], v[152:153] op_sel_hi:[1,0,1] neg_lo:[1,0,0] neg_hi:[1,0,0]
	ds_read_b128 v[160:163], v20 offset:48928
	s_waitcnt lgkmcnt(8)
	v_pk_fma_f32 v[186:187], v[12:13], v[166:167], v[186:187] op_sel:[0,1,0] neg_lo:[1,0,0] neg_hi:[1,0,0]
	v_pk_fma_f32 v[152:153], v[18:19], v[166:167], v[152:153] op_sel_hi:[1,0,1] neg_lo:[1,0,0] neg_hi:[1,0,0]
	v_pk_fma_f32 v[186:187], v[4:5], v[168:169], v[186:187] op_sel:[0,1,0] neg_lo:[1,0,0] neg_hi:[1,0,0]
	v_pk_fma_f32 v[152:153], v[8:9], v[168:169], v[152:153] op_sel_hi:[1,0,1] neg_lo:[1,0,0] neg_hi:[1,0,0]
	ds_read_b128 v[166:169], v20 offset:48944
	s_waitcnt lgkmcnt(8)
	v_pk_fma_f32 v[186:187], v[0:1], v[170:171], v[186:187] op_sel:[0,1,0] neg_lo:[1,0,0] neg_hi:[1,0,0]
	v_pk_fma_f32 v[152:153], v[2:3], v[170:171], v[152:153] op_sel_hi:[1,0,1] neg_lo:[1,0,0] neg_hi:[1,0,0]
	v_pk_fma_f32 v[186:187], v[28:29], v[172:173], v[186:187] op_sel:[0,1,0] neg_lo:[1,0,0] neg_hi:[1,0,0]
	v_pk_fma_f32 v[152:153], v[30:31], v[172:173], v[152:153] op_sel_hi:[1,0,1] neg_lo:[1,0,0] neg_hi:[1,0,0]
	ds_read_b128 v[170:173], v20 offset:48960
	s_waitcnt lgkmcnt(8)
	v_pk_fma_f32 v[186:187], v[34:35], v[174:175], v[186:187] op_sel:[0,1,0] neg_lo:[1,0,0] neg_hi:[1,0,0]
	v_pk_fma_f32 v[152:153], v[32:33], v[174:175], v[152:153] op_sel_hi:[1,0,1] neg_lo:[1,0,0] neg_hi:[1,0,0]
	v_pk_fma_f32 v[186:187], v[40:41], v[176:177], v[186:187] op_sel:[0,1,0] neg_lo:[1,0,0] neg_hi:[1,0,0]
	v_pk_fma_f32 v[152:153], v[36:37], v[176:177], v[152:153] op_sel_hi:[1,0,1] neg_lo:[1,0,0] neg_hi:[1,0,0]
	ds_read_b128 v[174:177], v20 offset:48976
	s_waitcnt lgkmcnt(8)
	v_pk_fma_f32 v[186:187], v[42:43], v[178:179], v[186:187] op_sel:[0,1,0] neg_lo:[1,0,0] neg_hi:[1,0,0]
	v_pk_fma_f32 v[152:153], v[38:39], v[178:179], v[152:153] op_sel_hi:[1,0,1] neg_lo:[1,0,0] neg_hi:[1,0,0]
	v_pk_fma_f32 v[186:187], v[46:47], v[180:181], v[186:187] op_sel:[0,1,0] neg_lo:[1,0,0] neg_hi:[1,0,0]
	v_pk_fma_f32 v[152:153], v[44:45], v[180:181], v[152:153] op_sel_hi:[1,0,1] neg_lo:[1,0,0] neg_hi:[1,0,0]
	ds_read_b128 v[178:181], v20 offset:48992
	s_waitcnt lgkmcnt(8)
	v_pk_fma_f32 v[186:187], v[50:51], v[182:183], v[186:187] op_sel:[0,1,0] neg_lo:[1,0,0] neg_hi:[1,0,0]
	v_pk_fma_f32 v[152:153], v[48:49], v[182:183], v[152:153] op_sel_hi:[1,0,1] neg_lo:[1,0,0] neg_hi:[1,0,0]
	v_pk_fma_f32 v[186:187], v[54:55], v[184:185], v[186:187] op_sel:[0,1,0] neg_lo:[1,0,0] neg_hi:[1,0,0]
	v_pk_fma_f32 v[152:153], v[52:53], v[184:185], v[152:153] op_sel_hi:[1,0,1] neg_lo:[1,0,0] neg_hi:[1,0,0]
	ds_read_b128 v[182:185], v20 offset:49008
	s_waitcnt lgkmcnt(8)
	v_pk_fma_f32 v[186:187], v[58:59], v[208:209], v[186:187] op_sel:[0,1,0] neg_lo:[1,0,0] neg_hi:[1,0,0]
	v_pk_fma_f32 v[152:153], v[56:57], v[208:209], v[152:153] op_sel_hi:[1,0,1] neg_lo:[1,0,0] neg_hi:[1,0,0]
	v_pk_fma_f32 v[186:187], v[62:63], v[210:211], v[186:187] op_sel:[0,1,0] neg_lo:[1,0,0] neg_hi:[1,0,0]
	v_pk_fma_f32 v[152:153], v[60:61], v[210:211], v[152:153] op_sel_hi:[1,0,1] neg_lo:[1,0,0] neg_hi:[1,0,0]
	ds_read_b128 v[208:211], v20 offset:49024
	s_waitcnt lgkmcnt(8)
	v_pk_fma_f32 v[186:187], v[212:213], v[66:67], v[186:187] op_sel:[1,0,0] neg_lo:[1,0,0] neg_hi:[1,0,0]
	v_pk_fma_f32 v[152:153], v[64:65], v[212:213], v[152:153] op_sel_hi:[1,0,1] neg_lo:[1,0,0] neg_hi:[1,0,0]
	v_pk_fma_f32 v[186:187], v[70:71], v[214:215], v[186:187] op_sel:[0,1,0] neg_lo:[1,0,0] neg_hi:[1,0,0]
	v_pk_fma_f32 v[68:69], v[68:69], v[214:215], v[152:153] op_sel_hi:[1,0,1] neg_lo:[1,0,0] neg_hi:[1,0,0]
	ds_read_b128 v[152:155], v20 offset:48896
	ds_read_b128 v[212:215], v20 offset:49040
	v_pk_add_f32 v[68:69], v[68:69], v[186:187]
	s_waitcnt lgkmcnt(1)
	v_pk_fma_f32 v[186:187], v[138:139], v[152:153], 0 op_sel:[0,1,0] op_sel_hi:[1,1,0] neg_lo:[1,0,0] neg_hi:[1,0,0]
	v_pk_fma_f32 v[252:253], v[128:129], v[152:153], v[70:71] op_sel_hi:[1,0,1] neg_lo:[1,0,0] neg_hi:[1,0,0]
	v_pk_fma_f32 v[186:187], v[134:135], v[154:155], v[186:187] op_sel:[0,1,0] neg_lo:[1,0,0] neg_hi:[1,0,0]
	v_pk_fma_f32 v[252:253], v[136:137], v[154:155], v[252:253] op_sel_hi:[1,0,1] neg_lo:[1,0,0] neg_hi:[1,0,0]
	v_pk_fma_f32 v[186:187], v[130:131], v[156:157], v[186:187] op_sel:[0,1,0] neg_lo:[1,0,0] neg_hi:[1,0,0]
	ds_read_b128 v[152:155], v20 offset:49152
	v_pk_fma_f32 v[186:187], v[84:85], v[158:159], v[186:187] op_sel:[0,1,0] neg_lo:[1,0,0] neg_hi:[1,0,0]
	v_pk_fma_f32 v[252:253], v[132:133], v[156:157], v[252:253] op_sel_hi:[1,0,1] neg_lo:[1,0,0] neg_hi:[1,0,0]
	v_pk_fma_f32 v[186:187], v[10:11], v[160:161], v[186:187] op_sel:[0,1,0] neg_lo:[1,0,0] neg_hi:[1,0,0]
	v_pk_fma_f32 v[252:253], v[122:123], v[158:159], v[252:253] op_sel_hi:[1,0,1] neg_lo:[1,0,0] neg_hi:[1,0,0]
	ds_read_b128 v[156:159], v20 offset:49168
	v_pk_fma_f32 v[186:187], v[6:7], v[162:163], v[186:187] op_sel:[0,1,0] neg_lo:[1,0,0] neg_hi:[1,0,0]
	v_pk_fma_f32 v[252:253], v[14:15], v[160:161], v[252:253] op_sel_hi:[1,0,1] neg_lo:[1,0,0] neg_hi:[1,0,0]
	v_pk_fma_f32 v[186:187], v[12:13], v[166:167], v[186:187] op_sel:[0,1,0] neg_lo:[1,0,0] neg_hi:[1,0,0]
	v_pk_fma_f32 v[252:253], v[16:17], v[162:163], v[252:253] op_sel_hi:[1,0,1] neg_lo:[1,0,0] neg_hi:[1,0,0]
	ds_read_b128 v[160:163], v20 offset:49184
	v_pk_fma_f32 v[186:187], v[4:5], v[168:169], v[186:187] op_sel:[0,1,0] neg_lo:[1,0,0] neg_hi:[1,0,0]
	v_pk_fma_f32 v[252:253], v[18:19], v[166:167], v[252:253] op_sel_hi:[1,0,1] neg_lo:[1,0,0] neg_hi:[1,0,0]
	v_pk_fma_f32 v[186:187], v[0:1], v[170:171], v[186:187] op_sel:[0,1,0] neg_lo:[1,0,0] neg_hi:[1,0,0]
	v_pk_fma_f32 v[252:253], v[8:9], v[168:169], v[252:253] op_sel_hi:[1,0,1] neg_lo:[1,0,0] neg_hi:[1,0,0]
	ds_read_b128 v[166:169], v20 offset:49200
	v_pk_fma_f32 v[186:187], v[28:29], v[172:173], v[186:187] op_sel:[0,1,0] neg_lo:[1,0,0] neg_hi:[1,0,0]
	v_pk_fma_f32 v[252:253], v[2:3], v[170:171], v[252:253] op_sel_hi:[1,0,1] neg_lo:[1,0,0] neg_hi:[1,0,0]
	v_pk_fma_f32 v[186:187], v[34:35], v[174:175], v[186:187] op_sel:[0,1,0] neg_lo:[1,0,0] neg_hi:[1,0,0]
	v_pk_fma_f32 v[252:253], v[30:31], v[172:173], v[252:253] op_sel_hi:[1,0,1] neg_lo:[1,0,0] neg_hi:[1,0,0]
	ds_read_b128 v[170:173], v20 offset:49216
	v_pk_fma_f32 v[186:187], v[40:41], v[176:177], v[186:187] op_sel:[0,1,0] neg_lo:[1,0,0] neg_hi:[1,0,0]
	v_pk_fma_f32 v[252:253], v[32:33], v[174:175], v[252:253] op_sel_hi:[1,0,1] neg_lo:[1,0,0] neg_hi:[1,0,0]
	v_pk_fma_f32 v[186:187], v[42:43], v[178:179], v[186:187] op_sel:[0,1,0] neg_lo:[1,0,0] neg_hi:[1,0,0]
	v_pk_fma_f32 v[252:253], v[36:37], v[176:177], v[252:253] op_sel_hi:[1,0,1] neg_lo:[1,0,0] neg_hi:[1,0,0]
	ds_read_b128 v[174:177], v20 offset:49232
	v_pk_fma_f32 v[186:187], v[46:47], v[180:181], v[186:187] op_sel:[0,1,0] neg_lo:[1,0,0] neg_hi:[1,0,0]
	v_pk_fma_f32 v[252:253], v[38:39], v[178:179], v[252:253] op_sel_hi:[1,0,1] neg_lo:[1,0,0] neg_hi:[1,0,0]
	v_pk_fma_f32 v[186:187], v[50:51], v[182:183], v[186:187] op_sel:[0,1,0] neg_lo:[1,0,0] neg_hi:[1,0,0]
	v_pk_fma_f32 v[252:253], v[44:45], v[180:181], v[252:253] op_sel_hi:[1,0,1] neg_lo:[1,0,0] neg_hi:[1,0,0]
	ds_read_b128 v[178:181], v20 offset:49248
	v_pk_fma_f32 v[186:187], v[54:55], v[184:185], v[186:187] op_sel:[0,1,0] neg_lo:[1,0,0] neg_hi:[1,0,0]
	v_pk_fma_f32 v[252:253], v[48:49], v[182:183], v[252:253] op_sel_hi:[1,0,1] neg_lo:[1,0,0] neg_hi:[1,0,0]
	v_pk_fma_f32 v[186:187], v[58:59], v[208:209], v[186:187] op_sel:[0,1,0] neg_lo:[1,0,0] neg_hi:[1,0,0]
	v_pk_fma_f32 v[252:253], v[52:53], v[184:185], v[252:253] op_sel_hi:[1,0,1] neg_lo:[1,0,0] neg_hi:[1,0,0]
	ds_read_b128 v[182:185], v20 offset:49264
	v_pk_fma_f32 v[186:187], v[62:63], v[210:211], v[186:187] op_sel:[0,1,0] neg_lo:[1,0,0] neg_hi:[1,0,0]
	v_pk_fma_f32 v[252:253], v[56:57], v[208:209], v[252:253] op_sel_hi:[1,0,1] neg_lo:[1,0,0] neg_hi:[1,0,0]
	s_waitcnt lgkmcnt(8)
	v_pk_fma_f32 v[186:187], v[66:67], v[212:213], v[186:187] op_sel:[0,1,0] neg_lo:[1,0,0] neg_hi:[1,0,0]
	v_pk_fma_f32 v[252:253], v[60:61], v[210:211], v[252:253] op_sel_hi:[1,0,1] neg_lo:[1,0,0] neg_hi:[1,0,0]
	ds_read_b128 v[208:211], v20 offset:49280
	v_pk_fma_f32 v[186:187], v[70:71], v[214:215], v[186:187] op_sel:[0,1,0] neg_lo:[1,0,0] neg_hi:[1,0,0]
	v_pk_fma_f32 v[252:253], v[64:65], v[212:213], v[252:253] op_sel_hi:[1,0,1] neg_lo:[1,0,0] neg_hi:[1,0,0]
	s_nop 0
	v_pk_fma_f32 v[252:253], v[214:215], v[68:69], v[252:253] op_sel_hi:[0,1,1] neg_lo:[1,0,0] neg_hi:[1,0,0]
	ds_read_b128 v[212:215], v20 offset:49296
	v_pk_add_f32 v[70:71], v[252:253], v[186:187]
	s_waitcnt lgkmcnt(9)
	v_pk_fma_f32 v[186:187], v[138:139], v[152:153], 0 op_sel:[0,1,0] op_sel_hi:[1,1,0] neg_lo:[1,0,0] neg_hi:[1,0,0]
	v_pk_mul_f32 v[152:153], v[128:129], v[152:153] op_sel_hi:[1,0]
	v_pk_fma_f32 v[186:187], v[134:135], v[154:155], v[186:187] op_sel:[0,1,0] neg_lo:[1,0,0] neg_hi:[1,0,0]
	v_pk_fma_f32 v[72:73], v[72:73], v[150:151], v[152:153] neg_lo:[0,0,1] neg_hi:[0,0,1]
	ds_read_b128 v[150:153], v20 offset:49408
	v_pk_fma_f32 v[72:73], v[136:137], v[154:155], v[72:73] op_sel_hi:[1,0,1] neg_lo:[1,0,0] neg_hi:[1,0,0]
	s_waitcnt lgkmcnt(9)
	v_pk_fma_f32 v[186:187], v[130:131], v[156:157], v[186:187] op_sel:[0,1,0] neg_lo:[1,0,0] neg_hi:[1,0,0]
	v_pk_fma_f32 v[72:73], v[132:133], v[156:157], v[72:73] op_sel_hi:[1,0,1] neg_lo:[1,0,0] neg_hi:[1,0,0]
	ds_read_b128 v[154:157], v20 offset:49424
	v_pk_fma_f32 v[186:187], v[84:85], v[158:159], v[186:187] op_sel:[0,1,0] neg_lo:[1,0,0] neg_hi:[1,0,0]
	v_pk_fma_f32 v[72:73], v[122:123], v[158:159], v[72:73] op_sel_hi:[1,0,1] neg_lo:[1,0,0] neg_hi:[1,0,0]
	s_waitcnt lgkmcnt(9)
	v_pk_fma_f32 v[186:187], v[10:11], v[160:161], v[186:187] op_sel:[0,1,0] neg_lo:[1,0,0] neg_hi:[1,0,0]
	v_pk_fma_f32 v[72:73], v[14:15], v[160:161], v[72:73] op_sel_hi:[1,0,1] neg_lo:[1,0,0] neg_hi:[1,0,0]
	ds_read_b128 v[158:161], v20 offset:49440
	v_pk_fma_f32 v[186:187], v[6:7], v[162:163], v[186:187] op_sel:[0,1,0] neg_lo:[1,0,0] neg_hi:[1,0,0]
	v_pk_fma_f32 v[72:73], v[16:17], v[162:163], v[72:73] op_sel_hi:[1,0,1] neg_lo:[1,0,0] neg_hi:[1,0,0]
	s_waitcnt lgkmcnt(9)
	v_pk_fma_f32 v[186:187], v[12:13], v[166:167], v[186:187] op_sel:[0,1,0] neg_lo:[1,0,0] neg_hi:[1,0,0]
	v_pk_fma_f32 v[72:73], v[18:19], v[166:167], v[72:73] op_sel_hi:[1,0,1] neg_lo:[1,0,0] neg_hi:[1,0,0]
	v_pk_fma_f32 v[186:187], v[4:5], v[168:169], v[186:187] op_sel:[0,1,0] neg_lo:[1,0,0] neg_hi:[1,0,0]
	v_pk_fma_f32 v[72:73], v[8:9], v[168:169], v[72:73] op_sel_hi:[1,0,1] neg_lo:[1,0,0] neg_hi:[1,0,0]
	ds_read_b128 v[166:169], v20 offset:49456
	s_waitcnt lgkmcnt(9)
	v_pk_fma_f32 v[186:187], v[0:1], v[170:171], v[186:187] op_sel:[0,1,0] neg_lo:[1,0,0] neg_hi:[1,0,0]
	v_pk_fma_f32 v[72:73], v[2:3], v[170:171], v[72:73] op_sel_hi:[1,0,1] neg_lo:[1,0,0] neg_hi:[1,0,0]
	v_pk_fma_f32 v[186:187], v[28:29], v[172:173], v[186:187] op_sel:[0,1,0] neg_lo:[1,0,0] neg_hi:[1,0,0]
	v_pk_fma_f32 v[72:73], v[30:31], v[172:173], v[72:73] op_sel_hi:[1,0,1] neg_lo:[1,0,0] neg_hi:[1,0,0]
	ds_read_b128 v[170:173], v20 offset:49472
	s_waitcnt lgkmcnt(9)
	v_pk_fma_f32 v[186:187], v[34:35], v[174:175], v[186:187] op_sel:[0,1,0] neg_lo:[1,0,0] neg_hi:[1,0,0]
	v_pk_fma_f32 v[72:73], v[32:33], v[174:175], v[72:73] op_sel_hi:[1,0,1] neg_lo:[1,0,0] neg_hi:[1,0,0]
	v_pk_fma_f32 v[186:187], v[40:41], v[176:177], v[186:187] op_sel:[0,1,0] neg_lo:[1,0,0] neg_hi:[1,0,0]
	v_pk_fma_f32 v[72:73], v[36:37], v[176:177], v[72:73] op_sel_hi:[1,0,1] neg_lo:[1,0,0] neg_hi:[1,0,0]
	ds_read_b128 v[174:177], v20 offset:49488
	s_waitcnt lgkmcnt(9)
	v_pk_fma_f32 v[186:187], v[42:43], v[178:179], v[186:187] op_sel:[0,1,0] neg_lo:[1,0,0] neg_hi:[1,0,0]
	v_pk_fma_f32 v[72:73], v[38:39], v[178:179], v[72:73] op_sel_hi:[1,0,1] neg_lo:[1,0,0] neg_hi:[1,0,0]
	v_pk_fma_f32 v[186:187], v[46:47], v[180:181], v[186:187] op_sel:[0,1,0] neg_lo:[1,0,0] neg_hi:[1,0,0]
	v_pk_fma_f32 v[72:73], v[44:45], v[180:181], v[72:73] op_sel_hi:[1,0,1] neg_lo:[1,0,0] neg_hi:[1,0,0]
	ds_read_b128 v[178:181], v20 offset:49504
	s_waitcnt lgkmcnt(9)
	v_pk_fma_f32 v[186:187], v[50:51], v[182:183], v[186:187] op_sel:[0,1,0] neg_lo:[1,0,0] neg_hi:[1,0,0]
	v_pk_fma_f32 v[72:73], v[48:49], v[182:183], v[72:73] op_sel_hi:[1,0,1] neg_lo:[1,0,0] neg_hi:[1,0,0]
	v_pk_fma_f32 v[186:187], v[54:55], v[184:185], v[186:187] op_sel:[0,1,0] neg_lo:[1,0,0] neg_hi:[1,0,0]
	v_pk_fma_f32 v[72:73], v[52:53], v[184:185], v[72:73] op_sel_hi:[1,0,1] neg_lo:[1,0,0] neg_hi:[1,0,0]
	ds_read_b128 v[182:185], v20 offset:49520
	s_waitcnt lgkmcnt(9)
	v_pk_fma_f32 v[186:187], v[58:59], v[208:209], v[186:187] op_sel:[0,1,0] neg_lo:[1,0,0] neg_hi:[1,0,0]
	v_pk_fma_f32 v[72:73], v[56:57], v[208:209], v[72:73] op_sel_hi:[1,0,1] neg_lo:[1,0,0] neg_hi:[1,0,0]
	v_pk_fma_f32 v[186:187], v[62:63], v[210:211], v[186:187] op_sel:[0,1,0] neg_lo:[1,0,0] neg_hi:[1,0,0]
	v_pk_fma_f32 v[72:73], v[60:61], v[210:211], v[72:73] op_sel_hi:[1,0,1] neg_lo:[1,0,0] neg_hi:[1,0,0]
	ds_read_b128 v[208:211], v20 offset:49536
	s_waitcnt lgkmcnt(9)
	v_pk_fma_f32 v[186:187], v[66:67], v[212:213], v[186:187] op_sel:[0,1,0] neg_lo:[1,0,0] neg_hi:[1,0,0]
	v_pk_fma_f32 v[72:73], v[64:65], v[212:213], v[72:73] op_sel_hi:[1,0,1] neg_lo:[1,0,0] neg_hi:[1,0,0]
	v_pk_fma_f32 v[186:187], v[214:215], v[70:71], v[186:187] op_sel:[1,0,0] neg_lo:[1,0,0] neg_hi:[1,0,0]
	v_pk_fma_f32 v[72:73], v[68:69], v[214:215], v[72:73] op_sel_hi:[1,0,1] neg_lo:[1,0,0] neg_hi:[1,0,0]
	ds_read_b128 v[212:215], v20 offset:49552
	v_pk_add_f32 v[72:73], v[72:73], v[186:187]
	s_waitcnt lgkmcnt(9)
	v_pk_fma_f32 v[162:163], v[138:139], v[150:151], 0 op_sel:[0,1,0] op_sel_hi:[1,1,0] neg_lo:[1,0,0] neg_hi:[1,0,0]
	v_pk_fma_f32 v[252:253], v[128:129], v[150:151], v[74:75] op_sel_hi:[1,0,1] neg_lo:[1,0,0] neg_hi:[1,0,0]
	v_pk_fma_f32 v[162:163], v[134:135], v[152:153], v[162:163] op_sel:[0,1,0] neg_lo:[1,0,0] neg_hi:[1,0,0]
	v_pk_fma_f32 v[252:253], v[136:137], v[152:153], v[252:253] op_sel_hi:[1,0,1] neg_lo:[1,0,0] neg_hi:[1,0,0]
	s_waitcnt lgkmcnt(8)
	v_pk_fma_f32 v[162:163], v[130:131], v[154:155], v[162:163] op_sel:[0,1,0] neg_lo:[1,0,0] neg_hi:[1,0,0]
	ds_read_b128 v[150:153], v20 offset:49664
	v_pk_fma_f32 v[162:163], v[84:85], v[156:157], v[162:163] op_sel:[0,1,0] neg_lo:[1,0,0] neg_hi:[1,0,0]
	v_pk_fma_f32 v[252:253], v[132:133], v[154:155], v[252:253] op_sel_hi:[1,0,1] neg_lo:[1,0,0] neg_hi:[1,0,0]
	s_waitcnt lgkmcnt(8)
	v_pk_fma_f32 v[162:163], v[10:11], v[158:159], v[162:163] op_sel:[0,1,0] neg_lo:[1,0,0] neg_hi:[1,0,0]
	v_pk_fma_f32 v[252:253], v[122:123], v[156:157], v[252:253] op_sel_hi:[1,0,1] neg_lo:[1,0,0] neg_hi:[1,0,0]
	v_pk_fma_f32 v[162:163], v[6:7], v[160:161], v[162:163] op_sel:[0,1,0] neg_lo:[1,0,0] neg_hi:[1,0,0]
	ds_read_b128 v[154:157], v20 offset:49680
	s_waitcnt lgkmcnt(8)
	v_pk_fma_f32 v[162:163], v[12:13], v[166:167], v[162:163] op_sel:[0,1,0] neg_lo:[1,0,0] neg_hi:[1,0,0]
	v_pk_fma_f32 v[252:253], v[14:15], v[158:159], v[252:253] op_sel_hi:[1,0,1] neg_lo:[1,0,0] neg_hi:[1,0,0]
	v_pk_fma_f32 v[162:163], v[4:5], v[168:169], v[162:163] op_sel:[0,1,0] neg_lo:[1,0,0] neg_hi:[1,0,0]
	v_pk_fma_f32 v[252:253], v[16:17], v[160:161], v[252:253] op_sel_hi:[1,0,1] neg_lo:[1,0,0] neg_hi:[1,0,0]
	ds_read_b128 v[158:161], v20 offset:49696
	s_waitcnt lgkmcnt(8)
	v_pk_fma_f32 v[162:163], v[0:1], v[170:171], v[162:163] op_sel:[0,1,0] neg_lo:[1,0,0] neg_hi:[1,0,0]
	v_pk_fma_f32 v[252:253], v[18:19], v[166:167], v[252:253] op_sel_hi:[1,0,1] neg_lo:[1,0,0] neg_hi:[1,0,0]
	v_pk_fma_f32 v[162:163], v[28:29], v[172:173], v[162:163] op_sel:[0,1,0] neg_lo:[1,0,0] neg_hi:[1,0,0]
	v_pk_fma_f32 v[252:253], v[8:9], v[168:169], v[252:253] op_sel_hi:[1,0,1] neg_lo:[1,0,0] neg_hi:[1,0,0]
	ds_read_b128 v[166:169], v20 offset:49712
	s_waitcnt lgkmcnt(8)
	v_pk_fma_f32 v[162:163], v[34:35], v[174:175], v[162:163] op_sel:[0,1,0] neg_lo:[1,0,0] neg_hi:[1,0,0]
	v_pk_fma_f32 v[252:253], v[2:3], v[170:171], v[252:253] op_sel_hi:[1,0,1] neg_lo:[1,0,0] neg_hi:[1,0,0]
	v_pk_fma_f32 v[162:163], v[40:41], v[176:177], v[162:163] op_sel:[0,1,0] neg_lo:[1,0,0] neg_hi:[1,0,0]
	v_pk_fma_f32 v[252:253], v[30:31], v[172:173], v[252:253] op_sel_hi:[1,0,1] neg_lo:[1,0,0] neg_hi:[1,0,0]
	ds_read_b128 v[170:173], v20 offset:49728
	s_waitcnt lgkmcnt(8)
	v_pk_fma_f32 v[162:163], v[42:43], v[178:179], v[162:163] op_sel:[0,1,0] neg_lo:[1,0,0] neg_hi:[1,0,0]
	v_pk_fma_f32 v[252:253], v[32:33], v[174:175], v[252:253] op_sel_hi:[1,0,1] neg_lo:[1,0,0] neg_hi:[1,0,0]
	v_pk_fma_f32 v[162:163], v[46:47], v[180:181], v[162:163] op_sel:[0,1,0] neg_lo:[1,0,0] neg_hi:[1,0,0]
	v_pk_fma_f32 v[252:253], v[36:37], v[176:177], v[252:253] op_sel_hi:[1,0,1] neg_lo:[1,0,0] neg_hi:[1,0,0]
	ds_read_b128 v[174:177], v20 offset:49744
	s_waitcnt lgkmcnt(8)
	v_pk_fma_f32 v[162:163], v[50:51], v[182:183], v[162:163] op_sel:[0,1,0] neg_lo:[1,0,0] neg_hi:[1,0,0]
	v_pk_fma_f32 v[252:253], v[38:39], v[178:179], v[252:253] op_sel_hi:[1,0,1] neg_lo:[1,0,0] neg_hi:[1,0,0]
	v_pk_fma_f32 v[162:163], v[54:55], v[184:185], v[162:163] op_sel:[0,1,0] neg_lo:[1,0,0] neg_hi:[1,0,0]
	v_pk_fma_f32 v[252:253], v[44:45], v[180:181], v[252:253] op_sel_hi:[1,0,1] neg_lo:[1,0,0] neg_hi:[1,0,0]
	ds_read_b128 v[178:181], v20 offset:49760
	s_waitcnt lgkmcnt(8)
	v_pk_fma_f32 v[162:163], v[58:59], v[208:209], v[162:163] op_sel:[0,1,0] neg_lo:[1,0,0] neg_hi:[1,0,0]
	v_pk_fma_f32 v[252:253], v[48:49], v[182:183], v[252:253] op_sel_hi:[1,0,1] neg_lo:[1,0,0] neg_hi:[1,0,0]
	v_pk_fma_f32 v[162:163], v[62:63], v[210:211], v[162:163] op_sel:[0,1,0] neg_lo:[1,0,0] neg_hi:[1,0,0]
	v_pk_fma_f32 v[252:253], v[52:53], v[184:185], v[252:253] op_sel_hi:[1,0,1] neg_lo:[1,0,0] neg_hi:[1,0,0]
	ds_read_b128 v[182:185], v20 offset:49776
	s_waitcnt lgkmcnt(8)
	v_pk_fma_f32 v[162:163], v[66:67], v[212:213], v[162:163] op_sel:[0,1,0] neg_lo:[1,0,0] neg_hi:[1,0,0]
	v_pk_fma_f32 v[252:253], v[56:57], v[208:209], v[252:253] op_sel_hi:[1,0,1] neg_lo:[1,0,0] neg_hi:[1,0,0]
	v_pk_fma_f32 v[162:163], v[70:71], v[214:215], v[162:163] op_sel:[0,1,0] neg_lo:[1,0,0] neg_hi:[1,0,0]
	v_pk_fma_f32 v[252:253], v[60:61], v[210:211], v[252:253] op_sel_hi:[1,0,1] neg_lo:[1,0,0] neg_hi:[1,0,0]
	ds_read_b128 v[208:211], v20 offset:49792
	v_pk_fma_f32 v[162:163], v[74:75], v[216:217], v[162:163] op_sel:[0,1,0] neg_lo:[1,0,0] neg_hi:[1,0,0]
	v_pk_fma_f32 v[252:253], v[64:65], v[212:213], v[252:253] op_sel_hi:[1,0,1] neg_lo:[1,0,0] neg_hi:[1,0,0]
	v_pk_fma_f32 v[162:163], v[78:79], v[218:219], v[162:163] op_sel:[0,1,0] neg_lo:[1,0,0] neg_hi:[1,0,0]
	v_pk_fma_f32 v[252:253], v[68:69], v[214:215], v[252:253] op_sel_hi:[1,0,1] neg_lo:[1,0,0] neg_hi:[1,0,0]
	ds_read_b128 v[212:215], v20 offset:49808
	v_pk_fma_f32 v[252:253], v[216:217], v[72:73], v[252:253] op_sel_hi:[0,1,1] neg_lo:[1,0,0] neg_hi:[1,0,0]
	s_nop 0
	v_pk_fma_f32 v[252:253], v[76:77], v[218:219], v[252:253] op_sel_hi:[1,0,1] neg_lo:[1,0,0] neg_hi:[1,0,0]
	ds_read_b128 v[216:219], v20 offset:49824
	v_pk_add_f32 v[74:75], v[252:253], v[162:163]
	s_waitcnt lgkmcnt(10)
	v_pk_fma_f32 v[162:163], v[138:139], v[150:151], 0 op_sel:[0,1,0] op_sel_hi:[1,1,0] neg_lo:[1,0,0] neg_hi:[1,0,0]
	v_pk_fma_f32 v[150:151], v[128:129], v[150:151], v[76:77] op_sel_hi:[1,0,1] neg_lo:[1,0,0] neg_hi:[1,0,0]
	v_pk_fma_f32 v[162:163], v[134:135], v[152:153], v[162:163] op_sel:[0,1,0] neg_lo:[1,0,0] neg_hi:[1,0,0]
	v_pk_fma_f32 v[150:151], v[136:137], v[152:153], v[150:151] op_sel_hi:[1,0,1] neg_lo:[1,0,0] neg_hi:[1,0,0]
	s_waitcnt lgkmcnt(9)
	v_pk_fma_f32 v[162:163], v[130:131], v[154:155], v[162:163] op_sel:[0,1,0] neg_lo:[1,0,0] neg_hi:[1,0,0]
	v_pk_fma_f32 v[150:151], v[132:133], v[154:155], v[150:151] op_sel_hi:[1,0,1] neg_lo:[1,0,0] neg_hi:[1,0,0]
	v_pk_fma_f32 v[162:163], v[84:85], v[156:157], v[162:163] op_sel:[0,1,0] neg_lo:[1,0,0] neg_hi:[1,0,0]
	v_pk_fma_f32 v[150:151], v[122:123], v[156:157], v[150:151] op_sel_hi:[1,0,1] neg_lo:[1,0,0] neg_hi:[1,0,0]
	ds_read_b128 v[154:157], v20 offset:49936
	s_waitcnt lgkmcnt(9)
	v_pk_fma_f32 v[162:163], v[10:11], v[158:159], v[162:163] op_sel:[0,1,0] neg_lo:[1,0,0] neg_hi:[1,0,0]
	v_pk_fma_f32 v[150:151], v[14:15], v[158:159], v[150:151] op_sel_hi:[1,0,1] neg_lo:[1,0,0] neg_hi:[1,0,0]
	v_pk_fma_f32 v[162:163], v[6:7], v[160:161], v[162:163] op_sel:[0,1,0] neg_lo:[1,0,0] neg_hi:[1,0,0]
	v_pk_fma_f32 v[150:151], v[16:17], v[160:161], v[150:151] op_sel_hi:[1,0,1] neg_lo:[1,0,0] neg_hi:[1,0,0]
	ds_read_b128 v[158:161], v20 offset:49952
	s_waitcnt lgkmcnt(9)
	v_pk_fma_f32 v[162:163], v[12:13], v[166:167], v[162:163] op_sel:[0,1,0] neg_lo:[1,0,0] neg_hi:[1,0,0]
	v_pk_fma_f32 v[150:151], v[18:19], v[166:167], v[150:151] op_sel_hi:[1,0,1] neg_lo:[1,0,0] neg_hi:[1,0,0]
	v_pk_fma_f32 v[162:163], v[4:5], v[168:169], v[162:163] op_sel:[0,1,0] neg_lo:[1,0,0] neg_hi:[1,0,0]
	v_pk_fma_f32 v[150:151], v[8:9], v[168:169], v[150:151] op_sel_hi:[1,0,1] neg_lo:[1,0,0] neg_hi:[1,0,0]
	ds_read_b128 v[166:169], v20 offset:49968
	s_waitcnt lgkmcnt(9)
	v_pk_fma_f32 v[162:163], v[0:1], v[170:171], v[162:163] op_sel:[0,1,0] neg_lo:[1,0,0] neg_hi:[1,0,0]
	v_pk_fma_f32 v[150:151], v[2:3], v[170:171], v[150:151] op_sel_hi:[1,0,1] neg_lo:[1,0,0] neg_hi:[1,0,0]
	v_pk_fma_f32 v[162:163], v[28:29], v[172:173], v[162:163] op_sel:[0,1,0] neg_lo:[1,0,0] neg_hi:[1,0,0]
	v_pk_fma_f32 v[150:151], v[30:31], v[172:173], v[150:151] op_sel_hi:[1,0,1] neg_lo:[1,0,0] neg_hi:[1,0,0]
	ds_read_b128 v[170:173], v20 offset:49984
	s_waitcnt lgkmcnt(9)
	v_pk_fma_f32 v[162:163], v[34:35], v[174:175], v[162:163] op_sel:[0,1,0] neg_lo:[1,0,0] neg_hi:[1,0,0]
	v_pk_fma_f32 v[150:151], v[32:33], v[174:175], v[150:151] op_sel_hi:[1,0,1] neg_lo:[1,0,0] neg_hi:[1,0,0]
	v_pk_fma_f32 v[162:163], v[40:41], v[176:177], v[162:163] op_sel:[0,1,0] neg_lo:[1,0,0] neg_hi:[1,0,0]
	v_pk_fma_f32 v[150:151], v[36:37], v[176:177], v[150:151] op_sel_hi:[1,0,1] neg_lo:[1,0,0] neg_hi:[1,0,0]
	ds_read_b128 v[174:177], v20 offset:50000
	s_waitcnt lgkmcnt(9)
	v_pk_fma_f32 v[162:163], v[42:43], v[178:179], v[162:163] op_sel:[0,1,0] neg_lo:[1,0,0] neg_hi:[1,0,0]
	v_pk_fma_f32 v[150:151], v[38:39], v[178:179], v[150:151] op_sel_hi:[1,0,1] neg_lo:[1,0,0] neg_hi:[1,0,0]
	v_pk_fma_f32 v[162:163], v[46:47], v[180:181], v[162:163] op_sel:[0,1,0] neg_lo:[1,0,0] neg_hi:[1,0,0]
	v_pk_fma_f32 v[150:151], v[44:45], v[180:181], v[150:151] op_sel_hi:[1,0,1] neg_lo:[1,0,0] neg_hi:[1,0,0]
	ds_read_b128 v[178:181], v20 offset:50016
	s_waitcnt lgkmcnt(9)
	v_pk_fma_f32 v[162:163], v[50:51], v[182:183], v[162:163] op_sel:[0,1,0] neg_lo:[1,0,0] neg_hi:[1,0,0]
	v_pk_fma_f32 v[150:151], v[48:49], v[182:183], v[150:151] op_sel_hi:[1,0,1] neg_lo:[1,0,0] neg_hi:[1,0,0]
	v_pk_fma_f32 v[162:163], v[54:55], v[184:185], v[162:163] op_sel:[0,1,0] neg_lo:[1,0,0] neg_hi:[1,0,0]
	v_pk_fma_f32 v[150:151], v[52:53], v[184:185], v[150:151] op_sel_hi:[1,0,1] neg_lo:[1,0,0] neg_hi:[1,0,0]
	ds_read_b128 v[182:185], v20 offset:50032
	s_waitcnt lgkmcnt(9)
	v_pk_fma_f32 v[162:163], v[58:59], v[208:209], v[162:163] op_sel:[0,1,0] neg_lo:[1,0,0] neg_hi:[1,0,0]
	v_pk_fma_f32 v[150:151], v[56:57], v[208:209], v[150:151] op_sel_hi:[1,0,1] neg_lo:[1,0,0] neg_hi:[1,0,0]
	v_pk_fma_f32 v[162:163], v[62:63], v[210:211], v[162:163] op_sel:[0,1,0] neg_lo:[1,0,0] neg_hi:[1,0,0]
	v_pk_fma_f32 v[150:151], v[60:61], v[210:211], v[150:151] op_sel_hi:[1,0,1] neg_lo:[1,0,0] neg_hi:[1,0,0]
	ds_read_b128 v[208:211], v20 offset:50048
	s_waitcnt lgkmcnt(9)
	v_pk_fma_f32 v[162:163], v[66:67], v[212:213], v[162:163] op_sel:[0,1,0] neg_lo:[1,0,0] neg_hi:[1,0,0]
	v_pk_fma_f32 v[150:151], v[64:65], v[212:213], v[150:151] op_sel_hi:[1,0,1] neg_lo:[1,0,0] neg_hi:[1,0,0]
	v_pk_fma_f32 v[162:163], v[70:71], v[214:215], v[162:163] op_sel:[0,1,0] neg_lo:[1,0,0] neg_hi:[1,0,0]
	v_pk_fma_f32 v[150:151], v[68:69], v[214:215], v[150:151] op_sel_hi:[1,0,1] neg_lo:[1,0,0] neg_hi:[1,0,0]
	ds_read_b128 v[212:215], v20 offset:50064
	s_waitcnt lgkmcnt(9)
	v_pk_fma_f32 v[162:163], v[216:217], v[74:75], v[162:163] op_sel:[1,0,0] neg_lo:[1,0,0] neg_hi:[1,0,0]
	v_pk_fma_f32 v[150:151], v[72:73], v[216:217], v[150:151] op_sel_hi:[1,0,1] neg_lo:[1,0,0] neg_hi:[1,0,0]
	v_pk_fma_f32 v[162:163], v[78:79], v[218:219], v[162:163] op_sel:[0,1,0] neg_lo:[1,0,0] neg_hi:[1,0,0]
	v_pk_fma_f32 v[76:77], v[76:77], v[218:219], v[150:151] op_sel_hi:[1,0,1] neg_lo:[1,0,0] neg_hi:[1,0,0]
	ds_read_b128 v[150:153], v20 offset:49920
	ds_read_b128 v[216:219], v20 offset:50080
	v_pk_add_f32 v[76:77], v[76:77], v[162:163]
	s_waitcnt lgkmcnt(1)
	v_pk_fma_f32 v[162:163], v[138:139], v[150:151], 0 op_sel:[0,1,0] op_sel_hi:[1,1,0] neg_lo:[1,0,0] neg_hi:[1,0,0]
	v_pk_fma_f32 v[252:253], v[128:129], v[150:151], v[78:79] op_sel_hi:[1,0,1] neg_lo:[1,0,0] neg_hi:[1,0,0]
	v_pk_fma_f32 v[162:163], v[134:135], v[152:153], v[162:163] op_sel:[0,1,0] neg_lo:[1,0,0] neg_hi:[1,0,0]
	v_pk_fma_f32 v[252:253], v[136:137], v[152:153], v[252:253] op_sel_hi:[1,0,1] neg_lo:[1,0,0] neg_hi:[1,0,0]
	v_pk_fma_f32 v[162:163], v[130:131], v[154:155], v[162:163] op_sel:[0,1,0] neg_lo:[1,0,0] neg_hi:[1,0,0]
	ds_read_b128 v[150:153], v20 offset:50176
	v_pk_fma_f32 v[162:163], v[84:85], v[156:157], v[162:163] op_sel:[0,1,0] neg_lo:[1,0,0] neg_hi:[1,0,0]
	v_pk_fma_f32 v[252:253], v[132:133], v[154:155], v[252:253] op_sel_hi:[1,0,1] neg_lo:[1,0,0] neg_hi:[1,0,0]
	v_pk_fma_f32 v[162:163], v[10:11], v[158:159], v[162:163] op_sel:[0,1,0] neg_lo:[1,0,0] neg_hi:[1,0,0]
	v_pk_fma_f32 v[252:253], v[122:123], v[156:157], v[252:253] op_sel_hi:[1,0,1] neg_lo:[1,0,0] neg_hi:[1,0,0]
	v_pk_fma_f32 v[162:163], v[6:7], v[160:161], v[162:163] op_sel:[0,1,0] neg_lo:[1,0,0] neg_hi:[1,0,0]
	ds_read_b128 v[154:157], v20 offset:50192
	v_pk_fma_f32 v[162:163], v[12:13], v[166:167], v[162:163] op_sel:[0,1,0] neg_lo:[1,0,0] neg_hi:[1,0,0]
	v_pk_fma_f32 v[252:253], v[14:15], v[158:159], v[252:253] op_sel_hi:[1,0,1] neg_lo:[1,0,0] neg_hi:[1,0,0]
	v_pk_fma_f32 v[162:163], v[4:5], v[168:169], v[162:163] op_sel:[0,1,0] neg_lo:[1,0,0] neg_hi:[1,0,0]
	v_pk_fma_f32 v[252:253], v[16:17], v[160:161], v[252:253] op_sel_hi:[1,0,1] neg_lo:[1,0,0] neg_hi:[1,0,0]
	ds_read_b128 v[158:161], v20 offset:50208
	v_pk_fma_f32 v[162:163], v[0:1], v[170:171], v[162:163] op_sel:[0,1,0] neg_lo:[1,0,0] neg_hi:[1,0,0]
	v_pk_fma_f32 v[252:253], v[18:19], v[166:167], v[252:253] op_sel_hi:[1,0,1] neg_lo:[1,0,0] neg_hi:[1,0,0]
	v_pk_fma_f32 v[162:163], v[28:29], v[172:173], v[162:163] op_sel:[0,1,0] neg_lo:[1,0,0] neg_hi:[1,0,0]
	v_pk_fma_f32 v[252:253], v[8:9], v[168:169], v[252:253] op_sel_hi:[1,0,1] neg_lo:[1,0,0] neg_hi:[1,0,0]
	ds_read_b128 v[166:169], v20 offset:50224
	v_pk_fma_f32 v[162:163], v[34:35], v[174:175], v[162:163] op_sel:[0,1,0] neg_lo:[1,0,0] neg_hi:[1,0,0]
	v_pk_fma_f32 v[252:253], v[2:3], v[170:171], v[252:253] op_sel_hi:[1,0,1] neg_lo:[1,0,0] neg_hi:[1,0,0]
	v_pk_fma_f32 v[162:163], v[40:41], v[176:177], v[162:163] op_sel:[0,1,0] neg_lo:[1,0,0] neg_hi:[1,0,0]
	v_pk_fma_f32 v[252:253], v[30:31], v[172:173], v[252:253] op_sel_hi:[1,0,1] neg_lo:[1,0,0] neg_hi:[1,0,0]
	ds_read_b128 v[170:173], v20 offset:50240
	v_pk_fma_f32 v[162:163], v[42:43], v[178:179], v[162:163] op_sel:[0,1,0] neg_lo:[1,0,0] neg_hi:[1,0,0]
	v_pk_fma_f32 v[252:253], v[32:33], v[174:175], v[252:253] op_sel_hi:[1,0,1] neg_lo:[1,0,0] neg_hi:[1,0,0]
	v_pk_fma_f32 v[162:163], v[46:47], v[180:181], v[162:163] op_sel:[0,1,0] neg_lo:[1,0,0] neg_hi:[1,0,0]
	v_pk_fma_f32 v[252:253], v[36:37], v[176:177], v[252:253] op_sel_hi:[1,0,1] neg_lo:[1,0,0] neg_hi:[1,0,0]
	ds_read_b128 v[174:177], v20 offset:50256
	v_pk_fma_f32 v[162:163], v[50:51], v[182:183], v[162:163] op_sel:[0,1,0] neg_lo:[1,0,0] neg_hi:[1,0,0]
	v_pk_fma_f32 v[252:253], v[38:39], v[178:179], v[252:253] op_sel_hi:[1,0,1] neg_lo:[1,0,0] neg_hi:[1,0,0]
	v_pk_fma_f32 v[162:163], v[54:55], v[184:185], v[162:163] op_sel:[0,1,0] neg_lo:[1,0,0] neg_hi:[1,0,0]
	v_pk_fma_f32 v[252:253], v[44:45], v[180:181], v[252:253] op_sel_hi:[1,0,1] neg_lo:[1,0,0] neg_hi:[1,0,0]
	ds_read_b128 v[178:181], v20 offset:50272
	v_pk_fma_f32 v[162:163], v[58:59], v[208:209], v[162:163] op_sel:[0,1,0] neg_lo:[1,0,0] neg_hi:[1,0,0]
	v_pk_fma_f32 v[252:253], v[48:49], v[182:183], v[252:253] op_sel_hi:[1,0,1] neg_lo:[1,0,0] neg_hi:[1,0,0]
	v_pk_fma_f32 v[162:163], v[62:63], v[210:211], v[162:163] op_sel:[0,1,0] neg_lo:[1,0,0] neg_hi:[1,0,0]
	v_pk_fma_f32 v[252:253], v[52:53], v[184:185], v[252:253] op_sel_hi:[1,0,1] neg_lo:[1,0,0] neg_hi:[1,0,0]
	ds_read_b128 v[182:185], v20 offset:50288
	v_pk_fma_f32 v[162:163], v[66:67], v[212:213], v[162:163] op_sel:[0,1,0] neg_lo:[1,0,0] neg_hi:[1,0,0]
	v_pk_fma_f32 v[252:253], v[56:57], v[208:209], v[252:253] op_sel_hi:[1,0,1] neg_lo:[1,0,0] neg_hi:[1,0,0]
	v_pk_fma_f32 v[162:163], v[70:71], v[214:215], v[162:163] op_sel:[0,1,0] neg_lo:[1,0,0] neg_hi:[1,0,0]
	v_pk_fma_f32 v[252:253], v[60:61], v[210:211], v[252:253] op_sel_hi:[1,0,1] neg_lo:[1,0,0] neg_hi:[1,0,0]
	ds_read_b128 v[208:211], v20 offset:50304
	s_waitcnt lgkmcnt(9)
	v_pk_fma_f32 v[162:163], v[74:75], v[216:217], v[162:163] op_sel:[0,1,0] neg_lo:[1,0,0] neg_hi:[1,0,0]
	v_pk_fma_f32 v[252:253], v[64:65], v[212:213], v[252:253] op_sel_hi:[1,0,1] neg_lo:[1,0,0] neg_hi:[1,0,0]
	v_pk_fma_f32 v[162:163], v[78:79], v[218:219], v[162:163] op_sel:[0,1,0] neg_lo:[1,0,0] neg_hi:[1,0,0]
	v_pk_fma_f32 v[252:253], v[68:69], v[214:215], v[252:253] op_sel_hi:[1,0,1] neg_lo:[1,0,0] neg_hi:[1,0,0]
	ds_read_b128 v[212:215], v20 offset:50320
	v_pk_fma_f32 v[252:253], v[72:73], v[216:217], v[252:253] op_sel_hi:[1,0,1] neg_lo:[1,0,0] neg_hi:[1,0,0]
	s_nop 0
	v_pk_fma_f32 v[252:253], v[218:219], v[76:77], v[252:253] op_sel_hi:[0,1,1] neg_lo:[1,0,0] neg_hi:[1,0,0]
	ds_read_b128 v[216:219], v20 offset:50336
	v_pk_add_f32 v[78:79], v[252:253], v[162:163]
	s_waitcnt lgkmcnt(10)
	v_pk_fma_f32 v[162:163], v[138:139], v[150:151], 0 op_sel:[0,1,0] op_sel_hi:[1,1,0] neg_lo:[1,0,0] neg_hi:[1,0,0]
	v_pk_mul_f32 v[150:151], v[128:129], v[150:151] op_sel_hi:[1,0]
	v_pk_fma_f32 v[162:163], v[134:135], v[152:153], v[162:163] op_sel:[0,1,0] neg_lo:[1,0,0] neg_hi:[1,0,0]
	v_pk_fma_f32 v[80:81], v[80:81], v[146:147], v[150:151] neg_lo:[0,0,1] neg_hi:[0,0,1]
	s_waitcnt lgkmcnt(9)
	v_pk_fma_f32 v[162:163], v[130:131], v[154:155], v[162:163] op_sel:[0,1,0] neg_lo:[1,0,0] neg_hi:[1,0,0]
	v_pk_fma_f32 v[80:81], v[136:137], v[152:153], v[80:81] op_sel_hi:[1,0,1] neg_lo:[1,0,0] neg_hi:[1,0,0]
	ds_read_b128 v[150:153], v20 offset:50432
	v_pk_fma_f32 v[80:81], v[132:133], v[154:155], v[80:81] op_sel_hi:[1,0,1] neg_lo:[1,0,0] neg_hi:[1,0,0]
	v_pk_fma_f32 v[162:163], v[84:85], v[156:157], v[162:163] op_sel:[0,1,0] neg_lo:[1,0,0] neg_hi:[1,0,0]
	v_pk_fma_f32 v[80:81], v[122:123], v[156:157], v[80:81] op_sel_hi:[1,0,1] neg_lo:[1,0,0] neg_hi:[1,0,0]
	ds_read_b128 v[154:157], v20 offset:50448
	s_waitcnt lgkmcnt(10)
	v_pk_fma_f32 v[162:163], v[10:11], v[158:159], v[162:163] op_sel:[0,1,0] neg_lo:[1,0,0] neg_hi:[1,0,0]
	v_pk_fma_f32 v[80:81], v[14:15], v[158:159], v[80:81] op_sel_hi:[1,0,1] neg_lo:[1,0,0] neg_hi:[1,0,0]
	v_pk_fma_f32 v[162:163], v[6:7], v[160:161], v[162:163] op_sel:[0,1,0] neg_lo:[1,0,0] neg_hi:[1,0,0]
	v_pk_fma_f32 v[80:81], v[16:17], v[160:161], v[80:81] op_sel_hi:[1,0,1] neg_lo:[1,0,0] neg_hi:[1,0,0]
	ds_read_b128 v[158:161], v20 offset:50464
	s_waitcnt lgkmcnt(10)
	v_pk_fma_f32 v[162:163], v[12:13], v[166:167], v[162:163] op_sel:[0,1,0] neg_lo:[1,0,0] neg_hi:[1,0,0]
	v_pk_fma_f32 v[80:81], v[18:19], v[166:167], v[80:81] op_sel_hi:[1,0,1] neg_lo:[1,0,0] neg_hi:[1,0,0]
	v_pk_fma_f32 v[162:163], v[4:5], v[168:169], v[162:163] op_sel:[0,1,0] neg_lo:[1,0,0] neg_hi:[1,0,0]
	v_pk_fma_f32 v[80:81], v[8:9], v[168:169], v[80:81] op_sel_hi:[1,0,1] neg_lo:[1,0,0] neg_hi:[1,0,0]
	ds_read_b128 v[166:169], v20 offset:50480
	s_waitcnt lgkmcnt(10)
	v_pk_fma_f32 v[162:163], v[0:1], v[170:171], v[162:163] op_sel:[0,1,0] neg_lo:[1,0,0] neg_hi:[1,0,0]
	v_pk_fma_f32 v[80:81], v[2:3], v[170:171], v[80:81] op_sel_hi:[1,0,1] neg_lo:[1,0,0] neg_hi:[1,0,0]
	v_pk_fma_f32 v[162:163], v[28:29], v[172:173], v[162:163] op_sel:[0,1,0] neg_lo:[1,0,0] neg_hi:[1,0,0]
	v_pk_fma_f32 v[80:81], v[30:31], v[172:173], v[80:81] op_sel_hi:[1,0,1] neg_lo:[1,0,0] neg_hi:[1,0,0]
	ds_read_b128 v[170:173], v20 offset:50496
	s_waitcnt lgkmcnt(10)
	v_pk_fma_f32 v[162:163], v[34:35], v[174:175], v[162:163] op_sel:[0,1,0] neg_lo:[1,0,0] neg_hi:[1,0,0]
	v_pk_fma_f32 v[80:81], v[32:33], v[174:175], v[80:81] op_sel_hi:[1,0,1] neg_lo:[1,0,0] neg_hi:[1,0,0]
	v_pk_fma_f32 v[162:163], v[40:41], v[176:177], v[162:163] op_sel:[0,1,0] neg_lo:[1,0,0] neg_hi:[1,0,0]
	v_pk_fma_f32 v[80:81], v[36:37], v[176:177], v[80:81] op_sel_hi:[1,0,1] neg_lo:[1,0,0] neg_hi:[1,0,0]
	ds_read_b128 v[174:177], v20 offset:50512
	s_waitcnt lgkmcnt(10)
	v_pk_fma_f32 v[162:163], v[42:43], v[178:179], v[162:163] op_sel:[0,1,0] neg_lo:[1,0,0] neg_hi:[1,0,0]
	v_pk_fma_f32 v[80:81], v[38:39], v[178:179], v[80:81] op_sel_hi:[1,0,1] neg_lo:[1,0,0] neg_hi:[1,0,0]
	v_pk_fma_f32 v[162:163], v[46:47], v[180:181], v[162:163] op_sel:[0,1,0] neg_lo:[1,0,0] neg_hi:[1,0,0]
	v_pk_fma_f32 v[80:81], v[44:45], v[180:181], v[80:81] op_sel_hi:[1,0,1] neg_lo:[1,0,0] neg_hi:[1,0,0]
	ds_read_b128 v[178:181], v20 offset:50528
	s_waitcnt lgkmcnt(10)
	v_pk_fma_f32 v[162:163], v[50:51], v[182:183], v[162:163] op_sel:[0,1,0] neg_lo:[1,0,0] neg_hi:[1,0,0]
	v_pk_fma_f32 v[80:81], v[48:49], v[182:183], v[80:81] op_sel_hi:[1,0,1] neg_lo:[1,0,0] neg_hi:[1,0,0]
	v_pk_fma_f32 v[162:163], v[54:55], v[184:185], v[162:163] op_sel:[0,1,0] neg_lo:[1,0,0] neg_hi:[1,0,0]
	v_pk_fma_f32 v[80:81], v[52:53], v[184:185], v[80:81] op_sel_hi:[1,0,1] neg_lo:[1,0,0] neg_hi:[1,0,0]
	ds_read_b128 v[182:185], v20 offset:50544
	s_waitcnt lgkmcnt(10)
	v_pk_fma_f32 v[162:163], v[58:59], v[208:209], v[162:163] op_sel:[0,1,0] neg_lo:[1,0,0] neg_hi:[1,0,0]
	v_pk_fma_f32 v[80:81], v[56:57], v[208:209], v[80:81] op_sel_hi:[1,0,1] neg_lo:[1,0,0] neg_hi:[1,0,0]
	v_pk_fma_f32 v[162:163], v[62:63], v[210:211], v[162:163] op_sel:[0,1,0] neg_lo:[1,0,0] neg_hi:[1,0,0]
	v_pk_fma_f32 v[80:81], v[60:61], v[210:211], v[80:81] op_sel_hi:[1,0,1] neg_lo:[1,0,0] neg_hi:[1,0,0]
	ds_read_b128 v[208:211], v20 offset:50560
	s_waitcnt lgkmcnt(10)
	v_pk_fma_f32 v[162:163], v[66:67], v[212:213], v[162:163] op_sel:[0,1,0] neg_lo:[1,0,0] neg_hi:[1,0,0]
	v_pk_fma_f32 v[80:81], v[64:65], v[212:213], v[80:81] op_sel_hi:[1,0,1] neg_lo:[1,0,0] neg_hi:[1,0,0]
	v_pk_fma_f32 v[162:163], v[70:71], v[214:215], v[162:163] op_sel:[0,1,0] neg_lo:[1,0,0] neg_hi:[1,0,0]
	v_pk_fma_f32 v[80:81], v[68:69], v[214:215], v[80:81] op_sel_hi:[1,0,1] neg_lo:[1,0,0] neg_hi:[1,0,0]
	ds_read_b128 v[212:215], v20 offset:50576
	s_waitcnt lgkmcnt(10)
	v_pk_fma_f32 v[162:163], v[74:75], v[216:217], v[162:163] op_sel:[0,1,0] neg_lo:[1,0,0] neg_hi:[1,0,0]
	v_pk_fma_f32 v[80:81], v[72:73], v[216:217], v[80:81] op_sel_hi:[1,0,1] neg_lo:[1,0,0] neg_hi:[1,0,0]
	v_pk_fma_f32 v[162:163], v[218:219], v[78:79], v[162:163] op_sel:[1,0,0] neg_lo:[1,0,0] neg_hi:[1,0,0]
	v_pk_fma_f32 v[80:81], v[76:77], v[218:219], v[80:81] op_sel_hi:[1,0,1] neg_lo:[1,0,0] neg_hi:[1,0,0]
	ds_read_b128 v[216:219], v20 offset:50592
	v_pk_add_f32 v[80:81], v[80:81], v[162:163]
	s_waitcnt lgkmcnt(10)
	v_pk_fma_f32 v[146:147], v[138:139], v[150:151], 0 op_sel:[0,1,0] op_sel_hi:[1,1,0] neg_lo:[1,0,0] neg_hi:[1,0,0]
	v_pk_fma_f32 v[252:253], v[128:129], v[150:151], v[82:83] op_sel_hi:[1,0,1] neg_lo:[1,0,0] neg_hi:[1,0,0]
	v_pk_fma_f32 v[146:147], v[134:135], v[152:153], v[146:147] op_sel:[0,1,0] neg_lo:[1,0,0] neg_hi:[1,0,0]
	v_pk_fma_f32 v[252:253], v[136:137], v[152:153], v[252:253] op_sel_hi:[1,0,1] neg_lo:[1,0,0] neg_hi:[1,0,0]
	s_waitcnt lgkmcnt(9)
	v_pk_fma_f32 v[146:147], v[130:131], v[154:155], v[146:147] op_sel:[0,1,0] neg_lo:[1,0,0] neg_hi:[1,0,0]
	ds_read_b128 v[150:153], v20 offset:50688
	v_pk_fma_f32 v[146:147], v[84:85], v[156:157], v[146:147] op_sel:[0,1,0] neg_lo:[1,0,0] neg_hi:[1,0,0]
	v_pk_fma_f32 v[252:253], v[132:133], v[154:155], v[252:253] op_sel_hi:[1,0,1] neg_lo:[1,0,0] neg_hi:[1,0,0]
	s_waitcnt lgkmcnt(9)
	v_pk_fma_f32 v[146:147], v[10:11], v[158:159], v[146:147] op_sel:[0,1,0] neg_lo:[1,0,0] neg_hi:[1,0,0]
	v_pk_fma_f32 v[252:253], v[122:123], v[156:157], v[252:253] op_sel_hi:[1,0,1] neg_lo:[1,0,0] neg_hi:[1,0,0]
	v_pk_fma_f32 v[146:147], v[6:7], v[160:161], v[146:147] op_sel:[0,1,0] neg_lo:[1,0,0] neg_hi:[1,0,0]
	ds_read_b128 v[154:157], v20 offset:50704
	s_waitcnt lgkmcnt(9)
	v_pk_fma_f32 v[146:147], v[12:13], v[166:167], v[146:147] op_sel:[0,1,0] neg_lo:[1,0,0] neg_hi:[1,0,0]
	v_pk_fma_f32 v[252:253], v[14:15], v[158:159], v[252:253] op_sel_hi:[1,0,1] neg_lo:[1,0,0] neg_hi:[1,0,0]
	v_pk_fma_f32 v[146:147], v[4:5], v[168:169], v[146:147] op_sel:[0,1,0] neg_lo:[1,0,0] neg_hi:[1,0,0]
	v_pk_fma_f32 v[252:253], v[16:17], v[160:161], v[252:253] op_sel_hi:[1,0,1] neg_lo:[1,0,0] neg_hi:[1,0,0]
	s_waitcnt lgkmcnt(8)
	v_pk_fma_f32 v[146:147], v[0:1], v[170:171], v[146:147] op_sel:[0,1,0] neg_lo:[1,0,0] neg_hi:[1,0,0]
	ds_read_b128 v[158:161], v20 offset:50720
	v_pk_fma_f32 v[146:147], v[28:29], v[172:173], v[146:147] op_sel:[0,1,0] neg_lo:[1,0,0] neg_hi:[1,0,0]
	v_pk_fma_f32 v[252:253], v[18:19], v[166:167], v[252:253] op_sel_hi:[1,0,1] neg_lo:[1,0,0] neg_hi:[1,0,0]
	s_waitcnt lgkmcnt(8)
	v_pk_fma_f32 v[146:147], v[34:35], v[174:175], v[146:147] op_sel:[0,1,0] neg_lo:[1,0,0] neg_hi:[1,0,0]
	v_pk_fma_f32 v[252:253], v[8:9], v[168:169], v[252:253] op_sel_hi:[1,0,1] neg_lo:[1,0,0] neg_hi:[1,0,0]
	ds_read_b128 v[166:169], v20 offset:50736
	v_pk_fma_f32 v[146:147], v[40:41], v[176:177], v[146:147] op_sel:[0,1,0] neg_lo:[1,0,0] neg_hi:[1,0,0]
	v_pk_fma_f32 v[252:253], v[2:3], v[170:171], v[252:253] op_sel_hi:[1,0,1] neg_lo:[1,0,0] neg_hi:[1,0,0]
	s_waitcnt lgkmcnt(8)
	v_pk_fma_f32 v[146:147], v[42:43], v[178:179], v[146:147] op_sel:[0,1,0] neg_lo:[1,0,0] neg_hi:[1,0,0]
	v_pk_fma_f32 v[252:253], v[30:31], v[172:173], v[252:253] op_sel_hi:[1,0,1] neg_lo:[1,0,0] neg_hi:[1,0,0]
	ds_read_b128 v[170:173], v20 offset:50752
	v_pk_fma_f32 v[146:147], v[46:47], v[180:181], v[146:147] op_sel:[0,1,0] neg_lo:[1,0,0] neg_hi:[1,0,0]
	v_pk_fma_f32 v[252:253], v[32:33], v[174:175], v[252:253] op_sel_hi:[1,0,1] neg_lo:[1,0,0] neg_hi:[1,0,0]
	s_waitcnt lgkmcnt(8)
	v_pk_fma_f32 v[146:147], v[50:51], v[182:183], v[146:147] op_sel:[0,1,0] neg_lo:[1,0,0] neg_hi:[1,0,0]
	v_pk_fma_f32 v[252:253], v[36:37], v[176:177], v[252:253] op_sel_hi:[1,0,1] neg_lo:[1,0,0] neg_hi:[1,0,0]
	ds_read_b128 v[174:177], v20 offset:50768
	v_pk_fma_f32 v[146:147], v[54:55], v[184:185], v[146:147] op_sel:[0,1,0] neg_lo:[1,0,0] neg_hi:[1,0,0]
	v_pk_fma_f32 v[252:253], v[38:39], v[178:179], v[252:253] op_sel_hi:[1,0,1] neg_lo:[1,0,0] neg_hi:[1,0,0]
	s_waitcnt lgkmcnt(8)
	v_pk_fma_f32 v[146:147], v[58:59], v[208:209], v[146:147] op_sel:[0,1,0] neg_lo:[1,0,0] neg_hi:[1,0,0]
	v_pk_fma_f32 v[252:253], v[44:45], v[180:181], v[252:253] op_sel_hi:[1,0,1] neg_lo:[1,0,0] neg_hi:[1,0,0]
	ds_read_b128 v[178:181], v20 offset:50784
	v_pk_fma_f32 v[146:147], v[62:63], v[210:211], v[146:147] op_sel:[0,1,0] neg_lo:[1,0,0] neg_hi:[1,0,0]
	v_pk_fma_f32 v[252:253], v[48:49], v[182:183], v[252:253] op_sel_hi:[1,0,1] neg_lo:[1,0,0] neg_hi:[1,0,0]
	s_waitcnt lgkmcnt(8)
	v_pk_fma_f32 v[146:147], v[66:67], v[212:213], v[146:147] op_sel:[0,1,0] neg_lo:[1,0,0] neg_hi:[1,0,0]
	v_pk_fma_f32 v[252:253], v[52:53], v[184:185], v[252:253] op_sel_hi:[1,0,1] neg_lo:[1,0,0] neg_hi:[1,0,0]
	ds_read_b128 v[182:185], v20 offset:50800
	v_pk_fma_f32 v[146:147], v[70:71], v[214:215], v[146:147] op_sel:[0,1,0] neg_lo:[1,0,0] neg_hi:[1,0,0]
	v_pk_fma_f32 v[252:253], v[56:57], v[208:209], v[252:253] op_sel_hi:[1,0,1] neg_lo:[1,0,0] neg_hi:[1,0,0]
	s_waitcnt lgkmcnt(8)
	v_pk_fma_f32 v[146:147], v[74:75], v[216:217], v[146:147] op_sel:[0,1,0] neg_lo:[1,0,0] neg_hi:[1,0,0]
	v_pk_fma_f32 v[252:253], v[60:61], v[210:211], v[252:253] op_sel_hi:[1,0,1] neg_lo:[1,0,0] neg_hi:[1,0,0]
	ds_read_b128 v[208:211], v20 offset:50816
	v_pk_fma_f32 v[146:147], v[78:79], v[218:219], v[146:147] op_sel:[0,1,0] neg_lo:[1,0,0] neg_hi:[1,0,0]
	v_pk_fma_f32 v[252:253], v[64:65], v[212:213], v[252:253] op_sel_hi:[1,0,1] neg_lo:[1,0,0] neg_hi:[1,0,0]
	v_pk_fma_f32 v[146:147], v[82:83], v[220:221], v[146:147] op_sel:[0,1,0] neg_lo:[1,0,0] neg_hi:[1,0,0]
	v_pk_fma_f32 v[252:253], v[68:69], v[214:215], v[252:253] op_sel_hi:[1,0,1] neg_lo:[1,0,0] neg_hi:[1,0,0]
	ds_read_b128 v[212:215], v20 offset:50832
	v_pk_fma_f32 v[146:147], v[88:89], v[222:223], v[146:147] op_sel:[0,1,0] neg_lo:[1,0,0] neg_hi:[1,0,0]
	v_pk_fma_f32 v[252:253], v[72:73], v[216:217], v[252:253] op_sel_hi:[1,0,1] neg_lo:[1,0,0] neg_hi:[1,0,0]
	s_nop 0
	v_pk_fma_f32 v[252:253], v[76:77], v[218:219], v[252:253] op_sel_hi:[1,0,1] neg_lo:[1,0,0] neg_hi:[1,0,0]
	ds_read_b128 v[216:219], v20 offset:50848
	v_pk_fma_f32 v[252:253], v[220:221], v[80:81], v[252:253] op_sel_hi:[0,1,1] neg_lo:[1,0,0] neg_hi:[1,0,0]
	s_nop 0
	v_pk_fma_f32 v[252:253], v[86:87], v[222:223], v[252:253] op_sel_hi:[1,0,1] neg_lo:[1,0,0] neg_hi:[1,0,0]
	ds_read_b128 v[220:223], v20 offset:50864
	v_pk_add_f32 v[82:83], v[252:253], v[146:147]
	s_waitcnt lgkmcnt(11)
	v_pk_fma_f32 v[146:147], v[138:139], v[150:151], 0 op_sel:[0,1,0] op_sel_hi:[1,1,0] neg_lo:[1,0,0] neg_hi:[1,0,0]
	v_pk_fma_f32 v[150:151], v[128:129], v[150:151], v[86:87] op_sel_hi:[1,0,1] neg_lo:[1,0,0] neg_hi:[1,0,0]
	v_pk_fma_f32 v[146:147], v[134:135], v[152:153], v[146:147] op_sel:[0,1,0] neg_lo:[1,0,0] neg_hi:[1,0,0]
	v_pk_fma_f32 v[150:151], v[136:137], v[152:153], v[150:151] op_sel_hi:[1,0,1] neg_lo:[1,0,0] neg_hi:[1,0,0]
	s_waitcnt lgkmcnt(10)
	v_pk_fma_f32 v[146:147], v[130:131], v[154:155], v[146:147] op_sel:[0,1,0] neg_lo:[1,0,0] neg_hi:[1,0,0]
	v_pk_fma_f32 v[150:151], v[132:133], v[154:155], v[150:151] op_sel_hi:[1,0,1] neg_lo:[1,0,0] neg_hi:[1,0,0]
	v_pk_fma_f32 v[146:147], v[84:85], v[156:157], v[146:147] op_sel:[0,1,0] neg_lo:[1,0,0] neg_hi:[1,0,0]
	v_pk_fma_f32 v[150:151], v[122:123], v[156:157], v[150:151] op_sel_hi:[1,0,1] neg_lo:[1,0,0] neg_hi:[1,0,0]
	ds_read_b128 v[154:157], v20 offset:50960
	s_waitcnt lgkmcnt(10)
	v_pk_fma_f32 v[146:147], v[10:11], v[158:159], v[146:147] op_sel:[0,1,0] neg_lo:[1,0,0] neg_hi:[1,0,0]
	v_pk_fma_f32 v[150:151], v[14:15], v[158:159], v[150:151] op_sel_hi:[1,0,1] neg_lo:[1,0,0] neg_hi:[1,0,0]
	v_pk_fma_f32 v[146:147], v[6:7], v[160:161], v[146:147] op_sel:[0,1,0] neg_lo:[1,0,0] neg_hi:[1,0,0]
	v_pk_fma_f32 v[150:151], v[16:17], v[160:161], v[150:151] op_sel_hi:[1,0,1] neg_lo:[1,0,0] neg_hi:[1,0,0]
	ds_read_b128 v[158:161], v20 offset:50976
	s_waitcnt lgkmcnt(10)
	v_pk_fma_f32 v[146:147], v[12:13], v[166:167], v[146:147] op_sel:[0,1,0] neg_lo:[1,0,0] neg_hi:[1,0,0]
	v_pk_fma_f32 v[150:151], v[18:19], v[166:167], v[150:151] op_sel_hi:[1,0,1] neg_lo:[1,0,0] neg_hi:[1,0,0]
	v_pk_fma_f32 v[146:147], v[4:5], v[168:169], v[146:147] op_sel:[0,1,0] neg_lo:[1,0,0] neg_hi:[1,0,0]
	v_pk_fma_f32 v[150:151], v[8:9], v[168:169], v[150:151] op_sel_hi:[1,0,1] neg_lo:[1,0,0] neg_hi:[1,0,0]
	ds_read_b128 v[166:169], v20 offset:50992
	s_waitcnt lgkmcnt(10)
	v_pk_fma_f32 v[146:147], v[0:1], v[170:171], v[146:147] op_sel:[0,1,0] neg_lo:[1,0,0] neg_hi:[1,0,0]
	v_pk_fma_f32 v[150:151], v[2:3], v[170:171], v[150:151] op_sel_hi:[1,0,1] neg_lo:[1,0,0] neg_hi:[1,0,0]
	v_pk_fma_f32 v[146:147], v[28:29], v[172:173], v[146:147] op_sel:[0,1,0] neg_lo:[1,0,0] neg_hi:[1,0,0]
	v_pk_fma_f32 v[150:151], v[30:31], v[172:173], v[150:151] op_sel_hi:[1,0,1] neg_lo:[1,0,0] neg_hi:[1,0,0]
	ds_read_b128 v[170:173], v20 offset:51008
	s_waitcnt lgkmcnt(10)
	v_pk_fma_f32 v[146:147], v[34:35], v[174:175], v[146:147] op_sel:[0,1,0] neg_lo:[1,0,0] neg_hi:[1,0,0]
	v_pk_fma_f32 v[150:151], v[32:33], v[174:175], v[150:151] op_sel_hi:[1,0,1] neg_lo:[1,0,0] neg_hi:[1,0,0]
	v_pk_fma_f32 v[146:147], v[40:41], v[176:177], v[146:147] op_sel:[0,1,0] neg_lo:[1,0,0] neg_hi:[1,0,0]
	v_pk_fma_f32 v[150:151], v[36:37], v[176:177], v[150:151] op_sel_hi:[1,0,1] neg_lo:[1,0,0] neg_hi:[1,0,0]
	ds_read_b128 v[174:177], v20 offset:51024
	s_waitcnt lgkmcnt(10)
	v_pk_fma_f32 v[146:147], v[42:43], v[178:179], v[146:147] op_sel:[0,1,0] neg_lo:[1,0,0] neg_hi:[1,0,0]
	v_pk_fma_f32 v[150:151], v[38:39], v[178:179], v[150:151] op_sel_hi:[1,0,1] neg_lo:[1,0,0] neg_hi:[1,0,0]
	v_pk_fma_f32 v[146:147], v[46:47], v[180:181], v[146:147] op_sel:[0,1,0] neg_lo:[1,0,0] neg_hi:[1,0,0]
	v_pk_fma_f32 v[150:151], v[44:45], v[180:181], v[150:151] op_sel_hi:[1,0,1] neg_lo:[1,0,0] neg_hi:[1,0,0]
	ds_read_b128 v[178:181], v20 offset:51040
	s_waitcnt lgkmcnt(10)
	v_pk_fma_f32 v[146:147], v[50:51], v[182:183], v[146:147] op_sel:[0,1,0] neg_lo:[1,0,0] neg_hi:[1,0,0]
	v_pk_fma_f32 v[150:151], v[48:49], v[182:183], v[150:151] op_sel_hi:[1,0,1] neg_lo:[1,0,0] neg_hi:[1,0,0]
	v_pk_fma_f32 v[146:147], v[54:55], v[184:185], v[146:147] op_sel:[0,1,0] neg_lo:[1,0,0] neg_hi:[1,0,0]
	v_pk_fma_f32 v[150:151], v[52:53], v[184:185], v[150:151] op_sel_hi:[1,0,1] neg_lo:[1,0,0] neg_hi:[1,0,0]
	ds_read_b128 v[182:185], v20 offset:51056
	s_waitcnt lgkmcnt(10)
	v_pk_fma_f32 v[146:147], v[58:59], v[208:209], v[146:147] op_sel:[0,1,0] neg_lo:[1,0,0] neg_hi:[1,0,0]
	v_pk_fma_f32 v[150:151], v[56:57], v[208:209], v[150:151] op_sel_hi:[1,0,1] neg_lo:[1,0,0] neg_hi:[1,0,0]
	v_pk_fma_f32 v[146:147], v[62:63], v[210:211], v[146:147] op_sel:[0,1,0] neg_lo:[1,0,0] neg_hi:[1,0,0]
	v_pk_fma_f32 v[150:151], v[60:61], v[210:211], v[150:151] op_sel_hi:[1,0,1] neg_lo:[1,0,0] neg_hi:[1,0,0]
	ds_read_b128 v[208:211], v20 offset:51072
	s_waitcnt lgkmcnt(10)
	v_pk_fma_f32 v[146:147], v[66:67], v[212:213], v[146:147] op_sel:[0,1,0] neg_lo:[1,0,0] neg_hi:[1,0,0]
	v_pk_fma_f32 v[150:151], v[64:65], v[212:213], v[150:151] op_sel_hi:[1,0,1] neg_lo:[1,0,0] neg_hi:[1,0,0]
	v_pk_fma_f32 v[146:147], v[70:71], v[214:215], v[146:147] op_sel:[0,1,0] neg_lo:[1,0,0] neg_hi:[1,0,0]
	v_pk_fma_f32 v[150:151], v[68:69], v[214:215], v[150:151] op_sel_hi:[1,0,1] neg_lo:[1,0,0] neg_hi:[1,0,0]
	ds_read_b128 v[212:215], v20 offset:51088
	s_waitcnt lgkmcnt(10)
	v_pk_fma_f32 v[146:147], v[74:75], v[216:217], v[146:147] op_sel:[0,1,0] neg_lo:[1,0,0] neg_hi:[1,0,0]
	v_pk_fma_f32 v[150:151], v[72:73], v[216:217], v[150:151] op_sel_hi:[1,0,1] neg_lo:[1,0,0] neg_hi:[1,0,0]
	v_pk_fma_f32 v[146:147], v[78:79], v[218:219], v[146:147] op_sel:[0,1,0] neg_lo:[1,0,0] neg_hi:[1,0,0]
	v_pk_fma_f32 v[150:151], v[76:77], v[218:219], v[150:151] op_sel_hi:[1,0,1] neg_lo:[1,0,0] neg_hi:[1,0,0]
	ds_read_b128 v[216:219], v20 offset:51104
	s_waitcnt lgkmcnt(10)
	v_pk_fma_f32 v[146:147], v[220:221], v[82:83], v[146:147] op_sel:[1,0,0] neg_lo:[1,0,0] neg_hi:[1,0,0]
	v_pk_fma_f32 v[150:151], v[80:81], v[220:221], v[150:151] op_sel_hi:[1,0,1] neg_lo:[1,0,0] neg_hi:[1,0,0]
	v_pk_fma_f32 v[146:147], v[88:89], v[222:223], v[146:147] op_sel:[0,1,0] neg_lo:[1,0,0] neg_hi:[1,0,0]
	v_pk_fma_f32 v[86:87], v[86:87], v[222:223], v[150:151] op_sel_hi:[1,0,1] neg_lo:[1,0,0] neg_hi:[1,0,0]
	ds_read_b128 v[150:153], v20 offset:50944
	ds_read_b128 v[220:223], v20 offset:51120
	v_pk_add_f32 v[86:87], v[86:87], v[146:147]
	s_waitcnt lgkmcnt(1)
	v_pk_fma_f32 v[146:147], v[138:139], v[150:151], 0 op_sel:[0,1,0] op_sel_hi:[1,1,0] neg_lo:[1,0,0] neg_hi:[1,0,0]
	v_pk_fma_f32 v[252:253], v[128:129], v[150:151], v[88:89] op_sel_hi:[1,0,1] neg_lo:[1,0,0] neg_hi:[1,0,0]
	v_pk_fma_f32 v[146:147], v[134:135], v[152:153], v[146:147] op_sel:[0,1,0] neg_lo:[1,0,0] neg_hi:[1,0,0]
	v_pk_fma_f32 v[252:253], v[136:137], v[152:153], v[252:253] op_sel_hi:[1,0,1] neg_lo:[1,0,0] neg_hi:[1,0,0]
	v_pk_fma_f32 v[146:147], v[130:131], v[154:155], v[146:147] op_sel:[0,1,0] neg_lo:[1,0,0] neg_hi:[1,0,0]
	ds_read_b128 v[150:153], v20 offset:51200
	v_pk_fma_f32 v[146:147], v[84:85], v[156:157], v[146:147] op_sel:[0,1,0] neg_lo:[1,0,0] neg_hi:[1,0,0]
	v_pk_fma_f32 v[252:253], v[132:133], v[154:155], v[252:253] op_sel_hi:[1,0,1] neg_lo:[1,0,0] neg_hi:[1,0,0]
	v_pk_fma_f32 v[146:147], v[10:11], v[158:159], v[146:147] op_sel:[0,1,0] neg_lo:[1,0,0] neg_hi:[1,0,0]
	v_pk_fma_f32 v[252:253], v[122:123], v[156:157], v[252:253] op_sel_hi:[1,0,1] neg_lo:[1,0,0] neg_hi:[1,0,0]
	v_pk_fma_f32 v[146:147], v[6:7], v[160:161], v[146:147] op_sel:[0,1,0] neg_lo:[1,0,0] neg_hi:[1,0,0]
	ds_read_b128 v[154:157], v20 offset:51216
	v_pk_fma_f32 v[146:147], v[12:13], v[166:167], v[146:147] op_sel:[0,1,0] neg_lo:[1,0,0] neg_hi:[1,0,0]
	v_pk_fma_f32 v[252:253], v[14:15], v[158:159], v[252:253] op_sel_hi:[1,0,1] neg_lo:[1,0,0] neg_hi:[1,0,0]
	v_pk_fma_f32 v[146:147], v[4:5], v[168:169], v[146:147] op_sel:[0,1,0] neg_lo:[1,0,0] neg_hi:[1,0,0]
	v_pk_fma_f32 v[252:253], v[16:17], v[160:161], v[252:253] op_sel_hi:[1,0,1] neg_lo:[1,0,0] neg_hi:[1,0,0]
	v_pk_fma_f32 v[146:147], v[0:1], v[170:171], v[146:147] op_sel:[0,1,0] neg_lo:[1,0,0] neg_hi:[1,0,0]
	ds_read_b128 v[158:161], v20 offset:51232
	v_pk_fma_f32 v[146:147], v[28:29], v[172:173], v[146:147] op_sel:[0,1,0] neg_lo:[1,0,0] neg_hi:[1,0,0]
	v_pk_fma_f32 v[252:253], v[18:19], v[166:167], v[252:253] op_sel_hi:[1,0,1] neg_lo:[1,0,0] neg_hi:[1,0,0]
	v_pk_fma_f32 v[146:147], v[34:35], v[174:175], v[146:147] op_sel:[0,1,0] neg_lo:[1,0,0] neg_hi:[1,0,0]
	v_pk_fma_f32 v[252:253], v[8:9], v[168:169], v[252:253] op_sel_hi:[1,0,1] neg_lo:[1,0,0] neg_hi:[1,0,0]
	v_pk_fma_f32 v[146:147], v[40:41], v[176:177], v[146:147] op_sel:[0,1,0] neg_lo:[1,0,0] neg_hi:[1,0,0]
	ds_read_b128 v[166:169], v20 offset:51248
	v_pk_fma_f32 v[146:147], v[42:43], v[178:179], v[146:147] op_sel:[0,1,0] neg_lo:[1,0,0] neg_hi:[1,0,0]
	v_pk_fma_f32 v[252:253], v[2:3], v[170:171], v[252:253] op_sel_hi:[1,0,1] neg_lo:[1,0,0] neg_hi:[1,0,0]
	v_pk_fma_f32 v[146:147], v[46:47], v[180:181], v[146:147] op_sel:[0,1,0] neg_lo:[1,0,0] neg_hi:[1,0,0]
	v_pk_fma_f32 v[252:253], v[30:31], v[172:173], v[252:253] op_sel_hi:[1,0,1] neg_lo:[1,0,0] neg_hi:[1,0,0]
	ds_read_b128 v[170:173], v20 offset:51264
	v_pk_fma_f32 v[146:147], v[50:51], v[182:183], v[146:147] op_sel:[0,1,0] neg_lo:[1,0,0] neg_hi:[1,0,0]
	v_pk_fma_f32 v[252:253], v[32:33], v[174:175], v[252:253] op_sel_hi:[1,0,1] neg_lo:[1,0,0] neg_hi:[1,0,0]
	v_pk_fma_f32 v[146:147], v[54:55], v[184:185], v[146:147] op_sel:[0,1,0] neg_lo:[1,0,0] neg_hi:[1,0,0]
	v_pk_fma_f32 v[252:253], v[36:37], v[176:177], v[252:253] op_sel_hi:[1,0,1] neg_lo:[1,0,0] neg_hi:[1,0,0]
	ds_read_b128 v[174:177], v20 offset:51280
	v_pk_fma_f32 v[146:147], v[58:59], v[208:209], v[146:147] op_sel:[0,1,0] neg_lo:[1,0,0] neg_hi:[1,0,0]
	v_pk_fma_f32 v[252:253], v[38:39], v[178:179], v[252:253] op_sel_hi:[1,0,1] neg_lo:[1,0,0] neg_hi:[1,0,0]
	v_pk_fma_f32 v[146:147], v[62:63], v[210:211], v[146:147] op_sel:[0,1,0] neg_lo:[1,0,0] neg_hi:[1,0,0]
	v_pk_fma_f32 v[252:253], v[44:45], v[180:181], v[252:253] op_sel_hi:[1,0,1] neg_lo:[1,0,0] neg_hi:[1,0,0]
	ds_read_b128 v[178:181], v20 offset:51296
	v_pk_fma_f32 v[146:147], v[66:67], v[212:213], v[146:147] op_sel:[0,1,0] neg_lo:[1,0,0] neg_hi:[1,0,0]
	v_pk_fma_f32 v[252:253], v[48:49], v[182:183], v[252:253] op_sel_hi:[1,0,1] neg_lo:[1,0,0] neg_hi:[1,0,0]
	v_pk_fma_f32 v[146:147], v[70:71], v[214:215], v[146:147] op_sel:[0,1,0] neg_lo:[1,0,0] neg_hi:[1,0,0]
	v_pk_fma_f32 v[252:253], v[52:53], v[184:185], v[252:253] op_sel_hi:[1,0,1] neg_lo:[1,0,0] neg_hi:[1,0,0]
	ds_read_b128 v[182:185], v20 offset:51312
	v_pk_fma_f32 v[146:147], v[74:75], v[216:217], v[146:147] op_sel:[0,1,0] neg_lo:[1,0,0] neg_hi:[1,0,0]
	v_pk_fma_f32 v[252:253], v[56:57], v[208:209], v[252:253] op_sel_hi:[1,0,1] neg_lo:[1,0,0] neg_hi:[1,0,0]
	v_pk_fma_f32 v[146:147], v[78:79], v[218:219], v[146:147] op_sel:[0,1,0] neg_lo:[1,0,0] neg_hi:[1,0,0]
	v_pk_fma_f32 v[252:253], v[60:61], v[210:211], v[252:253] op_sel_hi:[1,0,1] neg_lo:[1,0,0] neg_hi:[1,0,0]
	ds_read_b128 v[208:211], v20 offset:51328
	s_waitcnt lgkmcnt(9)
	v_pk_fma_f32 v[146:147], v[82:83], v[220:221], v[146:147] op_sel:[0,1,0] neg_lo:[1,0,0] neg_hi:[1,0,0]
	v_pk_fma_f32 v[252:253], v[64:65], v[212:213], v[252:253] op_sel_hi:[1,0,1] neg_lo:[1,0,0] neg_hi:[1,0,0]
	v_pk_fma_f32 v[146:147], v[88:89], v[222:223], v[146:147] op_sel:[0,1,0] neg_lo:[1,0,0] neg_hi:[1,0,0]
	v_pk_fma_f32 v[252:253], v[68:69], v[214:215], v[252:253] op_sel_hi:[1,0,1] neg_lo:[1,0,0] neg_hi:[1,0,0]
	ds_read_b128 v[212:215], v20 offset:51344
	v_pk_fma_f32 v[252:253], v[72:73], v[216:217], v[252:253] op_sel_hi:[1,0,1] neg_lo:[1,0,0] neg_hi:[1,0,0]
	s_nop 0
	v_pk_fma_f32 v[252:253], v[76:77], v[218:219], v[252:253] op_sel_hi:[1,0,1] neg_lo:[1,0,0] neg_hi:[1,0,0]
	ds_read_b128 v[216:219], v20 offset:51360
	v_pk_fma_f32 v[252:253], v[80:81], v[220:221], v[252:253] op_sel_hi:[1,0,1] neg_lo:[1,0,0] neg_hi:[1,0,0]
	s_nop 0
	v_pk_fma_f32 v[252:253], v[222:223], v[86:87], v[252:253] op_sel_hi:[0,1,1] neg_lo:[1,0,0] neg_hi:[1,0,0]
	ds_read_b128 v[220:223], v20 offset:51376
	v_pk_add_f32 v[88:89], v[252:253], v[146:147]
	s_waitcnt lgkmcnt(11)
	v_pk_fma_f32 v[146:147], v[138:139], v[150:151], 0 op_sel:[0,1,0] op_sel_hi:[1,1,0] neg_lo:[1,0,0] neg_hi:[1,0,0]
	v_pk_mul_f32 v[150:151], v[128:129], v[150:151] op_sel_hi:[1,0]
	v_pk_fma_f32 v[146:147], v[134:135], v[152:153], v[146:147] op_sel:[0,1,0] neg_lo:[1,0,0] neg_hi:[1,0,0]
	v_pk_fma_f32 v[90:91], v[90:91], v[112:113], v[150:151] neg_lo:[0,0,1] neg_hi:[0,0,1]
	s_waitcnt lgkmcnt(10)
	v_pk_fma_f32 v[146:147], v[130:131], v[154:155], v[146:147] op_sel:[0,1,0] neg_lo:[1,0,0] neg_hi:[1,0,0]
	v_pk_fma_f32 v[90:91], v[136:137], v[152:153], v[90:91] op_sel_hi:[1,0,1] neg_lo:[1,0,0] neg_hi:[1,0,0]
	ds_read_b128 v[150:153], v20 offset:51456
	v_pk_fma_f32 v[90:91], v[132:133], v[154:155], v[90:91] op_sel_hi:[1,0,1] neg_lo:[1,0,0] neg_hi:[1,0,0]
	v_pk_fma_f32 v[146:147], v[84:85], v[156:157], v[146:147] op_sel:[0,1,0] neg_lo:[1,0,0] neg_hi:[1,0,0]
	v_pk_fma_f32 v[90:91], v[122:123], v[156:157], v[90:91] op_sel_hi:[1,0,1] neg_lo:[1,0,0] neg_hi:[1,0,0]
	ds_read_b128 v[154:157], v20 offset:51472
	s_waitcnt lgkmcnt(11)
	v_pk_fma_f32 v[146:147], v[10:11], v[158:159], v[146:147] op_sel:[0,1,0] neg_lo:[1,0,0] neg_hi:[1,0,0]
	v_pk_fma_f32 v[90:91], v[14:15], v[158:159], v[90:91] op_sel_hi:[1,0,1] neg_lo:[1,0,0] neg_hi:[1,0,0]
	v_pk_fma_f32 v[146:147], v[6:7], v[160:161], v[146:147] op_sel:[0,1,0] neg_lo:[1,0,0] neg_hi:[1,0,0]
	v_pk_fma_f32 v[90:91], v[16:17], v[160:161], v[90:91] op_sel_hi:[1,0,1] neg_lo:[1,0,0] neg_hi:[1,0,0]
	ds_read_b128 v[158:161], v20 offset:51488
	s_waitcnt lgkmcnt(11)
	v_pk_fma_f32 v[146:147], v[12:13], v[166:167], v[146:147] op_sel:[0,1,0] neg_lo:[1,0,0] neg_hi:[1,0,0]
	v_pk_fma_f32 v[90:91], v[18:19], v[166:167], v[90:91] op_sel_hi:[1,0,1] neg_lo:[1,0,0] neg_hi:[1,0,0]
	v_pk_fma_f32 v[146:147], v[4:5], v[168:169], v[146:147] op_sel:[0,1,0] neg_lo:[1,0,0] neg_hi:[1,0,0]
	v_pk_fma_f32 v[90:91], v[8:9], v[168:169], v[90:91] op_sel_hi:[1,0,1] neg_lo:[1,0,0] neg_hi:[1,0,0]
	ds_read_b128 v[166:169], v20 offset:51504
	s_waitcnt lgkmcnt(11)
	v_pk_fma_f32 v[146:147], v[0:1], v[170:171], v[146:147] op_sel:[0,1,0] neg_lo:[1,0,0] neg_hi:[1,0,0]
	v_pk_fma_f32 v[90:91], v[2:3], v[170:171], v[90:91] op_sel_hi:[1,0,1] neg_lo:[1,0,0] neg_hi:[1,0,0]
	v_pk_fma_f32 v[146:147], v[28:29], v[172:173], v[146:147] op_sel:[0,1,0] neg_lo:[1,0,0] neg_hi:[1,0,0]
	v_pk_fma_f32 v[90:91], v[30:31], v[172:173], v[90:91] op_sel_hi:[1,0,1] neg_lo:[1,0,0] neg_hi:[1,0,0]
	ds_read_b128 v[170:173], v20 offset:51520
	s_waitcnt lgkmcnt(11)
	v_pk_fma_f32 v[146:147], v[34:35], v[174:175], v[146:147] op_sel:[0,1,0] neg_lo:[1,0,0] neg_hi:[1,0,0]
	v_pk_fma_f32 v[90:91], v[32:33], v[174:175], v[90:91] op_sel_hi:[1,0,1] neg_lo:[1,0,0] neg_hi:[1,0,0]
	v_pk_fma_f32 v[146:147], v[40:41], v[176:177], v[146:147] op_sel:[0,1,0] neg_lo:[1,0,0] neg_hi:[1,0,0]
	v_pk_fma_f32 v[90:91], v[36:37], v[176:177], v[90:91] op_sel_hi:[1,0,1] neg_lo:[1,0,0] neg_hi:[1,0,0]
	ds_read_b128 v[174:177], v20 offset:51536
	s_waitcnt lgkmcnt(11)
	v_pk_fma_f32 v[146:147], v[42:43], v[178:179], v[146:147] op_sel:[0,1,0] neg_lo:[1,0,0] neg_hi:[1,0,0]
	v_pk_fma_f32 v[90:91], v[38:39], v[178:179], v[90:91] op_sel_hi:[1,0,1] neg_lo:[1,0,0] neg_hi:[1,0,0]
	v_pk_fma_f32 v[146:147], v[46:47], v[180:181], v[146:147] op_sel:[0,1,0] neg_lo:[1,0,0] neg_hi:[1,0,0]
	v_pk_fma_f32 v[90:91], v[44:45], v[180:181], v[90:91] op_sel_hi:[1,0,1] neg_lo:[1,0,0] neg_hi:[1,0,0]
	ds_read_b128 v[178:181], v20 offset:51552
	s_waitcnt lgkmcnt(11)
	v_pk_fma_f32 v[146:147], v[50:51], v[182:183], v[146:147] op_sel:[0,1,0] neg_lo:[1,0,0] neg_hi:[1,0,0]
	v_pk_fma_f32 v[90:91], v[48:49], v[182:183], v[90:91] op_sel_hi:[1,0,1] neg_lo:[1,0,0] neg_hi:[1,0,0]
	v_pk_fma_f32 v[146:147], v[54:55], v[184:185], v[146:147] op_sel:[0,1,0] neg_lo:[1,0,0] neg_hi:[1,0,0]
	v_pk_fma_f32 v[90:91], v[52:53], v[184:185], v[90:91] op_sel_hi:[1,0,1] neg_lo:[1,0,0] neg_hi:[1,0,0]
	ds_read_b128 v[182:185], v20 offset:51568
	s_waitcnt lgkmcnt(11)
	v_pk_fma_f32 v[146:147], v[58:59], v[208:209], v[146:147] op_sel:[0,1,0] neg_lo:[1,0,0] neg_hi:[1,0,0]
	v_pk_fma_f32 v[90:91], v[56:57], v[208:209], v[90:91] op_sel_hi:[1,0,1] neg_lo:[1,0,0] neg_hi:[1,0,0]
	v_pk_fma_f32 v[146:147], v[62:63], v[210:211], v[146:147] op_sel:[0,1,0] neg_lo:[1,0,0] neg_hi:[1,0,0]
	v_pk_fma_f32 v[90:91], v[60:61], v[210:211], v[90:91] op_sel_hi:[1,0,1] neg_lo:[1,0,0] neg_hi:[1,0,0]
	ds_read_b128 v[208:211], v20 offset:51584
	s_waitcnt lgkmcnt(11)
	v_pk_fma_f32 v[146:147], v[66:67], v[212:213], v[146:147] op_sel:[0,1,0] neg_lo:[1,0,0] neg_hi:[1,0,0]
	v_pk_fma_f32 v[90:91], v[64:65], v[212:213], v[90:91] op_sel_hi:[1,0,1] neg_lo:[1,0,0] neg_hi:[1,0,0]
	v_pk_fma_f32 v[146:147], v[70:71], v[214:215], v[146:147] op_sel:[0,1,0] neg_lo:[1,0,0] neg_hi:[1,0,0]
	v_pk_fma_f32 v[90:91], v[68:69], v[214:215], v[90:91] op_sel_hi:[1,0,1] neg_lo:[1,0,0] neg_hi:[1,0,0]
	ds_read_b128 v[212:215], v20 offset:51600
	s_waitcnt lgkmcnt(11)
	v_pk_fma_f32 v[146:147], v[74:75], v[216:217], v[146:147] op_sel:[0,1,0] neg_lo:[1,0,0] neg_hi:[1,0,0]
	v_pk_fma_f32 v[90:91], v[72:73], v[216:217], v[90:91] op_sel_hi:[1,0,1] neg_lo:[1,0,0] neg_hi:[1,0,0]
	v_pk_fma_f32 v[146:147], v[78:79], v[218:219], v[146:147] op_sel:[0,1,0] neg_lo:[1,0,0] neg_hi:[1,0,0]
	v_pk_fma_f32 v[90:91], v[76:77], v[218:219], v[90:91] op_sel_hi:[1,0,1] neg_lo:[1,0,0] neg_hi:[1,0,0]
	ds_read_b128 v[216:219], v20 offset:51616
	s_waitcnt lgkmcnt(11)
	v_pk_fma_f32 v[146:147], v[82:83], v[220:221], v[146:147] op_sel:[0,1,0] neg_lo:[1,0,0] neg_hi:[1,0,0]
	v_pk_fma_f32 v[90:91], v[80:81], v[220:221], v[90:91] op_sel_hi:[1,0,1] neg_lo:[1,0,0] neg_hi:[1,0,0]
	v_pk_fma_f32 v[146:147], v[222:223], v[88:89], v[146:147] op_sel:[1,0,0] neg_lo:[1,0,0] neg_hi:[1,0,0]
	v_pk_fma_f32 v[90:91], v[86:87], v[222:223], v[90:91] op_sel_hi:[1,0,1] neg_lo:[1,0,0] neg_hi:[1,0,0]
	ds_read_b128 v[220:223], v20 offset:51632
	v_pk_add_f32 v[90:91], v[90:91], v[146:147]
	s_waitcnt lgkmcnt(11)
	v_pk_fma_f32 v[112:113], v[138:139], v[150:151], 0 op_sel:[0,1,0] op_sel_hi:[1,1,0] neg_lo:[1,0,0] neg_hi:[1,0,0]
	v_pk_fma_f32 v[252:253], v[128:129], v[150:151], v[92:93] op_sel_hi:[1,0,1] neg_lo:[1,0,0] neg_hi:[1,0,0]
	v_pk_fma_f32 v[112:113], v[134:135], v[152:153], v[112:113] op_sel:[0,1,0] neg_lo:[1,0,0] neg_hi:[1,0,0]
	v_pk_fma_f32 v[252:253], v[136:137], v[152:153], v[252:253] op_sel_hi:[1,0,1] neg_lo:[1,0,0] neg_hi:[1,0,0]
	s_waitcnt lgkmcnt(10)
	v_pk_fma_f32 v[112:113], v[130:131], v[154:155], v[112:113] op_sel:[0,1,0] neg_lo:[1,0,0] neg_hi:[1,0,0]
	ds_read_b128 v[150:153], v20 offset:51712
	v_pk_fma_f32 v[112:113], v[84:85], v[156:157], v[112:113] op_sel:[0,1,0] neg_lo:[1,0,0] neg_hi:[1,0,0]
	v_pk_fma_f32 v[252:253], v[132:133], v[154:155], v[252:253] op_sel_hi:[1,0,1] neg_lo:[1,0,0] neg_hi:[1,0,0]
	s_waitcnt lgkmcnt(10)
	v_pk_fma_f32 v[112:113], v[10:11], v[158:159], v[112:113] op_sel:[0,1,0] neg_lo:[1,0,0] neg_hi:[1,0,0]
	v_pk_fma_f32 v[252:253], v[122:123], v[156:157], v[252:253] op_sel_hi:[1,0,1] neg_lo:[1,0,0] neg_hi:[1,0,0]
	v_pk_fma_f32 v[112:113], v[6:7], v[160:161], v[112:113] op_sel:[0,1,0] neg_lo:[1,0,0] neg_hi:[1,0,0]
	ds_read_b128 v[154:157], v20 offset:51728
	s_waitcnt lgkmcnt(10)
	v_pk_fma_f32 v[112:113], v[12:13], v[166:167], v[112:113] op_sel:[0,1,0] neg_lo:[1,0,0] neg_hi:[1,0,0]
	v_pk_fma_f32 v[252:253], v[14:15], v[158:159], v[252:253] op_sel_hi:[1,0,1] neg_lo:[1,0,0] neg_hi:[1,0,0]
	v_pk_fma_f32 v[112:113], v[4:5], v[168:169], v[112:113] op_sel:[0,1,0] neg_lo:[1,0,0] neg_hi:[1,0,0]
	v_pk_fma_f32 v[252:253], v[16:17], v[160:161], v[252:253] op_sel_hi:[1,0,1] neg_lo:[1,0,0] neg_hi:[1,0,0]
	s_waitcnt lgkmcnt(9)
	v_pk_fma_f32 v[112:113], v[0:1], v[170:171], v[112:113] op_sel:[0,1,0] neg_lo:[1,0,0] neg_hi:[1,0,0]
	ds_read_b128 v[158:161], v20 offset:51744
	v_pk_fma_f32 v[112:113], v[28:29], v[172:173], v[112:113] op_sel:[0,1,0] neg_lo:[1,0,0] neg_hi:[1,0,0]
	v_pk_fma_f32 v[252:253], v[18:19], v[166:167], v[252:253] op_sel_hi:[1,0,1] neg_lo:[1,0,0] neg_hi:[1,0,0]
	s_waitcnt lgkmcnt(9)
	v_pk_fma_f32 v[112:113], v[34:35], v[174:175], v[112:113] op_sel:[0,1,0] neg_lo:[1,0,0] neg_hi:[1,0,0]
	v_pk_fma_f32 v[252:253], v[8:9], v[168:169], v[252:253] op_sel_hi:[1,0,1] neg_lo:[1,0,0] neg_hi:[1,0,0]
	v_pk_fma_f32 v[112:113], v[40:41], v[176:177], v[112:113] op_sel:[0,1,0] neg_lo:[1,0,0] neg_hi:[1,0,0]
	ds_read_b128 v[166:169], v20 offset:51760
	s_waitcnt lgkmcnt(9)
	v_pk_fma_f32 v[112:113], v[42:43], v[178:179], v[112:113] op_sel:[0,1,0] neg_lo:[1,0,0] neg_hi:[1,0,0]
	v_pk_fma_f32 v[252:253], v[2:3], v[170:171], v[252:253] op_sel_hi:[1,0,1] neg_lo:[1,0,0] neg_hi:[1,0,0]
	v_pk_fma_f32 v[112:113], v[46:47], v[180:181], v[112:113] op_sel:[0,1,0] neg_lo:[1,0,0] neg_hi:[1,0,0]
	v_pk_fma_f32 v[252:253], v[30:31], v[172:173], v[252:253] op_sel_hi:[1,0,1] neg_lo:[1,0,0] neg_hi:[1,0,0]
	s_waitcnt lgkmcnt(8)
	v_pk_fma_f32 v[112:113], v[50:51], v[182:183], v[112:113] op_sel:[0,1,0] neg_lo:[1,0,0] neg_hi:[1,0,0]
	ds_read_b128 v[170:173], v20 offset:51776
	v_pk_fma_f32 v[112:113], v[54:55], v[184:185], v[112:113] op_sel:[0,1,0] neg_lo:[1,0,0] neg_hi:[1,0,0]
	v_pk_fma_f32 v[252:253], v[32:33], v[174:175], v[252:253] op_sel_hi:[1,0,1] neg_lo:[1,0,0] neg_hi:[1,0,0]
	s_waitcnt lgkmcnt(8)
	v_pk_fma_f32 v[112:113], v[58:59], v[208:209], v[112:113] op_sel:[0,1,0] neg_lo:[1,0,0] neg_hi:[1,0,0]
	v_pk_fma_f32 v[252:253], v[36:37], v[176:177], v[252:253] op_sel_hi:[1,0,1] neg_lo:[1,0,0] neg_hi:[1,0,0]
	ds_read_b128 v[174:177], v20 offset:51792
	v_pk_fma_f32 v[112:113], v[62:63], v[210:211], v[112:113] op_sel:[0,1,0] neg_lo:[1,0,0] neg_hi:[1,0,0]
	v_pk_fma_f32 v[252:253], v[38:39], v[178:179], v[252:253] op_sel_hi:[1,0,1] neg_lo:[1,0,0] neg_hi:[1,0,0]
	s_waitcnt lgkmcnt(8)
	v_pk_fma_f32 v[112:113], v[66:67], v[212:213], v[112:113] op_sel:[0,1,0] neg_lo:[1,0,0] neg_hi:[1,0,0]
	v_pk_fma_f32 v[252:253], v[44:45], v[180:181], v[252:253] op_sel_hi:[1,0,1] neg_lo:[1,0,0] neg_hi:[1,0,0]
	ds_read_b128 v[178:181], v20 offset:51808
	v_pk_fma_f32 v[112:113], v[70:71], v[214:215], v[112:113] op_sel:[0,1,0] neg_lo:[1,0,0] neg_hi:[1,0,0]
	v_pk_fma_f32 v[252:253], v[48:49], v[182:183], v[252:253] op_sel_hi:[1,0,1] neg_lo:[1,0,0] neg_hi:[1,0,0]
	s_waitcnt lgkmcnt(8)
	v_pk_fma_f32 v[112:113], v[74:75], v[216:217], v[112:113] op_sel:[0,1,0] neg_lo:[1,0,0] neg_hi:[1,0,0]
	v_pk_fma_f32 v[252:253], v[52:53], v[184:185], v[252:253] op_sel_hi:[1,0,1] neg_lo:[1,0,0] neg_hi:[1,0,0]
	ds_read_b128 v[182:185], v20 offset:51824
	v_pk_fma_f32 v[112:113], v[78:79], v[218:219], v[112:113] op_sel:[0,1,0] neg_lo:[1,0,0] neg_hi:[1,0,0]
	v_pk_fma_f32 v[252:253], v[56:57], v[208:209], v[252:253] op_sel_hi:[1,0,1] neg_lo:[1,0,0] neg_hi:[1,0,0]
	s_waitcnt lgkmcnt(8)
	v_pk_fma_f32 v[112:113], v[82:83], v[220:221], v[112:113] op_sel:[0,1,0] neg_lo:[1,0,0] neg_hi:[1,0,0]
	v_pk_fma_f32 v[252:253], v[60:61], v[210:211], v[252:253] op_sel_hi:[1,0,1] neg_lo:[1,0,0] neg_hi:[1,0,0]
	ds_read_b128 v[208:211], v20 offset:51840
	v_pk_fma_f32 v[112:113], v[88:89], v[222:223], v[112:113] op_sel:[0,1,0] neg_lo:[1,0,0] neg_hi:[1,0,0]
	v_pk_fma_f32 v[252:253], v[64:65], v[212:213], v[252:253] op_sel_hi:[1,0,1] neg_lo:[1,0,0] neg_hi:[1,0,0]
	v_pk_fma_f32 v[112:113], v[92:93], v[224:225], v[112:113] op_sel:[0,1,0] neg_lo:[1,0,0] neg_hi:[1,0,0]
	v_pk_fma_f32 v[252:253], v[68:69], v[214:215], v[252:253] op_sel_hi:[1,0,1] neg_lo:[1,0,0] neg_hi:[1,0,0]
	ds_read_b128 v[212:215], v20 offset:51856
	v_pk_fma_f32 v[112:113], v[96:97], v[226:227], v[112:113] op_sel:[0,1,0] neg_lo:[1,0,0] neg_hi:[1,0,0]
	v_pk_fma_f32 v[252:253], v[72:73], v[216:217], v[252:253] op_sel_hi:[1,0,1] neg_lo:[1,0,0] neg_hi:[1,0,0]
	s_waitcnt lgkmcnt(9)
	v_pk_fma_f32 v[146:147], v[128:129], v[150:151], v[94:95] op_sel_hi:[1,0,1] neg_lo:[1,0,0] neg_hi:[1,0,0]
	v_pk_fma_f32 v[252:253], v[76:77], v[218:219], v[252:253] op_sel_hi:[1,0,1] neg_lo:[1,0,0] neg_hi:[1,0,0]
	ds_read_b128 v[216:219], v20 offset:51872
	v_pk_fma_f32 v[252:253], v[80:81], v[220:221], v[252:253] op_sel_hi:[1,0,1] neg_lo:[1,0,0] neg_hi:[1,0,0]
	v_pk_fma_f32 v[146:147], v[136:137], v[152:153], v[146:147] op_sel_hi:[1,0,1] neg_lo:[1,0,0] neg_hi:[1,0,0]
	v_pk_fma_f32 v[252:253], v[86:87], v[222:223], v[252:253] op_sel_hi:[1,0,1] neg_lo:[1,0,0] neg_hi:[1,0,0]
	ds_read_b128 v[220:223], v20 offset:51888
	v_pk_fma_f32 v[252:253], v[224:225], v[90:91], v[252:253] op_sel_hi:[0,1,1] neg_lo:[1,0,0] neg_hi:[1,0,0]
	s_waitcnt lgkmcnt(10)
	v_pk_fma_f32 v[146:147], v[132:133], v[154:155], v[146:147] op_sel_hi:[1,0,1] neg_lo:[1,0,0] neg_hi:[1,0,0]
	v_pk_fma_f32 v[252:253], v[94:95], v[226:227], v[252:253] op_sel_hi:[1,0,1] neg_lo:[1,0,0] neg_hi:[1,0,0]
	ds_read_b128 v[224:227], v20 offset:51904
	v_pk_add_f32 v[92:93], v[252:253], v[112:113]
	v_pk_fma_f32 v[112:113], v[138:139], v[150:151], 0 op_sel:[0,1,0] op_sel_hi:[1,1,0] neg_lo:[1,0,0] neg_hi:[1,0,0]
	v_pk_fma_f32 v[146:147], v[122:123], v[156:157], v[146:147] op_sel_hi:[1,0,1] neg_lo:[1,0,0] neg_hi:[1,0,0]
	v_pk_fma_f32 v[112:113], v[134:135], v[152:153], v[112:113] op_sel:[0,1,0] neg_lo:[1,0,0] neg_hi:[1,0,0]
	ds_read_b128 v[150:153], v20 offset:51968
	v_pk_fma_f32 v[112:113], v[130:131], v[154:155], v[112:113] op_sel:[0,1,0] neg_lo:[1,0,0] neg_hi:[1,0,0]
	s_waitcnt lgkmcnt(11)
	v_pk_fma_f32 v[146:147], v[14:15], v[158:159], v[146:147] op_sel_hi:[1,0,1] neg_lo:[1,0,0] neg_hi:[1,0,0]
	v_pk_fma_f32 v[112:113], v[84:85], v[156:157], v[112:113] op_sel:[0,1,0] neg_lo:[1,0,0] neg_hi:[1,0,0]
	ds_read_b128 v[154:157], v20 offset:51984
	v_pk_fma_f32 v[112:113], v[10:11], v[158:159], v[112:113] op_sel:[0,1,0] neg_lo:[1,0,0] neg_hi:[1,0,0]
	v_pk_fma_f32 v[146:147], v[16:17], v[160:161], v[146:147] op_sel_hi:[1,0,1] neg_lo:[1,0,0] neg_hi:[1,0,0]
	v_pk_fma_f32 v[112:113], v[6:7], v[160:161], v[112:113] op_sel:[0,1,0] neg_lo:[1,0,0] neg_hi:[1,0,0]
	ds_read_b128 v[158:161], v20 offset:52000
	s_waitcnt lgkmcnt(12)
	v_pk_fma_f32 v[112:113], v[12:13], v[166:167], v[112:113] op_sel:[0,1,0] neg_lo:[1,0,0] neg_hi:[1,0,0]
	v_pk_fma_f32 v[146:147], v[18:19], v[166:167], v[146:147] op_sel_hi:[1,0,1] neg_lo:[1,0,0] neg_hi:[1,0,0]
	v_pk_fma_f32 v[112:113], v[4:5], v[168:169], v[112:113] op_sel:[0,1,0] neg_lo:[1,0,0] neg_hi:[1,0,0]
	v_pk_fma_f32 v[146:147], v[8:9], v[168:169], v[146:147] op_sel_hi:[1,0,1] neg_lo:[1,0,0] neg_hi:[1,0,0]
	s_waitcnt lgkmcnt(11)
	v_pk_fma_f32 v[112:113], v[0:1], v[170:171], v[112:113] op_sel:[0,1,0] neg_lo:[1,0,0] neg_hi:[1,0,0]
	ds_read_b128 v[166:169], v20 offset:52016
	v_pk_fma_f32 v[112:113], v[28:29], v[172:173], v[112:113] op_sel:[0,1,0] neg_lo:[1,0,0] neg_hi:[1,0,0]
	v_pk_fma_f32 v[146:147], v[2:3], v[170:171], v[146:147] op_sel_hi:[1,0,1] neg_lo:[1,0,0] neg_hi:[1,0,0]
	s_waitcnt lgkmcnt(11)
	v_pk_fma_f32 v[112:113], v[34:35], v[174:175], v[112:113] op_sel:[0,1,0] neg_lo:[1,0,0] neg_hi:[1,0,0]
	v_pk_fma_f32 v[146:147], v[30:31], v[172:173], v[146:147] op_sel_hi:[1,0,1] neg_lo:[1,0,0] neg_hi:[1,0,0]
	v_pk_fma_f32 v[112:113], v[40:41], v[176:177], v[112:113] op_sel:[0,1,0] neg_lo:[1,0,0] neg_hi:[1,0,0]
	ds_read_b128 v[170:173], v20 offset:52032
	s_waitcnt lgkmcnt(11)
	v_pk_fma_f32 v[112:113], v[42:43], v[178:179], v[112:113] op_sel:[0,1,0] neg_lo:[1,0,0] neg_hi:[1,0,0]
	v_pk_fma_f32 v[146:147], v[32:33], v[174:175], v[146:147] op_sel_hi:[1,0,1] neg_lo:[1,0,0] neg_hi:[1,0,0]
	v_pk_fma_f32 v[112:113], v[46:47], v[180:181], v[112:113] op_sel:[0,1,0] neg_lo:[1,0,0] neg_hi:[1,0,0]
	v_pk_fma_f32 v[146:147], v[36:37], v[176:177], v[146:147] op_sel_hi:[1,0,1] neg_lo:[1,0,0] neg_hi:[1,0,0]
	s_waitcnt lgkmcnt(10)
	v_pk_fma_f32 v[112:113], v[50:51], v[182:183], v[112:113] op_sel:[0,1,0] neg_lo:[1,0,0] neg_hi:[1,0,0]
	ds_read_b128 v[174:177], v20 offset:52048
	v_pk_fma_f32 v[112:113], v[54:55], v[184:185], v[112:113] op_sel:[0,1,0] neg_lo:[1,0,0] neg_hi:[1,0,0]
	v_pk_fma_f32 v[146:147], v[38:39], v[178:179], v[146:147] op_sel_hi:[1,0,1] neg_lo:[1,0,0] neg_hi:[1,0,0]
	s_waitcnt lgkmcnt(10)
	v_pk_fma_f32 v[112:113], v[58:59], v[208:209], v[112:113] op_sel:[0,1,0] neg_lo:[1,0,0] neg_hi:[1,0,0]
	v_pk_fma_f32 v[146:147], v[44:45], v[180:181], v[146:147] op_sel_hi:[1,0,1] neg_lo:[1,0,0] neg_hi:[1,0,0]
	ds_read_b128 v[178:181], v20 offset:52064
	v_pk_fma_f32 v[112:113], v[62:63], v[210:211], v[112:113] op_sel:[0,1,0] neg_lo:[1,0,0] neg_hi:[1,0,0]
	v_pk_fma_f32 v[146:147], v[48:49], v[182:183], v[146:147] op_sel_hi:[1,0,1] neg_lo:[1,0,0] neg_hi:[1,0,0]
	s_waitcnt lgkmcnt(10)
	v_pk_fma_f32 v[112:113], v[66:67], v[212:213], v[112:113] op_sel:[0,1,0] neg_lo:[1,0,0] neg_hi:[1,0,0]
	v_pk_fma_f32 v[146:147], v[52:53], v[184:185], v[146:147] op_sel_hi:[1,0,1] neg_lo:[1,0,0] neg_hi:[1,0,0]
	ds_read_b128 v[182:185], v20 offset:52080
	v_pk_fma_f32 v[112:113], v[70:71], v[214:215], v[112:113] op_sel:[0,1,0] neg_lo:[1,0,0] neg_hi:[1,0,0]
	v_pk_fma_f32 v[146:147], v[56:57], v[208:209], v[146:147] op_sel_hi:[1,0,1] neg_lo:[1,0,0] neg_hi:[1,0,0]
	s_waitcnt lgkmcnt(10)
	v_pk_fma_f32 v[112:113], v[74:75], v[216:217], v[112:113] op_sel:[0,1,0] neg_lo:[1,0,0] neg_hi:[1,0,0]
	v_pk_fma_f32 v[146:147], v[60:61], v[210:211], v[146:147] op_sel_hi:[1,0,1] neg_lo:[1,0,0] neg_hi:[1,0,0]
	ds_read_b128 v[208:211], v20 offset:52096
	v_pk_fma_f32 v[112:113], v[78:79], v[218:219], v[112:113] op_sel:[0,1,0] neg_lo:[1,0,0] neg_hi:[1,0,0]
	v_pk_fma_f32 v[146:147], v[64:65], v[212:213], v[146:147] op_sel_hi:[1,0,1] neg_lo:[1,0,0] neg_hi:[1,0,0]
	s_waitcnt lgkmcnt(10)
	v_pk_fma_f32 v[112:113], v[82:83], v[220:221], v[112:113] op_sel:[0,1,0] neg_lo:[1,0,0] neg_hi:[1,0,0]
	v_pk_fma_f32 v[146:147], v[68:69], v[214:215], v[146:147] op_sel_hi:[1,0,1] neg_lo:[1,0,0] neg_hi:[1,0,0]
	ds_read_b128 v[212:215], v20 offset:52112
	v_pk_fma_f32 v[112:113], v[88:89], v[222:223], v[112:113] op_sel:[0,1,0] neg_lo:[1,0,0] neg_hi:[1,0,0]
	v_pk_fma_f32 v[146:147], v[72:73], v[216:217], v[146:147] op_sel_hi:[1,0,1] neg_lo:[1,0,0] neg_hi:[1,0,0]
	s_waitcnt lgkmcnt(10)
	v_pk_fma_f32 v[112:113], v[224:225], v[92:93], v[112:113] op_sel:[1,0,0] neg_lo:[1,0,0] neg_hi:[1,0,0]
	v_pk_fma_f32 v[146:147], v[76:77], v[218:219], v[146:147] op_sel_hi:[1,0,1] neg_lo:[1,0,0] neg_hi:[1,0,0]
	ds_read_b128 v[216:219], v20 offset:52128
	v_pk_fma_f32 v[112:113], v[96:97], v[226:227], v[112:113] op_sel:[0,1,0] neg_lo:[1,0,0] neg_hi:[1,0,0]
	v_pk_fma_f32 v[146:147], v[80:81], v[220:221], v[146:147] op_sel_hi:[1,0,1] neg_lo:[1,0,0] neg_hi:[1,0,0]
	s_waitcnt lgkmcnt(10)
	v_pk_fma_f32 v[252:253], v[128:129], v[150:151], v[96:97] op_sel_hi:[1,0,1] neg_lo:[1,0,0] neg_hi:[1,0,0]
	v_pk_fma_f32 v[146:147], v[86:87], v[222:223], v[146:147] op_sel_hi:[1,0,1] neg_lo:[1,0,0] neg_hi:[1,0,0]
	ds_read_b128 v[220:223], v20 offset:52144
	v_pk_fma_f32 v[146:147], v[90:91], v[224:225], v[146:147] op_sel_hi:[1,0,1] neg_lo:[1,0,0] neg_hi:[1,0,0]
	v_pk_fma_f32 v[252:253], v[136:137], v[152:153], v[252:253] op_sel_hi:[1,0,1] neg_lo:[1,0,0] neg_hi:[1,0,0]
	v_pk_fma_f32 v[94:95], v[94:95], v[226:227], v[146:147] op_sel_hi:[1,0,1] neg_lo:[1,0,0] neg_hi:[1,0,0]
	ds_read_b128 v[224:227], v20 offset:52160
	v_pk_add_f32 v[94:95], v[94:95], v[112:113]
	v_pk_fma_f32 v[112:113], v[138:139], v[150:151], 0 op_sel:[0,1,0] op_sel_hi:[1,1,0] neg_lo:[1,0,0] neg_hi:[1,0,0]
	s_waitcnt lgkmcnt(11)
	v_pk_fma_f32 v[252:253], v[132:133], v[154:155], v[252:253] op_sel_hi:[1,0,1] neg_lo:[1,0,0] neg_hi:[1,0,0]
	v_pk_fma_f32 v[112:113], v[134:135], v[152:153], v[112:113] op_sel:[0,1,0] neg_lo:[1,0,0] neg_hi:[1,0,0]
	ds_read_b128 v[150:153], v20 offset:52224
	v_pk_fma_f32 v[112:113], v[130:131], v[154:155], v[112:113] op_sel:[0,1,0] neg_lo:[1,0,0] neg_hi:[1,0,0]
	v_pk_fma_f32 v[252:253], v[122:123], v[156:157], v[252:253] op_sel_hi:[1,0,1] neg_lo:[1,0,0] neg_hi:[1,0,0]
	v_pk_fma_f32 v[112:113], v[84:85], v[156:157], v[112:113] op_sel:[0,1,0] neg_lo:[1,0,0] neg_hi:[1,0,0]
	ds_read_b128 v[154:157], v20 offset:52240
	s_waitcnt lgkmcnt(12)
	v_pk_fma_f32 v[112:113], v[10:11], v[158:159], v[112:113] op_sel:[0,1,0] neg_lo:[1,0,0] neg_hi:[1,0,0]
	v_pk_fma_f32 v[252:253], v[14:15], v[158:159], v[252:253] op_sel_hi:[1,0,1] neg_lo:[1,0,0] neg_hi:[1,0,0]
	v_pk_fma_f32 v[112:113], v[6:7], v[160:161], v[112:113] op_sel:[0,1,0] neg_lo:[1,0,0] neg_hi:[1,0,0]
	v_pk_fma_f32 v[252:253], v[16:17], v[160:161], v[252:253] op_sel_hi:[1,0,1] neg_lo:[1,0,0] neg_hi:[1,0,0]
	s_waitcnt lgkmcnt(11)
	v_pk_fma_f32 v[112:113], v[12:13], v[166:167], v[112:113] op_sel:[0,1,0] neg_lo:[1,0,0] neg_hi:[1,0,0]
	ds_read_b128 v[158:161], v20 offset:52256
	v_pk_fma_f32 v[112:113], v[4:5], v[168:169], v[112:113] op_sel:[0,1,0] neg_lo:[1,0,0] neg_hi:[1,0,0]
	v_pk_fma_f32 v[252:253], v[18:19], v[166:167], v[252:253] op_sel_hi:[1,0,1] neg_lo:[1,0,0] neg_hi:[1,0,0]
	s_waitcnt lgkmcnt(11)
	v_pk_fma_f32 v[112:113], v[0:1], v[170:171], v[112:113] op_sel:[0,1,0] neg_lo:[1,0,0] neg_hi:[1,0,0]
	v_pk_fma_f32 v[252:253], v[8:9], v[168:169], v[252:253] op_sel_hi:[1,0,1] neg_lo:[1,0,0] neg_hi:[1,0,0]
	v_pk_fma_f32 v[112:113], v[28:29], v[172:173], v[112:113] op_sel:[0,1,0] neg_lo:[1,0,0] neg_hi:[1,0,0]
	ds_read_b128 v[166:169], v20 offset:52272
	s_waitcnt lgkmcnt(11)
	v_pk_fma_f32 v[112:113], v[34:35], v[174:175], v[112:113] op_sel:[0,1,0] neg_lo:[1,0,0] neg_hi:[1,0,0]
	v_pk_fma_f32 v[252:253], v[2:3], v[170:171], v[252:253] op_sel_hi:[1,0,1] neg_lo:[1,0,0] neg_hi:[1,0,0]
	v_pk_fma_f32 v[112:113], v[40:41], v[176:177], v[112:113] op_sel:[0,1,0] neg_lo:[1,0,0] neg_hi:[1,0,0]
	v_pk_fma_f32 v[252:253], v[30:31], v[172:173], v[252:253] op_sel_hi:[1,0,1] neg_lo:[1,0,0] neg_hi:[1,0,0]
	s_waitcnt lgkmcnt(10)
	v_pk_fma_f32 v[112:113], v[42:43], v[178:179], v[112:113] op_sel:[0,1,0] neg_lo:[1,0,0] neg_hi:[1,0,0]
	ds_read_b128 v[170:173], v20 offset:52288
	v_pk_fma_f32 v[112:113], v[46:47], v[180:181], v[112:113] op_sel:[0,1,0] neg_lo:[1,0,0] neg_hi:[1,0,0]
	v_pk_fma_f32 v[252:253], v[32:33], v[174:175], v[252:253] op_sel_hi:[1,0,1] neg_lo:[1,0,0] neg_hi:[1,0,0]
	s_waitcnt lgkmcnt(10)
	v_pk_fma_f32 v[112:113], v[50:51], v[182:183], v[112:113] op_sel:[0,1,0] neg_lo:[1,0,0] neg_hi:[1,0,0]
	v_pk_fma_f32 v[252:253], v[36:37], v[176:177], v[252:253] op_sel_hi:[1,0,1] neg_lo:[1,0,0] neg_hi:[1,0,0]
	v_pk_fma_f32 v[112:113], v[54:55], v[184:185], v[112:113] op_sel:[0,1,0] neg_lo:[1,0,0] neg_hi:[1,0,0]
	ds_read_b128 v[174:177], v20 offset:52304
	s_waitcnt lgkmcnt(10)
	v_pk_fma_f32 v[112:113], v[58:59], v[208:209], v[112:113] op_sel:[0,1,0] neg_lo:[1,0,0] neg_hi:[1,0,0]
	v_pk_fma_f32 v[252:253], v[38:39], v[178:179], v[252:253] op_sel_hi:[1,0,1] neg_lo:[1,0,0] neg_hi:[1,0,0]
	v_pk_fma_f32 v[112:113], v[62:63], v[210:211], v[112:113] op_sel:[0,1,0] neg_lo:[1,0,0] neg_hi:[1,0,0]
	v_pk_fma_f32 v[252:253], v[44:45], v[180:181], v[252:253] op_sel_hi:[1,0,1] neg_lo:[1,0,0] neg_hi:[1,0,0]
	ds_read_b128 v[178:181], v20 offset:52320
	s_waitcnt lgkmcnt(10)
	v_pk_fma_f32 v[112:113], v[66:67], v[212:213], v[112:113] op_sel:[0,1,0] neg_lo:[1,0,0] neg_hi:[1,0,0]
	v_pk_fma_f32 v[252:253], v[48:49], v[182:183], v[252:253] op_sel_hi:[1,0,1] neg_lo:[1,0,0] neg_hi:[1,0,0]
	v_pk_fma_f32 v[112:113], v[70:71], v[214:215], v[112:113] op_sel:[0,1,0] neg_lo:[1,0,0] neg_hi:[1,0,0]
	v_pk_fma_f32 v[252:253], v[52:53], v[184:185], v[252:253] op_sel_hi:[1,0,1] neg_lo:[1,0,0] neg_hi:[1,0,0]
	ds_read_b128 v[182:185], v20 offset:52336
	s_waitcnt lgkmcnt(10)
	v_pk_fma_f32 v[112:113], v[74:75], v[216:217], v[112:113] op_sel:[0,1,0] neg_lo:[1,0,0] neg_hi:[1,0,0]
	v_pk_fma_f32 v[252:253], v[56:57], v[208:209], v[252:253] op_sel_hi:[1,0,1] neg_lo:[1,0,0] neg_hi:[1,0,0]
	v_pk_fma_f32 v[112:113], v[78:79], v[218:219], v[112:113] op_sel:[0,1,0] neg_lo:[1,0,0] neg_hi:[1,0,0]
	v_pk_fma_f32 v[252:253], v[60:61], v[210:211], v[252:253] op_sel_hi:[1,0,1] neg_lo:[1,0,0] neg_hi:[1,0,0]
	ds_read_b128 v[208:211], v20 offset:52352
	s_waitcnt lgkmcnt(10)
	v_pk_fma_f32 v[112:113], v[82:83], v[220:221], v[112:113] op_sel:[0,1,0] neg_lo:[1,0,0] neg_hi:[1,0,0]
	v_pk_fma_f32 v[252:253], v[64:65], v[212:213], v[252:253] op_sel_hi:[1,0,1] neg_lo:[1,0,0] neg_hi:[1,0,0]
	v_pk_fma_f32 v[112:113], v[88:89], v[222:223], v[112:113] op_sel:[0,1,0] neg_lo:[1,0,0] neg_hi:[1,0,0]
	v_pk_fma_f32 v[252:253], v[68:69], v[214:215], v[252:253] op_sel_hi:[1,0,1] neg_lo:[1,0,0] neg_hi:[1,0,0]
	ds_read_b128 v[212:215], v20 offset:52368
	s_waitcnt lgkmcnt(10)
	v_pk_fma_f32 v[112:113], v[92:93], v[224:225], v[112:113] op_sel:[0,1,0] neg_lo:[1,0,0] neg_hi:[1,0,0]
	v_pk_fma_f32 v[252:253], v[72:73], v[216:217], v[252:253] op_sel_hi:[1,0,1] neg_lo:[1,0,0] neg_hi:[1,0,0]
	v_pk_fma_f32 v[112:113], v[96:97], v[226:227], v[112:113] op_sel:[0,1,0] neg_lo:[1,0,0] neg_hi:[1,0,0]
	v_pk_fma_f32 v[252:253], v[76:77], v[218:219], v[252:253] op_sel_hi:[1,0,1] neg_lo:[1,0,0] neg_hi:[1,0,0]
	ds_read_b128 v[216:219], v20 offset:52384
	v_pk_fma_f32 v[252:253], v[80:81], v[220:221], v[252:253] op_sel_hi:[1,0,1] neg_lo:[1,0,0] neg_hi:[1,0,0]
	s_waitcnt lgkmcnt(10)
	v_pk_mul_f32 v[146:147], v[128:129], v[150:151] op_sel_hi:[1,0]
	v_pk_fma_f32 v[252:253], v[86:87], v[222:223], v[252:253] op_sel_hi:[1,0,1] neg_lo:[1,0,0] neg_hi:[1,0,0]
	ds_read_b128 v[220:223], v20 offset:52400
	v_pk_fma_f32 v[252:253], v[90:91], v[224:225], v[252:253] op_sel_hi:[1,0,1] neg_lo:[1,0,0] neg_hi:[1,0,0]
	v_pk_fma_f32 v[98:99], v[98:99], v[110:111], v[146:147] neg_lo:[0,0,1] neg_hi:[0,0,1]
	v_pk_fma_f32 v[252:253], v[226:227], v[94:95], v[252:253] op_sel_hi:[0,1,1] neg_lo:[1,0,0] neg_hi:[1,0,0]
	ds_read_b128 v[224:227], v20 offset:52416
	v_pk_add_f32 v[96:97], v[252:253], v[112:113]
	v_pk_fma_f32 v[112:113], v[138:139], v[150:151], 0 op_sel:[0,1,0] op_sel_hi:[1,1,0] neg_lo:[1,0,0] neg_hi:[1,0,0]
	v_pk_fma_f32 v[98:99], v[136:137], v[152:153], v[98:99] op_sel_hi:[1,0,1] neg_lo:[1,0,0] neg_hi:[1,0,0]
	v_pk_fma_f32 v[112:113], v[134:135], v[152:153], v[112:113] op_sel:[0,1,0] neg_lo:[1,0,0] neg_hi:[1,0,0]
	ds_read_b128 v[150:153], v20 offset:52496
	s_waitcnt lgkmcnt(12)
	v_pk_fma_f32 v[112:113], v[130:131], v[154:155], v[112:113] op_sel:[0,1,0] neg_lo:[1,0,0] neg_hi:[1,0,0]
	v_pk_fma_f32 v[98:99], v[132:133], v[154:155], v[98:99] op_sel_hi:[1,0,1] neg_lo:[1,0,0] neg_hi:[1,0,0]
	v_pk_fma_f32 v[112:113], v[84:85], v[156:157], v[112:113] op_sel:[0,1,0] neg_lo:[1,0,0] neg_hi:[1,0,0]
	v_pk_fma_f32 v[98:99], v[122:123], v[156:157], v[98:99] op_sel_hi:[1,0,1] neg_lo:[1,0,0] neg_hi:[1,0,0]
	s_waitcnt lgkmcnt(11)
	v_pk_fma_f32 v[112:113], v[10:11], v[158:159], v[112:113] op_sel:[0,1,0] neg_lo:[1,0,0] neg_hi:[1,0,0]
	ds_read_b128 v[154:157], v20 offset:52512
	v_pk_fma_f32 v[112:113], v[6:7], v[160:161], v[112:113] op_sel:[0,1,0] neg_lo:[1,0,0] neg_hi:[1,0,0]
	v_pk_fma_f32 v[98:99], v[14:15], v[158:159], v[98:99] op_sel_hi:[1,0,1] neg_lo:[1,0,0] neg_hi:[1,0,0]
	s_waitcnt lgkmcnt(11)
	v_pk_fma_f32 v[112:113], v[12:13], v[166:167], v[112:113] op_sel:[0,1,0] neg_lo:[1,0,0] neg_hi:[1,0,0]
	v_pk_fma_f32 v[98:99], v[16:17], v[160:161], v[98:99] op_sel_hi:[1,0,1] neg_lo:[1,0,0] neg_hi:[1,0,0]
	v_pk_fma_f32 v[112:113], v[4:5], v[168:169], v[112:113] op_sel:[0,1,0] neg_lo:[1,0,0] neg_hi:[1,0,0]
	ds_read_b128 v[158:161], v20 offset:52528
	s_waitcnt lgkmcnt(11)
	v_pk_fma_f32 v[112:113], v[0:1], v[170:171], v[112:113] op_sel:[0,1,0] neg_lo:[1,0,0] neg_hi:[1,0,0]
	v_pk_fma_f32 v[98:99], v[18:19], v[166:167], v[98:99] op_sel_hi:[1,0,1] neg_lo:[1,0,0] neg_hi:[1,0,0]
	v_pk_fma_f32 v[112:113], v[28:29], v[172:173], v[112:113] op_sel:[0,1,0] neg_lo:[1,0,0] neg_hi:[1,0,0]
	v_pk_fma_f32 v[98:99], v[8:9], v[168:169], v[98:99] op_sel_hi:[1,0,1] neg_lo:[1,0,0] neg_hi:[1,0,0]
	s_waitcnt lgkmcnt(10)
	v_pk_fma_f32 v[112:113], v[34:35], v[174:175], v[112:113] op_sel:[0,1,0] neg_lo:[1,0,0] neg_hi:[1,0,0]
	ds_read_b128 v[166:169], v20 offset:52544
	v_pk_fma_f32 v[112:113], v[40:41], v[176:177], v[112:113] op_sel:[0,1,0] neg_lo:[1,0,0] neg_hi:[1,0,0]
	v_pk_fma_f32 v[98:99], v[2:3], v[170:171], v[98:99] op_sel_hi:[1,0,1] neg_lo:[1,0,0] neg_hi:[1,0,0]
	s_waitcnt lgkmcnt(10)
	v_pk_fma_f32 v[112:113], v[42:43], v[178:179], v[112:113] op_sel:[0,1,0] neg_lo:[1,0,0] neg_hi:[1,0,0]
	v_pk_fma_f32 v[98:99], v[30:31], v[172:173], v[98:99] op_sel_hi:[1,0,1] neg_lo:[1,0,0] neg_hi:[1,0,0]
	v_pk_fma_f32 v[112:113], v[46:47], v[180:181], v[112:113] op_sel:[0,1,0] neg_lo:[1,0,0] neg_hi:[1,0,0]
	ds_read_b128 v[170:173], v20 offset:52560
	s_waitcnt lgkmcnt(10)
	v_pk_fma_f32 v[112:113], v[50:51], v[182:183], v[112:113] op_sel:[0,1,0] neg_lo:[1,0,0] neg_hi:[1,0,0]
	v_pk_fma_f32 v[98:99], v[32:33], v[174:175], v[98:99] op_sel_hi:[1,0,1] neg_lo:[1,0,0] neg_hi:[1,0,0]
	v_pk_fma_f32 v[112:113], v[54:55], v[184:185], v[112:113] op_sel:[0,1,0] neg_lo:[1,0,0] neg_hi:[1,0,0]
	v_pk_fma_f32 v[98:99], v[36:37], v[176:177], v[98:99] op_sel_hi:[1,0,1] neg_lo:[1,0,0] neg_hi:[1,0,0]
	s_waitcnt lgkmcnt(9)
	v_pk_fma_f32 v[112:113], v[58:59], v[208:209], v[112:113] op_sel:[0,1,0] neg_lo:[1,0,0] neg_hi:[1,0,0]
	ds_read_b128 v[174:177], v20 offset:52576
	v_pk_fma_f32 v[112:113], v[62:63], v[210:211], v[112:113] op_sel:[0,1,0] neg_lo:[1,0,0] neg_hi:[1,0,0]
	v_pk_fma_f32 v[98:99], v[38:39], v[178:179], v[98:99] op_sel_hi:[1,0,1] neg_lo:[1,0,0] neg_hi:[1,0,0]
	s_waitcnt lgkmcnt(9)
	v_pk_fma_f32 v[112:113], v[66:67], v[212:213], v[112:113] op_sel:[0,1,0] neg_lo:[1,0,0] neg_hi:[1,0,0]
	v_pk_fma_f32 v[98:99], v[44:45], v[180:181], v[98:99] op_sel_hi:[1,0,1] neg_lo:[1,0,0] neg_hi:[1,0,0]
	ds_read_b128 v[178:181], v20 offset:52592
	v_pk_fma_f32 v[112:113], v[70:71], v[214:215], v[112:113] op_sel:[0,1,0] neg_lo:[1,0,0] neg_hi:[1,0,0]
	v_pk_fma_f32 v[98:99], v[48:49], v[182:183], v[98:99] op_sel_hi:[1,0,1] neg_lo:[1,0,0] neg_hi:[1,0,0]
	s_waitcnt lgkmcnt(9)
	v_pk_fma_f32 v[112:113], v[74:75], v[216:217], v[112:113] op_sel:[0,1,0] neg_lo:[1,0,0] neg_hi:[1,0,0]
	v_pk_fma_f32 v[98:99], v[52:53], v[184:185], v[98:99] op_sel_hi:[1,0,1] neg_lo:[1,0,0] neg_hi:[1,0,0]
	ds_read_b128 v[182:185], v20 offset:52608
	v_pk_fma_f32 v[112:113], v[78:79], v[218:219], v[112:113] op_sel:[0,1,0] neg_lo:[1,0,0] neg_hi:[1,0,0]
	v_pk_fma_f32 v[98:99], v[56:57], v[208:209], v[98:99] op_sel_hi:[1,0,1] neg_lo:[1,0,0] neg_hi:[1,0,0]
	s_waitcnt lgkmcnt(9)
	v_pk_fma_f32 v[112:113], v[82:83], v[220:221], v[112:113] op_sel:[0,1,0] neg_lo:[1,0,0] neg_hi:[1,0,0]
	v_pk_fma_f32 v[98:99], v[60:61], v[210:211], v[98:99] op_sel_hi:[1,0,1] neg_lo:[1,0,0] neg_hi:[1,0,0]
	ds_read_b128 v[208:211], v20 offset:52624
	v_pk_fma_f32 v[112:113], v[88:89], v[222:223], v[112:113] op_sel:[0,1,0] neg_lo:[1,0,0] neg_hi:[1,0,0]
	v_pk_fma_f32 v[98:99], v[64:65], v[212:213], v[98:99] op_sel_hi:[1,0,1] neg_lo:[1,0,0] neg_hi:[1,0,0]
	s_waitcnt lgkmcnt(9)
	v_pk_fma_f32 v[112:113], v[92:93], v[224:225], v[112:113] op_sel:[0,1,0] neg_lo:[1,0,0] neg_hi:[1,0,0]
	v_pk_fma_f32 v[98:99], v[68:69], v[214:215], v[98:99] op_sel_hi:[1,0,1] neg_lo:[1,0,0] neg_hi:[1,0,0]
	ds_read_b128 v[212:215], v20 offset:52640
	v_pk_fma_f32 v[112:113], v[226:227], v[96:97], v[112:113] op_sel:[1,0,0] neg_lo:[1,0,0] neg_hi:[1,0,0]
	v_pk_fma_f32 v[98:99], v[72:73], v[216:217], v[98:99] op_sel_hi:[1,0,1] neg_lo:[1,0,0] neg_hi:[1,0,0]
	s_nop 0
	v_pk_fma_f32 v[98:99], v[76:77], v[218:219], v[98:99] op_sel_hi:[1,0,1] neg_lo:[1,0,0] neg_hi:[1,0,0]
	ds_read_b128 v[216:219], v20 offset:52656
	v_pk_fma_f32 v[98:99], v[80:81], v[220:221], v[98:99] op_sel_hi:[1,0,1] neg_lo:[1,0,0] neg_hi:[1,0,0]
	s_nop 0
	v_pk_fma_f32 v[98:99], v[86:87], v[222:223], v[98:99] op_sel_hi:[1,0,1] neg_lo:[1,0,0] neg_hi:[1,0,0]
	ds_read_b128 v[220:223], v20 offset:52672
	v_pk_fma_f32 v[98:99], v[90:91], v[224:225], v[98:99] op_sel_hi:[1,0,1] neg_lo:[1,0,0] neg_hi:[1,0,0]
	s_nop 0
	v_pk_fma_f32 v[98:99], v[94:95], v[226:227], v[98:99] op_sel_hi:[1,0,1] neg_lo:[1,0,0] neg_hi:[1,0,0]
	ds_read_b128 v[224:227], v20 offset:52688
	v_pk_add_f32 v[98:99], v[98:99], v[112:113]
	ds_read_b128 v[110:113], v20 offset:52480
	s_waitcnt lgkmcnt(0)
	v_pk_fma_f32 v[146:147], v[138:139], v[110:111], 0 op_sel:[0,1,0] op_sel_hi:[1,1,0] neg_lo:[1,0,0] neg_hi:[1,0,0]
	v_pk_fma_f32 v[252:253], v[128:129], v[110:111], v[100:101] op_sel_hi:[1,0,1] neg_lo:[1,0,0] neg_hi:[1,0,0]
	v_pk_fma_f32 v[146:147], v[134:135], v[112:113], v[146:147] op_sel:[0,1,0] neg_lo:[1,0,0] neg_hi:[1,0,0]
	v_pk_fma_f32 v[252:253], v[136:137], v[112:113], v[252:253] op_sel_hi:[1,0,1] neg_lo:[1,0,0] neg_hi:[1,0,0]
	v_pk_fma_f32 v[146:147], v[130:131], v[150:151], v[146:147] op_sel:[0,1,0] neg_lo:[1,0,0] neg_hi:[1,0,0]
	ds_read_b128 v[110:113], v20 offset:52736
	v_pk_fma_f32 v[146:147], v[84:85], v[152:153], v[146:147] op_sel:[0,1,0] neg_lo:[1,0,0] neg_hi:[1,0,0]
	v_pk_fma_f32 v[252:253], v[132:133], v[150:151], v[252:253] op_sel_hi:[1,0,1] neg_lo:[1,0,0] neg_hi:[1,0,0]
	v_pk_fma_f32 v[146:147], v[10:11], v[154:155], v[146:147] op_sel:[0,1,0] neg_lo:[1,0,0] neg_hi:[1,0,0]
	v_pk_fma_f32 v[252:253], v[122:123], v[152:153], v[252:253] op_sel_hi:[1,0,1] neg_lo:[1,0,0] neg_hi:[1,0,0]
	v_pk_fma_f32 v[146:147], v[6:7], v[156:157], v[146:147] op_sel:[0,1,0] neg_lo:[1,0,0] neg_hi:[1,0,0]
	ds_read_b128 v[150:153], v20 offset:52752
	v_pk_fma_f32 v[146:147], v[12:13], v[158:159], v[146:147] op_sel:[0,1,0] neg_lo:[1,0,0] neg_hi:[1,0,0]
	v_pk_fma_f32 v[252:253], v[14:15], v[154:155], v[252:253] op_sel_hi:[1,0,1] neg_lo:[1,0,0] neg_hi:[1,0,0]
	v_pk_fma_f32 v[146:147], v[4:5], v[160:161], v[146:147] op_sel:[0,1,0] neg_lo:[1,0,0] neg_hi:[1,0,0]
	v_pk_fma_f32 v[252:253], v[16:17], v[156:157], v[252:253] op_sel_hi:[1,0,1] neg_lo:[1,0,0] neg_hi:[1,0,0]
	v_pk_fma_f32 v[146:147], v[0:1], v[166:167], v[146:147] op_sel:[0,1,0] neg_lo:[1,0,0] neg_hi:[1,0,0]
	ds_read_b128 v[154:157], v20 offset:52768
	v_pk_fma_f32 v[146:147], v[28:29], v[168:169], v[146:147] op_sel:[0,1,0] neg_lo:[1,0,0] neg_hi:[1,0,0]
	v_pk_fma_f32 v[252:253], v[18:19], v[158:159], v[252:253] op_sel_hi:[1,0,1] neg_lo:[1,0,0] neg_hi:[1,0,0]
	v_pk_fma_f32 v[146:147], v[34:35], v[170:171], v[146:147] op_sel:[0,1,0] neg_lo:[1,0,0] neg_hi:[1,0,0]
	v_pk_fma_f32 v[252:253], v[8:9], v[160:161], v[252:253] op_sel_hi:[1,0,1] neg_lo:[1,0,0] neg_hi:[1,0,0]
	v_pk_fma_f32 v[146:147], v[40:41], v[172:173], v[146:147] op_sel:[0,1,0] neg_lo:[1,0,0] neg_hi:[1,0,0]
	ds_read_b128 v[158:161], v20 offset:52784
	v_pk_fma_f32 v[146:147], v[42:43], v[174:175], v[146:147] op_sel:[0,1,0] neg_lo:[1,0,0] neg_hi:[1,0,0]
	v_pk_fma_f32 v[252:253], v[2:3], v[166:167], v[252:253] op_sel_hi:[1,0,1] neg_lo:[1,0,0] neg_hi:[1,0,0]
	v_pk_fma_f32 v[146:147], v[46:47], v[176:177], v[146:147] op_sel:[0,1,0] neg_lo:[1,0,0] neg_hi:[1,0,0]
	v_pk_fma_f32 v[252:253], v[30:31], v[168:169], v[252:253] op_sel_hi:[1,0,1] neg_lo:[1,0,0] neg_hi:[1,0,0]
	v_pk_fma_f32 v[146:147], v[50:51], v[178:179], v[146:147] op_sel:[0,1,0] neg_lo:[1,0,0] neg_hi:[1,0,0]
	ds_read_b128 v[166:169], v20 offset:52800
	v_pk_fma_f32 v[146:147], v[54:55], v[180:181], v[146:147] op_sel:[0,1,0] neg_lo:[1,0,0] neg_hi:[1,0,0]
	v_pk_fma_f32 v[252:253], v[32:33], v[170:171], v[252:253] op_sel_hi:[1,0,1] neg_lo:[1,0,0] neg_hi:[1,0,0]
	v_pk_fma_f32 v[146:147], v[58:59], v[182:183], v[146:147] op_sel:[0,1,0] neg_lo:[1,0,0] neg_hi:[1,0,0]
	v_pk_fma_f32 v[252:253], v[36:37], v[172:173], v[252:253] op_sel_hi:[1,0,1] neg_lo:[1,0,0] neg_hi:[1,0,0]
	v_pk_fma_f32 v[146:147], v[62:63], v[184:185], v[146:147] op_sel:[0,1,0] neg_lo:[1,0,0] neg_hi:[1,0,0]
	ds_read_b128 v[170:173], v20 offset:52816
	v_pk_fma_f32 v[146:147], v[66:67], v[208:209], v[146:147] op_sel:[0,1,0] neg_lo:[1,0,0] neg_hi:[1,0,0]
	v_pk_fma_f32 v[252:253], v[38:39], v[174:175], v[252:253] op_sel_hi:[1,0,1] neg_lo:[1,0,0] neg_hi:[1,0,0]
	v_pk_fma_f32 v[146:147], v[70:71], v[210:211], v[146:147] op_sel:[0,1,0] neg_lo:[1,0,0] neg_hi:[1,0,0]
	v_pk_fma_f32 v[252:253], v[44:45], v[176:177], v[252:253] op_sel_hi:[1,0,1] neg_lo:[1,0,0] neg_hi:[1,0,0]
	ds_read_b128 v[174:177], v20 offset:52832
	v_pk_fma_f32 v[146:147], v[74:75], v[212:213], v[146:147] op_sel:[0,1,0] neg_lo:[1,0,0] neg_hi:[1,0,0]
	v_pk_fma_f32 v[252:253], v[48:49], v[178:179], v[252:253] op_sel_hi:[1,0,1] neg_lo:[1,0,0] neg_hi:[1,0,0]
	v_pk_fma_f32 v[146:147], v[78:79], v[214:215], v[146:147] op_sel:[0,1,0] neg_lo:[1,0,0] neg_hi:[1,0,0]
	v_pk_fma_f32 v[252:253], v[52:53], v[180:181], v[252:253] op_sel_hi:[1,0,1] neg_lo:[1,0,0] neg_hi:[1,0,0]
	ds_read_b128 v[178:181], v20 offset:52848
	v_pk_fma_f32 v[146:147], v[82:83], v[216:217], v[146:147] op_sel:[0,1,0] neg_lo:[1,0,0] neg_hi:[1,0,0]
	v_pk_fma_f32 v[252:253], v[56:57], v[182:183], v[252:253] op_sel_hi:[1,0,1] neg_lo:[1,0,0] neg_hi:[1,0,0]
	v_pk_fma_f32 v[146:147], v[88:89], v[218:219], v[146:147] op_sel:[0,1,0] neg_lo:[1,0,0] neg_hi:[1,0,0]
	v_pk_fma_f32 v[252:253], v[60:61], v[184:185], v[252:253] op_sel_hi:[1,0,1] neg_lo:[1,0,0] neg_hi:[1,0,0]
	ds_read_b128 v[182:185], v20 offset:52864
	v_pk_fma_f32 v[146:147], v[92:93], v[220:221], v[146:147] op_sel:[0,1,0] neg_lo:[1,0,0] neg_hi:[1,0,0]
	v_pk_fma_f32 v[252:253], v[64:65], v[208:209], v[252:253] op_sel_hi:[1,0,1] neg_lo:[1,0,0] neg_hi:[1,0,0]
	v_pk_fma_f32 v[146:147], v[96:97], v[222:223], v[146:147] op_sel:[0,1,0] neg_lo:[1,0,0] neg_hi:[1,0,0]
	v_pk_fma_f32 v[252:253], v[68:69], v[210:211], v[252:253] op_sel_hi:[1,0,1] neg_lo:[1,0,0] neg_hi:[1,0,0]
	ds_read_b128 v[208:211], v20 offset:52880
	v_pk_fma_f32 v[146:147], v[100:101], v[224:225], v[146:147] op_sel:[0,1,0] neg_lo:[1,0,0] neg_hi:[1,0,0]
	v_pk_fma_f32 v[252:253], v[72:73], v[212:213], v[252:253] op_sel_hi:[1,0,1] neg_lo:[1,0,0] neg_hi:[1,0,0]
	v_pk_fma_f32 v[146:147], v[104:105], v[226:227], v[146:147] op_sel:[0,1,0] neg_lo:[1,0,0] neg_hi:[1,0,0]
	v_pk_fma_f32 v[252:253], v[76:77], v[214:215], v[252:253] op_sel_hi:[1,0,1] neg_lo:[1,0,0] neg_hi:[1,0,0]
	ds_read_b128 v[212:215], v20 offset:52896
	v_pk_fma_f32 v[252:253], v[80:81], v[216:217], v[252:253] op_sel_hi:[1,0,1] neg_lo:[1,0,0] neg_hi:[1,0,0]
	s_nop 0
	v_pk_fma_f32 v[252:253], v[86:87], v[218:219], v[252:253] op_sel_hi:[1,0,1] neg_lo:[1,0,0] neg_hi:[1,0,0]
	ds_read_b128 v[216:219], v20 offset:52912
	v_pk_fma_f32 v[252:253], v[90:91], v[220:221], v[252:253] op_sel_hi:[1,0,1] neg_lo:[1,0,0] neg_hi:[1,0,0]
	s_nop 0
	v_pk_fma_f32 v[252:253], v[94:95], v[222:223], v[252:253] op_sel_hi:[1,0,1] neg_lo:[1,0,0] neg_hi:[1,0,0]
	ds_read_b128 v[220:223], v20 offset:52928
	v_pk_fma_f32 v[252:253], v[224:225], v[98:99], v[252:253] op_sel_hi:[0,1,1] neg_lo:[1,0,0] neg_hi:[1,0,0]
	s_nop 0
	v_pk_fma_f32 v[252:253], v[102:103], v[226:227], v[252:253] op_sel_hi:[1,0,1] neg_lo:[1,0,0] neg_hi:[1,0,0]
	ds_read_b128 v[224:227], v20 offset:52944
	v_pk_add_f32 v[100:101], v[252:253], v[146:147]
	s_waitcnt lgkmcnt(13)
	v_pk_fma_f32 v[146:147], v[138:139], v[110:111], 0 op_sel:[0,1,0] op_sel_hi:[1,1,0] neg_lo:[1,0,0] neg_hi:[1,0,0]
	v_pk_fma_f32 v[110:111], v[128:129], v[110:111], v[102:103] op_sel_hi:[1,0,1] neg_lo:[1,0,0] neg_hi:[1,0,0]
	v_pk_fma_f32 v[146:147], v[134:135], v[112:113], v[146:147] op_sel:[0,1,0] neg_lo:[1,0,0] neg_hi:[1,0,0]
	v_pk_fma_f32 v[110:111], v[136:137], v[112:113], v[110:111] op_sel_hi:[1,0,1] neg_lo:[1,0,0] neg_hi:[1,0,0]
	s_waitcnt lgkmcnt(12)
	v_pk_fma_f32 v[146:147], v[130:131], v[150:151], v[146:147] op_sel:[0,1,0] neg_lo:[1,0,0] neg_hi:[1,0,0]
	v_pk_fma_f32 v[110:111], v[132:133], v[150:151], v[110:111] op_sel_hi:[1,0,1] neg_lo:[1,0,0] neg_hi:[1,0,0]
	v_pk_fma_f32 v[146:147], v[84:85], v[152:153], v[146:147] op_sel:[0,1,0] neg_lo:[1,0,0] neg_hi:[1,0,0]
	v_pk_fma_f32 v[110:111], v[122:123], v[152:153], v[110:111] op_sel_hi:[1,0,1] neg_lo:[1,0,0] neg_hi:[1,0,0]
	ds_read_b128 v[150:153], v20 offset:53008
	s_waitcnt lgkmcnt(12)
	v_pk_fma_f32 v[146:147], v[10:11], v[154:155], v[146:147] op_sel:[0,1,0] neg_lo:[1,0,0] neg_hi:[1,0,0]
	v_pk_fma_f32 v[110:111], v[14:15], v[154:155], v[110:111] op_sel_hi:[1,0,1] neg_lo:[1,0,0] neg_hi:[1,0,0]
	v_pk_fma_f32 v[146:147], v[6:7], v[156:157], v[146:147] op_sel:[0,1,0] neg_lo:[1,0,0] neg_hi:[1,0,0]
	v_pk_fma_f32 v[110:111], v[16:17], v[156:157], v[110:111] op_sel_hi:[1,0,1] neg_lo:[1,0,0] neg_hi:[1,0,0]
	ds_read_b128 v[154:157], v20 offset:53024
	s_waitcnt lgkmcnt(12)
	v_pk_fma_f32 v[146:147], v[12:13], v[158:159], v[146:147] op_sel:[0,1,0] neg_lo:[1,0,0] neg_hi:[1,0,0]
	v_pk_fma_f32 v[110:111], v[18:19], v[158:159], v[110:111] op_sel_hi:[1,0,1] neg_lo:[1,0,0] neg_hi:[1,0,0]
	v_pk_fma_f32 v[146:147], v[4:5], v[160:161], v[146:147] op_sel:[0,1,0] neg_lo:[1,0,0] neg_hi:[1,0,0]
	v_pk_fma_f32 v[110:111], v[8:9], v[160:161], v[110:111] op_sel_hi:[1,0,1] neg_lo:[1,0,0] neg_hi:[1,0,0]
	ds_read_b128 v[158:161], v20 offset:53040
	s_waitcnt lgkmcnt(12)
	v_pk_fma_f32 v[146:147], v[0:1], v[166:167], v[146:147] op_sel:[0,1,0] neg_lo:[1,0,0] neg_hi:[1,0,0]
	v_pk_fma_f32 v[110:111], v[2:3], v[166:167], v[110:111] op_sel_hi:[1,0,1] neg_lo:[1,0,0] neg_hi:[1,0,0]
	v_pk_fma_f32 v[146:147], v[28:29], v[168:169], v[146:147] op_sel:[0,1,0] neg_lo:[1,0,0] neg_hi:[1,0,0]
	v_pk_fma_f32 v[110:111], v[30:31], v[168:169], v[110:111] op_sel_hi:[1,0,1] neg_lo:[1,0,0] neg_hi:[1,0,0]
	ds_read_b128 v[166:169], v20 offset:53056
	s_waitcnt lgkmcnt(12)
	v_pk_fma_f32 v[146:147], v[34:35], v[170:171], v[146:147] op_sel:[0,1,0] neg_lo:[1,0,0] neg_hi:[1,0,0]
	v_pk_fma_f32 v[110:111], v[32:33], v[170:171], v[110:111] op_sel_hi:[1,0,1] neg_lo:[1,0,0] neg_hi:[1,0,0]
	v_pk_fma_f32 v[146:147], v[40:41], v[172:173], v[146:147] op_sel:[0,1,0] neg_lo:[1,0,0] neg_hi:[1,0,0]
	v_pk_fma_f32 v[110:111], v[36:37], v[172:173], v[110:111] op_sel_hi:[1,0,1] neg_lo:[1,0,0] neg_hi:[1,0,0]
	ds_read_b128 v[170:173], v20 offset:53072
	s_waitcnt lgkmcnt(12)
	v_pk_fma_f32 v[146:147], v[42:43], v[174:175], v[146:147] op_sel:[0,1,0] neg_lo:[1,0,0] neg_hi:[1,0,0]
	v_pk_fma_f32 v[110:111], v[38:39], v[174:175], v[110:111] op_sel_hi:[1,0,1] neg_lo:[1,0,0] neg_hi:[1,0,0]
	v_pk_fma_f32 v[146:147], v[46:47], v[176:177], v[146:147] op_sel:[0,1,0] neg_lo:[1,0,0] neg_hi:[1,0,0]
	v_pk_fma_f32 v[110:111], v[44:45], v[176:177], v[110:111] op_sel_hi:[1,0,1] neg_lo:[1,0,0] neg_hi:[1,0,0]
	ds_read_b128 v[174:177], v20 offset:53088
	s_waitcnt lgkmcnt(12)
	v_pk_fma_f32 v[146:147], v[50:51], v[178:179], v[146:147] op_sel:[0,1,0] neg_lo:[1,0,0] neg_hi:[1,0,0]
	v_pk_fma_f32 v[110:111], v[48:49], v[178:179], v[110:111] op_sel_hi:[1,0,1] neg_lo:[1,0,0] neg_hi:[1,0,0]
	v_pk_fma_f32 v[146:147], v[54:55], v[180:181], v[146:147] op_sel:[0,1,0] neg_lo:[1,0,0] neg_hi:[1,0,0]
	v_pk_fma_f32 v[110:111], v[52:53], v[180:181], v[110:111] op_sel_hi:[1,0,1] neg_lo:[1,0,0] neg_hi:[1,0,0]
	ds_read_b128 v[178:181], v20 offset:53104
	s_waitcnt lgkmcnt(12)
	v_pk_fma_f32 v[146:147], v[58:59], v[182:183], v[146:147] op_sel:[0,1,0] neg_lo:[1,0,0] neg_hi:[1,0,0]
	v_pk_fma_f32 v[110:111], v[56:57], v[182:183], v[110:111] op_sel_hi:[1,0,1] neg_lo:[1,0,0] neg_hi:[1,0,0]
	v_pk_fma_f32 v[146:147], v[62:63], v[184:185], v[146:147] op_sel:[0,1,0] neg_lo:[1,0,0] neg_hi:[1,0,0]
	v_pk_fma_f32 v[110:111], v[60:61], v[184:185], v[110:111] op_sel_hi:[1,0,1] neg_lo:[1,0,0] neg_hi:[1,0,0]
	ds_read_b128 v[182:185], v20 offset:53120
	s_waitcnt lgkmcnt(12)
	v_pk_fma_f32 v[146:147], v[66:67], v[208:209], v[146:147] op_sel:[0,1,0] neg_lo:[1,0,0] neg_hi:[1,0,0]
	v_pk_fma_f32 v[110:111], v[64:65], v[208:209], v[110:111] op_sel_hi:[1,0,1] neg_lo:[1,0,0] neg_hi:[1,0,0]
	v_pk_fma_f32 v[146:147], v[70:71], v[210:211], v[146:147] op_sel:[0,1,0] neg_lo:[1,0,0] neg_hi:[1,0,0]
	v_pk_fma_f32 v[110:111], v[68:69], v[210:211], v[110:111] op_sel_hi:[1,0,1] neg_lo:[1,0,0] neg_hi:[1,0,0]
	ds_read_b128 v[208:211], v20 offset:53136
	s_waitcnt lgkmcnt(12)
	v_pk_fma_f32 v[146:147], v[74:75], v[212:213], v[146:147] op_sel:[0,1,0] neg_lo:[1,0,0] neg_hi:[1,0,0]
	v_pk_fma_f32 v[110:111], v[72:73], v[212:213], v[110:111] op_sel_hi:[1,0,1] neg_lo:[1,0,0] neg_hi:[1,0,0]
	v_pk_fma_f32 v[146:147], v[78:79], v[214:215], v[146:147] op_sel:[0,1,0] neg_lo:[1,0,0] neg_hi:[1,0,0]
	v_pk_fma_f32 v[110:111], v[76:77], v[214:215], v[110:111] op_sel_hi:[1,0,1] neg_lo:[1,0,0] neg_hi:[1,0,0]
	ds_read_b128 v[212:215], v20 offset:53152
	s_waitcnt lgkmcnt(12)
	v_pk_fma_f32 v[146:147], v[82:83], v[216:217], v[146:147] op_sel:[0,1,0] neg_lo:[1,0,0] neg_hi:[1,0,0]
	v_pk_fma_f32 v[110:111], v[80:81], v[216:217], v[110:111] op_sel_hi:[1,0,1] neg_lo:[1,0,0] neg_hi:[1,0,0]
	v_pk_fma_f32 v[146:147], v[88:89], v[218:219], v[146:147] op_sel:[0,1,0] neg_lo:[1,0,0] neg_hi:[1,0,0]
	v_pk_fma_f32 v[110:111], v[86:87], v[218:219], v[110:111] op_sel_hi:[1,0,1] neg_lo:[1,0,0] neg_hi:[1,0,0]
	ds_read_b128 v[216:219], v20 offset:53168
	s_waitcnt lgkmcnt(12)
	v_pk_fma_f32 v[146:147], v[92:93], v[220:221], v[146:147] op_sel:[0,1,0] neg_lo:[1,0,0] neg_hi:[1,0,0]
	v_pk_fma_f32 v[110:111], v[90:91], v[220:221], v[110:111] op_sel_hi:[1,0,1] neg_lo:[1,0,0] neg_hi:[1,0,0]
	v_pk_fma_f32 v[146:147], v[96:97], v[222:223], v[146:147] op_sel:[0,1,0] neg_lo:[1,0,0] neg_hi:[1,0,0]
	v_pk_fma_f32 v[110:111], v[94:95], v[222:223], v[110:111] op_sel_hi:[1,0,1] neg_lo:[1,0,0] neg_hi:[1,0,0]
	ds_read_b128 v[220:223], v20 offset:53184
	s_waitcnt lgkmcnt(12)
	v_pk_fma_f32 v[146:147], v[224:225], v[100:101], v[146:147] op_sel:[1,0,0] neg_lo:[1,0,0] neg_hi:[1,0,0]
	v_pk_fma_f32 v[110:111], v[98:99], v[224:225], v[110:111] op_sel_hi:[1,0,1] neg_lo:[1,0,0] neg_hi:[1,0,0]
	v_pk_fma_f32 v[146:147], v[104:105], v[226:227], v[146:147] op_sel:[0,1,0] neg_lo:[1,0,0] neg_hi:[1,0,0]
	v_pk_fma_f32 v[102:103], v[102:103], v[226:227], v[110:111] op_sel_hi:[1,0,1] neg_lo:[1,0,0] neg_hi:[1,0,0]
	ds_read_b128 v[110:113], v20 offset:52992
	ds_read_b128 v[224:227], v20 offset:53200
	v_pk_add_f32 v[102:103], v[102:103], v[146:147]
	s_waitcnt lgkmcnt(1)
	v_pk_fma_f32 v[146:147], v[138:139], v[110:111], 0 op_sel:[0,1,0] op_sel_hi:[1,1,0] neg_lo:[1,0,0] neg_hi:[1,0,0]
	v_pk_fma_f32 v[252:253], v[128:129], v[110:111], v[104:105] op_sel_hi:[1,0,1] neg_lo:[1,0,0] neg_hi:[1,0,0]
	v_pk_fma_f32 v[146:147], v[134:135], v[112:113], v[146:147] op_sel:[0,1,0] neg_lo:[1,0,0] neg_hi:[1,0,0]
	v_pk_fma_f32 v[252:253], v[136:137], v[112:113], v[252:253] op_sel_hi:[1,0,1] neg_lo:[1,0,0] neg_hi:[1,0,0]
	v_pk_fma_f32 v[146:147], v[130:131], v[150:151], v[146:147] op_sel:[0,1,0] neg_lo:[1,0,0] neg_hi:[1,0,0]
	ds_read_b128 v[110:113], v20 offset:53248
	v_pk_fma_f32 v[146:147], v[84:85], v[152:153], v[146:147] op_sel:[0,1,0] neg_lo:[1,0,0] neg_hi:[1,0,0]
	v_pk_fma_f32 v[252:253], v[132:133], v[150:151], v[252:253] op_sel_hi:[1,0,1] neg_lo:[1,0,0] neg_hi:[1,0,0]
	v_pk_fma_f32 v[146:147], v[10:11], v[154:155], v[146:147] op_sel:[0,1,0] neg_lo:[1,0,0] neg_hi:[1,0,0]
	v_pk_fma_f32 v[252:253], v[122:123], v[152:153], v[252:253] op_sel_hi:[1,0,1] neg_lo:[1,0,0] neg_hi:[1,0,0]
	v_pk_fma_f32 v[146:147], v[6:7], v[156:157], v[146:147] op_sel:[0,1,0] neg_lo:[1,0,0] neg_hi:[1,0,0]
	ds_read_b128 v[150:153], v20 offset:53264
	v_pk_fma_f32 v[146:147], v[12:13], v[158:159], v[146:147] op_sel:[0,1,0] neg_lo:[1,0,0] neg_hi:[1,0,0]
	v_pk_fma_f32 v[252:253], v[14:15], v[154:155], v[252:253] op_sel_hi:[1,0,1] neg_lo:[1,0,0] neg_hi:[1,0,0]
	v_pk_fma_f32 v[146:147], v[4:5], v[160:161], v[146:147] op_sel:[0,1,0] neg_lo:[1,0,0] neg_hi:[1,0,0]
	v_pk_fma_f32 v[252:253], v[16:17], v[156:157], v[252:253] op_sel_hi:[1,0,1] neg_lo:[1,0,0] neg_hi:[1,0,0]
	v_pk_fma_f32 v[146:147], v[0:1], v[166:167], v[146:147] op_sel:[0,1,0] neg_lo:[1,0,0] neg_hi:[1,0,0]
	ds_read_b128 v[154:157], v20 offset:53280
	v_pk_fma_f32 v[146:147], v[28:29], v[168:169], v[146:147] op_sel:[0,1,0] neg_lo:[1,0,0] neg_hi:[1,0,0]
	v_pk_fma_f32 v[252:253], v[18:19], v[158:159], v[252:253] op_sel_hi:[1,0,1] neg_lo:[1,0,0] neg_hi:[1,0,0]
	v_pk_fma_f32 v[146:147], v[34:35], v[170:171], v[146:147] op_sel:[0,1,0] neg_lo:[1,0,0] neg_hi:[1,0,0]
	v_pk_fma_f32 v[252:253], v[8:9], v[160:161], v[252:253] op_sel_hi:[1,0,1] neg_lo:[1,0,0] neg_hi:[1,0,0]
	v_pk_fma_f32 v[146:147], v[40:41], v[172:173], v[146:147] op_sel:[0,1,0] neg_lo:[1,0,0] neg_hi:[1,0,0]
	ds_read_b128 v[158:161], v20 offset:53296
	v_pk_fma_f32 v[146:147], v[42:43], v[174:175], v[146:147] op_sel:[0,1,0] neg_lo:[1,0,0] neg_hi:[1,0,0]
	v_pk_fma_f32 v[252:253], v[2:3], v[166:167], v[252:253] op_sel_hi:[1,0,1] neg_lo:[1,0,0] neg_hi:[1,0,0]
	v_pk_fma_f32 v[146:147], v[46:47], v[176:177], v[146:147] op_sel:[0,1,0] neg_lo:[1,0,0] neg_hi:[1,0,0]
	v_pk_fma_f32 v[252:253], v[30:31], v[168:169], v[252:253] op_sel_hi:[1,0,1] neg_lo:[1,0,0] neg_hi:[1,0,0]
	v_pk_fma_f32 v[146:147], v[50:51], v[178:179], v[146:147] op_sel:[0,1,0] neg_lo:[1,0,0] neg_hi:[1,0,0]
	ds_read_b128 v[166:169], v20 offset:53312
	v_pk_fma_f32 v[146:147], v[54:55], v[180:181], v[146:147] op_sel:[0,1,0] neg_lo:[1,0,0] neg_hi:[1,0,0]
	v_pk_fma_f32 v[252:253], v[32:33], v[170:171], v[252:253] op_sel_hi:[1,0,1] neg_lo:[1,0,0] neg_hi:[1,0,0]
	v_pk_fma_f32 v[146:147], v[58:59], v[182:183], v[146:147] op_sel:[0,1,0] neg_lo:[1,0,0] neg_hi:[1,0,0]
	v_pk_fma_f32 v[252:253], v[36:37], v[172:173], v[252:253] op_sel_hi:[1,0,1] neg_lo:[1,0,0] neg_hi:[1,0,0]
	v_pk_fma_f32 v[146:147], v[62:63], v[184:185], v[146:147] op_sel:[0,1,0] neg_lo:[1,0,0] neg_hi:[1,0,0]
	ds_read_b128 v[170:173], v20 offset:53328
	v_pk_fma_f32 v[146:147], v[66:67], v[208:209], v[146:147] op_sel:[0,1,0] neg_lo:[1,0,0] neg_hi:[1,0,0]
	v_pk_fma_f32 v[252:253], v[38:39], v[174:175], v[252:253] op_sel_hi:[1,0,1] neg_lo:[1,0,0] neg_hi:[1,0,0]
	v_pk_fma_f32 v[146:147], v[70:71], v[210:211], v[146:147] op_sel:[0,1,0] neg_lo:[1,0,0] neg_hi:[1,0,0]
	v_pk_fma_f32 v[252:253], v[44:45], v[176:177], v[252:253] op_sel_hi:[1,0,1] neg_lo:[1,0,0] neg_hi:[1,0,0]
	ds_read_b128 v[174:177], v20 offset:53344
	v_pk_fma_f32 v[146:147], v[74:75], v[212:213], v[146:147] op_sel:[0,1,0] neg_lo:[1,0,0] neg_hi:[1,0,0]
	v_pk_fma_f32 v[252:253], v[48:49], v[178:179], v[252:253] op_sel_hi:[1,0,1] neg_lo:[1,0,0] neg_hi:[1,0,0]
	v_pk_fma_f32 v[146:147], v[78:79], v[214:215], v[146:147] op_sel:[0,1,0] neg_lo:[1,0,0] neg_hi:[1,0,0]
	v_pk_fma_f32 v[252:253], v[52:53], v[180:181], v[252:253] op_sel_hi:[1,0,1] neg_lo:[1,0,0] neg_hi:[1,0,0]
	ds_read_b128 v[178:181], v20 offset:53360
	v_pk_fma_f32 v[146:147], v[82:83], v[216:217], v[146:147] op_sel:[0,1,0] neg_lo:[1,0,0] neg_hi:[1,0,0]
	v_pk_fma_f32 v[252:253], v[56:57], v[182:183], v[252:253] op_sel_hi:[1,0,1] neg_lo:[1,0,0] neg_hi:[1,0,0]
	v_pk_fma_f32 v[146:147], v[88:89], v[218:219], v[146:147] op_sel:[0,1,0] neg_lo:[1,0,0] neg_hi:[1,0,0]
	v_pk_fma_f32 v[252:253], v[60:61], v[184:185], v[252:253] op_sel_hi:[1,0,1] neg_lo:[1,0,0] neg_hi:[1,0,0]
	ds_read_b128 v[182:185], v20 offset:53376
	v_pk_fma_f32 v[146:147], v[92:93], v[220:221], v[146:147] op_sel:[0,1,0] neg_lo:[1,0,0] neg_hi:[1,0,0]
	v_pk_fma_f32 v[252:253], v[64:65], v[208:209], v[252:253] op_sel_hi:[1,0,1] neg_lo:[1,0,0] neg_hi:[1,0,0]
	v_pk_fma_f32 v[146:147], v[96:97], v[222:223], v[146:147] op_sel:[0,1,0] neg_lo:[1,0,0] neg_hi:[1,0,0]
	v_pk_fma_f32 v[252:253], v[68:69], v[210:211], v[252:253] op_sel_hi:[1,0,1] neg_lo:[1,0,0] neg_hi:[1,0,0]
	ds_read_b128 v[208:211], v20 offset:53392
	s_waitcnt lgkmcnt(10)
	v_pk_fma_f32 v[146:147], v[100:101], v[224:225], v[146:147] op_sel:[0,1,0] neg_lo:[1,0,0] neg_hi:[1,0,0]
	v_pk_fma_f32 v[252:253], v[72:73], v[212:213], v[252:253] op_sel_hi:[1,0,1] neg_lo:[1,0,0] neg_hi:[1,0,0]
	v_pk_fma_f32 v[146:147], v[104:105], v[226:227], v[146:147] op_sel:[0,1,0] neg_lo:[1,0,0] neg_hi:[1,0,0]
	v_pk_fma_f32 v[252:253], v[76:77], v[214:215], v[252:253] op_sel_hi:[1,0,1] neg_lo:[1,0,0] neg_hi:[1,0,0]
	ds_read_b128 v[212:215], v20 offset:53408
	v_pk_fma_f32 v[252:253], v[80:81], v[216:217], v[252:253] op_sel_hi:[1,0,1] neg_lo:[1,0,0] neg_hi:[1,0,0]
	s_nop 0
	v_pk_fma_f32 v[252:253], v[86:87], v[218:219], v[252:253] op_sel_hi:[1,0,1] neg_lo:[1,0,0] neg_hi:[1,0,0]
	ds_read_b128 v[216:219], v20 offset:53424
	v_pk_fma_f32 v[252:253], v[90:91], v[220:221], v[252:253] op_sel_hi:[1,0,1] neg_lo:[1,0,0] neg_hi:[1,0,0]
	s_nop 0
	v_pk_fma_f32 v[252:253], v[94:95], v[222:223], v[252:253] op_sel_hi:[1,0,1] neg_lo:[1,0,0] neg_hi:[1,0,0]
	ds_read_b128 v[220:223], v20 offset:53440
	v_pk_fma_f32 v[252:253], v[98:99], v[224:225], v[252:253] op_sel_hi:[1,0,1] neg_lo:[1,0,0] neg_hi:[1,0,0]
	s_nop 0
	v_pk_fma_f32 v[252:253], v[226:227], v[102:103], v[252:253] op_sel_hi:[0,1,1] neg_lo:[1,0,0] neg_hi:[1,0,0]
	ds_read_b128 v[224:227], v20 offset:53456
	v_pk_add_f32 v[104:105], v[252:253], v[146:147]
	s_waitcnt lgkmcnt(13)
	v_pk_fma_f32 v[146:147], v[138:139], v[110:111], 0 op_sel:[0,1,0] op_sel_hi:[1,1,0] neg_lo:[1,0,0] neg_hi:[1,0,0]
	v_pk_mul_f32 v[110:111], v[128:129], v[110:111] op_sel_hi:[1,0]
	v_pk_fma_f32 v[146:147], v[134:135], v[112:113], v[146:147] op_sel:[0,1,0] neg_lo:[1,0,0] neg_hi:[1,0,0]
	v_pk_fma_f32 v[106:107], v[106:107], v[108:109], v[110:111] neg_lo:[0,0,1] neg_hi:[0,0,1]
	ds_read_b128 v[108:111], v20 offset:53504
	v_pk_fma_f32 v[106:107], v[136:137], v[112:113], v[106:107] op_sel_hi:[1,0,1] neg_lo:[1,0,0] neg_hi:[1,0,0]
	s_waitcnt lgkmcnt(13)
	v_pk_fma_f32 v[146:147], v[130:131], v[150:151], v[146:147] op_sel:[0,1,0] neg_lo:[1,0,0] neg_hi:[1,0,0]
	v_pk_fma_f32 v[106:107], v[132:133], v[150:151], v[106:107] op_sel_hi:[1,0,1] neg_lo:[1,0,0] neg_hi:[1,0,0]
	v_pk_fma_f32 v[146:147], v[84:85], v[152:153], v[146:147] op_sel:[0,1,0] neg_lo:[1,0,0] neg_hi:[1,0,0]
	v_pk_fma_f32 v[106:107], v[122:123], v[152:153], v[106:107] op_sel_hi:[1,0,1] neg_lo:[1,0,0] neg_hi:[1,0,0]
	ds_read_b128 v[150:153], v20 offset:53520
	s_waitcnt lgkmcnt(13)
	v_pk_fma_f32 v[146:147], v[10:11], v[154:155], v[146:147] op_sel:[0,1,0] neg_lo:[1,0,0] neg_hi:[1,0,0]
	v_pk_fma_f32 v[106:107], v[14:15], v[154:155], v[106:107] op_sel_hi:[1,0,1] neg_lo:[1,0,0] neg_hi:[1,0,0]
	v_pk_fma_f32 v[146:147], v[6:7], v[156:157], v[146:147] op_sel:[0,1,0] neg_lo:[1,0,0] neg_hi:[1,0,0]
	v_pk_fma_f32 v[106:107], v[16:17], v[156:157], v[106:107] op_sel_hi:[1,0,1] neg_lo:[1,0,0] neg_hi:[1,0,0]
	ds_read_b128 v[154:157], v20 offset:53536
	s_waitcnt lgkmcnt(13)
	v_pk_fma_f32 v[146:147], v[12:13], v[158:159], v[146:147] op_sel:[0,1,0] neg_lo:[1,0,0] neg_hi:[1,0,0]
	v_pk_fma_f32 v[106:107], v[18:19], v[158:159], v[106:107] op_sel_hi:[1,0,1] neg_lo:[1,0,0] neg_hi:[1,0,0]
	v_pk_fma_f32 v[146:147], v[4:5], v[160:161], v[146:147] op_sel:[0,1,0] neg_lo:[1,0,0] neg_hi:[1,0,0]
	v_pk_fma_f32 v[106:107], v[8:9], v[160:161], v[106:107] op_sel_hi:[1,0,1] neg_lo:[1,0,0] neg_hi:[1,0,0]
	ds_read_b128 v[158:161], v20 offset:53552
	s_waitcnt lgkmcnt(13)
	v_pk_fma_f32 v[146:147], v[0:1], v[166:167], v[146:147] op_sel:[0,1,0] neg_lo:[1,0,0] neg_hi:[1,0,0]
	v_pk_fma_f32 v[106:107], v[2:3], v[166:167], v[106:107] op_sel_hi:[1,0,1] neg_lo:[1,0,0] neg_hi:[1,0,0]
	v_pk_fma_f32 v[146:147], v[28:29], v[168:169], v[146:147] op_sel:[0,1,0] neg_lo:[1,0,0] neg_hi:[1,0,0]
	v_pk_fma_f32 v[106:107], v[30:31], v[168:169], v[106:107] op_sel_hi:[1,0,1] neg_lo:[1,0,0] neg_hi:[1,0,0]
	ds_read_b128 v[166:169], v20 offset:53568
	s_waitcnt lgkmcnt(13)
	v_pk_fma_f32 v[146:147], v[34:35], v[170:171], v[146:147] op_sel:[0,1,0] neg_lo:[1,0,0] neg_hi:[1,0,0]
	v_pk_fma_f32 v[106:107], v[32:33], v[170:171], v[106:107] op_sel_hi:[1,0,1] neg_lo:[1,0,0] neg_hi:[1,0,0]
	v_pk_fma_f32 v[146:147], v[40:41], v[172:173], v[146:147] op_sel:[0,1,0] neg_lo:[1,0,0] neg_hi:[1,0,0]
	v_pk_fma_f32 v[106:107], v[36:37], v[172:173], v[106:107] op_sel_hi:[1,0,1] neg_lo:[1,0,0] neg_hi:[1,0,0]
	ds_read_b128 v[170:173], v20 offset:53584
	s_waitcnt lgkmcnt(13)
	v_pk_fma_f32 v[146:147], v[42:43], v[174:175], v[146:147] op_sel:[0,1,0] neg_lo:[1,0,0] neg_hi:[1,0,0]
	v_pk_fma_f32 v[106:107], v[38:39], v[174:175], v[106:107] op_sel_hi:[1,0,1] neg_lo:[1,0,0] neg_hi:[1,0,0]
	v_pk_fma_f32 v[146:147], v[46:47], v[176:177], v[146:147] op_sel:[0,1,0] neg_lo:[1,0,0] neg_hi:[1,0,0]
	v_pk_fma_f32 v[106:107], v[44:45], v[176:177], v[106:107] op_sel_hi:[1,0,1] neg_lo:[1,0,0] neg_hi:[1,0,0]
	ds_read_b128 v[174:177], v20 offset:53600
	s_waitcnt lgkmcnt(13)
	v_pk_fma_f32 v[146:147], v[50:51], v[178:179], v[146:147] op_sel:[0,1,0] neg_lo:[1,0,0] neg_hi:[1,0,0]
	v_pk_fma_f32 v[106:107], v[48:49], v[178:179], v[106:107] op_sel_hi:[1,0,1] neg_lo:[1,0,0] neg_hi:[1,0,0]
	v_pk_fma_f32 v[146:147], v[54:55], v[180:181], v[146:147] op_sel:[0,1,0] neg_lo:[1,0,0] neg_hi:[1,0,0]
	v_pk_fma_f32 v[106:107], v[52:53], v[180:181], v[106:107] op_sel_hi:[1,0,1] neg_lo:[1,0,0] neg_hi:[1,0,0]
	ds_read_b128 v[178:181], v20 offset:53616
	s_waitcnt lgkmcnt(13)
	v_pk_fma_f32 v[146:147], v[58:59], v[182:183], v[146:147] op_sel:[0,1,0] neg_lo:[1,0,0] neg_hi:[1,0,0]
	v_pk_fma_f32 v[106:107], v[56:57], v[182:183], v[106:107] op_sel_hi:[1,0,1] neg_lo:[1,0,0] neg_hi:[1,0,0]
	v_pk_fma_f32 v[146:147], v[62:63], v[184:185], v[146:147] op_sel:[0,1,0] neg_lo:[1,0,0] neg_hi:[1,0,0]
	v_pk_fma_f32 v[106:107], v[60:61], v[184:185], v[106:107] op_sel_hi:[1,0,1] neg_lo:[1,0,0] neg_hi:[1,0,0]
	ds_read_b128 v[182:185], v20 offset:53632
	s_waitcnt lgkmcnt(13)
	v_pk_fma_f32 v[146:147], v[66:67], v[208:209], v[146:147] op_sel:[0,1,0] neg_lo:[1,0,0] neg_hi:[1,0,0]
	v_pk_fma_f32 v[106:107], v[64:65], v[208:209], v[106:107] op_sel_hi:[1,0,1] neg_lo:[1,0,0] neg_hi:[1,0,0]
	v_pk_fma_f32 v[146:147], v[70:71], v[210:211], v[146:147] op_sel:[0,1,0] neg_lo:[1,0,0] neg_hi:[1,0,0]
	v_pk_fma_f32 v[106:107], v[68:69], v[210:211], v[106:107] op_sel_hi:[1,0,1] neg_lo:[1,0,0] neg_hi:[1,0,0]
	ds_read_b128 v[208:211], v20 offset:53648
	s_waitcnt lgkmcnt(13)
	v_pk_fma_f32 v[146:147], v[74:75], v[212:213], v[146:147] op_sel:[0,1,0] neg_lo:[1,0,0] neg_hi:[1,0,0]
	v_pk_fma_f32 v[106:107], v[72:73], v[212:213], v[106:107] op_sel_hi:[1,0,1] neg_lo:[1,0,0] neg_hi:[1,0,0]
	v_pk_fma_f32 v[146:147], v[78:79], v[214:215], v[146:147] op_sel:[0,1,0] neg_lo:[1,0,0] neg_hi:[1,0,0]
	v_pk_fma_f32 v[106:107], v[76:77], v[214:215], v[106:107] op_sel_hi:[1,0,1] neg_lo:[1,0,0] neg_hi:[1,0,0]
	ds_read_b128 v[212:215], v20 offset:53664
	s_waitcnt lgkmcnt(13)
	v_pk_fma_f32 v[146:147], v[82:83], v[216:217], v[146:147] op_sel:[0,1,0] neg_lo:[1,0,0] neg_hi:[1,0,0]
	v_pk_fma_f32 v[106:107], v[80:81], v[216:217], v[106:107] op_sel_hi:[1,0,1] neg_lo:[1,0,0] neg_hi:[1,0,0]
	v_pk_fma_f32 v[146:147], v[88:89], v[218:219], v[146:147] op_sel:[0,1,0] neg_lo:[1,0,0] neg_hi:[1,0,0]
	v_pk_fma_f32 v[106:107], v[86:87], v[218:219], v[106:107] op_sel_hi:[1,0,1] neg_lo:[1,0,0] neg_hi:[1,0,0]
	ds_read_b128 v[216:219], v20 offset:53680
	s_waitcnt lgkmcnt(13)
	v_pk_fma_f32 v[146:147], v[92:93], v[220:221], v[146:147] op_sel:[0,1,0] neg_lo:[1,0,0] neg_hi:[1,0,0]
	v_pk_fma_f32 v[106:107], v[90:91], v[220:221], v[106:107] op_sel_hi:[1,0,1] neg_lo:[1,0,0] neg_hi:[1,0,0]
	v_pk_fma_f32 v[146:147], v[96:97], v[222:223], v[146:147] op_sel:[0,1,0] neg_lo:[1,0,0] neg_hi:[1,0,0]
	v_pk_fma_f32 v[106:107], v[94:95], v[222:223], v[106:107] op_sel_hi:[1,0,1] neg_lo:[1,0,0] neg_hi:[1,0,0]
	ds_read_b128 v[220:223], v20 offset:53696
	s_waitcnt lgkmcnt(13)
	v_pk_fma_f32 v[146:147], v[100:101], v[224:225], v[146:147] op_sel:[0,1,0] neg_lo:[1,0,0] neg_hi:[1,0,0]
	v_pk_fma_f32 v[106:107], v[98:99], v[224:225], v[106:107] op_sel_hi:[1,0,1] neg_lo:[1,0,0] neg_hi:[1,0,0]
	v_pk_fma_f32 v[146:147], v[226:227], v[104:105], v[146:147] op_sel:[1,0,0] neg_lo:[1,0,0] neg_hi:[1,0,0]
	v_pk_fma_f32 v[106:107], v[102:103], v[226:227], v[106:107] op_sel_hi:[1,0,1] neg_lo:[1,0,0] neg_hi:[1,0,0]
	ds_read_b128 v[224:227], v20 offset:53712
	v_pk_add_f32 v[106:107], v[106:107], v[146:147]
	s_waitcnt lgkmcnt(13)
	v_pk_fma_f32 v[112:113], v[138:139], v[108:109], 0 op_sel:[0,1,0] op_sel_hi:[1,1,0] neg_lo:[1,0,0] neg_hi:[1,0,0]
	v_pk_fma_f32 v[108:109], v[128:129], v[108:109], v[148:149] op_sel_hi:[1,0,1] neg_lo:[1,0,0] neg_hi:[1,0,0]
	v_pk_fma_f32 v[112:113], v[134:135], v[110:111], v[112:113] op_sel:[0,1,0] neg_lo:[1,0,0] neg_hi:[1,0,0]
	v_pk_fma_f32 v[108:109], v[136:137], v[110:111], v[108:109] op_sel_hi:[1,0,1] neg_lo:[1,0,0] neg_hi:[1,0,0]
	s_waitcnt lgkmcnt(12)
	v_pk_fma_f32 v[112:113], v[130:131], v[150:151], v[112:113] op_sel:[0,1,0] neg_lo:[1,0,0] neg_hi:[1,0,0]
	v_pk_fma_f32 v[108:109], v[132:133], v[150:151], v[108:109] op_sel_hi:[1,0,1] neg_lo:[1,0,0] neg_hi:[1,0,0]
	v_pk_fma_f32 v[112:113], v[84:85], v[152:153], v[112:113] op_sel:[0,1,0] neg_lo:[1,0,0] neg_hi:[1,0,0]
	v_pk_fma_f32 v[108:109], v[122:123], v[152:153], v[108:109] op_sel_hi:[1,0,1] neg_lo:[1,0,0] neg_hi:[1,0,0]
	s_waitcnt lgkmcnt(11)
	v_pk_fma_f32 v[112:113], v[10:11], v[154:155], v[112:113] op_sel:[0,1,0] neg_lo:[1,0,0] neg_hi:[1,0,0]
	ds_read_b128 v[150:153], v20 offset:53792
	v_pk_fma_f32 v[108:109], v[14:15], v[154:155], v[108:109] op_sel_hi:[1,0,1] neg_lo:[1,0,0] neg_hi:[1,0,0]
	v_pk_fma_f32 v[112:113], v[6:7], v[156:157], v[112:113] op_sel:[0,1,0] neg_lo:[1,0,0] neg_hi:[1,0,0]
	v_pk_fma_f32 v[108:109], v[16:17], v[156:157], v[108:109] op_sel_hi:[1,0,1] neg_lo:[1,0,0] neg_hi:[1,0,0]
	ds_read_b128 v[154:157], v20 offset:53808
	s_waitcnt lgkmcnt(12)
	v_pk_fma_f32 v[112:113], v[12:13], v[158:159], v[112:113] op_sel:[0,1,0] neg_lo:[1,0,0] neg_hi:[1,0,0]
	v_pk_fma_f32 v[108:109], v[18:19], v[158:159], v[108:109] op_sel_hi:[1,0,1] neg_lo:[1,0,0] neg_hi:[1,0,0]
	v_pk_fma_f32 v[112:113], v[4:5], v[160:161], v[112:113] op_sel:[0,1,0] neg_lo:[1,0,0] neg_hi:[1,0,0]
	v_pk_fma_f32 v[108:109], v[8:9], v[160:161], v[108:109] op_sel_hi:[1,0,1] neg_lo:[1,0,0] neg_hi:[1,0,0]
	ds_read_b128 v[158:161], v20 offset:53824
	s_waitcnt lgkmcnt(12)
	v_pk_fma_f32 v[112:113], v[0:1], v[166:167], v[112:113] op_sel:[0,1,0] neg_lo:[1,0,0] neg_hi:[1,0,0]
	v_pk_fma_f32 v[108:109], v[2:3], v[166:167], v[108:109] op_sel_hi:[1,0,1] neg_lo:[1,0,0] neg_hi:[1,0,0]
	v_pk_fma_f32 v[112:113], v[28:29], v[168:169], v[112:113] op_sel:[0,1,0] neg_lo:[1,0,0] neg_hi:[1,0,0]
	v_pk_fma_f32 v[108:109], v[30:31], v[168:169], v[108:109] op_sel_hi:[1,0,1] neg_lo:[1,0,0] neg_hi:[1,0,0]
	ds_read_b128 v[166:169], v20 offset:53840
	s_waitcnt lgkmcnt(12)
	v_pk_fma_f32 v[112:113], v[34:35], v[170:171], v[112:113] op_sel:[0,1,0] neg_lo:[1,0,0] neg_hi:[1,0,0]
	v_pk_fma_f32 v[108:109], v[32:33], v[170:171], v[108:109] op_sel_hi:[1,0,1] neg_lo:[1,0,0] neg_hi:[1,0,0]
	v_pk_fma_f32 v[112:113], v[40:41], v[172:173], v[112:113] op_sel:[0,1,0] neg_lo:[1,0,0] neg_hi:[1,0,0]
	v_pk_fma_f32 v[108:109], v[36:37], v[172:173], v[108:109] op_sel_hi:[1,0,1] neg_lo:[1,0,0] neg_hi:[1,0,0]
	ds_read_b128 v[170:173], v20 offset:53856
	s_waitcnt lgkmcnt(12)
	v_pk_fma_f32 v[112:113], v[42:43], v[174:175], v[112:113] op_sel:[0,1,0] neg_lo:[1,0,0] neg_hi:[1,0,0]
	v_pk_fma_f32 v[108:109], v[38:39], v[174:175], v[108:109] op_sel_hi:[1,0,1] neg_lo:[1,0,0] neg_hi:[1,0,0]
	v_pk_fma_f32 v[112:113], v[46:47], v[176:177], v[112:113] op_sel:[0,1,0] neg_lo:[1,0,0] neg_hi:[1,0,0]
	v_pk_fma_f32 v[108:109], v[44:45], v[176:177], v[108:109] op_sel_hi:[1,0,1] neg_lo:[1,0,0] neg_hi:[1,0,0]
	ds_read_b128 v[174:177], v20 offset:53872
	s_waitcnt lgkmcnt(12)
	v_pk_fma_f32 v[112:113], v[50:51], v[178:179], v[112:113] op_sel:[0,1,0] neg_lo:[1,0,0] neg_hi:[1,0,0]
	v_pk_fma_f32 v[108:109], v[48:49], v[178:179], v[108:109] op_sel_hi:[1,0,1] neg_lo:[1,0,0] neg_hi:[1,0,0]
	v_pk_fma_f32 v[112:113], v[54:55], v[180:181], v[112:113] op_sel:[0,1,0] neg_lo:[1,0,0] neg_hi:[1,0,0]
	v_pk_fma_f32 v[108:109], v[52:53], v[180:181], v[108:109] op_sel_hi:[1,0,1] neg_lo:[1,0,0] neg_hi:[1,0,0]
	ds_read_b128 v[178:181], v20 offset:53888
	s_waitcnt lgkmcnt(12)
	v_pk_fma_f32 v[112:113], v[58:59], v[182:183], v[112:113] op_sel:[0,1,0] neg_lo:[1,0,0] neg_hi:[1,0,0]
	v_pk_fma_f32 v[108:109], v[56:57], v[182:183], v[108:109] op_sel_hi:[1,0,1] neg_lo:[1,0,0] neg_hi:[1,0,0]
	v_pk_fma_f32 v[112:113], v[62:63], v[184:185], v[112:113] op_sel:[0,1,0] neg_lo:[1,0,0] neg_hi:[1,0,0]
	v_pk_fma_f32 v[108:109], v[60:61], v[184:185], v[108:109] op_sel_hi:[1,0,1] neg_lo:[1,0,0] neg_hi:[1,0,0]
	ds_read_b128 v[182:185], v20 offset:53904
	s_waitcnt lgkmcnt(12)
	v_pk_fma_f32 v[112:113], v[66:67], v[208:209], v[112:113] op_sel:[0,1,0] neg_lo:[1,0,0] neg_hi:[1,0,0]
	v_pk_fma_f32 v[108:109], v[64:65], v[208:209], v[108:109] op_sel_hi:[1,0,1] neg_lo:[1,0,0] neg_hi:[1,0,0]
	v_pk_fma_f32 v[112:113], v[70:71], v[210:211], v[112:113] op_sel:[0,1,0] neg_lo:[1,0,0] neg_hi:[1,0,0]
	v_pk_fma_f32 v[108:109], v[68:69], v[210:211], v[108:109] op_sel_hi:[1,0,1] neg_lo:[1,0,0] neg_hi:[1,0,0]
	ds_read_b128 v[208:211], v20 offset:53920
	s_waitcnt lgkmcnt(12)
	v_pk_fma_f32 v[112:113], v[74:75], v[212:213], v[112:113] op_sel:[0,1,0] neg_lo:[1,0,0] neg_hi:[1,0,0]
	v_pk_fma_f32 v[108:109], v[72:73], v[212:213], v[108:109] op_sel_hi:[1,0,1] neg_lo:[1,0,0] neg_hi:[1,0,0]
	v_pk_fma_f32 v[112:113], v[78:79], v[214:215], v[112:113] op_sel:[0,1,0] neg_lo:[1,0,0] neg_hi:[1,0,0]
	v_pk_fma_f32 v[108:109], v[76:77], v[214:215], v[108:109] op_sel_hi:[1,0,1] neg_lo:[1,0,0] neg_hi:[1,0,0]
	ds_read_b128 v[212:215], v20 offset:53936
	s_waitcnt lgkmcnt(12)
	v_pk_fma_f32 v[112:113], v[82:83], v[216:217], v[112:113] op_sel:[0,1,0] neg_lo:[1,0,0] neg_hi:[1,0,0]
	v_pk_fma_f32 v[108:109], v[80:81], v[216:217], v[108:109] op_sel_hi:[1,0,1] neg_lo:[1,0,0] neg_hi:[1,0,0]
	v_pk_fma_f32 v[112:113], v[88:89], v[218:219], v[112:113] op_sel:[0,1,0] neg_lo:[1,0,0] neg_hi:[1,0,0]
	v_pk_fma_f32 v[108:109], v[86:87], v[218:219], v[108:109] op_sel_hi:[1,0,1] neg_lo:[1,0,0] neg_hi:[1,0,0]
	ds_read_b128 v[216:219], v20 offset:53952
	s_waitcnt lgkmcnt(12)
	v_pk_fma_f32 v[112:113], v[92:93], v[220:221], v[112:113] op_sel:[0,1,0] neg_lo:[1,0,0] neg_hi:[1,0,0]
	v_pk_fma_f32 v[108:109], v[90:91], v[220:221], v[108:109] op_sel_hi:[1,0,1] neg_lo:[1,0,0] neg_hi:[1,0,0]
	v_pk_fma_f32 v[112:113], v[96:97], v[222:223], v[112:113] op_sel:[0,1,0] neg_lo:[1,0,0] neg_hi:[1,0,0]
	v_pk_fma_f32 v[108:109], v[94:95], v[222:223], v[108:109] op_sel_hi:[1,0,1] neg_lo:[1,0,0] neg_hi:[1,0,0]
	ds_read_b128 v[220:223], v20 offset:53968
	s_waitcnt lgkmcnt(12)
	v_pk_fma_f32 v[112:113], v[100:101], v[224:225], v[112:113] op_sel:[0,1,0] neg_lo:[1,0,0] neg_hi:[1,0,0]
	v_pk_fma_f32 v[108:109], v[98:99], v[224:225], v[108:109] op_sel_hi:[1,0,1] neg_lo:[1,0,0] neg_hi:[1,0,0]
	v_pk_fma_f32 v[112:113], v[104:105], v[226:227], v[112:113] op_sel:[0,1,0] neg_lo:[1,0,0] neg_hi:[1,0,0]
	v_pk_fma_f32 v[108:109], v[102:103], v[226:227], v[108:109] op_sel_hi:[1,0,1] neg_lo:[1,0,0] neg_hi:[1,0,0]
	ds_read_b128 v[224:227], v20 offset:53984
	v_pk_fma_f32 v[112:113], v[148:149], v[228:229], v[112:113] op_sel:[0,1,0] neg_lo:[1,0,0] neg_hi:[1,0,0]
	ds_read_b128 v[146:149], v20 offset:53776
	v_pk_fma_f32 v[108:109], v[228:229], v[106:107], v[108:109] op_sel_hi:[0,1,1] neg_lo:[1,0,0] neg_hi:[1,0,0]
	v_pk_fma_f32 v[112:113], v[142:143], v[230:231], v[112:113] op_sel:[0,1,0] neg_lo:[1,0,0] neg_hi:[1,0,0]
	v_pk_fma_f32 v[108:109], v[144:145], v[230:231], v[108:109] op_sel_hi:[1,0,1] neg_lo:[1,0,0] neg_hi:[1,0,0]
	s_nop 0
	v_pk_add_f32 v[108:109], v[108:109], v[112:113]
	ds_read_b128 v[110:113], v20 offset:53760
	s_waitcnt lgkmcnt(0)
	v_pk_fma_f32 v[162:163], v[138:139], v[110:111], 0 op_sel:[0,1,0] op_sel_hi:[1,1,0] neg_lo:[1,0,0] neg_hi:[1,0,0]
	v_pk_fma_f32 v[110:111], v[128:129], v[110:111], v[144:145] op_sel_hi:[1,0,1] neg_lo:[1,0,0] neg_hi:[1,0,0]
	v_pk_fma_f32 v[162:163], v[134:135], v[112:113], v[162:163] op_sel:[0,1,0] neg_lo:[1,0,0] neg_hi:[1,0,0]
	v_pk_fma_f32 v[110:111], v[136:137], v[112:113], v[110:111] op_sel_hi:[1,0,1] neg_lo:[1,0,0] neg_hi:[1,0,0]
	v_pk_fma_f32 v[162:163], v[130:131], v[146:147], v[162:163] op_sel:[0,1,0] neg_lo:[1,0,0] neg_hi:[1,0,0]
	v_pk_fma_f32 v[110:111], v[132:133], v[146:147], v[110:111] op_sel_hi:[1,0,1] neg_lo:[1,0,0] neg_hi:[1,0,0]
	v_pk_fma_f32 v[162:163], v[84:85], v[148:149], v[162:163] op_sel:[0,1,0] neg_lo:[1,0,0] neg_hi:[1,0,0]
	v_pk_fma_f32 v[110:111], v[122:123], v[148:149], v[110:111] op_sel_hi:[1,0,1] neg_lo:[1,0,0] neg_hi:[1,0,0]
	v_pk_fma_f32 v[162:163], v[10:11], v[150:151], v[162:163] op_sel:[0,1,0] neg_lo:[1,0,0] neg_hi:[1,0,0]
	v_pk_fma_f32 v[110:111], v[14:15], v[150:151], v[110:111] op_sel_hi:[1,0,1] neg_lo:[1,0,0] neg_hi:[1,0,0]
	ds_read_b128 v[148:151], v20 offset:54032
	v_pk_fma_f32 v[162:163], v[6:7], v[152:153], v[162:163] op_sel:[0,1,0] neg_lo:[1,0,0] neg_hi:[1,0,0]
	v_pk_fma_f32 v[110:111], v[16:17], v[152:153], v[110:111] op_sel_hi:[1,0,1] neg_lo:[1,0,0] neg_hi:[1,0,0]
	v_pk_fma_f32 v[162:163], v[12:13], v[154:155], v[162:163] op_sel:[0,1,0] neg_lo:[1,0,0] neg_hi:[1,0,0]
	v_pk_fma_f32 v[110:111], v[18:19], v[154:155], v[110:111] op_sel_hi:[1,0,1] neg_lo:[1,0,0] neg_hi:[1,0,0]
	ds_read_b128 v[152:155], v20 offset:54048
	v_pk_fma_f32 v[162:163], v[4:5], v[156:157], v[162:163] op_sel:[0,1,0] neg_lo:[1,0,0] neg_hi:[1,0,0]
	v_pk_fma_f32 v[110:111], v[8:9], v[156:157], v[110:111] op_sel_hi:[1,0,1] neg_lo:[1,0,0] neg_hi:[1,0,0]
	v_pk_fma_f32 v[162:163], v[0:1], v[158:159], v[162:163] op_sel:[0,1,0] neg_lo:[1,0,0] neg_hi:[1,0,0]
	v_pk_fma_f32 v[110:111], v[2:3], v[158:159], v[110:111] op_sel_hi:[1,0,1] neg_lo:[1,0,0] neg_hi:[1,0,0]
	ds_read_b128 v[156:159], v20 offset:54064
	v_pk_fma_f32 v[162:163], v[28:29], v[160:161], v[162:163] op_sel:[0,1,0] neg_lo:[1,0,0] neg_hi:[1,0,0]
	v_pk_fma_f32 v[110:111], v[30:31], v[160:161], v[110:111] op_sel_hi:[1,0,1] neg_lo:[1,0,0] neg_hi:[1,0,0]
	v_pk_fma_f32 v[162:163], v[34:35], v[166:167], v[162:163] op_sel:[0,1,0] neg_lo:[1,0,0] neg_hi:[1,0,0]
	v_pk_fma_f32 v[110:111], v[32:33], v[166:167], v[110:111] op_sel_hi:[1,0,1] neg_lo:[1,0,0] neg_hi:[1,0,0]
	v_pk_fma_f32 v[162:163], v[40:41], v[168:169], v[162:163] op_sel:[0,1,0] neg_lo:[1,0,0] neg_hi:[1,0,0]
	v_pk_fma_f32 v[110:111], v[36:37], v[168:169], v[110:111] op_sel_hi:[1,0,1] neg_lo:[1,0,0] neg_hi:[1,0,0]
	ds_read_b128 v[166:169], v20 offset:54096
	v_pk_fma_f32 v[162:163], v[42:43], v[170:171], v[162:163] op_sel:[0,1,0] neg_lo:[1,0,0] neg_hi:[1,0,0]
	v_pk_fma_f32 v[110:111], v[38:39], v[170:171], v[110:111] op_sel_hi:[1,0,1] neg_lo:[1,0,0] neg_hi:[1,0,0]
	v_pk_fma_f32 v[162:163], v[46:47], v[172:173], v[162:163] op_sel:[0,1,0] neg_lo:[1,0,0] neg_hi:[1,0,0]
	v_pk_fma_f32 v[110:111], v[44:45], v[172:173], v[110:111] op_sel_hi:[1,0,1] neg_lo:[1,0,0] neg_hi:[1,0,0]
	ds_read_b128 v[170:173], v20 offset:54112
	v_pk_fma_f32 v[162:163], v[50:51], v[174:175], v[162:163] op_sel:[0,1,0] neg_lo:[1,0,0] neg_hi:[1,0,0]
	v_pk_fma_f32 v[110:111], v[48:49], v[174:175], v[110:111] op_sel_hi:[1,0,1] neg_lo:[1,0,0] neg_hi:[1,0,0]
	v_pk_fma_f32 v[162:163], v[54:55], v[176:177], v[162:163] op_sel:[0,1,0] neg_lo:[1,0,0] neg_hi:[1,0,0]
	v_pk_fma_f32 v[110:111], v[52:53], v[176:177], v[110:111] op_sel_hi:[1,0,1] neg_lo:[1,0,0] neg_hi:[1,0,0]
	ds_read_b128 v[174:177], v20 offset:54128
	v_pk_fma_f32 v[162:163], v[58:59], v[178:179], v[162:163] op_sel:[0,1,0] neg_lo:[1,0,0] neg_hi:[1,0,0]
	v_pk_fma_f32 v[110:111], v[56:57], v[178:179], v[110:111] op_sel_hi:[1,0,1] neg_lo:[1,0,0] neg_hi:[1,0,0]
	v_pk_fma_f32 v[162:163], v[62:63], v[180:181], v[162:163] op_sel:[0,1,0] neg_lo:[1,0,0] neg_hi:[1,0,0]
	v_pk_fma_f32 v[110:111], v[60:61], v[180:181], v[110:111] op_sel_hi:[1,0,1] neg_lo:[1,0,0] neg_hi:[1,0,0]
	ds_read_b128 v[178:181], v20 offset:54144
	v_pk_fma_f32 v[162:163], v[66:67], v[182:183], v[162:163] op_sel:[0,1,0] neg_lo:[1,0,0] neg_hi:[1,0,0]
	v_pk_fma_f32 v[110:111], v[64:65], v[182:183], v[110:111] op_sel_hi:[1,0,1] neg_lo:[1,0,0] neg_hi:[1,0,0]
	v_pk_fma_f32 v[162:163], v[70:71], v[184:185], v[162:163] op_sel:[0,1,0] neg_lo:[1,0,0] neg_hi:[1,0,0]
	v_pk_fma_f32 v[110:111], v[68:69], v[184:185], v[110:111] op_sel_hi:[1,0,1] neg_lo:[1,0,0] neg_hi:[1,0,0]
	ds_read_b128 v[182:185], v20 offset:54160
	v_pk_fma_f32 v[162:163], v[74:75], v[208:209], v[162:163] op_sel:[0,1,0] neg_lo:[1,0,0] neg_hi:[1,0,0]
	v_pk_fma_f32 v[110:111], v[72:73], v[208:209], v[110:111] op_sel_hi:[1,0,1] neg_lo:[1,0,0] neg_hi:[1,0,0]
	v_pk_fma_f32 v[162:163], v[78:79], v[210:211], v[162:163] op_sel:[0,1,0] neg_lo:[1,0,0] neg_hi:[1,0,0]
	v_pk_fma_f32 v[110:111], v[76:77], v[210:211], v[110:111] op_sel_hi:[1,0,1] neg_lo:[1,0,0] neg_hi:[1,0,0]
	ds_read_b128 v[208:211], v20 offset:54176
	v_pk_fma_f32 v[162:163], v[82:83], v[212:213], v[162:163] op_sel:[0,1,0] neg_lo:[1,0,0] neg_hi:[1,0,0]
	v_pk_fma_f32 v[110:111], v[80:81], v[212:213], v[110:111] op_sel_hi:[1,0,1] neg_lo:[1,0,0] neg_hi:[1,0,0]
	v_pk_fma_f32 v[162:163], v[88:89], v[214:215], v[162:163] op_sel:[0,1,0] neg_lo:[1,0,0] neg_hi:[1,0,0]
	v_pk_fma_f32 v[110:111], v[86:87], v[214:215], v[110:111] op_sel_hi:[1,0,1] neg_lo:[1,0,0] neg_hi:[1,0,0]
	ds_read_b128 v[212:215], v20 offset:54192
	v_pk_fma_f32 v[162:163], v[92:93], v[216:217], v[162:163] op_sel:[0,1,0] neg_lo:[1,0,0] neg_hi:[1,0,0]
	v_pk_fma_f32 v[110:111], v[90:91], v[216:217], v[110:111] op_sel_hi:[1,0,1] neg_lo:[1,0,0] neg_hi:[1,0,0]
	v_pk_fma_f32 v[162:163], v[96:97], v[218:219], v[162:163] op_sel:[0,1,0] neg_lo:[1,0,0] neg_hi:[1,0,0]
	v_pk_fma_f32 v[110:111], v[94:95], v[218:219], v[110:111] op_sel_hi:[1,0,1] neg_lo:[1,0,0] neg_hi:[1,0,0]
	ds_read_b128 v[216:219], v20 offset:54208
	v_pk_fma_f32 v[162:163], v[100:101], v[220:221], v[162:163] op_sel:[0,1,0] neg_lo:[1,0,0] neg_hi:[1,0,0]
	v_pk_fma_f32 v[110:111], v[98:99], v[220:221], v[110:111] op_sel_hi:[1,0,1] neg_lo:[1,0,0] neg_hi:[1,0,0]
	v_pk_fma_f32 v[162:163], v[104:105], v[222:223], v[162:163] op_sel:[0,1,0] neg_lo:[1,0,0] neg_hi:[1,0,0]
	v_pk_fma_f32 v[110:111], v[102:103], v[222:223], v[110:111] op_sel_hi:[1,0,1] neg_lo:[1,0,0] neg_hi:[1,0,0]
	ds_read_b128 v[220:223], v20 offset:54224
	v_pk_fma_f32 v[162:163], v[224:225], v[108:109], v[162:163] op_sel:[1,0,0] neg_lo:[1,0,0] neg_hi:[1,0,0]
	v_pk_fma_f32 v[110:111], v[106:107], v[224:225], v[110:111] op_sel_hi:[1,0,1] neg_lo:[1,0,0] neg_hi:[1,0,0]
	v_pk_fma_f32 v[162:163], v[142:143], v[226:227], v[162:163] op_sel:[0,1,0] neg_lo:[1,0,0] neg_hi:[1,0,0]
	v_pk_fma_f32 v[110:111], v[144:145], v[226:227], v[110:111] op_sel_hi:[1,0,1] neg_lo:[1,0,0] neg_hi:[1,0,0]
	ds_read_b128 v[144:147], v20 offset:54016
	ds_read_b128 v[224:227], v20 offset:54240
	v_pk_add_f32 v[110:111], v[110:111], v[162:163]
	ds_read_b128 v[160:163], v20 offset:54080
	s_waitcnt lgkmcnt(2)
	v_pk_fma_f32 v[112:113], v[138:139], v[144:145], 0 op_sel:[0,1,0] op_sel_hi:[1,1,0] neg_lo:[1,0,0] neg_hi:[1,0,0]
	v_pk_fma_f32 v[252:253], v[128:129], v[144:145], v[142:143] op_sel_hi:[1,0,1] neg_lo:[1,0,0] neg_hi:[1,0,0]
	v_pk_fma_f32 v[112:113], v[134:135], v[146:147], v[112:113] op_sel:[0,1,0] neg_lo:[1,0,0] neg_hi:[1,0,0]
	v_pk_fma_f32 v[252:253], v[136:137], v[146:147], v[252:253] op_sel_hi:[1,0,1] neg_lo:[1,0,0] neg_hi:[1,0,0]
	v_pk_fma_f32 v[112:113], v[130:131], v[148:149], v[112:113] op_sel:[0,1,0] neg_lo:[1,0,0] neg_hi:[1,0,0]
	v_pk_fma_f32 v[252:253], v[132:133], v[148:149], v[252:253] op_sel_hi:[1,0,1] neg_lo:[1,0,0] neg_hi:[1,0,0]
	v_pk_fma_f32 v[112:113], v[84:85], v[150:151], v[112:113] op_sel:[0,1,0] neg_lo:[1,0,0] neg_hi:[1,0,0]
	ds_read_b128 v[146:149], v20 offset:54288
	v_pk_fma_f32 v[112:113], v[10:11], v[152:153], v[112:113] op_sel:[0,1,0] neg_lo:[1,0,0] neg_hi:[1,0,0]
	v_pk_fma_f32 v[252:253], v[122:123], v[150:151], v[252:253] op_sel_hi:[1,0,1] neg_lo:[1,0,0] neg_hi:[1,0,0]
	v_pk_fma_f32 v[112:113], v[6:7], v[154:155], v[112:113] op_sel:[0,1,0] neg_lo:[1,0,0] neg_hi:[1,0,0]
	v_pk_fma_f32 v[252:253], v[14:15], v[152:153], v[252:253] op_sel_hi:[1,0,1] neg_lo:[1,0,0] neg_hi:[1,0,0]
	v_pk_fma_f32 v[112:113], v[12:13], v[156:157], v[112:113] op_sel:[0,1,0] neg_lo:[1,0,0] neg_hi:[1,0,0]
	ds_read_b128 v[150:153], v20 offset:54304
	v_pk_fma_f32 v[112:113], v[4:5], v[158:159], v[112:113] op_sel:[0,1,0] neg_lo:[1,0,0] neg_hi:[1,0,0]
	v_pk_fma_f32 v[252:253], v[16:17], v[154:155], v[252:253] op_sel_hi:[1,0,1] neg_lo:[1,0,0] neg_hi:[1,0,0]
	s_waitcnt lgkmcnt(2)
	v_pk_fma_f32 v[112:113], v[0:1], v[160:161], v[112:113] op_sel:[0,1,0] neg_lo:[1,0,0] neg_hi:[1,0,0]
	v_pk_fma_f32 v[252:253], v[18:19], v[156:157], v[252:253] op_sel_hi:[1,0,1] neg_lo:[1,0,0] neg_hi:[1,0,0]
	v_pk_fma_f32 v[112:113], v[28:29], v[162:163], v[112:113] op_sel:[0,1,0] neg_lo:[1,0,0] neg_hi:[1,0,0]
	ds_read_b128 v[154:157], v20 offset:54320
	v_pk_fma_f32 v[112:113], v[34:35], v[166:167], v[112:113] op_sel:[0,1,0] neg_lo:[1,0,0] neg_hi:[1,0,0]
	v_pk_fma_f32 v[252:253], v[8:9], v[158:159], v[252:253] op_sel_hi:[1,0,1] neg_lo:[1,0,0] neg_hi:[1,0,0]
	v_pk_fma_f32 v[112:113], v[40:41], v[168:169], v[112:113] op_sel:[0,1,0] neg_lo:[1,0,0] neg_hi:[1,0,0]
	v_pk_fma_f32 v[252:253], v[2:3], v[160:161], v[252:253] op_sel_hi:[1,0,1] neg_lo:[1,0,0] neg_hi:[1,0,0]
	v_pk_fma_f32 v[112:113], v[42:43], v[170:171], v[112:113] op_sel:[0,1,0] neg_lo:[1,0,0] neg_hi:[1,0,0]
	ds_read_b128 v[158:161], v20 offset:54336
	v_pk_fma_f32 v[112:113], v[46:47], v[172:173], v[112:113] op_sel:[0,1,0] neg_lo:[1,0,0] neg_hi:[1,0,0]
	v_pk_fma_f32 v[252:253], v[30:31], v[162:163], v[252:253] op_sel_hi:[1,0,1] neg_lo:[1,0,0] neg_hi:[1,0,0]
	v_pk_fma_f32 v[112:113], v[50:51], v[174:175], v[112:113] op_sel:[0,1,0] neg_lo:[1,0,0] neg_hi:[1,0,0]
	v_pk_fma_f32 v[252:253], v[32:33], v[166:167], v[252:253] op_sel_hi:[1,0,1] neg_lo:[1,0,0] neg_hi:[1,0,0]
	v_pk_fma_f32 v[112:113], v[54:55], v[176:177], v[112:113] op_sel:[0,1,0] neg_lo:[1,0,0] neg_hi:[1,0,0]
	v_pk_fma_f32 v[252:253], v[36:37], v[168:169], v[252:253] op_sel_hi:[1,0,1] neg_lo:[1,0,0] neg_hi:[1,0,0]
	v_pk_fma_f32 v[112:113], v[58:59], v[178:179], v[112:113] op_sel:[0,1,0] neg_lo:[1,0,0] neg_hi:[1,0,0]
	ds_read_b128 v[166:169], v20 offset:54352
	v_pk_fma_f32 v[112:113], v[62:63], v[180:181], v[112:113] op_sel:[0,1,0] neg_lo:[1,0,0] neg_hi:[1,0,0]
	v_pk_fma_f32 v[252:253], v[38:39], v[170:171], v[252:253] op_sel_hi:[1,0,1] neg_lo:[1,0,0] neg_hi:[1,0,0]
	v_pk_fma_f32 v[112:113], v[66:67], v[182:183], v[112:113] op_sel:[0,1,0] neg_lo:[1,0,0] neg_hi:[1,0,0]
	v_pk_fma_f32 v[252:253], v[44:45], v[172:173], v[252:253] op_sel_hi:[1,0,1] neg_lo:[1,0,0] neg_hi:[1,0,0]
	v_pk_fma_f32 v[112:113], v[70:71], v[184:185], v[112:113] op_sel:[0,1,0] neg_lo:[1,0,0] neg_hi:[1,0,0]
	ds_read_b128 v[170:173], v20 offset:54368
	v_pk_fma_f32 v[112:113], v[74:75], v[208:209], v[112:113] op_sel:[0,1,0] neg_lo:[1,0,0] neg_hi:[1,0,0]
	v_pk_fma_f32 v[252:253], v[48:49], v[174:175], v[252:253] op_sel_hi:[1,0,1] neg_lo:[1,0,0] neg_hi:[1,0,0]
	v_pk_fma_f32 v[112:113], v[78:79], v[210:211], v[112:113] op_sel:[0,1,0] neg_lo:[1,0,0] neg_hi:[1,0,0]
	v_pk_fma_f32 v[252:253], v[52:53], v[176:177], v[252:253] op_sel_hi:[1,0,1] neg_lo:[1,0,0] neg_hi:[1,0,0]
	v_pk_fma_f32 v[112:113], v[82:83], v[212:213], v[112:113] op_sel:[0,1,0] neg_lo:[1,0,0] neg_hi:[1,0,0]
	ds_read_b128 v[174:177], v20 offset:54384
	v_pk_fma_f32 v[112:113], v[88:89], v[214:215], v[112:113] op_sel:[0,1,0] neg_lo:[1,0,0] neg_hi:[1,0,0]
	v_pk_fma_f32 v[252:253], v[56:57], v[178:179], v[252:253] op_sel_hi:[1,0,1] neg_lo:[1,0,0] neg_hi:[1,0,0]
	v_pk_fma_f32 v[112:113], v[92:93], v[216:217], v[112:113] op_sel:[0,1,0] neg_lo:[1,0,0] neg_hi:[1,0,0]
	v_pk_fma_f32 v[252:253], v[60:61], v[180:181], v[252:253] op_sel_hi:[1,0,1] neg_lo:[1,0,0] neg_hi:[1,0,0]
	ds_read_b128 v[178:181], v20 offset:54400
	v_pk_fma_f32 v[112:113], v[96:97], v[218:219], v[112:113] op_sel:[0,1,0] neg_lo:[1,0,0] neg_hi:[1,0,0]
	v_pk_fma_f32 v[252:253], v[64:65], v[182:183], v[252:253] op_sel_hi:[1,0,1] neg_lo:[1,0,0] neg_hi:[1,0,0]
	v_pk_fma_f32 v[112:113], v[100:101], v[220:221], v[112:113] op_sel:[0,1,0] neg_lo:[1,0,0] neg_hi:[1,0,0]
	v_pk_fma_f32 v[252:253], v[68:69], v[184:185], v[252:253] op_sel_hi:[1,0,1] neg_lo:[1,0,0] neg_hi:[1,0,0]
	ds_read_b128 v[182:185], v20 offset:54416
	v_pk_fma_f32 v[112:113], v[104:105], v[222:223], v[112:113] op_sel:[0,1,0] neg_lo:[1,0,0] neg_hi:[1,0,0]
	v_pk_fma_f32 v[252:253], v[72:73], v[208:209], v[252:253] op_sel_hi:[1,0,1] neg_lo:[1,0,0] neg_hi:[1,0,0]
	v_pk_fma_f32 v[112:113], v[108:109], v[224:225], v[112:113] op_sel:[0,1,0] neg_lo:[1,0,0] neg_hi:[1,0,0]
	v_pk_fma_f32 v[252:253], v[76:77], v[210:211], v[252:253] op_sel_hi:[1,0,1] neg_lo:[1,0,0] neg_hi:[1,0,0]
	ds_read_b128 v[208:211], v20 offset:54432
	v_pk_fma_f32 v[112:113], v[142:143], v[226:227], v[112:113] op_sel:[0,1,0] neg_lo:[1,0,0] neg_hi:[1,0,0]
	ds_read_b128 v[142:145], v20 offset:54272
	v_pk_fma_f32 v[252:253], v[80:81], v[212:213], v[252:253] op_sel_hi:[1,0,1] neg_lo:[1,0,0] neg_hi:[1,0,0]
	s_waitcnt lgkmcnt(0)
	v_pk_fma_f32 v[162:163], v[138:139], v[142:143], 0 op_sel:[0,1,0] op_sel_hi:[1,1,0] neg_lo:[1,0,0] neg_hi:[1,0,0]
	v_pk_fma_f32 v[252:253], v[86:87], v[214:215], v[252:253] op_sel_hi:[1,0,1] neg_lo:[1,0,0] neg_hi:[1,0,0]
	ds_read_b128 v[212:215], v20 offset:54448
	v_pk_fma_f32 v[252:253], v[90:91], v[216:217], v[252:253] op_sel_hi:[1,0,1] neg_lo:[1,0,0] neg_hi:[1,0,0]
	v_pk_mul_f32 v[142:143], v[128:129], v[142:143] op_sel_hi:[1,0]
	v_pk_fma_f32 v[252:253], v[94:95], v[218:219], v[252:253] op_sel_hi:[1,0,1] neg_lo:[1,0,0] neg_hi:[1,0,0]
	ds_read_b128 v[216:219], v20 offset:54464
	v_pk_fma_f32 v[252:253], v[98:99], v[220:221], v[252:253] op_sel_hi:[1,0,1] neg_lo:[1,0,0] neg_hi:[1,0,0]
	v_pk_fma_f32 v[114:115], v[114:115], v[140:141], v[142:143] neg_lo:[0,0,1] neg_hi:[0,0,1]
	v_pk_fma_f32 v[252:253], v[102:103], v[222:223], v[252:253] op_sel_hi:[1,0,1] neg_lo:[1,0,0] neg_hi:[1,0,0]
	ds_read_b128 v[220:223], v20 offset:54480
	v_pk_fma_f32 v[252:253], v[106:107], v[224:225], v[252:253] op_sel_hi:[1,0,1] neg_lo:[1,0,0] neg_hi:[1,0,0]
	v_pk_fma_f32 v[162:163], v[134:135], v[144:145], v[162:163] op_sel:[0,1,0] neg_lo:[1,0,0] neg_hi:[1,0,0]
	v_pk_fma_f32 v[252:253], v[226:227], v[110:111], v[252:253] op_sel_hi:[0,1,1] neg_lo:[1,0,0] neg_hi:[1,0,0]
	ds_read_b128 v[224:227], v20 offset:54496
	v_pk_add_f32 v[112:113], v[252:253], v[112:113]
	v_pk_fma_f32 v[114:115], v[136:137], v[144:145], v[114:115] op_sel_hi:[1,0,1] neg_lo:[1,0,0] neg_hi:[1,0,0]
	v_pk_fma_f32 v[162:163], v[130:131], v[146:147], v[162:163] op_sel:[0,1,0] neg_lo:[1,0,0] neg_hi:[1,0,0]
	v_pk_fma_f32 v[114:115], v[132:133], v[146:147], v[114:115] op_sel_hi:[1,0,1] neg_lo:[1,0,0] neg_hi:[1,0,0]
	v_pk_fma_f32 v[162:163], v[84:85], v[148:149], v[162:163] op_sel:[0,1,0] neg_lo:[1,0,0] neg_hi:[1,0,0]
	v_pk_fma_f32 v[114:115], v[122:123], v[148:149], v[114:115] op_sel_hi:[1,0,1] neg_lo:[1,0,0] neg_hi:[1,0,0]
	ds_read_b128 v[140:143], v20 offset:54528
	v_pk_fma_f32 v[162:163], v[10:11], v[150:151], v[162:163] op_sel:[0,1,0] neg_lo:[1,0,0] neg_hi:[1,0,0]
	ds_read_b128 v[144:147], v20 offset:54544
	v_pk_fma_f32 v[114:115], v[14:15], v[150:151], v[114:115] op_sel_hi:[1,0,1] neg_lo:[1,0,0] neg_hi:[1,0,0]
	ds_read_b128 v[148:151], v20 offset:54560
	v_pk_fma_f32 v[162:163], v[6:7], v[152:153], v[162:163] op_sel:[0,1,0] neg_lo:[1,0,0] neg_hi:[1,0,0]
	v_pk_fma_f32 v[114:115], v[16:17], v[152:153], v[114:115] op_sel_hi:[1,0,1] neg_lo:[1,0,0] neg_hi:[1,0,0]
	v_pk_fma_f32 v[162:163], v[12:13], v[154:155], v[162:163] op_sel:[0,1,0] neg_lo:[1,0,0] neg_hi:[1,0,0]
	v_pk_fma_f32 v[114:115], v[18:19], v[154:155], v[114:115] op_sel_hi:[1,0,1] neg_lo:[1,0,0] neg_hi:[1,0,0]
	ds_read_b128 v[152:155], v20 offset:54576
	v_pk_fma_f32 v[162:163], v[4:5], v[156:157], v[162:163] op_sel:[0,1,0] neg_lo:[1,0,0] neg_hi:[1,0,0]
	v_pk_fma_f32 v[114:115], v[8:9], v[156:157], v[114:115] op_sel_hi:[1,0,1] neg_lo:[1,0,0] neg_hi:[1,0,0]
	v_pk_fma_f32 v[162:163], v[0:1], v[158:159], v[162:163] op_sel:[0,1,0] neg_lo:[1,0,0] neg_hi:[1,0,0]
	v_pk_fma_f32 v[114:115], v[2:3], v[158:159], v[114:115] op_sel_hi:[1,0,1] neg_lo:[1,0,0] neg_hi:[1,0,0]
	ds_read_b128 v[156:159], v20 offset:54592
	v_pk_fma_f32 v[162:163], v[28:29], v[160:161], v[162:163] op_sel:[0,1,0] neg_lo:[1,0,0] neg_hi:[1,0,0]
	v_pk_fma_f32 v[114:115], v[30:31], v[160:161], v[114:115] op_sel_hi:[1,0,1] neg_lo:[1,0,0] neg_hi:[1,0,0]
	v_pk_fma_f32 v[162:163], v[34:35], v[166:167], v[162:163] op_sel:[0,1,0] neg_lo:[1,0,0] neg_hi:[1,0,0]
	v_pk_fma_f32 v[114:115], v[32:33], v[166:167], v[114:115] op_sel_hi:[1,0,1] neg_lo:[1,0,0] neg_hi:[1,0,0]
	v_pk_fma_f32 v[162:163], v[40:41], v[168:169], v[162:163] op_sel:[0,1,0] neg_lo:[1,0,0] neg_hi:[1,0,0]
	v_pk_fma_f32 v[114:115], v[36:37], v[168:169], v[114:115] op_sel_hi:[1,0,1] neg_lo:[1,0,0] neg_hi:[1,0,0]
	ds_read_b128 v[166:169], v20 offset:54624
	v_pk_fma_f32 v[162:163], v[42:43], v[170:171], v[162:163] op_sel:[0,1,0] neg_lo:[1,0,0] neg_hi:[1,0,0]
	v_pk_fma_f32 v[114:115], v[38:39], v[170:171], v[114:115] op_sel_hi:[1,0,1] neg_lo:[1,0,0] neg_hi:[1,0,0]
	v_pk_fma_f32 v[162:163], v[46:47], v[172:173], v[162:163] op_sel:[0,1,0] neg_lo:[1,0,0] neg_hi:[1,0,0]
	v_pk_fma_f32 v[114:115], v[44:45], v[172:173], v[114:115] op_sel_hi:[1,0,1] neg_lo:[1,0,0] neg_hi:[1,0,0]
	ds_read_b128 v[170:173], v20 offset:54640
	v_pk_fma_f32 v[162:163], v[50:51], v[174:175], v[162:163] op_sel:[0,1,0] neg_lo:[1,0,0] neg_hi:[1,0,0]
	v_pk_fma_f32 v[114:115], v[48:49], v[174:175], v[114:115] op_sel_hi:[1,0,1] neg_lo:[1,0,0] neg_hi:[1,0,0]
	v_pk_fma_f32 v[162:163], v[54:55], v[176:177], v[162:163] op_sel:[0,1,0] neg_lo:[1,0,0] neg_hi:[1,0,0]
	v_pk_fma_f32 v[114:115], v[52:53], v[176:177], v[114:115] op_sel_hi:[1,0,1] neg_lo:[1,0,0] neg_hi:[1,0,0]
	ds_read_b128 v[174:177], v20 offset:54656
	v_pk_fma_f32 v[162:163], v[58:59], v[178:179], v[162:163] op_sel:[0,1,0] neg_lo:[1,0,0] neg_hi:[1,0,0]
	v_pk_fma_f32 v[114:115], v[56:57], v[178:179], v[114:115] op_sel_hi:[1,0,1] neg_lo:[1,0,0] neg_hi:[1,0,0]
	v_pk_fma_f32 v[162:163], v[62:63], v[180:181], v[162:163] op_sel:[0,1,0] neg_lo:[1,0,0] neg_hi:[1,0,0]
	v_pk_fma_f32 v[114:115], v[60:61], v[180:181], v[114:115] op_sel_hi:[1,0,1] neg_lo:[1,0,0] neg_hi:[1,0,0]
	ds_read_b128 v[178:181], v20 offset:54672
	v_pk_fma_f32 v[162:163], v[66:67], v[182:183], v[162:163] op_sel:[0,1,0] neg_lo:[1,0,0] neg_hi:[1,0,0]
	v_pk_fma_f32 v[114:115], v[64:65], v[182:183], v[114:115] op_sel_hi:[1,0,1] neg_lo:[1,0,0] neg_hi:[1,0,0]
	v_pk_fma_f32 v[162:163], v[70:71], v[184:185], v[162:163] op_sel:[0,1,0] neg_lo:[1,0,0] neg_hi:[1,0,0]
	v_pk_fma_f32 v[114:115], v[68:69], v[184:185], v[114:115] op_sel_hi:[1,0,1] neg_lo:[1,0,0] neg_hi:[1,0,0]
	ds_read_b128 v[182:185], v20 offset:54688
	v_pk_fma_f32 v[162:163], v[74:75], v[208:209], v[162:163] op_sel:[0,1,0] neg_lo:[1,0,0] neg_hi:[1,0,0]
	v_pk_fma_f32 v[114:115], v[72:73], v[208:209], v[114:115] op_sel_hi:[1,0,1] neg_lo:[1,0,0] neg_hi:[1,0,0]
	v_pk_fma_f32 v[162:163], v[78:79], v[210:211], v[162:163] op_sel:[0,1,0] neg_lo:[1,0,0] neg_hi:[1,0,0]
	v_pk_fma_f32 v[114:115], v[76:77], v[210:211], v[114:115] op_sel_hi:[1,0,1] neg_lo:[1,0,0] neg_hi:[1,0,0]
	ds_read_b128 v[208:211], v20 offset:54704
	s_waitcnt lgkmcnt(14)
	v_pk_fma_f32 v[162:163], v[82:83], v[212:213], v[162:163] op_sel:[0,1,0] neg_lo:[1,0,0] neg_hi:[1,0,0]
	v_pk_fma_f32 v[114:115], v[80:81], v[212:213], v[114:115] op_sel_hi:[1,0,1] neg_lo:[1,0,0] neg_hi:[1,0,0]
	v_pk_fma_f32 v[162:163], v[88:89], v[214:215], v[162:163] op_sel:[0,1,0] neg_lo:[1,0,0] neg_hi:[1,0,0]
	v_pk_fma_f32 v[114:115], v[86:87], v[214:215], v[114:115] op_sel_hi:[1,0,1] neg_lo:[1,0,0] neg_hi:[1,0,0]
	ds_read_b128 v[212:215], v20 offset:54720
	s_waitcnt lgkmcnt(14)
	v_pk_fma_f32 v[162:163], v[92:93], v[216:217], v[162:163] op_sel:[0,1,0] neg_lo:[1,0,0] neg_hi:[1,0,0]
	v_pk_fma_f32 v[114:115], v[90:91], v[216:217], v[114:115] op_sel_hi:[1,0,1] neg_lo:[1,0,0] neg_hi:[1,0,0]
	v_pk_fma_f32 v[162:163], v[96:97], v[218:219], v[162:163] op_sel:[0,1,0] neg_lo:[1,0,0] neg_hi:[1,0,0]
	v_pk_fma_f32 v[114:115], v[94:95], v[218:219], v[114:115] op_sel_hi:[1,0,1] neg_lo:[1,0,0] neg_hi:[1,0,0]
	ds_read_b128 v[216:219], v20 offset:54736
	s_waitcnt lgkmcnt(14)
	v_pk_fma_f32 v[162:163], v[100:101], v[220:221], v[162:163] op_sel:[0,1,0] neg_lo:[1,0,0] neg_hi:[1,0,0]
	v_pk_fma_f32 v[114:115], v[98:99], v[220:221], v[114:115] op_sel_hi:[1,0,1] neg_lo:[1,0,0] neg_hi:[1,0,0]
	v_pk_fma_f32 v[162:163], v[104:105], v[222:223], v[162:163] op_sel:[0,1,0] neg_lo:[1,0,0] neg_hi:[1,0,0]
	v_pk_fma_f32 v[114:115], v[102:103], v[222:223], v[114:115] op_sel_hi:[1,0,1] neg_lo:[1,0,0] neg_hi:[1,0,0]
	ds_read_b128 v[220:223], v20 offset:54752
	s_waitcnt lgkmcnt(14)
	v_pk_fma_f32 v[162:163], v[108:109], v[224:225], v[162:163] op_sel:[0,1,0] neg_lo:[1,0,0] neg_hi:[1,0,0]
	v_pk_fma_f32 v[114:115], v[106:107], v[224:225], v[114:115] op_sel_hi:[1,0,1] neg_lo:[1,0,0] neg_hi:[1,0,0]
	v_pk_fma_f32 v[162:163], v[226:227], v[112:113], v[162:163] op_sel:[1,0,0] neg_lo:[1,0,0] neg_hi:[1,0,0]
	v_pk_fma_f32 v[114:115], v[110:111], v[226:227], v[114:115] op_sel_hi:[1,0,1] neg_lo:[1,0,0] neg_hi:[1,0,0]
	ds_read_b128 v[224:227], v20 offset:54768
	v_pk_add_f32 v[114:115], v[114:115], v[162:163]
	s_waitcnt lgkmcnt(14)
	v_pk_fma_f32 v[186:187], v[138:139], v[140:141], 0 op_sel:[0,1,0] op_sel_hi:[1,1,0] neg_lo:[1,0,0] neg_hi:[1,0,0]
	ds_read_b128 v[160:163], v20 offset:54608
	v_pk_fma_f32 v[186:187], v[134:135], v[142:143], v[186:187] op_sel:[0,1,0] neg_lo:[1,0,0] neg_hi:[1,0,0]
	v_pk_fma_f32 v[252:253], v[128:129], v[140:141], v[116:117] op_sel_hi:[1,0,1] neg_lo:[1,0,0] neg_hi:[1,0,0]
	s_waitcnt lgkmcnt(14)
	v_pk_fma_f32 v[186:187], v[130:131], v[144:145], v[186:187] op_sel:[0,1,0] neg_lo:[1,0,0] neg_hi:[1,0,0]
	v_pk_fma_f32 v[252:253], v[136:137], v[142:143], v[252:253] op_sel_hi:[1,0,1] neg_lo:[1,0,0] neg_hi:[1,0,0]
	v_pk_fma_f32 v[186:187], v[84:85], v[146:147], v[186:187] op_sel:[0,1,0] neg_lo:[1,0,0] neg_hi:[1,0,0]
	ds_read_b128 v[140:143], v20 offset:54784
	s_waitcnt lgkmcnt(14)
	v_pk_fma_f32 v[186:187], v[10:11], v[148:149], v[186:187] op_sel:[0,1,0] neg_lo:[1,0,0] neg_hi:[1,0,0]
	v_pk_fma_f32 v[252:253], v[132:133], v[144:145], v[252:253] op_sel_hi:[1,0,1] neg_lo:[1,0,0] neg_hi:[1,0,0]
	v_pk_fma_f32 v[186:187], v[6:7], v[150:151], v[186:187] op_sel:[0,1,0] neg_lo:[1,0,0] neg_hi:[1,0,0]
	v_pk_fma_f32 v[252:253], v[122:123], v[146:147], v[252:253] op_sel_hi:[1,0,1] neg_lo:[1,0,0] neg_hi:[1,0,0]
	s_waitcnt lgkmcnt(13)
	v_pk_fma_f32 v[186:187], v[12:13], v[152:153], v[186:187] op_sel:[0,1,0] neg_lo:[1,0,0] neg_hi:[1,0,0]
	ds_read_b128 v[144:147], v20 offset:54800
	v_pk_fma_f32 v[186:187], v[4:5], v[154:155], v[186:187] op_sel:[0,1,0] neg_lo:[1,0,0] neg_hi:[1,0,0]
	v_pk_fma_f32 v[252:253], v[14:15], v[148:149], v[252:253] op_sel_hi:[1,0,1] neg_lo:[1,0,0] neg_hi:[1,0,0]
	s_waitcnt lgkmcnt(13)
	v_pk_fma_f32 v[186:187], v[0:1], v[156:157], v[186:187] op_sel:[0,1,0] neg_lo:[1,0,0] neg_hi:[1,0,0]
	v_pk_fma_f32 v[252:253], v[16:17], v[150:151], v[252:253] op_sel_hi:[1,0,1] neg_lo:[1,0,0] neg_hi:[1,0,0]
	v_pk_fma_f32 v[186:187], v[28:29], v[158:159], v[186:187] op_sel:[0,1,0] neg_lo:[1,0,0] neg_hi:[1,0,0]
	ds_read_b128 v[148:151], v20 offset:54816
	s_waitcnt lgkmcnt(3)
	v_pk_fma_f32 v[186:187], v[34:35], v[160:161], v[186:187] op_sel:[0,1,0] neg_lo:[1,0,0] neg_hi:[1,0,0]
	v_pk_fma_f32 v[252:253], v[18:19], v[152:153], v[252:253] op_sel_hi:[1,0,1] neg_lo:[1,0,0] neg_hi:[1,0,0]
	v_pk_fma_f32 v[186:187], v[40:41], v[162:163], v[186:187] op_sel:[0,1,0] neg_lo:[1,0,0] neg_hi:[1,0,0]
	v_pk_fma_f32 v[252:253], v[8:9], v[154:155], v[252:253] op_sel_hi:[1,0,1] neg_lo:[1,0,0] neg_hi:[1,0,0]
	v_pk_fma_f32 v[186:187], v[42:43], v[166:167], v[186:187] op_sel:[0,1,0] neg_lo:[1,0,0] neg_hi:[1,0,0]
	ds_read_b128 v[152:155], v20 offset:54832
	v_pk_fma_f32 v[186:187], v[46:47], v[168:169], v[186:187] op_sel:[0,1,0] neg_lo:[1,0,0] neg_hi:[1,0,0]
	v_pk_fma_f32 v[252:253], v[2:3], v[156:157], v[252:253] op_sel_hi:[1,0,1] neg_lo:[1,0,0] neg_hi:[1,0,0]
	v_pk_fma_f32 v[186:187], v[50:51], v[170:171], v[186:187] op_sel:[0,1,0] neg_lo:[1,0,0] neg_hi:[1,0,0]
	v_pk_fma_f32 v[252:253], v[30:31], v[158:159], v[252:253] op_sel_hi:[1,0,1] neg_lo:[1,0,0] neg_hi:[1,0,0]
	v_pk_fma_f32 v[186:187], v[54:55], v[172:173], v[186:187] op_sel:[0,1,0] neg_lo:[1,0,0] neg_hi:[1,0,0]
	ds_read_b128 v[156:159], v20 offset:54848
	v_pk_fma_f32 v[186:187], v[58:59], v[174:175], v[186:187] op_sel:[0,1,0] neg_lo:[1,0,0] neg_hi:[1,0,0]
	v_pk_fma_f32 v[252:253], v[32:33], v[160:161], v[252:253] op_sel_hi:[1,0,1] neg_lo:[1,0,0] neg_hi:[1,0,0]
	v_pk_fma_f32 v[186:187], v[62:63], v[176:177], v[186:187] op_sel:[0,1,0] neg_lo:[1,0,0] neg_hi:[1,0,0]
	v_pk_fma_f32 v[252:253], v[36:37], v[162:163], v[252:253] op_sel_hi:[1,0,1] neg_lo:[1,0,0] neg_hi:[1,0,0]
	v_pk_fma_f32 v[186:187], v[66:67], v[178:179], v[186:187] op_sel:[0,1,0] neg_lo:[1,0,0] neg_hi:[1,0,0]
	ds_read_b128 v[160:163], v20 offset:54864
	v_pk_fma_f32 v[186:187], v[70:71], v[180:181], v[186:187] op_sel:[0,1,0] neg_lo:[1,0,0] neg_hi:[1,0,0]
	v_pk_fma_f32 v[252:253], v[38:39], v[166:167], v[252:253] op_sel_hi:[1,0,1] neg_lo:[1,0,0] neg_hi:[1,0,0]
	v_pk_fma_f32 v[186:187], v[74:75], v[182:183], v[186:187] op_sel:[0,1,0] neg_lo:[1,0,0] neg_hi:[1,0,0]
	v_pk_fma_f32 v[252:253], v[44:45], v[168:169], v[252:253] op_sel_hi:[1,0,1] neg_lo:[1,0,0] neg_hi:[1,0,0]
	v_pk_fma_f32 v[186:187], v[78:79], v[184:185], v[186:187] op_sel:[0,1,0] neg_lo:[1,0,0] neg_hi:[1,0,0]
	ds_read_b128 v[166:169], v20 offset:54880
	v_pk_fma_f32 v[186:187], v[82:83], v[208:209], v[186:187] op_sel:[0,1,0] neg_lo:[1,0,0] neg_hi:[1,0,0]
	v_pk_fma_f32 v[252:253], v[48:49], v[170:171], v[252:253] op_sel_hi:[1,0,1] neg_lo:[1,0,0] neg_hi:[1,0,0]
	v_pk_fma_f32 v[186:187], v[88:89], v[210:211], v[186:187] op_sel:[0,1,0] neg_lo:[1,0,0] neg_hi:[1,0,0]
	v_pk_fma_f32 v[252:253], v[52:53], v[172:173], v[252:253] op_sel_hi:[1,0,1] neg_lo:[1,0,0] neg_hi:[1,0,0]
	v_pk_fma_f32 v[186:187], v[92:93], v[212:213], v[186:187] op_sel:[0,1,0] neg_lo:[1,0,0] neg_hi:[1,0,0]
	ds_read_b128 v[170:173], v20 offset:54896
	v_pk_fma_f32 v[186:187], v[96:97], v[214:215], v[186:187] op_sel:[0,1,0] neg_lo:[1,0,0] neg_hi:[1,0,0]
	v_pk_fma_f32 v[252:253], v[56:57], v[174:175], v[252:253] op_sel_hi:[1,0,1] neg_lo:[1,0,0] neg_hi:[1,0,0]
	v_pk_fma_f32 v[186:187], v[100:101], v[216:217], v[186:187] op_sel:[0,1,0] neg_lo:[1,0,0] neg_hi:[1,0,0]
	v_pk_fma_f32 v[252:253], v[60:61], v[176:177], v[252:253] op_sel_hi:[1,0,1] neg_lo:[1,0,0] neg_hi:[1,0,0]
	ds_read_b128 v[174:177], v20 offset:54912
	v_pk_fma_f32 v[186:187], v[104:105], v[218:219], v[186:187] op_sel:[0,1,0] neg_lo:[1,0,0] neg_hi:[1,0,0]
	v_pk_fma_f32 v[252:253], v[64:65], v[178:179], v[252:253] op_sel_hi:[1,0,1] neg_lo:[1,0,0] neg_hi:[1,0,0]
	v_pk_fma_f32 v[186:187], v[108:109], v[220:221], v[186:187] op_sel:[0,1,0] neg_lo:[1,0,0] neg_hi:[1,0,0]
	v_pk_fma_f32 v[252:253], v[68:69], v[180:181], v[252:253] op_sel_hi:[1,0,1] neg_lo:[1,0,0] neg_hi:[1,0,0]
	ds_read_b128 v[178:181], v20 offset:54928
	v_pk_fma_f32 v[186:187], v[112:113], v[222:223], v[186:187] op_sel:[0,1,0] neg_lo:[1,0,0] neg_hi:[1,0,0]
	v_pk_fma_f32 v[252:253], v[72:73], v[182:183], v[252:253] op_sel_hi:[1,0,1] neg_lo:[1,0,0] neg_hi:[1,0,0]
	v_pk_fma_f32 v[186:187], v[116:117], v[224:225], v[186:187] op_sel:[0,1,0] neg_lo:[1,0,0] neg_hi:[1,0,0]
	v_pk_fma_f32 v[252:253], v[76:77], v[184:185], v[252:253] op_sel_hi:[1,0,1] neg_lo:[1,0,0] neg_hi:[1,0,0]
	ds_read_b128 v[182:185], v20 offset:54944
	v_pk_fma_f32 v[186:187], v[120:121], v[226:227], v[186:187] op_sel:[0,1,0] neg_lo:[1,0,0] neg_hi:[1,0,0]
	v_pk_fma_f32 v[252:253], v[80:81], v[208:209], v[252:253] op_sel_hi:[1,0,1] neg_lo:[1,0,0] neg_hi:[1,0,0]
	s_nop 0
	v_pk_fma_f32 v[252:253], v[86:87], v[210:211], v[252:253] op_sel_hi:[1,0,1] neg_lo:[1,0,0] neg_hi:[1,0,0]
	ds_read_b128 v[208:211], v20 offset:54960
	v_pk_fma_f32 v[252:253], v[90:91], v[212:213], v[252:253] op_sel_hi:[1,0,1] neg_lo:[1,0,0] neg_hi:[1,0,0]
	s_nop 0
	v_pk_fma_f32 v[252:253], v[94:95], v[214:215], v[252:253] op_sel_hi:[1,0,1] neg_lo:[1,0,0] neg_hi:[1,0,0]
	ds_read_b128 v[212:215], v20 offset:54976
	v_pk_fma_f32 v[252:253], v[98:99], v[216:217], v[252:253] op_sel_hi:[1,0,1] neg_lo:[1,0,0] neg_hi:[1,0,0]
	s_nop 0
	v_pk_fma_f32 v[252:253], v[102:103], v[218:219], v[252:253] op_sel_hi:[1,0,1] neg_lo:[1,0,0] neg_hi:[1,0,0]
	ds_read_b128 v[216:219], v20 offset:54992
	v_pk_fma_f32 v[252:253], v[106:107], v[220:221], v[252:253] op_sel_hi:[1,0,1] neg_lo:[1,0,0] neg_hi:[1,0,0]
	s_nop 0
	v_pk_fma_f32 v[252:253], v[110:111], v[222:223], v[252:253] op_sel_hi:[1,0,1] neg_lo:[1,0,0] neg_hi:[1,0,0]
	ds_read_b128 v[220:223], v20 offset:55008
	v_pk_fma_f32 v[252:253], v[224:225], v[114:115], v[252:253] op_sel_hi:[0,1,1] neg_lo:[1,0,0] neg_hi:[1,0,0]
	s_nop 0
	v_pk_fma_f32 v[252:253], v[118:119], v[226:227], v[252:253] op_sel_hi:[1,0,1] neg_lo:[1,0,0] neg_hi:[1,0,0]
	s_nop 0
	v_pk_add_f32 v[116:117], v[252:253], v[186:187]
	s_waitcnt lgkmcnt(14)
	v_pk_fma_f32 v[186:187], v[138:139], v[140:141], 0 op_sel:[0,1,0] op_sel_hi:[1,1,0] neg_lo:[1,0,0] neg_hi:[1,0,0]
	ds_read_b128 v[224:227], v20 offset:55024
	v_pk_fma_f32 v[140:141], v[128:129], v[140:141], v[118:119] op_sel_hi:[1,0,1] neg_lo:[1,0,0] neg_hi:[1,0,0]
	v_pk_fma_f32 v[186:187], v[134:135], v[142:143], v[186:187] op_sel:[0,1,0] neg_lo:[1,0,0] neg_hi:[1,0,0]
	v_pk_fma_f32 v[140:141], v[136:137], v[142:143], v[140:141] op_sel_hi:[1,0,1] neg_lo:[1,0,0] neg_hi:[1,0,0]
	s_waitcnt lgkmcnt(14)
	v_pk_fma_f32 v[186:187], v[130:131], v[144:145], v[186:187] op_sel:[0,1,0] neg_lo:[1,0,0] neg_hi:[1,0,0]
	v_pk_fma_f32 v[140:141], v[132:133], v[144:145], v[140:141] op_sel_hi:[1,0,1] neg_lo:[1,0,0] neg_hi:[1,0,0]
	v_pk_fma_f32 v[186:187], v[84:85], v[146:147], v[186:187] op_sel:[0,1,0] neg_lo:[1,0,0] neg_hi:[1,0,0]
	v_pk_fma_f32 v[140:141], v[122:123], v[146:147], v[140:141] op_sel_hi:[1,0,1] neg_lo:[1,0,0] neg_hi:[1,0,0]
	s_waitcnt lgkmcnt(13)
	v_pk_fma_f32 v[186:187], v[10:11], v[148:149], v[186:187] op_sel:[0,1,0] neg_lo:[1,0,0] neg_hi:[1,0,0]
	v_pk_fma_f32 v[140:141], v[14:15], v[148:149], v[140:141] op_sel_hi:[1,0,1] neg_lo:[1,0,0] neg_hi:[1,0,0]
	v_pk_fma_f32 v[186:187], v[6:7], v[150:151], v[186:187] op_sel:[0,1,0] neg_lo:[1,0,0] neg_hi:[1,0,0]
	v_pk_fma_f32 v[140:141], v[16:17], v[150:151], v[140:141] op_sel_hi:[1,0,1] neg_lo:[1,0,0] neg_hi:[1,0,0]
	ds_read_b128 v[144:147], v20 offset:55056
	ds_read_b128 v[148:151], v20 offset:55072
	s_waitcnt lgkmcnt(14)
	v_pk_fma_f32 v[186:187], v[12:13], v[152:153], v[186:187] op_sel:[0,1,0] neg_lo:[1,0,0] neg_hi:[1,0,0]
	v_pk_fma_f32 v[140:141], v[18:19], v[152:153], v[140:141] op_sel_hi:[1,0,1] neg_lo:[1,0,0] neg_hi:[1,0,0]
	v_pk_fma_f32 v[186:187], v[4:5], v[154:155], v[186:187] op_sel:[0,1,0] neg_lo:[1,0,0] neg_hi:[1,0,0]
	v_pk_fma_f32 v[140:141], v[8:9], v[154:155], v[140:141] op_sel_hi:[1,0,1] neg_lo:[1,0,0] neg_hi:[1,0,0]
	ds_read_b128 v[152:155], v20 offset:55088
	s_waitcnt lgkmcnt(14)
	v_pk_fma_f32 v[186:187], v[0:1], v[156:157], v[186:187] op_sel:[0,1,0] neg_lo:[1,0,0] neg_hi:[1,0,0]
	v_pk_fma_f32 v[140:141], v[2:3], v[156:157], v[140:141] op_sel_hi:[1,0,1] neg_lo:[1,0,0] neg_hi:[1,0,0]
	v_pk_fma_f32 v[186:187], v[28:29], v[158:159], v[186:187] op_sel:[0,1,0] neg_lo:[1,0,0] neg_hi:[1,0,0]
	v_pk_fma_f32 v[140:141], v[30:31], v[158:159], v[140:141] op_sel_hi:[1,0,1] neg_lo:[1,0,0] neg_hi:[1,0,0]
	ds_read_b128 v[156:159], v20 offset:55104
	s_waitcnt lgkmcnt(14)
	v_pk_fma_f32 v[186:187], v[34:35], v[160:161], v[186:187] op_sel:[0,1,0] neg_lo:[1,0,0] neg_hi:[1,0,0]
	v_pk_fma_f32 v[140:141], v[32:33], v[160:161], v[140:141] op_sel_hi:[1,0,1] neg_lo:[1,0,0] neg_hi:[1,0,0]
	v_pk_fma_f32 v[186:187], v[40:41], v[162:163], v[186:187] op_sel:[0,1,0] neg_lo:[1,0,0] neg_hi:[1,0,0]
	v_pk_fma_f32 v[140:141], v[36:37], v[162:163], v[140:141] op_sel_hi:[1,0,1] neg_lo:[1,0,0] neg_hi:[1,0,0]
	ds_read_b128 v[160:163], v20 offset:55120
	s_waitcnt lgkmcnt(14)
	v_pk_fma_f32 v[186:187], v[42:43], v[166:167], v[186:187] op_sel:[0,1,0] neg_lo:[1,0,0] neg_hi:[1,0,0]
	v_pk_fma_f32 v[140:141], v[38:39], v[166:167], v[140:141] op_sel_hi:[1,0,1] neg_lo:[1,0,0] neg_hi:[1,0,0]
	v_pk_fma_f32 v[186:187], v[46:47], v[168:169], v[186:187] op_sel:[0,1,0] neg_lo:[1,0,0] neg_hi:[1,0,0]
	v_pk_fma_f32 v[140:141], v[44:45], v[168:169], v[140:141] op_sel_hi:[1,0,1] neg_lo:[1,0,0] neg_hi:[1,0,0]
	ds_read_b128 v[166:169], v20 offset:55136
	s_waitcnt lgkmcnt(14)
	v_pk_fma_f32 v[186:187], v[50:51], v[170:171], v[186:187] op_sel:[0,1,0] neg_lo:[1,0,0] neg_hi:[1,0,0]
	v_pk_fma_f32 v[140:141], v[48:49], v[170:171], v[140:141] op_sel_hi:[1,0,1] neg_lo:[1,0,0] neg_hi:[1,0,0]
	v_pk_fma_f32 v[186:187], v[54:55], v[172:173], v[186:187] op_sel:[0,1,0] neg_lo:[1,0,0] neg_hi:[1,0,0]
	v_pk_fma_f32 v[140:141], v[52:53], v[172:173], v[140:141] op_sel_hi:[1,0,1] neg_lo:[1,0,0] neg_hi:[1,0,0]
	ds_read_b128 v[170:173], v20 offset:55152
	s_waitcnt lgkmcnt(14)
	v_pk_fma_f32 v[186:187], v[58:59], v[174:175], v[186:187] op_sel:[0,1,0] neg_lo:[1,0,0] neg_hi:[1,0,0]
	v_pk_fma_f32 v[140:141], v[56:57], v[174:175], v[140:141] op_sel_hi:[1,0,1] neg_lo:[1,0,0] neg_hi:[1,0,0]
	v_pk_fma_f32 v[186:187], v[62:63], v[176:177], v[186:187] op_sel:[0,1,0] neg_lo:[1,0,0] neg_hi:[1,0,0]
	v_pk_fma_f32 v[140:141], v[60:61], v[176:177], v[140:141] op_sel_hi:[1,0,1] neg_lo:[1,0,0] neg_hi:[1,0,0]
	ds_read_b128 v[174:177], v20 offset:55168
	s_waitcnt lgkmcnt(14)
	v_pk_fma_f32 v[186:187], v[66:67], v[178:179], v[186:187] op_sel:[0,1,0] neg_lo:[1,0,0] neg_hi:[1,0,0]
	v_pk_fma_f32 v[140:141], v[64:65], v[178:179], v[140:141] op_sel_hi:[1,0,1] neg_lo:[1,0,0] neg_hi:[1,0,0]
	v_pk_fma_f32 v[186:187], v[70:71], v[180:181], v[186:187] op_sel:[0,1,0] neg_lo:[1,0,0] neg_hi:[1,0,0]
	v_pk_fma_f32 v[140:141], v[68:69], v[180:181], v[140:141] op_sel_hi:[1,0,1] neg_lo:[1,0,0] neg_hi:[1,0,0]
	ds_read_b128 v[178:181], v20 offset:55184
	s_waitcnt lgkmcnt(14)
	v_pk_fma_f32 v[186:187], v[74:75], v[182:183], v[186:187] op_sel:[0,1,0] neg_lo:[1,0,0] neg_hi:[1,0,0]
	v_pk_fma_f32 v[140:141], v[72:73], v[182:183], v[140:141] op_sel_hi:[1,0,1] neg_lo:[1,0,0] neg_hi:[1,0,0]
	v_pk_fma_f32 v[186:187], v[78:79], v[184:185], v[186:187] op_sel:[0,1,0] neg_lo:[1,0,0] neg_hi:[1,0,0]
	v_pk_fma_f32 v[140:141], v[76:77], v[184:185], v[140:141] op_sel_hi:[1,0,1] neg_lo:[1,0,0] neg_hi:[1,0,0]
	ds_read_b128 v[182:185], v20 offset:55200
	s_waitcnt lgkmcnt(14)
	v_pk_fma_f32 v[186:187], v[82:83], v[208:209], v[186:187] op_sel:[0,1,0] neg_lo:[1,0,0] neg_hi:[1,0,0]
	v_pk_fma_f32 v[140:141], v[80:81], v[208:209], v[140:141] op_sel_hi:[1,0,1] neg_lo:[1,0,0] neg_hi:[1,0,0]
	v_pk_fma_f32 v[186:187], v[88:89], v[210:211], v[186:187] op_sel:[0,1,0] neg_lo:[1,0,0] neg_hi:[1,0,0]
	v_pk_fma_f32 v[140:141], v[86:87], v[210:211], v[140:141] op_sel_hi:[1,0,1] neg_lo:[1,0,0] neg_hi:[1,0,0]
	ds_read_b128 v[208:211], v20 offset:55216
	s_waitcnt lgkmcnt(14)
	v_pk_fma_f32 v[186:187], v[92:93], v[212:213], v[186:187] op_sel:[0,1,0] neg_lo:[1,0,0] neg_hi:[1,0,0]
	v_pk_fma_f32 v[140:141], v[90:91], v[212:213], v[140:141] op_sel_hi:[1,0,1] neg_lo:[1,0,0] neg_hi:[1,0,0]
	v_pk_fma_f32 v[186:187], v[96:97], v[214:215], v[186:187] op_sel:[0,1,0] neg_lo:[1,0,0] neg_hi:[1,0,0]
	v_pk_fma_f32 v[140:141], v[94:95], v[214:215], v[140:141] op_sel_hi:[1,0,1] neg_lo:[1,0,0] neg_hi:[1,0,0]
	ds_read_b128 v[212:215], v20 offset:55232
	s_waitcnt lgkmcnt(14)
	v_pk_fma_f32 v[186:187], v[100:101], v[216:217], v[186:187] op_sel:[0,1,0] neg_lo:[1,0,0] neg_hi:[1,0,0]
	v_pk_fma_f32 v[140:141], v[98:99], v[216:217], v[140:141] op_sel_hi:[1,0,1] neg_lo:[1,0,0] neg_hi:[1,0,0]
	v_pk_fma_f32 v[186:187], v[104:105], v[218:219], v[186:187] op_sel:[0,1,0] neg_lo:[1,0,0] neg_hi:[1,0,0]
	v_pk_fma_f32 v[140:141], v[102:103], v[218:219], v[140:141] op_sel_hi:[1,0,1] neg_lo:[1,0,0] neg_hi:[1,0,0]
	ds_read_b128 v[216:219], v20 offset:55248
	s_waitcnt lgkmcnt(14)
	v_pk_fma_f32 v[186:187], v[108:109], v[220:221], v[186:187] op_sel:[0,1,0] neg_lo:[1,0,0] neg_hi:[1,0,0]
	v_pk_fma_f32 v[140:141], v[106:107], v[220:221], v[140:141] op_sel_hi:[1,0,1] neg_lo:[1,0,0] neg_hi:[1,0,0]
	v_pk_fma_f32 v[186:187], v[112:113], v[222:223], v[186:187] op_sel:[0,1,0] neg_lo:[1,0,0] neg_hi:[1,0,0]
	v_pk_fma_f32 v[140:141], v[110:111], v[222:223], v[140:141] op_sel_hi:[1,0,1] neg_lo:[1,0,0] neg_hi:[1,0,0]
	ds_read_b128 v[220:223], v20 offset:55264
	s_waitcnt lgkmcnt(14)
	v_pk_fma_f32 v[186:187], v[224:225], v[116:117], v[186:187] op_sel:[1,0,0] neg_lo:[1,0,0] neg_hi:[1,0,0]
	v_pk_fma_f32 v[140:141], v[114:115], v[224:225], v[140:141] op_sel_hi:[1,0,1] neg_lo:[1,0,0] neg_hi:[1,0,0]
	v_pk_fma_f32 v[186:187], v[120:121], v[226:227], v[186:187] op_sel:[0,1,0] neg_lo:[1,0,0] neg_hi:[1,0,0]
	v_pk_fma_f32 v[118:119], v[118:119], v[226:227], v[140:141] op_sel_hi:[1,0,1] neg_lo:[1,0,0] neg_hi:[1,0,0]
	ds_read_b128 v[140:143], v20 offset:55040
	v_pk_add_f32 v[118:119], v[118:119], v[186:187]
	s_waitcnt lgkmcnt(0)
	v_pk_fma_f32 v[186:187], v[138:139], v[140:141], 0 op_sel:[0,1,0] op_sel_hi:[1,1,0] neg_lo:[1,0,0] neg_hi:[1,0,0]
	ds_read_b128 v[224:227], v20 offset:55280
	v_pk_fma_f32 v[186:187], v[134:135], v[142:143], v[186:187] op_sel:[0,1,0] neg_lo:[1,0,0] neg_hi:[1,0,0]
	s_nop 0
	v_pk_fma_f32 v[186:187], v[130:131], v[144:145], v[186:187] op_sel:[0,1,0] neg_lo:[1,0,0] neg_hi:[1,0,0]
	s_nop 0
	v_pk_fma_f32 v[186:187], v[84:85], v[146:147], v[186:187] op_sel:[0,1,0] neg_lo:[1,0,0] neg_hi:[1,0,0]
	s_nop 0
	v_pk_fma_f32 v[186:187], v[10:11], v[148:149], v[186:187] op_sel:[0,1,0] neg_lo:[1,0,0] neg_hi:[1,0,0]
	s_nop 0
	v_pk_fma_f32 v[186:187], v[6:7], v[150:151], v[186:187] op_sel:[0,1,0] neg_lo:[1,0,0] neg_hi:[1,0,0]
	s_nop 0
	v_pk_fma_f32 v[186:187], v[12:13], v[152:153], v[186:187] op_sel:[0,1,0] neg_lo:[1,0,0] neg_hi:[1,0,0]
	s_nop 0
	v_pk_fma_f32 v[186:187], v[4:5], v[154:155], v[186:187] op_sel:[0,1,0] neg_lo:[1,0,0] neg_hi:[1,0,0]
	s_nop 0
	v_pk_fma_f32 v[186:187], v[0:1], v[156:157], v[186:187] op_sel:[0,1,0] neg_lo:[1,0,0] neg_hi:[1,0,0]
	s_nop 0
	v_pk_fma_f32 v[186:187], v[28:29], v[158:159], v[186:187] op_sel:[0,1,0] neg_lo:[1,0,0] neg_hi:[1,0,0]
	s_nop 0
	v_pk_fma_f32 v[186:187], v[34:35], v[160:161], v[186:187] op_sel:[0,1,0] neg_lo:[1,0,0] neg_hi:[1,0,0]
	s_nop 0
	v_pk_fma_f32 v[186:187], v[40:41], v[162:163], v[186:187] op_sel:[0,1,0] neg_lo:[1,0,0] neg_hi:[1,0,0]
	s_nop 0
	v_pk_fma_f32 v[186:187], v[42:43], v[166:167], v[186:187] op_sel:[0,1,0] neg_lo:[1,0,0] neg_hi:[1,0,0]
	s_nop 0
	v_pk_fma_f32 v[186:187], v[46:47], v[168:169], v[186:187] op_sel:[0,1,0] neg_lo:[1,0,0] neg_hi:[1,0,0]
	s_nop 0
	v_pk_fma_f32 v[186:187], v[50:51], v[170:171], v[186:187] op_sel:[0,1,0] neg_lo:[1,0,0] neg_hi:[1,0,0]
	s_nop 0
	v_pk_fma_f32 v[186:187], v[54:55], v[172:173], v[186:187] op_sel:[0,1,0] neg_lo:[1,0,0] neg_hi:[1,0,0]
	s_nop 0
	v_pk_fma_f32 v[186:187], v[58:59], v[174:175], v[186:187] op_sel:[0,1,0] neg_lo:[1,0,0] neg_hi:[1,0,0]
	s_nop 0
	v_pk_fma_f32 v[186:187], v[62:63], v[176:177], v[186:187] op_sel:[0,1,0] neg_lo:[1,0,0] neg_hi:[1,0,0]
	s_nop 0
	v_pk_fma_f32 v[186:187], v[66:67], v[178:179], v[186:187] op_sel:[0,1,0] neg_lo:[1,0,0] neg_hi:[1,0,0]
	s_nop 0
	v_pk_fma_f32 v[186:187], v[70:71], v[180:181], v[186:187] op_sel:[0,1,0] neg_lo:[1,0,0] neg_hi:[1,0,0]
	s_nop 0
	v_pk_fma_f32 v[186:187], v[74:75], v[182:183], v[186:187] op_sel:[0,1,0] neg_lo:[1,0,0] neg_hi:[1,0,0]
	s_nop 0
	v_pk_fma_f32 v[186:187], v[78:79], v[184:185], v[186:187] op_sel:[0,1,0] neg_lo:[1,0,0] neg_hi:[1,0,0]
	s_nop 0
	v_pk_fma_f32 v[186:187], v[82:83], v[208:209], v[186:187] op_sel:[0,1,0] neg_lo:[1,0,0] neg_hi:[1,0,0]
	s_nop 0
	v_pk_fma_f32 v[186:187], v[88:89], v[210:211], v[186:187] op_sel:[0,1,0] neg_lo:[1,0,0] neg_hi:[1,0,0]
	s_nop 0
	v_pk_fma_f32 v[186:187], v[92:93], v[212:213], v[186:187] op_sel:[0,1,0] neg_lo:[1,0,0] neg_hi:[1,0,0]
	s_nop 0
	v_pk_fma_f32 v[186:187], v[96:97], v[214:215], v[186:187] op_sel:[0,1,0] neg_lo:[1,0,0] neg_hi:[1,0,0]
	s_nop 0
	v_pk_fma_f32 v[186:187], v[100:101], v[216:217], v[186:187] op_sel:[0,1,0] neg_lo:[1,0,0] neg_hi:[1,0,0]
	s_nop 0
	v_pk_fma_f32 v[186:187], v[104:105], v[218:219], v[186:187] op_sel:[0,1,0] neg_lo:[1,0,0] neg_hi:[1,0,0]
	s_nop 0
	v_pk_fma_f32 v[186:187], v[108:109], v[220:221], v[186:187] op_sel:[0,1,0] neg_lo:[1,0,0] neg_hi:[1,0,0]
	s_nop 0
	v_pk_fma_f32 v[186:187], v[112:113], v[222:223], v[186:187] op_sel:[0,1,0] neg_lo:[1,0,0] neg_hi:[1,0,0]
	s_nop 0
	s_waitcnt lgkmcnt(0)
	v_pk_fma_f32 v[186:187], v[116:117], v[224:225], v[186:187] op_sel:[0,1,0] neg_lo:[1,0,0] neg_hi:[1,0,0]
	s_nop 0
	v_pk_fma_f32 v[186:187], v[120:121], v[226:227], v[186:187] op_sel:[0,1,0] neg_lo:[1,0,0] neg_hi:[1,0,0]
	s_waitcnt lgkmcnt(0)
	v_lshlrev_b32_e32 v20, 1, v127
	v_lshl_add_u64 v[124:125], v[124:125], 0, v[20:21]
	v_mov_b32_e32 v127, v21
	v_pk_fma_f32 v[120:121], v[128:129], v[140:141], v[120:121] op_sel_hi:[1,0,1] neg_lo:[1,0,0] neg_hi:[1,0,0]
	v_lshl_add_u64 v[140:141], v[124:125], 0, v[126:127]
	v_lshlrev_b64 v[124:125], 13, v[22:23]
	v_lshl_add_u64 v[124:125], s[20:21], 0, v[124:125]
	v_lshl_add_u64 v[124:125], v[124:125], 0, v[20:21]
	v_lshl_add_u64 v[124:125], v[124:125], 0, v[126:127]
	v_add_co_u32_e32 v126, vcc, s58, v140
	v_cvt_pk_bf16_f32 v20, v128, s0
	s_nop 0
	v_addc_co_u32_e32 v127, vcc, 0, v141, vcc
	global_store_short v[126:127], v20, off
	v_cvt_pk_bf16_f32 v20, v129, s0
	v_add_co_u32_e32 v126, vcc, s76, v140
	global_store_short v[124:125], v20, off
	v_cvt_pk_bf16_f32 v20, v138, s0
	v_addc_co_u32_e32 v127, vcc, 0, v141, vcc
	global_store_short v[126:127], v20, off
	v_add_co_u32_e32 v126, vcc, s58, v124
	v_cvt_pk_bf16_f32 v20, v139, s0
	s_nop 0
	v_addc_co_u32_e32 v127, vcc, 0, v125, vcc
	global_store_short v[126:127], v20, off
	v_add_co_u32_e32 v126, vcc, s77, v140
	v_cvt_pk_bf16_f32 v20, v136, s0
	s_nop 0
	v_addc_co_u32_e32 v127, vcc, 0, v141, vcc
	global_store_short v[126:127], v20, off
	v_cvt_pk_bf16_f32 v20, v137, s0
	s_movk_i32 s0, 0x4000
	v_add_co_u32_e32 v126, vcc, s0, v124
	v_pk_fma_f32 v[120:121], v[136:137], v[142:143], v[120:121] op_sel_hi:[1,0,1] neg_lo:[1,0,0] neg_hi:[1,0,0]
	s_nop 0
	v_addc_co_u32_e32 v127, vcc, 0, v125, vcc
	global_store_short v[126:127], v20, off
	v_add_co_u32_e32 v126, vcc, s54, v140
	v_cvt_pk_bf16_f32 v20, v134, s0
	s_nop 0
	v_addc_co_u32_e32 v127, vcc, 0, v141, vcc
	global_store_short v[126:127], v20, off
	v_add_co_u32_e32 v126, vcc, s29, v124
	v_cvt_pk_bf16_f32 v20, v135, s0
	s_nop 0
	v_addc_co_u32_e32 v127, vcc, 0, v125, vcc
	global_store_short v[126:127], v20, off
	v_add_co_u32_e32 v126, vcc, s86, v140
	v_cvt_pk_bf16_f32 v20, v132, s0
	s_nop 0
	v_addc_co_u32_e32 v127, vcc, 0, v141, vcc
	global_store_short v[126:127], v20, off
	v_add_co_u32_e32 v126, vcc, s76, v124
	v_cvt_pk_bf16_f32 v20, v133, s0
	s_nop 0
	v_addc_co_u32_e32 v127, vcc, 0, v125, vcc
	global_store_short v[126:127], v20, off
	v_add_co_u32_e32 v126, vcc, s87, v140
	v_cvt_pk_bf16_f32 v20, v130, s0
	s_nop 0
	v_addc_co_u32_e32 v127, vcc, 0, v141, vcc
	global_store_short v[126:127], v20, off
	v_cvt_pk_bf16_f32 v20, v131, s0
	s_mov_b32 s0, 0xa000
	v_add_co_u32_e32 v126, vcc, s0, v124
	v_pk_fma_f32 v[120:121], v[132:133], v[144:145], v[120:121] op_sel_hi:[1,0,1] neg_lo:[1,0,0] neg_hi:[1,0,0]
	s_nop 0
	v_addc_co_u32_e32 v127, vcc, 0, v125, vcc
	global_store_short v[126:127], v20, off
	v_add_co_u32_e32 v126, vcc, s88, v140
	v_pk_fma_f32 v[120:121], v[122:123], v[146:147], v[120:121] op_sel_hi:[1,0,1] neg_lo:[1,0,0] neg_hi:[1,0,0]
	s_nop 0
	v_addc_co_u32_e32 v127, vcc, 0, v141, vcc
	v_cvt_pk_bf16_f32 v20, v122, s0
	v_add_co_u32_e32 v122, vcc, s30, v124
	global_store_short v[126:127], v20, off
	v_cvt_pk_bf16_f32 v20, v123, s0
	v_addc_co_u32_e32 v123, vcc, 0, v125, vcc
	global_store_short v[122:123], v20, off
	v_add_co_u32_e32 v122, vcc, s89, v140
	v_cvt_pk_bf16_f32 v20, v84, s0
	s_nop 0
	v_addc_co_u32_e32 v123, vcc, 0, v141, vcc
	v_add_co_u32_e32 v84, vcc, s77, v124
	global_store_short v[122:123], v20, off
	v_cvt_pk_bf16_f32 v20, v85, s0
	v_addc_co_u32_e32 v85, vcc, 0, v125, vcc
	global_store_short v[84:85], v20, off
	v_add_co_u32_e32 v84, vcc, s90, v140
	v_pk_fma_f32 v[120:121], v[14:15], v[148:149], v[120:121] op_sel_hi:[1,0,1] neg_lo:[1,0,0] neg_hi:[1,0,0]
	v_cvt_pk_bf16_f32 v14, v14, s0
	v_addc_co_u32_e32 v85, vcc, 0, v141, vcc
	v_cvt_pk_bf16_f32 v20, v15, s0
	s_mov_b32 s0, 0x10000
	global_store_short v[84:85], v14, off
	v_add_co_u32_e32 v14, vcc, s0, v124
	v_cvt_pk_bf16_f32 v10, v10, s0
	s_nop 0
	v_addc_co_u32_e32 v15, vcc, 0, v125, vcc
	global_store_short v[14:15], v20, off
	v_add_co_u32_e32 v14, vcc, s91, v140
	v_pk_fma_f32 v[120:121], v[16:17], v[150:151], v[120:121] op_sel_hi:[1,0,1] neg_lo:[1,0,0] neg_hi:[1,0,0]
	s_nop 0
	v_addc_co_u32_e32 v15, vcc, 0, v141, vcc
	global_store_short v[14:15], v10, off
	v_cvt_pk_bf16_f32 v14, v11, s0
	s_mov_b32 s0, 0x12000
	v_add_co_u32_e32 v10, vcc, s0, v124
	v_cvt_pk_bf16_f32 v6, v6, s0
	s_nop 0
	v_addc_co_u32_e32 v11, vcc, 0, v125, vcc
	global_store_short v[10:11], v14, off
	v_add_co_u32_e32 v10, vcc, s92, v140
	v_cvt_pk_bf16_f32 v14, v16, s0
	s_nop 0
	v_addc_co_u32_e32 v11, vcc, 0, v141, vcc
	global_store_short v[10:11], v14, off
	v_add_co_u32_e32 v10, vcc, s54, v124
	v_cvt_pk_bf16_f32 v14, v17, s0
	s_nop 0
	v_addc_co_u32_e32 v11, vcc, 0, v125, vcc
	global_store_short v[10:11], v14, off
	v_add_co_u32_e32 v10, vcc, s93, v140
	v_pk_fma_f32 v[120:121], v[18:19], v[152:153], v[120:121] op_sel_hi:[1,0,1] neg_lo:[1,0,0] neg_hi:[1,0,0]
	s_nop 0
	v_addc_co_u32_e32 v11, vcc, 0, v141, vcc
	global_store_short v[10:11], v6, off
	v_cvt_pk_bf16_f32 v10, v7, s0
	s_mov_b32 s0, 0x16000
	v_add_co_u32_e32 v6, vcc, s0, v124
	v_pk_fma_f32 v[120:121], v[8:9], v[154:155], v[120:121] op_sel_hi:[1,0,1] neg_lo:[1,0,0] neg_hi:[1,0,0]
	s_nop 0
	v_addc_co_u32_e32 v7, vcc, 0, v125, vcc
	global_store_short v[6:7], v10, off
	v_add_co_u32_e32 v6, vcc, s94, v140
	v_cvt_pk_bf16_f32 v10, v18, s0
	s_nop 0
	v_addc_co_u32_e32 v7, vcc, 0, v141, vcc
	global_store_short v[6:7], v10, off
	v_cvt_pk_bf16_f32 v10, v19, s0
	s_mov_b32 s0, 0x18000
	v_add_co_u32_e32 v6, vcc, s0, v124
	v_cvt_pk_bf16_f32 v8, v8, s0
	s_nop 0
	v_addc_co_u32_e32 v7, vcc, 0, v125, vcc
	global_store_short v[6:7], v10, off
	v_add_co_u32_e32 v6, vcc, s95, v140
	v_cvt_pk_bf16_f32 v10, v12, s0
	s_nop 0
	v_addc_co_u32_e32 v7, vcc, 0, v141, vcc
	global_store_short v[6:7], v10, off
	v_add_co_u32_e32 v6, vcc, s86, v124
	v_cvt_pk_bf16_f32 v10, v13, s0
	s_nop 0
	v_addc_co_u32_e32 v7, vcc, 0, v125, vcc
	global_store_short v[6:7], v10, off
	v_add_co_u32_e32 v6, vcc, s96, v140
	v_pk_fma_f32 v[120:121], v[2:3], v[156:157], v[120:121] op_sel_hi:[1,0,1] neg_lo:[1,0,0] neg_hi:[1,0,0]
	s_nop 0
	v_addc_co_u32_e32 v7, vcc, 0, v141, vcc
	global_store_short v[6:7], v8, off
	v_cvt_pk_bf16_f32 v8, v9, s0
	s_mov_b32 s0, 0x1c000
	v_add_co_u32_e32 v6, vcc, s0, v124
	v_cvt_pk_bf16_f32 v4, v4, s0
	s_nop 0
	v_addc_co_u32_e32 v7, vcc, 0, v125, vcc
	global_store_short v[6:7], v8, off
	v_add_co_u32_e32 v6, vcc, s97, v140
	v_cvt_pk_bf16_f32 v2, v2, s0
	s_nop 0
	v_addc_co_u32_e32 v7, vcc, 0, v141, vcc
	global_store_short v[6:7], v4, off
	v_add_co_u32_e32 v4, vcc, s35, v124
	v_cvt_pk_bf16_f32 v6, v5, s0
	s_nop 0
	v_addc_co_u32_e32 v5, vcc, 0, v125, vcc
	global_store_short v[4:5], v6, off
	v_add_co_u32_e32 v4, vcc, s3, v140
	v_cvt_pk_bf16_f32 v0, v0, s0
	s_nop 0
	v_addc_co_u32_e32 v5, vcc, 0, v141, vcc
	global_store_short v[4:5], v2, off
	v_add_co_u32_e32 v2, vcc, s87, v124
	v_cvt_pk_bf16_f32 v4, v3, s0
	s_nop 0
	v_addc_co_u32_e32 v3, vcc, 0, v125, vcc
	global_store_short v[2:3], v4, off
	v_add_co_u32_e32 v2, vcc, s31, v140
	v_pk_fma_f32 v[120:121], v[30:31], v[158:159], v[120:121] op_sel_hi:[1,0,1] neg_lo:[1,0,0] neg_hi:[1,0,0]
	s_nop 0
	v_addc_co_u32_e32 v3, vcc, 0, v141, vcc
	global_store_short v[2:3], v0, off
	v_cvt_pk_bf16_f32 v2, v1, s0
	s_mov_b32 s0, 0x22000
	v_add_co_u32_e32 v0, vcc, s0, v124
	v_pk_fma_f32 v[120:121], v[32:33], v[160:161], v[120:121] op_sel_hi:[1,0,1] neg_lo:[1,0,0] neg_hi:[1,0,0]
	s_nop 0
	v_addc_co_u32_e32 v1, vcc, 0, v125, vcc
	global_store_short v[0:1], v2, off
	v_add_co_u32_e32 v0, vcc, s34, v140
	v_cvt_pk_bf16_f32 v2, v30, s0
	s_nop 0
	v_addc_co_u32_e32 v1, vcc, 0, v141, vcc
	global_store_short v[0:1], v2, off
	v_add_co_u32_e32 v0, vcc, s60, v124
	v_cvt_pk_bf16_f32 v2, v31, s0
	s_nop 0
	v_addc_co_u32_e32 v1, vcc, 0, v125, vcc
	global_store_short v[0:1], v2, off
	v_add_co_u32_e32 v0, vcc, s56, v140
	v_cvt_pk_bf16_f32 v2, v28, s0
	s_nop 0
	v_addc_co_u32_e32 v1, vcc, 0, v141, vcc
	global_store_short v[0:1], v2, off
	v_add_co_u32_e32 v0, vcc, s88, v124
	v_cvt_pk_bf16_f32 v2, v29, s0
	s_nop 0
	v_addc_co_u32_e32 v1, vcc, 0, v125, vcc
	global_store_short v[0:1], v2, off
	v_add_co_u32_e32 v0, vcc, s57, v140
	v_cvt_pk_bf16_f32 v2, v32, s0
	s_nop 0
	v_addc_co_u32_e32 v1, vcc, 0, v141, vcc
	global_store_short v[0:1], v2, off
	v_cvt_pk_bf16_f32 v2, v33, s0
	s_mov_b32 s0, 0x28000
	v_add_co_u32_e32 v0, vcc, s0, v124
	v_pk_fma_f32 v[120:121], v[36:37], v[162:163], v[120:121] op_sel_hi:[1,0,1] neg_lo:[1,0,0] neg_hi:[1,0,0]
	s_nop 0
	v_addc_co_u32_e32 v1, vcc, 0, v125, vcc
	global_store_short v[0:1], v2, off
	v_cvt_pk_bf16_f32 v2, v34, s0
	s_mov_b32 s0, 0x80000
	v_add_co_u32_e32 v0, vcc, s0, v140
	v_pk_fma_f32 v[120:121], v[38:39], v[166:167], v[120:121] op_sel_hi:[1,0,1] neg_lo:[1,0,0] neg_hi:[1,0,0]
	s_nop 0
	v_addc_co_u32_e32 v1, vcc, 0, v141, vcc
	global_store_short v[0:1], v2, off
	v_add_co_u32_e32 v0, vcc, s61, v124
	v_cvt_pk_bf16_f32 v2, v35, s0
	s_nop 0
	v_addc_co_u32_e32 v1, vcc, 0, v125, vcc
	global_store_short v[0:1], v2, off
	v_cvt_pk_bf16_f32 v2, v36, s0
	s_mov_b32 s0, 0x86000
	v_add_co_u32_e32 v0, vcc, s0, v140
	v_pk_fma_f32 v[120:121], v[44:45], v[168:169], v[120:121] op_sel_hi:[1,0,1] neg_lo:[1,0,0] neg_hi:[1,0,0]
	s_nop 0
	v_addc_co_u32_e32 v1, vcc, 0, v141, vcc
	global_store_short v[0:1], v2, off
	v_add_co_u32_e32 v0, vcc, s89, v124
	v_cvt_pk_bf16_f32 v2, v37, s0
	s_nop 0
	v_addc_co_u32_e32 v1, vcc, 0, v125, vcc
	global_store_short v[0:1], v2, off
	v_cvt_pk_bf16_f32 v2, v40, s0
	s_mov_b32 s0, 0x8c000
	v_add_co_u32_e32 v0, vcc, s0, v140
	v_pk_fma_f32 v[120:121], v[48:49], v[170:171], v[120:121] op_sel_hi:[1,0,1] neg_lo:[1,0,0] neg_hi:[1,0,0]
	s_nop 0
	v_addc_co_u32_e32 v1, vcc, 0, v141, vcc
	global_store_short v[0:1], v2, off
	v_cvt_pk_bf16_f32 v2, v41, s0
	s_mov_b32 s0, 0x2e000
	v_add_co_u32_e32 v0, vcc, s0, v124
	v_pk_fma_f32 v[120:121], v[52:53], v[172:173], v[120:121] op_sel_hi:[1,0,1] neg_lo:[1,0,0] neg_hi:[1,0,0]
	s_nop 0
	v_addc_co_u32_e32 v1, vcc, 0, v125, vcc
	global_store_short v[0:1], v2, off
	v_cvt_pk_bf16_f32 v2, v38, s0
	s_mov_b32 s0, 0x92000
	v_add_co_u32_e32 v0, vcc, s0, v140
	v_pk_fma_f32 v[120:121], v[56:57], v[174:175], v[120:121] op_sel_hi:[1,0,1] neg_lo:[1,0,0] neg_hi:[1,0,0]
	s_nop 0
	v_addc_co_u32_e32 v1, vcc, 0, v141, vcc
	global_store_short v[0:1], v2, off
	v_add_co_u32_e32 v0, vcc, s66, v124
	v_cvt_pk_bf16_f32 v2, v39, s0
	s_nop 0
	v_addc_co_u32_e32 v1, vcc, 0, v125, vcc
	global_store_short v[0:1], v2, off
	v_cvt_pk_bf16_f32 v2, v42, s0
	s_mov_b32 s0, 0x98000
	v_add_co_u32_e32 v0, vcc, s0, v140
	v_pk_fma_f32 v[120:121], v[60:61], v[176:177], v[120:121] op_sel_hi:[1,0,1] neg_lo:[1,0,0] neg_hi:[1,0,0]
	s_nop 0
	v_addc_co_u32_e32 v1, vcc, 0, v141, vcc
	global_store_short v[0:1], v2, off
	v_add_co_u32_e32 v0, vcc, s90, v124
	v_cvt_pk_bf16_f32 v2, v43, s0
	s_nop 0
	v_addc_co_u32_e32 v1, vcc, 0, v125, vcc
	global_store_short v[0:1], v2, off
	v_cvt_pk_bf16_f32 v2, v44, s0
	s_mov_b32 s0, 0x9e000
	v_add_co_u32_e32 v0, vcc, s0, v140
	v_pk_fma_f32 v[120:121], v[64:65], v[178:179], v[120:121] op_sel_hi:[1,0,1] neg_lo:[1,0,0] neg_hi:[1,0,0]
	s_nop 0
	v_addc_co_u32_e32 v1, vcc, 0, v141, vcc
	global_store_short v[0:1], v2, off
	v_cvt_pk_bf16_f32 v2, v45, s0
	s_mov_b32 s0, 0x34000
	v_add_co_u32_e32 v0, vcc, s0, v124
	v_pk_fma_f32 v[120:121], v[68:69], v[180:181], v[120:121] op_sel_hi:[1,0,1] neg_lo:[1,0,0] neg_hi:[1,0,0]
	s_nop 0
	v_addc_co_u32_e32 v1, vcc, 0, v125, vcc
	global_store_short v[0:1], v2, off
	v_cvt_pk_bf16_f32 v2, v46, s0
	s_mov_b32 s0, 0xa4000
	v_add_co_u32_e32 v0, vcc, s0, v140
	v_pk_fma_f32 v[120:121], v[72:73], v[182:183], v[120:121] op_sel_hi:[1,0,1] neg_lo:[1,0,0] neg_hi:[1,0,0]
	s_nop 0
	v_addc_co_u32_e32 v1, vcc, 0, v141, vcc
	global_store_short v[0:1], v2, off
	v_add_co_u32_e32 v0, vcc, s67, v124
	v_cvt_pk_bf16_f32 v2, v47, s0
	s_nop 0
	v_addc_co_u32_e32 v1, vcc, 0, v125, vcc
	global_store_short v[0:1], v2, off
	v_cvt_pk_bf16_f32 v2, v48, s0
	s_mov_b32 s0, 0xaa000
	v_add_co_u32_e32 v0, vcc, s0, v140
	v_pk_fma_f32 v[120:121], v[76:77], v[184:185], v[120:121] op_sel_hi:[1,0,1] neg_lo:[1,0,0] neg_hi:[1,0,0]
	s_nop 0
	v_addc_co_u32_e32 v1, vcc, 0, v141, vcc
	global_store_short v[0:1], v2, off
	v_add_co_u32_e32 v0, vcc, s91, v124
	v_cvt_pk_bf16_f32 v2, v49, s0
	s_nop 0
	v_addc_co_u32_e32 v1, vcc, 0, v125, vcc
	global_store_short v[0:1], v2, off
	v_cvt_pk_bf16_f32 v2, v50, s0
	s_mov_b32 s0, 0xb0000
	v_add_co_u32_e32 v0, vcc, s0, v140
	v_pk_fma_f32 v[120:121], v[80:81], v[208:209], v[120:121] op_sel_hi:[1,0,1] neg_lo:[1,0,0] neg_hi:[1,0,0]
	s_nop 0
	v_addc_co_u32_e32 v1, vcc, 0, v141, vcc
	global_store_short v[0:1], v2, off
	v_cvt_pk_bf16_f32 v2, v51, s0
	s_mov_b32 s0, 0x3a000
	v_add_co_u32_e32 v0, vcc, s0, v124
	v_pk_fma_f32 v[120:121], v[86:87], v[210:211], v[120:121] op_sel_hi:[1,0,1] neg_lo:[1,0,0] neg_hi:[1,0,0]
	s_nop 0
	v_addc_co_u32_e32 v1, vcc, 0, v125, vcc
	global_store_short v[0:1], v2, off
	v_cvt_pk_bf16_f32 v2, v52, s0
	s_mov_b32 s0, 0xb6000
	v_add_co_u32_e32 v0, vcc, s0, v140
	v_pk_fma_f32 v[120:121], v[90:91], v[212:213], v[120:121] op_sel_hi:[1,0,1] neg_lo:[1,0,0] neg_hi:[1,0,0]
	s_nop 0
	v_addc_co_u32_e32 v1, vcc, 0, v141, vcc
	global_store_short v[0:1], v2, off
	v_add_co_u32_e32 v0, vcc, s64, v124
	v_cvt_pk_bf16_f32 v2, v53, s0
	s_nop 0
	v_addc_co_u32_e32 v1, vcc, 0, v125, vcc
	global_store_short v[0:1], v2, off
	v_cvt_pk_bf16_f32 v2, v54, s0
	s_mov_b32 s0, 0xbc000
	v_add_co_u32_e32 v0, vcc, s0, v140
	v_pk_fma_f32 v[120:121], v[94:95], v[214:215], v[120:121] op_sel_hi:[1,0,1] neg_lo:[1,0,0] neg_hi:[1,0,0]
	s_nop 0
	v_addc_co_u32_e32 v1, vcc, 0, v141, vcc
	global_store_short v[0:1], v2, off
	v_add_co_u32_e32 v0, vcc, s92, v124
	v_cvt_pk_bf16_f32 v2, v55, s0
	s_nop 0
	v_addc_co_u32_e32 v1, vcc, 0, v125, vcc
	global_store_short v[0:1], v2, off
	v_cvt_pk_bf16_f32 v2, v56, s0
	s_mov_b32 s0, 0xc2000
	v_add_co_u32_e32 v0, vcc, s0, v140
	v_pk_fma_f32 v[120:121], v[98:99], v[216:217], v[120:121] op_sel_hi:[1,0,1] neg_lo:[1,0,0] neg_hi:[1,0,0]
	s_nop 0
	v_addc_co_u32_e32 v1, vcc, 0, v141, vcc
	global_store_short v[0:1], v2, off
	v_cvt_pk_bf16_f32 v2, v57, s0
	s_mov_b32 s0, 0x40000
	v_add_co_u32_e32 v0, vcc, s0, v124
	v_pk_fma_f32 v[120:121], v[102:103], v[218:219], v[120:121] op_sel_hi:[1,0,1] neg_lo:[1,0,0] neg_hi:[1,0,0]
	s_nop 0
	v_addc_co_u32_e32 v1, vcc, 0, v125, vcc
	global_store_short v[0:1], v2, off
	v_cvt_pk_bf16_f32 v2, v58, s0
	s_mov_b32 s0, 0xc8000
	v_add_co_u32_e32 v0, vcc, s0, v140
	v_pk_fma_f32 v[120:121], v[106:107], v[220:221], v[120:121] op_sel_hi:[1,0,1] neg_lo:[1,0,0] neg_hi:[1,0,0]
	s_nop 0
	v_addc_co_u32_e32 v1, vcc, 0, v141, vcc
	global_store_short v[0:1], v2, off
	v_add_co_u32_e32 v0, vcc, s65, v124
	v_cvt_pk_bf16_f32 v2, v59, s0
	s_nop 0
	v_addc_co_u32_e32 v1, vcc, 0, v125, vcc
	global_store_short v[0:1], v2, off
	v_cvt_pk_bf16_f32 v2, v60, s0
	s_mov_b32 s0, 0xce000
	v_add_co_u32_e32 v0, vcc, s0, v140
	v_pk_fma_f32 v[120:121], v[110:111], v[222:223], v[120:121] op_sel_hi:[1,0,1] neg_lo:[1,0,0] neg_hi:[1,0,0]
	s_nop 0
	v_addc_co_u32_e32 v1, vcc, 0, v141, vcc
	global_store_short v[0:1], v2, off
	v_add_co_u32_e32 v0, vcc, s93, v124
	v_cvt_pk_bf16_f32 v2, v61, s0
	s_nop 0
	v_addc_co_u32_e32 v1, vcc, 0, v125, vcc
	global_store_short v[0:1], v2, off
	v_cvt_pk_bf16_f32 v2, v62, s0
	s_mov_b32 s0, 0xd4000
	v_add_co_u32_e32 v0, vcc, s0, v140
	v_pk_fma_f32 v[120:121], v[114:115], v[224:225], v[120:121] op_sel_hi:[1,0,1] neg_lo:[1,0,0] neg_hi:[1,0,0]
	s_nop 0
	v_addc_co_u32_e32 v1, vcc, 0, v141, vcc
	global_store_short v[0:1], v2, off
	v_cvt_pk_bf16_f32 v2, v63, s0
	s_mov_b32 s0, 0x46000
	v_add_co_u32_e32 v0, vcc, s0, v124
	v_pk_fma_f32 v[120:121], v[226:227], v[118:119], v[120:121] op_sel_hi:[0,1,1] neg_lo:[1,0,0] neg_hi:[1,0,0]
	s_nop 0
	v_addc_co_u32_e32 v1, vcc, 0, v125, vcc
	global_store_short v[0:1], v2, off
	v_cvt_pk_bf16_f32 v2, v64, s0
	s_mov_b32 s0, 0xda000
	v_add_co_u32_e32 v0, vcc, s0, v140
	v_pk_add_f32 v[120:121], v[120:121], v[186:187]
	s_nop 0
	v_addc_co_u32_e32 v1, vcc, 0, v141, vcc
	global_store_short v[0:1], v2, off
	v_add_co_u32_e32 v0, vcc, s74, v124
	v_cvt_pk_bf16_f32 v2, v65, s0
	s_nop 0
	v_addc_co_u32_e32 v1, vcc, 0, v125, vcc
	global_store_short v[0:1], v2, off
	v_cvt_pk_bf16_f32 v2, v66, s0
	s_mov_b32 s0, 0xe0000
	v_add_co_u32_e32 v0, vcc, s0, v140
	v_add_u32_e32 v8, v196, v26
	s_nop 0
	v_addc_co_u32_e32 v1, vcc, 0, v141, vcc
	global_store_short v[0:1], v2, off
	v_add_co_u32_e32 v0, vcc, s94, v124
	v_cvt_pk_bf16_f32 v2, v67, s0
	s_nop 0
	v_addc_co_u32_e32 v1, vcc, 0, v125, vcc
	global_store_short v[0:1], v2, off
	v_cvt_pk_bf16_f32 v2, v68, s0
	s_mov_b32 s0, 0xe6000
	v_add_co_u32_e32 v0, vcc, s0, v140
	v_or_b32_e32 v6, v22, v24
	s_nop 0
	v_addc_co_u32_e32 v1, vcc, 0, v141, vcc
	global_store_short v[0:1], v2, off
	v_cvt_pk_bf16_f32 v2, v69, s0
	s_mov_b32 s0, 0x4c000
	v_add_co_u32_e32 v0, vcc, s0, v124
	v_mul_lo_u32 v10, v23, s29
	s_nop 0
	v_addc_co_u32_e32 v1, vcc, 0, v125, vcc
	global_store_short v[0:1], v2, off
	v_cvt_pk_bf16_f32 v2, v70, s0
	s_mov_b32 s0, 0xec000
	v_add_co_u32_e32 v0, vcc, s0, v140
	v_lshlrev_b32_e32 v20, 1, v27
	s_nop 0
	v_addc_co_u32_e32 v1, vcc, 0, v141, vcc
	global_store_short v[0:1], v2, off
	v_add_co_u32_e32 v0, vcc, s75, v124
	v_cvt_pk_bf16_f32 v2, v71, s0
	s_nop 0
	v_addc_co_u32_e32 v1, vcc, 0, v125, vcc
	global_store_short v[0:1], v2, off
	v_cvt_pk_bf16_f32 v2, v72, s0
	s_mov_b32 s0, 0xf2000
	v_add_co_u32_e32 v0, vcc, s0, v140
	v_mov_b32_e32 v27, v21
	s_nop 0
	v_addc_co_u32_e32 v1, vcc, 0, v141, vcc
	global_store_short v[0:1], v2, off
	v_add_co_u32_e32 v0, vcc, s95, v124
	v_cvt_pk_bf16_f32 v2, v73, s0
	s_nop 0
	v_addc_co_u32_e32 v1, vcc, 0, v125, vcc
	global_store_short v[0:1], v2, off
	v_cvt_pk_bf16_f32 v2, v74, s0
	s_mov_b32 s0, 0xf8000
	v_add_co_u32_e32 v0, vcc, s0, v140
	s_nop 1
	v_addc_co_u32_e32 v1, vcc, 0, v141, vcc
	global_store_short v[0:1], v2, off
	v_cvt_pk_bf16_f32 v2, v75, s0
	s_mov_b32 s0, 0x52000
	v_add_co_u32_e32 v0, vcc, s0, v124
	s_nop 1
	v_addc_co_u32_e32 v1, vcc, 0, v125, vcc
	global_store_short v[0:1], v2, off
	v_cvt_pk_bf16_f32 v2, v76, s0
	s_mov_b32 s0, 0xfe000
	v_add_co_u32_e32 v0, vcc, s0, v140
	s_nop 1
	v_addc_co_u32_e32 v1, vcc, 0, v141, vcc
	global_store_short v[0:1], v2, off
	v_add_co_u32_e32 v0, vcc, s59, v124
	v_cvt_pk_bf16_f32 v2, v77, s0
	s_nop 0
	v_addc_co_u32_e32 v1, vcc, 0, v125, vcc
	global_store_short v[0:1], v2, off
	v_cvt_pk_bf16_f32 v2, v78, s0
	s_mov_b32 s0, 0x104000
	v_add_co_u32_e32 v0, vcc, s0, v140
	s_nop 1
	v_addc_co_u32_e32 v1, vcc, 0, v141, vcc
	global_store_short v[0:1], v2, off
	v_add_co_u32_e32 v0, vcc, s96, v124
	v_cvt_pk_bf16_f32 v2, v79, s0
	s_nop 0
	v_addc_co_u32_e32 v1, vcc, 0, v125, vcc
	global_store_short v[0:1], v2, off
	v_cvt_pk_bf16_f32 v2, v80, s0
	s_mov_b32 s0, 0x10a000
	v_add_co_u32_e32 v0, vcc, s0, v140
	s_nop 1
	v_addc_co_u32_e32 v1, vcc, 0, v141, vcc
	global_store_short v[0:1], v2, off
	v_cvt_pk_bf16_f32 v2, v81, s0
	s_mov_b32 s0, 0x58000
	v_add_co_u32_e32 v0, vcc, s0, v124
	s_nop 1
	v_addc_co_u32_e32 v1, vcc, 0, v125, vcc
	global_store_short v[0:1], v2, off
	v_cvt_pk_bf16_f32 v2, v82, s0
	s_mov_b32 s0, 0x110000
	v_add_co_u32_e32 v0, vcc, s0, v140
	s_nop 1
	v_addc_co_u32_e32 v1, vcc, 0, v141, vcc
	global_store_short v[0:1], v2, off
	v_add_co_u32_e32 v0, vcc, s22, v124
	v_cvt_pk_bf16_f32 v2, v83, s0
	s_nop 0
	v_addc_co_u32_e32 v1, vcc, 0, v125, vcc
	global_store_short v[0:1], v2, off
	v_cvt_pk_bf16_f32 v2, v86, s0
	s_mov_b32 s0, 0x116000
	v_add_co_u32_e32 v0, vcc, s0, v140
	s_nop 1
	v_addc_co_u32_e32 v1, vcc, 0, v141, vcc
	global_store_short v[0:1], v2, off
	v_add_co_u32_e32 v0, vcc, s97, v124
	v_cvt_pk_bf16_f32 v2, v87, s0
	s_nop 0
	v_addc_co_u32_e32 v1, vcc, 0, v125, vcc
	global_store_short v[0:1], v2, off
	v_cvt_pk_bf16_f32 v2, v88, s0
	s_mov_b32 s0, 0x11c000
	v_add_co_u32_e32 v0, vcc, s0, v140
	s_nop 1
	v_addc_co_u32_e32 v1, vcc, 0, v141, vcc
	global_store_short v[0:1], v2, off
	v_cvt_pk_bf16_f32 v2, v89, s0
	s_mov_b32 s0, 0x5e000
	v_add_co_u32_e32 v0, vcc, s0, v124
	s_nop 1
	v_addc_co_u32_e32 v1, vcc, 0, v125, vcc
	global_store_short v[0:1], v2, off
	v_cvt_pk_bf16_f32 v2, v90, s0
	s_mov_b32 s0, 0x122000
	v_add_co_u32_e32 v0, vcc, s0, v140
	s_nop 1
	v_addc_co_u32_e32 v1, vcc, 0, v141, vcc
	global_store_short v[0:1], v2, off
	v_add_co_u32_e32 v0, vcc, s23, v124
	v_cvt_pk_bf16_f32 v2, v91, s0
	s_nop 0
	v_addc_co_u32_e32 v1, vcc, 0, v125, vcc
	global_store_short v[0:1], v2, off
	v_cvt_pk_bf16_f32 v2, v92, s0
	s_mov_b32 s0, 0x128000
	v_add_co_u32_e32 v0, vcc, s0, v140
	s_nop 1
	v_addc_co_u32_e32 v1, vcc, 0, v141, vcc
	global_store_short v[0:1], v2, off
	v_add_co_u32_e32 v0, vcc, s3, v124
	v_cvt_pk_bf16_f32 v2, v93, s0
	s_nop 0
	v_addc_co_u32_e32 v1, vcc, 0, v125, vcc
	global_store_short v[0:1], v2, off
	v_cvt_pk_bf16_f32 v2, v94, s0
	s_mov_b32 s0, 0x12e000
	v_add_co_u32_e32 v0, vcc, s0, v140
	s_nop 1
	v_addc_co_u32_e32 v1, vcc, 0, v141, vcc
	global_store_short v[0:1], v2, off
	v_cvt_pk_bf16_f32 v2, v95, s0
	s_mov_b32 s0, 0x64000
	v_add_co_u32_e32 v0, vcc, s0, v124
	s_nop 1
	v_addc_co_u32_e32 v1, vcc, 0, v125, vcc
	global_store_short v[0:1], v2, off
	v_cvt_pk_bf16_f32 v2, v96, s0
	s_mov_b32 s0, 0x134000
	v_add_co_u32_e32 v0, vcc, s0, v140
	s_nop 1
	v_addc_co_u32_e32 v1, vcc, 0, v141, vcc
	global_store_short v[0:1], v2, off
	v_add_co_u32_e32 v0, vcc, s12, v124
	v_cvt_pk_bf16_f32 v2, v97, s0
	s_nop 0
	v_addc_co_u32_e32 v1, vcc, 0, v125, vcc
	global_store_short v[0:1], v2, off
	v_cvt_pk_bf16_f32 v2, v98, s0
	s_mov_b32 s0, 0x13a000
	v_add_co_u32_e32 v0, vcc, s0, v140
	s_nop 1
	v_addc_co_u32_e32 v1, vcc, 0, v141, vcc
	global_store_short v[0:1], v2, off
	v_add_co_u32_e32 v0, vcc, s31, v124
	v_cvt_pk_bf16_f32 v2, v99, s0
	s_nop 0
	v_addc_co_u32_e32 v1, vcc, 0, v125, vcc
	global_store_short v[0:1], v2, off
	v_cvt_pk_bf16_f32 v2, v100, s0
	s_mov_b32 s0, 0x140000
	v_add_co_u32_e32 v0, vcc, s0, v140
	s_nop 1
	v_addc_co_u32_e32 v1, vcc, 0, v141, vcc
	global_store_short v[0:1], v2, off
	v_cvt_pk_bf16_f32 v2, v101, s0
	s_mov_b32 s0, 0x6a000
	v_add_co_u32_e32 v0, vcc, s0, v124
	s_nop 1
	v_addc_co_u32_e32 v1, vcc, 0, v125, vcc
	global_store_short v[0:1], v2, off
	v_cvt_pk_bf16_f32 v2, v102, s0
	s_mov_b32 s0, 0x146000
	v_add_co_u32_e32 v0, vcc, s0, v140
	s_nop 1
	v_addc_co_u32_e32 v1, vcc, 0, v141, vcc
	global_store_short v[0:1], v2, off
	v_add_co_u32_e32 v0, vcc, s13, v124
	v_cvt_pk_bf16_f32 v2, v103, s0
	s_nop 0
	v_addc_co_u32_e32 v1, vcc, 0, v125, vcc
	global_store_short v[0:1], v2, off
	v_cvt_pk_bf16_f32 v2, v104, s0
	s_mov_b32 s0, 0x14c000
	v_add_co_u32_e32 v0, vcc, s0, v140
	s_nop 1
	v_addc_co_u32_e32 v1, vcc, 0, v141, vcc
	global_store_short v[0:1], v2, off
	v_add_co_u32_e32 v0, vcc, s34, v124
	v_cvt_pk_bf16_f32 v2, v105, s0
	s_nop 0
	v_addc_co_u32_e32 v1, vcc, 0, v125, vcc
	global_store_short v[0:1], v2, off
	v_cvt_pk_bf16_f32 v2, v106, s0
	s_mov_b32 s0, 0x152000
	v_add_co_u32_e32 v0, vcc, s0, v140
	s_nop 1
	v_addc_co_u32_e32 v1, vcc, 0, v141, vcc
	global_store_short v[0:1], v2, off
	v_cvt_pk_bf16_f32 v2, v107, s0
	s_mov_b32 s0, 0x70000
	v_add_co_u32_e32 v0, vcc, s0, v124
	s_nop 1
	v_addc_co_u32_e32 v1, vcc, 0, v125, vcc
	global_store_short v[0:1], v2, off
	v_cvt_pk_bf16_f32 v2, v108, s0
	s_mov_b32 s0, 0x158000
	v_add_co_u32_e32 v0, vcc, s0, v140
	s_nop 1
	v_addc_co_u32_e32 v1, vcc, 0, v141, vcc
	global_store_short v[0:1], v2, off
	v_add_co_u32_e32 v0, vcc, s28, v124
	v_cvt_pk_bf16_f32 v2, v109, s0
	s_nop 0
	v_addc_co_u32_e32 v1, vcc, 0, v125, vcc
	global_store_short v[0:1], v2, off
	v_cvt_pk_bf16_f32 v2, v110, s0
	s_mov_b32 s0, 0x15e000
	v_add_co_u32_e32 v0, vcc, s0, v140
	s_nop 1
	v_addc_co_u32_e32 v1, vcc, 0, v141, vcc
	global_store_short v[0:1], v2, off
	v_add_co_u32_e32 v0, vcc, s56, v124
	v_cvt_pk_bf16_f32 v2, v111, s0
	s_nop 0
	v_addc_co_u32_e32 v1, vcc, 0, v125, vcc
	global_store_short v[0:1], v2, off
	v_cvt_pk_bf16_f32 v2, v112, s0
	s_mov_b32 s0, 0x164000
	v_add_co_u32_e32 v0, vcc, s0, v140
	s_nop 1
	v_addc_co_u32_e32 v1, vcc, 0, v141, vcc
	global_store_short v[0:1], v2, off
	v_cvt_pk_bf16_f32 v2, v113, s0
	s_mov_b32 s0, 0x76000
	v_add_co_u32_e32 v0, vcc, s0, v124
	s_nop 1
	v_addc_co_u32_e32 v1, vcc, 0, v125, vcc
	global_store_short v[0:1], v2, off
	v_cvt_pk_bf16_f32 v2, v114, s0
	s_mov_b32 s0, 0x16a000
	v_add_co_u32_e32 v0, vcc, s0, v140
	s_nop 1
	v_addc_co_u32_e32 v1, vcc, 0, v141, vcc
	global_store_short v[0:1], v2, off
	v_add_co_u32_e32 v0, vcc, s52, v124
	v_cvt_pk_bf16_f32 v2, v115, s0
	s_nop 0
	v_addc_co_u32_e32 v1, vcc, 0, v125, vcc
	global_store_short v[0:1], v2, off
	v_cvt_pk_bf16_f32 v2, v116, s0
	s_mov_b32 s0, 0x170000
	v_add_co_u32_e32 v0, vcc, s0, v140
	s_nop 1
	v_addc_co_u32_e32 v1, vcc, 0, v141, vcc
	global_store_short v[0:1], v2, off
	v_add_co_u32_e32 v0, vcc, s57, v124
	v_cvt_pk_bf16_f32 v2, v117, s0
	s_nop 0
	v_addc_co_u32_e32 v1, vcc, 0, v125, vcc
	global_store_short v[0:1], v2, off
	v_cvt_pk_bf16_f32 v2, v118, s0
	s_mov_b32 s0, 0x176000
	v_add_co_u32_e32 v0, vcc, s0, v140
	s_nop 1
	v_addc_co_u32_e32 v1, vcc, 0, v141, vcc
	global_store_short v[0:1], v2, off
	v_cvt_pk_bf16_f32 v2, v119, s0
	s_mov_b32 s0, 0x7c000
	v_add_co_u32_e32 v0, vcc, s0, v124
	s_nop 1
	v_addc_co_u32_e32 v1, vcc, 0, v125, vcc
	global_store_short v[0:1], v2, off
	v_cvt_pk_bf16_f32 v2, v120, s0
	s_mov_b32 s0, 0x17c000
	v_add_co_u32_e32 v0, vcc, s0, v140
	s_nop 1
	v_addc_co_u32_e32 v1, vcc, 0, v141, vcc
	global_store_short v[0:1], v2, off
	v_add_co_u32_e32 v0, vcc, s53, v124
	v_cvt_pk_bf16_f32 v2, v121, s0
	s_nop 0
	v_addc_co_u32_e32 v1, vcc, 0, v125, vcc
	global_store_short v[0:1], v2, off
	v_and_b32_e32 v0, 56, v195
	v_mul_u32_u24_e32 v9, 0x110, v0
	v_add_u32_e32 v0, v8, v201
	ds_read_b128 v[2:5], v0 offset:4096
	v_mov_b64_e32 v[0:1], s[68:69]
	v_mad_u64_u32 v[6:7], s[0:1], v6, s29, v[0:1]
	v_add_u32_e32 v7, v10, v7
	v_lshl_add_u64 v[6:7], v[6:7], 0, v[20:21]
	v_lshl_add_u64 v[6:7], v[6:7], 0, v[26:27]
	s_waitcnt lgkmcnt(0)
	global_store_dwordx4 v[6:7], v[2:5], off
	v_add_co_u32_e32 v6, vcc, s27, v6
	s_nop 0
	v_lshrrev_b32_e32 v2, 2, v194
	v_and_b32_e32 v2, 62, v2
	v_add3_u32 v2, v196, v2, v9
	ds_read_u16 v3, v2 offset:21504
	ds_read_u16 v4, v2 offset:21776
	ds_read_u16 v5, v2 offset:22048
	ds_read_u16 v11, v2 offset:22320
	ds_read_u16 v12, v2 offset:22592
	ds_read_u16 v13, v2 offset:22864
	ds_read_u16 v14, v2 offset:23136
	ds_read_u16 v2, v2 offset:23408
	s_waitcnt lgkmcnt(7)
	v_lshlrev_b32_e32 v3, 16, v3
	s_waitcnt lgkmcnt(6)
	v_lshlrev_b32_e32 v4, 16, v4
	s_waitcnt lgkmcnt(5)
	v_lshlrev_b32_e32 v5, 16, v5
	s_waitcnt lgkmcnt(4)
	v_lshlrev_b32_e32 v11, 16, v11
	s_waitcnt lgkmcnt(3)
	v_lshlrev_b32_e32 v12, 16, v12
	s_waitcnt lgkmcnt(2)
	v_lshlrev_b32_e32 v13, 16, v13
	s_waitcnt lgkmcnt(1)
	v_lshlrev_b32_e32 v14, 16, v14
	s_waitcnt lgkmcnt(0)
	v_lshlrev_b32_e32 v15, 16, v2
	v_cvt_pk_bf16_f32 v2, v3, v4
	v_cvt_pk_bf16_f32 v3, v5, v11
	v_cvt_pk_bf16_f32 v4, v12, v13
	v_cvt_pk_bf16_f32 v5, v14, v15
	v_addc_co_u32_e32 v7, vcc, 0, v7, vcc
	global_store_dwordx4 v[6:7], v[2:5], off
	v_or_b32_e32 v6, v22, v198
	v_mad_u64_u32 v[6:7], s[0:1], v6, s29, v[0:1]
	v_add_u32_e32 v2, v8, v204
	ds_read_b128 v[2:5], v2 offset:4096
	v_add_u32_e32 v7, v10, v7
	v_lshl_add_u64 v[6:7], v[6:7], 0, v[20:21]
	v_lshl_add_u64 v[6:7], v[6:7], 0, v[26:27]
	s_waitcnt lgkmcnt(0)
	global_store_dwordx4 v[6:7], v[2:5], off
	v_add_co_u32_e32 v6, vcc, s27, v6
	s_nop 0
	v_lshrrev_b32_e32 v2, 2, v197
	v_and_b32_e32 v2, 0x7e, v2
	v_add3_u32 v2, v196, v2, v9
	ds_read_u16 v3, v2 offset:21504
	ds_read_u16 v4, v2 offset:21776
	ds_read_u16 v5, v2 offset:22048
	ds_read_u16 v11, v2 offset:22320
	ds_read_u16 v12, v2 offset:22592
	ds_read_u16 v13, v2 offset:22864
	ds_read_u16 v14, v2 offset:23136
	ds_read_u16 v2, v2 offset:23408
	s_waitcnt lgkmcnt(7)
	v_lshlrev_b32_e32 v3, 16, v3
	s_waitcnt lgkmcnt(6)
	v_lshlrev_b32_e32 v4, 16, v4
	s_waitcnt lgkmcnt(5)
	v_lshlrev_b32_e32 v5, 16, v5
	s_waitcnt lgkmcnt(4)
	v_lshlrev_b32_e32 v11, 16, v11
	s_waitcnt lgkmcnt(3)
	v_lshlrev_b32_e32 v12, 16, v12
	s_waitcnt lgkmcnt(2)
	v_lshlrev_b32_e32 v13, 16, v13
	s_waitcnt lgkmcnt(1)
	v_lshlrev_b32_e32 v14, 16, v14
	s_waitcnt lgkmcnt(0)
	v_lshlrev_b32_e32 v15, 16, v2
	v_cvt_pk_bf16_f32 v2, v3, v4
	v_cvt_pk_bf16_f32 v3, v5, v11
	v_cvt_pk_bf16_f32 v4, v12, v13
	v_cvt_pk_bf16_f32 v5, v14, v15
	v_addc_co_u32_e32 v7, vcc, 0, v7, vcc
	global_store_dwordx4 v[6:7], v[2:5], off
	v_or_b32_e32 v6, v22, v200
	v_mad_u64_u32 v[6:7], s[0:1], v6, s29, v[0:1]
	v_add_u32_e32 v2, v8, v205
	ds_read_b128 v[2:5], v2 offset:4096
	v_add_u32_e32 v7, v10, v7
	v_lshl_add_u64 v[6:7], v[6:7], 0, v[20:21]
	v_lshl_add_u64 v[6:7], v[6:7], 0, v[26:27]
	s_waitcnt lgkmcnt(0)
	global_store_dwordx4 v[6:7], v[2:5], off
	v_add_co_u32_e32 v6, vcc, s27, v6
	s_nop 0
	v_lshrrev_b32_e32 v2, 2, v199
	v_and_b32_e32 v2, 0xfe, v2
	v_add3_u32 v2, v196, v2, v9
	ds_read_u16 v3, v2 offset:21504
	ds_read_u16 v4, v2 offset:21776
	ds_read_u16 v5, v2 offset:22048
	ds_read_u16 v11, v2 offset:22320
	ds_read_u16 v12, v2 offset:22592
	ds_read_u16 v13, v2 offset:22864
	ds_read_u16 v14, v2 offset:23136
	ds_read_u16 v2, v2 offset:23408
	s_waitcnt lgkmcnt(7)
	v_lshlrev_b32_e32 v3, 16, v3
	s_waitcnt lgkmcnt(6)
	v_lshlrev_b32_e32 v4, 16, v4
	s_waitcnt lgkmcnt(5)
	v_lshlrev_b32_e32 v5, 16, v5
	s_waitcnt lgkmcnt(4)
	v_lshlrev_b32_e32 v11, 16, v11
	s_waitcnt lgkmcnt(3)
	v_lshlrev_b32_e32 v12, 16, v12
	s_waitcnt lgkmcnt(2)
	v_lshlrev_b32_e32 v13, 16, v13
	s_waitcnt lgkmcnt(1)
	v_lshlrev_b32_e32 v14, 16, v14
	s_waitcnt lgkmcnt(0)
	v_lshlrev_b32_e32 v15, 16, v2
	v_cvt_pk_bf16_f32 v2, v3, v4
	v_cvt_pk_bf16_f32 v3, v5, v11
	v_cvt_pk_bf16_f32 v4, v12, v13
	v_cvt_pk_bf16_f32 v5, v14, v15
	v_addc_co_u32_e32 v7, vcc, 0, v7, vcc
	global_store_dwordx4 v[6:7], v[2:5], off
	v_or_b32_e32 v6, v22, v203
	v_mad_u64_u32 v[0:1], s[0:1], v6, s29, v[0:1]
	v_add_u32_e32 v2, v8, v206
	ds_read_b128 v[2:5], v2 offset:4096
	v_add_u32_e32 v1, v10, v1
	v_lshl_add_u64 v[0:1], v[0:1], 0, v[20:21]
	v_lshl_add_u64 v[6:7], v[0:1], 0, v[26:27]
	v_lshrrev_b32_e32 v0, 2, v202
	v_and_b32_e32 v0, 0xfe, v0
	v_add3_u32 v0, v196, v0, v9
	s_waitcnt lgkmcnt(0)
	global_store_dwordx4 v[6:7], v[2:5], off
	ds_read_u16 v1, v0 offset:21504
	ds_read_u16 v2, v0 offset:21776
	ds_read_u16 v3, v0 offset:22048
	ds_read_u16 v4, v0 offset:22320
	ds_read_u16 v5, v0 offset:22592
	ds_read_u16 v8, v0 offset:22864
	ds_read_u16 v9, v0 offset:23136
	ds_read_u16 v0, v0 offset:23408
	s_waitcnt lgkmcnt(7)
	v_lshlrev_b32_e32 v1, 16, v1
	s_waitcnt lgkmcnt(6)
	v_lshlrev_b32_e32 v2, 16, v2
	s_waitcnt lgkmcnt(5)
	v_lshlrev_b32_e32 v3, 16, v3
	s_waitcnt lgkmcnt(4)
	v_lshlrev_b32_e32 v4, 16, v4
	s_waitcnt lgkmcnt(3)
	v_lshlrev_b32_e32 v5, 16, v5
	s_waitcnt lgkmcnt(2)
	v_lshlrev_b32_e32 v8, 16, v8
	s_waitcnt lgkmcnt(1)
	v_lshlrev_b32_e32 v9, 16, v9
	s_waitcnt lgkmcnt(0)
	v_lshlrev_b32_e32 v10, 16, v0
	v_cvt_pk_bf16_f32 v0, v1, v2
	v_cvt_pk_bf16_f32 v1, v3, v4
	v_add_co_u32_e32 v4, vcc, 0x1000, v6
	v_cvt_pk_bf16_f32 v2, v5, v8
	v_cvt_pk_bf16_f32 v3, v9, v10
	v_addc_co_u32_e32 v5, vcc, 0, v7, vcc
	global_store_dwordx4 v[4:5], v[0:3], off
	s_cbranch_scc1 .LBB0_325

.LBB0_436:
	s_waitcnt lgkmcnt(0)
	ds_read_b128 v[194:197], v142
	ds_read_b32 v198, v166
	ds_read_b32 v199, v167
	v_mov_b32_e32 v80, 0
	v_mov_b32_e32 v81, 0
	v_mov_b32_e32 v82, 0
	v_mov_b32_e32 v83, 0
	v_mov_b32_e32 v236, 0
	v_mov_b32_e32 v237, 0
	v_mov_b32_e32 v238, 0
	v_mov_b32_e32 v239, 0
	global_load_dwordx4 v[64:67], v[0:1], off
	v_add_co_u32_e32 v0, vcc, 0x400, v0
	s_nop 1
	v_addc_co_u32_e32 v1, vcc, 0, v1, vcc
	s_cmp_eq_u64 s[14:15], 0
	s_cbranch_scc1 .Lml_none_p0
	s_cmp_eq_u64 s[12:13], 0
	s_cbranch_scc1 .Lml_only1_p0
	ds_read_b128 v[116:119], v100 offset:17408
	ds_read_b128 v[204:207], v169
	ds_read_b128 v[220:223], v171
	ds_read_b128 v[178:181], v100 offset:17472
	ds_read_b128 v[208:211], v169 offset:64
	ds_read_b128 v[224:227], v171 offset:64
	ds_read_b128 v[182:185], v100 offset:17536
	ds_read_b128 v[212:215], v169 offset:128
	ds_read_b128 v[228:231], v171 offset:128
	ds_read_b128 v[186:189], v100 offset:17600
	ds_read_b128 v[216:219], v169 offset:192
	ds_read_b128 v[232:235], v171 offset:192
	s_waitcnt lgkmcnt(9)
	v_mfma_f32_16x16x32_bf16 v[80:83], v[116:119], v[204:207], 0
	v_mfma_f32_16x16x32_bf16 v[236:239], v[116:119], v[220:223], 0
	s_waitcnt lgkmcnt(6)
	v_mfma_f32_16x16x32_bf16 v[80:83], v[178:181], v[208:211], v[80:83]
	v_mfma_f32_16x16x32_bf16 v[236:239], v[178:181], v[224:227], v[236:239]
	s_waitcnt lgkmcnt(3)
	v_mfma_f32_16x16x32_bf16 v[80:83], v[182:185], v[212:215], v[80:83]
	v_mfma_f32_16x16x32_bf16 v[236:239], v[182:185], v[228:231], v[236:239]
	s_waitcnt lgkmcnt(0)
	v_mfma_f32_16x16x32_bf16 v[80:83], v[186:189], v[216:219], v[80:83]
	v_mfma_f32_16x16x32_bf16 v[236:239], v[186:189], v[232:235], v[236:239]
	s_branch .Lml_none_p0
.Lml_only1_p0:
	ds_read_b128 v[116:119], v100 offset:17408
	ds_read_b128 v[220:223], v171
	ds_read_b128 v[178:181], v100 offset:17472
	ds_read_b128 v[224:227], v171 offset:64
	ds_read_b128 v[182:185], v100 offset:17536
	ds_read_b128 v[228:231], v171 offset:128
	ds_read_b128 v[186:189], v100 offset:17600
	ds_read_b128 v[232:235], v171 offset:192
	s_waitcnt lgkmcnt(6)
	v_mfma_f32_16x16x32_bf16 v[236:239], v[116:119], v[220:223], 0
	s_waitcnt lgkmcnt(4)
	v_mfma_f32_16x16x32_bf16 v[236:239], v[178:181], v[224:227], v[236:239]
	s_waitcnt lgkmcnt(2)
	v_mfma_f32_16x16x32_bf16 v[236:239], v[182:185], v[228:231], v[236:239]
	s_waitcnt lgkmcnt(0)
	v_mfma_f32_16x16x32_bf16 v[236:239], v[186:189], v[232:235], v[236:239]
.Lml_none_p0:
	s_waitcnt lgkmcnt(0)
	global_load_dwordx4 v[32:35], v[240:241], off
	global_load_dwordx4 v[36:39], v[240:241], off offset:2048
	v_lshl_add_u64 v[240:241], v[240:241], 0, s[98:99]
	v_sub_f32_e32 v200, v194, v198
	v_sub_f32_e32 v201, v195, v198
	v_sub_f32_e32 v202, v196, v198
	v_sub_f32_e32 v203, v197, v198
	v_min_f32_e32 v200, 0, v200
	v_min_f32_e32 v201, 0, v201
	v_min_f32_e32 v202, 0, v202
	v_min_f32_e32 v203, 0, v203
	v_mul_f32_e32 v200, 0x3fb8aa3b, v200
	v_mul_f32_e32 v201, 0x3fb8aa3b, v201
	v_mul_f32_e32 v202, 0x3fb8aa3b, v202
	v_mul_f32_e32 v203, 0x3fb8aa3b, v203
	v_exp_f32_e32 v200, v200
	v_exp_f32_e32 v201, v201
	v_exp_f32_e32 v202, v202
	v_exp_f32_e32 v203, v203
	v_mul_f32_e32 v200, v80, v200
	v_mul_f32_e32 v201, v81, v201
	v_mul_f32_e32 v202, v82, v202
	v_mul_f32_e32 v203, v83, v203
	v_cndmask_b32_e64 v200, 0, v200, s[40:41]
	v_cndmask_b32_e64 v201, 0, v201, s[42:43]
	v_cndmask_b32_e64 v202, 0, v202, s[44:45]
	v_cndmask_b32_e64 v203, 0, v203, s[46:47]
	v_cvt_pk_bf16_f32 v82, v200, v201
	v_cvt_pk_bf16_f32 v83, v202, v203
	ds_write_b64 v170, v[82:83]
	global_load_dwordx4 v[44:47], v[244:245], off
	global_load_dwordx4 v[48:51], v[244:245], off offset:2048
	v_lshl_add_u64 v[244:245], v[244:245], 0, s[98:99]
	v_sub_f32_e32 v200, v194, v199
	v_sub_f32_e32 v201, v195, v199
	v_sub_f32_e32 v202, v196, v199
	v_sub_f32_e32 v203, v197, v199
	v_min_f32_e32 v200, 0, v200
	v_min_f32_e32 v201, 0, v201
	v_min_f32_e32 v202, 0, v202
	v_min_f32_e32 v203, 0, v203
	v_mul_f32_e32 v200, 0x3fb8aa3b, v200
	v_mul_f32_e32 v201, 0x3fb8aa3b, v201
	v_mul_f32_e32 v202, 0x3fb8aa3b, v202
	v_mul_f32_e32 v203, 0x3fb8aa3b, v203
	v_exp_f32_e32 v200, v200
	v_exp_f32_e32 v201, v201
	v_exp_f32_e32 v202, v202
	v_exp_f32_e32 v203, v203
	v_mul_f32_e32 v200, v236, v200
	v_mul_f32_e32 v201, v237, v201
	v_mul_f32_e32 v202, v238, v202
	v_mul_f32_e32 v203, v239, v203
	v_cndmask_b32_e64 v200, 0, v200, s[48:49]
	v_cndmask_b32_e64 v201, 0, v201, s[50:51]
	v_cndmask_b32_e64 v202, 0, v202, s[52:53]
	v_cndmask_b32_e64 v203, 0, v203, s[54:55]
	v_cvt_pk_bf16_f32 v82, v200, v201
	v_cvt_pk_bf16_f32 v83, v202, v203
	ds_write_b64 v172, v[82:83]
	ds_read_b128 v[80:83], v100
	ds_read_b128 v[116:119], v101 offset:34816
	ds_read_b128 v[178:181], v100 offset:64
	ds_read_b128 v[182:185], v101 offset:34880
	ds_read_b128 v[186:189], v253 offset:43520
	ds_read_b128 v[190:193], v253 offset:43584
	s_waitcnt lgkmcnt(4)
	v_mfma_f32_16x16x32_bf16 v[116:119], v[80:83], v[116:119], 0
	v_mul_f32_e64 v70, v70, v114
	v_mul_f32_e64 v71, v71, v114
	v_pk_mul_f32 v[68:69], v[68:69], v[114:115] op_sel_hi:[1,0]
	v_pk_mul_f32 v[78:79], v[78:79], v[114:115] op_sel_hi:[1,0]
	s_waitcnt lgkmcnt(2)
	v_mfma_f32_16x16x32_bf16 v[116:119], v[178:181], v[182:185], v[116:119]
	ds_read_b128 v[182:185], v100 offset:128
	v_pk_mul_f32 v[76:77], v[76:77], v[114:115] op_sel_hi:[1,0]
	v_pk_mul_f32 v[74:75], v[74:75], v[114:115] op_sel_hi:[1,0]
	s_waitcnt lgkmcnt(2)
	v_mfma_f32_16x16x32_bf16 v[80:83], v[80:83], v[186:189], 0
	v_mul_f32_e64 v72, v72, v114
	v_mul_f32_e64 v73, v73, v114
	s_waitcnt lgkmcnt(1)
	v_mfma_f32_16x16x32_bf16 v[80:83], v[178:181], v[190:193], v[80:83]
	ds_read_b128 v[178:181], v101 offset:34944
	ds_read_b128 v[186:189], v100 offset:192
	ds_read_b128 v[190:193], v101 offset:35008
	s_waitcnt lgkmcnt(2)
	v_mfma_f32_16x16x32_bf16 v[116:119], v[182:185], v[178:181], v[116:119]
	ds_read_b128 v[178:181], v253 offset:43648
	ds_read_b128 v[194:197], v253 offset:43712
	s_waitcnt lgkmcnt(0)
	s_barrier
	v_mfma_f32_16x16x32_bf16 v[80:83], v[182:185], v[178:181], v[80:83]
	ds_read_b128 v[178:181], v146
	ds_read_b128 v[182:185], v147
	v_mfma_f32_16x16x32_bf16 v[80:83], v[186:189], v[194:197], v[80:83]
	s_waitcnt lgkmcnt(0)
	v_max_f32_e32 v252, v182, v182
	v_mfma_f32_16x16x32_bf16 v[116:119], v[186:189], v[190:193], v[116:119]
	ds_read_b128 v[186:189], v127
	ds_read_b128 v[190:193], v127 offset:64
	ds_read_b128 v[194:197], v128
	ds_read_b128 v[198:201], v128 offset:64
	ds_read_b128 v[202:205], v254 offset:4608
	ds_read_b128 v[206:209], v254 offset:4672
	v_pk_mul_f32 v[82:83], v[82:83], v[180:181]
	v_pk_mul_f32 v[80:81], v[80:81], v[178:179]
	v_pk_mul_f32 v[118:119], v[118:119], v[180:181]
	v_pk_mul_f32 v[116:117], v[116:117], v[178:179]
	s_waitcnt lgkmcnt(1)
	v_mfma_f32_16x16x32_bf16 v[80:83], v[186:189], v[202:205], v[80:83]
	v_add_u32_e32 v180, v103, v129
	ds_read_b128 v[202:205], v102 offset:47872
	ds_read_b128 v[210:213], v102 offset:47936
	ds_read_b128 v[214:217], v180
	ds_read_b128 v[218:221], v180 offset:64
	s_waitcnt vmcnt(7)
	ds_bpermute_b32 v182, v124, v56
	s_waitcnt lgkmcnt(5)
	v_mfma_f32_16x16x32_bf16 v[80:83], v[190:193], v[206:209], v[80:83]
	global_load_dwordx4 v[40:43], v[242:243], off
	v_lshl_add_u64 v[242:243], v[242:243], 0, s[100:101]
	ds_read_b128 v[206:209], v173
	ds_read_b128 v[222:225], v173 offset:64
	ds_read_b128 v[226:229], v173 offset:2304
	ds_read_b128 v[230:233], v173 offset:2368
	v_mfma_f32_16x16x32_bf16 v[116:119], v[186:189], v[194:197], v[116:119]
	s_nop 2
	v_max_f32_e64 v251, |v80|, |v80|
	v_max_f32_e32 v80, v183, v183
	s_waitcnt lgkmcnt(0)
	v_max_f32_e64 v251, |v251|, |v251|
	v_max_f32_e32 v251, v251, v252
	v_max_f32_e64 v252, |v81|, |v81|
	v_rcp_f32_e32 v251, v251
	v_mfma_f32_16x16x32_bf16 v[116:119], v[190:193], v[198:201], v[116:119]
	global_load_dwordx4 v[52:55], v[246:247], off
	v_lshl_add_u64 v[246:247], v[246:247], 0, s[100:101]
	s_waitcnt lgkmcnt(0)
	v_max_f32_e64 v252, |v252|, |v252|
	v_max_f32_e32 v252, v252, v80
	v_rcp_f32_e32 v252, v252
	v_max_f32_e64 v80, |v82|, |v82|
	s_nop 2
	v_mul_f32_e32 v251, v116, v251
	v_cvt_pk_bf16_f32 v251, v251, s0
	ds_write_b16 v174, v251
	v_mul_f32_e32 v251, v117, v252
	v_cvt_pk_bf16_f32 v251, v251, s0
	ds_write_b16 v174, v251 offset:80
	s_waitcnt lgkmcnt(2)
	v_max_f32_e64 v251, |v80|, |v80|
	v_max_f32_e32 v252, v184, v184
	v_max_f32_e32 v251, v251, v252
	v_max_f32_e64 v252, |v83|, |v83|
	v_rcp_f32_e32 v251, v251
	v_mfma_f32_16x16x32_bf16 v[80:83], v[202:205], v[226:229], v[68:71]
	s_waitcnt lgkmcnt(0)
	v_max_f32_e64 v252, |v252|, |v252|
	s_nop 0
	v_max_f32_e32 v68, v185, v185
	v_max_f32_e32 v252, v252, v68
	v_rcp_f32_e32 v252, v252
	v_mfma_f32_16x16x32_bf16 v[76:79], v[202:205], v[214:217], v[76:79]
	s_mov_b64 s[94:95], exec
	s_mov_b64 exec, s[4:5]
	global_load_dwordx4 v[60:63], v[248:249], off
	s_mov_b64 exec, s[94:95]
	v_lshl_add_u64 v[248:249], v[248:249], 0, s[98:99]
	v_mul_f32_e32 v251, v118, v251
	v_cvt_pk_bf16_f32 v251, v251, s0
	ds_write_b16 v174, v251 offset:160
	v_mfma_f32_16x16x32_bf16 v[72:75], v[202:205], v[206:209], v[72:75]
	v_mul_f32_e32 v251, v119, v252
	v_cvt_pk_bf16_f32 v251, v251, s0
	ds_write_b16 v174, v251 offset:240
	v_mfma_f32_16x16x32_bf16 v[76:79], v[210:213], v[218:221], v[76:79]
	v_max_f32_e32 v251, v177, v177
	v_max_f32_e32 v252, v58, v58
	v_max_f32_e32 v251, v251, v252
	v_mfma_f32_16x16x32_bf16 v[68:71], v[210:213], v[222:225], v[72:75]
	ds_bpermute_b32 v181, v124, v251
	v_mfma_f32_16x16x32_bf16 v[72:75], v[210:213], v[230:233], v[80:83]
	s_nop 2
	v_cvt_pk_bf16_f32 v80, v76, v77
	v_cvt_pk_bf16_f32 v81, v78, v79
	ds_write_b64 v175, v[80:81] offset:34816
	v_cvt_pk_bf16_f32 v80, v68, v69
	v_cvt_pk_bf16_f32 v81, v70, v71
	ds_write_b64 v176, v[80:81] offset:34816
	v_cvt_pk_bf16_f32 v80, v72, v73
	v_cvt_pk_bf16_f32 v81, v74, v75
	ds_write_b64 v176, v[80:81] offset:39168
	s_and_saveexec_b64 s[92:93], s[6:7]
	s_cbranch_execz .LBB0_456
	ds_write_b32 v133, v57
	ds_write_b32 v132, v251

.LBB0_469:
	v_sub_f32_e32 v251, v177, v181
	v_mul_f32_e32 v251, 0x3fb8aa3b, v251
	v_exp_f32_e32 v114, v251
	s_waitcnt lgkmcnt(0)
	ds_read_b128 v[204:207], v142
	ds_read_b32 v143, v166
	ds_read_b32 v144, v167
	v_mov_b32_e32 v80, 0
	v_mov_b32_e32 v81, 0
	v_mov_b32_e32 v82, 0
	v_mov_b32_e32 v83, 0
	v_mov_b32_e32 v200, 0
	v_mov_b32_e32 v201, 0
	v_mov_b32_e32 v202, 0
	v_mov_b32_e32 v203, 0
	global_load_dwordx4 v[56:59], v[0:1], off
	v_add_co_u32_e32 v0, vcc, 0x400, v0
	s_nop 1
	v_addc_co_u32_e32 v1, vcc, 0, v1, vcc
	s_cmp_eq_u64 s[14:15], 0
	s_cbranch_scc1 .Lml_none_p1
	s_cmp_eq_u64 s[12:13], 0
	s_cbranch_scc1 .Lml_only1_p1
	ds_read_b128 v[184:187], v100 offset:17408
	ds_read_b128 v[208:211], v169
	ds_read_b128 v[224:227], v171
	ds_read_b128 v[188:191], v100 offset:17472
	ds_read_b128 v[212:215], v169 offset:64
	ds_read_b128 v[228:231], v171 offset:64
	ds_read_b128 v[192:195], v100 offset:17536
	ds_read_b128 v[216:219], v169 offset:128
	ds_read_b128 v[232:235], v171 offset:128
	ds_read_b128 v[196:199], v100 offset:17600
	ds_read_b128 v[220:223], v169 offset:192
	ds_read_b128 v[236:239], v171 offset:192
	s_waitcnt lgkmcnt(9)
	v_mfma_f32_16x16x32_bf16 v[80:83], v[184:187], v[208:211], 0
	v_mfma_f32_16x16x32_bf16 v[200:203], v[184:187], v[224:227], 0
	s_waitcnt lgkmcnt(6)
	v_mfma_f32_16x16x32_bf16 v[80:83], v[188:191], v[212:215], v[80:83]
	v_mfma_f32_16x16x32_bf16 v[200:203], v[188:191], v[228:231], v[200:203]
	s_waitcnt lgkmcnt(3)
	v_mfma_f32_16x16x32_bf16 v[80:83], v[192:195], v[216:219], v[80:83]
	v_mfma_f32_16x16x32_bf16 v[200:203], v[192:195], v[232:235], v[200:203]
	s_waitcnt lgkmcnt(0)
	v_mfma_f32_16x16x32_bf16 v[80:83], v[196:199], v[220:223], v[80:83]
	v_mfma_f32_16x16x32_bf16 v[200:203], v[196:199], v[236:239], v[200:203]
	s_branch .Lml_none_p1
.Lml_only1_p1:
	ds_read_b128 v[184:187], v100 offset:17408
	ds_read_b128 v[224:227], v171
	ds_read_b128 v[188:191], v100 offset:17472
	ds_read_b128 v[228:231], v171 offset:64
	ds_read_b128 v[192:195], v100 offset:17536
	ds_read_b128 v[232:235], v171 offset:128
	ds_read_b128 v[196:199], v100 offset:17600
	ds_read_b128 v[236:239], v171 offset:192
	s_waitcnt lgkmcnt(6)
	v_mfma_f32_16x16x32_bf16 v[200:203], v[184:187], v[224:227], 0
	s_waitcnt lgkmcnt(4)
	v_mfma_f32_16x16x32_bf16 v[200:203], v[188:191], v[228:231], v[200:203]
	s_waitcnt lgkmcnt(2)
	v_mfma_f32_16x16x32_bf16 v[200:203], v[192:195], v[232:235], v[200:203]
	s_waitcnt lgkmcnt(0)
	v_mfma_f32_16x16x32_bf16 v[200:203], v[196:199], v[236:239], v[200:203]
.Lml_none_p1:
	s_waitcnt lgkmcnt(0)
	global_load_dwordx4 v[8:11], v[240:241], off
	global_load_dwordx4 v[12:15], v[240:241], off offset:2048
	v_lshl_add_u64 v[240:241], v[240:241], 0, s[98:99]
	v_sub_f32_e32 v145, v204, v143
	v_sub_f32_e32 v111, v205, v143
	v_sub_f32_e32 v251, v206, v143
	v_sub_f32_e32 v252, v207, v143
	v_min_f32_e32 v145, 0, v145
	v_min_f32_e32 v111, 0, v111
	v_min_f32_e32 v251, 0, v251
	v_min_f32_e32 v252, 0, v252
	v_mul_f32_e32 v145, 0x3fb8aa3b, v145
	v_mul_f32_e32 v111, 0x3fb8aa3b, v111
	v_mul_f32_e32 v251, 0x3fb8aa3b, v251
	v_mul_f32_e32 v252, 0x3fb8aa3b, v252
	v_exp_f32_e32 v145, v145
	v_exp_f32_e32 v111, v111
	v_exp_f32_e32 v251, v251
	v_exp_f32_e32 v252, v252
	v_mul_f32_e32 v145, v80, v145
	v_mul_f32_e32 v111, v81, v111
	v_mul_f32_e32 v251, v82, v251
	v_mul_f32_e32 v252, v83, v252
	v_cndmask_b32_e64 v145, 0, v145, s[40:41]
	v_cndmask_b32_e64 v111, 0, v111, s[42:43]
	v_cndmask_b32_e64 v251, 0, v251, s[44:45]
	v_cndmask_b32_e64 v252, 0, v252, s[46:47]
	v_cvt_pk_bf16_f32 v82, v145, v111
	v_cvt_pk_bf16_f32 v83, v251, v252
	ds_write_b64 v170, v[82:83]
	global_load_dwordx4 v[20:23], v[244:245], off
	global_load_dwordx4 v[24:27], v[244:245], off offset:2048
	v_lshl_add_u64 v[244:245], v[244:245], 0, s[98:99]
	v_sub_f32_e32 v145, v204, v144
	v_sub_f32_e32 v111, v205, v144
	v_sub_f32_e32 v251, v206, v144
	v_sub_f32_e32 v252, v207, v144
	v_min_f32_e32 v145, 0, v145
	v_min_f32_e32 v111, 0, v111
	v_min_f32_e32 v251, 0, v251
	v_min_f32_e32 v252, 0, v252
	v_mul_f32_e32 v145, 0x3fb8aa3b, v145
	v_mul_f32_e32 v111, 0x3fb8aa3b, v111
	v_mul_f32_e32 v251, 0x3fb8aa3b, v251
	v_mul_f32_e32 v252, 0x3fb8aa3b, v252
	v_exp_f32_e32 v145, v145
	v_exp_f32_e32 v111, v111
	v_exp_f32_e32 v251, v251
	v_exp_f32_e32 v252, v252
	v_mul_f32_e32 v145, v200, v145
	v_mul_f32_e32 v111, v201, v111
	v_mul_f32_e32 v251, v202, v251
	v_mul_f32_e32 v252, v203, v252
	v_cndmask_b32_e64 v145, 0, v145, s[48:49]
	v_cndmask_b32_e64 v111, 0, v111, s[50:51]
	v_cndmask_b32_e64 v251, 0, v251, s[52:53]
	v_cndmask_b32_e64 v252, 0, v252, s[54:55]
	v_cvt_pk_bf16_f32 v82, v145, v111
	v_cvt_pk_bf16_f32 v83, v251, v252
	ds_write_b64 v172, v[82:83]
	ds_read_b128 v[80:83], v100
	ds_read_b128 v[184:187], v101 offset:34816
	ds_read_b128 v[188:191], v100 offset:64
	ds_read_b128 v[192:195], v101 offset:34880
	ds_read_b128 v[196:199], v253 offset:43520
	ds_read_b128 v[200:203], v253 offset:43584
	s_waitcnt lgkmcnt(4)
	v_mfma_f32_16x16x32_bf16 v[184:187], v[80:83], v[184:187], 0
	v_add_f32_e32 v177, v181, v182
	v_pk_mul_f32 v[78:79], v[78:79], v[114:115] op_sel_hi:[1,0]
	v_pk_mul_f32 v[76:77], v[76:77], v[114:115] op_sel_hi:[1,0]
	s_waitcnt lgkmcnt(1)
	v_mfma_f32_16x16x32_bf16 v[80:83], v[80:83], v[196:199], 0
	v_mul_f32_e64 v70, v70, v114
	v_mul_f32_e64 v71, v71, v114
	v_pk_mul_f32 v[68:69], v[68:69], v[114:115] op_sel_hi:[1,0]
	v_pk_mul_f32 v[74:75], v[74:75], v[114:115] op_sel_hi:[1,0]
	v_mfma_f32_16x16x32_bf16 v[184:187], v[188:191], v[192:195], v[184:187]
	ds_read_b128 v[192:195], v100 offset:128
	ds_read_b128 v[196:199], v101 offset:34944
	v_pk_mul_f32 v[72:73], v[72:73], v[114:115] op_sel_hi:[1,0]
	s_add_i32 s72, s1, 1
	s_waitcnt lgkmcnt(2)
	v_mfma_f32_16x16x32_bf16 v[80:83], v[188:191], v[200:203], v[80:83]
	ds_read_b128 v[188:191], v253 offset:43648
	ds_read_b128 v[200:203], v100 offset:192
	ds_read_b128 v[204:207], v101 offset:35008
	s_cmpk_lt_u32 s72, 0x7f
	s_cselect_b64 s[92:93], -1, 0
	s_waitcnt lgkmcnt(3)
	v_mfma_f32_16x16x32_bf16 v[184:187], v[192:195], v[196:199], v[184:187]
	ds_read_b128 v[196:199], v253 offset:43712
	s_waitcnt lgkmcnt(0)
	s_barrier
	v_mfma_f32_16x16x32_bf16 v[80:83], v[192:195], v[188:191], v[80:83]
	ds_read_b128 v[188:191], v147
	ds_read_b128 v[192:195], v146
	s_cmpk_gt_u32 s72, 0x7e
	v_mfma_f32_16x16x32_bf16 v[80:83], v[200:203], v[196:199], v[80:83]
	ds_read_b128 v[196:199], v127
	v_mfma_f32_16x16x32_bf16 v[182:185], v[200:203], v[204:207], v[184:187]
	ds_read_b128 v[200:203], v254 offset:4608
	ds_read_b128 v[204:207], v127 offset:64
	ds_read_b128 v[208:211], v128
	ds_read_b128 v[212:215], v128 offset:64
	ds_read_b128 v[216:219], v254 offset:4672
	s_waitcnt lgkmcnt(6)
	v_pk_mul_f32 v[82:83], v[82:83], v[194:195]
	v_pk_mul_f32 v[80:81], v[80:81], v[192:193]
	v_pk_mul_f32 v[184:185], v[184:185], v[194:195]
	v_pk_mul_f32 v[182:183], v[182:183], v[192:193]
	s_waitcnt lgkmcnt(4)
	v_mfma_f32_16x16x32_bf16 v[80:83], v[196:199], v[200:203], v[80:83]
	ds_read_b128 v[192:195], v102 offset:47872
	ds_read_b128 v[200:203], v102 offset:47936
	ds_read_b128 v[220:223], v180
	ds_read_b128 v[224:227], v180 offset:64
	s_waitcnt lgkmcnt(4)
	v_mfma_f32_16x16x32_bf16 v[80:83], v[204:207], v[216:219], v[80:83]
	global_load_dwordx4 v[16:19], v[242:243], off
	v_lshl_add_u64 v[242:243], v[242:243], 0, s[100:101]
	ds_read_b128 v[216:219], v173
	ds_read_b128 v[228:231], v173 offset:64
	ds_read_b128 v[232:235], v173 offset:2304
	ds_read_b128 v[236:239], v173 offset:2368
	v_mfma_f32_16x16x32_bf16 v[180:183], v[196:199], v[208:211], v[182:185]
	s_nop 2
	v_max_f32_e64 v251, |v80|, |v80|
	v_max_f32_e32 v80, v188, v188
	v_max_f32_e64 v111, |v83|, |v83|
	v_mfma_f32_16x16x32_bf16 v[180:183], v[204:207], v[212:215], v[180:183]
	global_load_dwordx4 v[28:31], v[246:247], off
	v_lshl_add_u64 v[246:247], v[246:247], 0, s[100:101]
	s_waitcnt lgkmcnt(0)
	v_max_f32_e64 v251, |v251|, |v251|
	v_max_f32_e32 v251, v251, v80
	v_max_f32_e64 v80, |v81|, |v81|
	v_rcp_f32_e32 v251, v251
	v_max_f32_e32 v81, v189, v189
	v_mfma_f32_16x16x32_bf16 v[76:79], v[192:195], v[220:223], v[76:79]
	s_waitcnt lgkmcnt(0)
	v_max_f32_e64 v80, |v80|, |v80|
	v_max_f32_e32 v80, v80, v81
	v_rcp_f32_e32 v80, v80
	v_max_f32_e64 v81, |v82|, |v82|
	v_mul_f32_e32 v251, v180, v251
	v_cvt_pk_bf16_f32 v251, v251, s0
	ds_write_b16 v174, v251
	v_mul_f32_e32 v251, v181, v80
	v_cvt_pk_bf16_f32 v251, v251, s0
	ds_write_b16 v174, v251 offset:80
	s_waitcnt lgkmcnt(2)
	v_max_f32_e64 v251, |v81|, |v81|
	v_max_f32_e32 v80, v190, v190
	v_max_f32_e32 v251, v251, v80
	v_rcp_f32_e32 v251, v251
	v_mfma_f32_16x16x32_bf16 v[68:71], v[192:195], v[216:219], v[68:71]
	s_mov_b64 s[94:95], exec
	s_mov_b64 exec, s[4:5]
	global_load_dwordx4 v[4:7], v[248:249], off
	s_mov_b64 exec, s[94:95]
	v_lshl_add_u64 v[248:249], v[248:249], 0, s[98:99]
	v_mul_f32_e32 v251, v182, v251
	v_mfma_f32_16x16x32_bf16 v[80:83], v[192:195], v[232:235], v[72:75]
	v_cvt_pk_bf16_f32 v251, v251, s0
	ds_write_b16 v174, v251 offset:160
	s_nop 0
	v_max_f32_e64 v72, |v111|, |v111|
	v_max_f32_e32 v73, v191, v191
	v_max_f32_e32 v72, v72, v73
	v_rcp_f32_e32 v111, v72
	v_mfma_f32_16x16x32_bf16 v[76:79], v[200:203], v[224:227], v[76:79]
	v_mul_f32_e32 v251, v183, v111
	v_mfma_f32_16x16x32_bf16 v[72:75], v[200:203], v[228:231], v[68:71]
	v_cvt_pk_bf16_f32 v251, v251, s0
	ds_write_b16 v174, v251 offset:240
	v_mfma_f32_16x16x32_bf16 v[68:71], v[200:203], v[236:239], v[80:83]
	s_nop 2
	v_cvt_pk_bf16_f32 v80, v76, v77
	v_cvt_pk_bf16_f32 v81, v78, v79
	ds_write_b64 v175, v[80:81] offset:34816
	v_cvt_pk_bf16_f32 v80, v72, v73
	v_cvt_pk_bf16_f32 v81, v74, v75
	ds_write_b64 v176, v[80:81] offset:34816
	v_cvt_pk_bf16_f32 v80, v68, v69
	v_cvt_pk_bf16_f32 v81, v70, v71
	ds_write_b64 v176, v[80:81] offset:39168
	s_cbranch_scc1 .LBB0_493
	s_waitcnt vmcnt(9)
	v_max_f32_e32 v251, v177, v177
	v_max_f32_e32 v252, v66, v66
	v_max_f32_e32 v81, v251, v252
	ds_bpermute_b32 v251, v124, v81
	ds_bpermute_b32 v80, v124, v64
	s_and_saveexec_b64 s[94:95], s[6:7]
	s_cbranch_execz .LBB0_492
	ds_write_b32 v133, v65
	ds_write_b32 v132, v81
